# also removed vmcnt(0) drain before prologue DMAs of the 64-row (TM=1) GEMM tiles
# baseline (speedup 1.0000x reference)
; #define RAW_BARRIER() do { asm volatile("s_waitcnt lgkmcnt(0)" ::: "memory"); __builtin_amdgcn_s_barrier(); } while (0)
; template <int N> DI void wait_vmcnt() { asm volatile("s_waitcnt vmcnt(%0)" ::"n"(N) : "memory"); }
;     ...
;   const int tid = threadIdx.x, lane = tid & 63, w = __builtin_amdgcn_readfirstlane(tid >> 6), wm = w >> 1, wn = w & 1;
; #pragma unroll
;   for (int i = 0; i < TM; i++)
; #pragma unroll
;     for (int j = 0; j < NJ; j++) acc[i][j] = f32x4{0.f, 0.f, 0.f, 0.f};
;   const u16* ga[NIA];
;   const u16* gb[NIB];
; #pragma unroll
;   for (int ii = 0; ii < NIA; ii++) {
;     int r = (w * NIA + ii) * 8 + (lane >> 3), c = (lane & 7) ^ ((r >> 1) & 7);
;     ga[ii] = A + (size_t)(m0 + r) * 1024 + c * 8;
;   }
; #pragma unroll
;   for (int ii = 0; ii < NIB; ii++) {
;     int r = (w * NIB + ii) * 8 + (lane >> 3), c = (lane & 7) ^ ((r >> 1) & 7);
;     gb[ii] = brow(r) + c * 8;
;   }
;   auto glds = [&](int kt, int st) {
;     char* da = smem + st * STAGE + w * (NIA * 1024);
;     char* db = smem + st * STAGE + BM * 128 + w * (NIB * 1024);
; #pragma unroll
;     for (int ii = 0; ii < NIA; ii++) __builtin_amdgcn_global_load_lds((const unsigned*)(ga[ii] + kt * 64), (unsigned*)(da + ii * 1024), 16, 0, 0);
; #pragma unroll
;     for (int ii = 0; ii < NIB; ii++) __builtin_amdgcn_global_load_lds((const unsigned*)(gb[ii] + kt * 64), (unsigned*)(db + ii * 1024), 16, 0, 0);
;   };
;   const int l15 = lane & 15, l4 = lane >> 4;
;   const int swz = (l15 >> 1) & 7;
;   __syncthreads();
;   wait_vmcnt<0>();
;   glds(0, 0);
;   if (NST == 3) glds(1, 1);
;   for (int kt = 0; kt < 16; kt++) {
;     if (NST == 3) { if (kt + 1 < 16) wait_vmcnt<NI>(); else wait_vmcnt<0>(); }
;     else wait_vmcnt<0>();
;     RAW_BARRIER();
;     if (NST == 3) { if (kt + 2 < 16) glds(kt + 2, (kt + 2) % 3); }
;     else { if (kt + 1 < 16) glds(kt + 1, (kt + 1) & 1); }
;     const char* As = smem + (NST == 3 ? kt % 3 : kt & 1) * STAGE;
; DI void phase1(const P& p, char* smem, int bid, int nb) {
;     ...
;   for (int t = bid; t < 4 * 24; t += nb) phase1_tile<1>(p, smem, TP + (t / 24) * 64, (t % 24) * 128);
.LBB0_96:
	s_mul_hi_i32 s2, s62, 0x2aaaaaab
	s_lshr_b32 s3, s2, 31
	s_ashr_i32 s2, s2, 2
	s_add_i32 s63, s2, s3
	v_readfirstlane_b32 s3, v1
	s_lshr_b32 s54, s3, 6
	s_lshl_b32 s2, s63, 6
	s_lshl_b32 s55, s54, 4
	s_mulk_i32 s63, 0xc00
	s_sub_i32 s64, s55, s63
	s_add_i32 s2, s2, 0x8000
	v_lshl_or_b32 v2, s54, 3, v187
	s_add_i32 s64, s64, s33
	v_lshrrev_b32_e32 v3, 1, v2
	v_add_u32_e32 v2, s2, v2
	v_add_u32_e32 v4, s64, v187
	v_xor_b32_e32 v8, v3, v1
	v_ashrrev_i32_e32 v3, 31, v2
	v_ashrrev_i32_e32 v5, 31, v4
	s_load_dwordx16 s[80:95], s[0:1], 0x98
	v_lshlrev_b64 v[6:7], 11, v[2:3]
	v_lshlrev_b64 v[2:3], 11, v[4:5]
	v_or3_b32 v5, s55, v187, 8
	v_lshrrev_b32_e32 v5, 1, v5
	v_add_u32_e32 v4, 8, v4
	v_xor_b32_e32 v9, v5, v1
	v_ashrrev_i32_e32 v5, 31, v4
	v_lshlrev_b64 v[4:5], 11, v[4:5]
	v_lshlrev_b32_e32 v9, 4, v9
	s_lshl_b32 s54, s54, 10
	s_waitcnt lgkmcnt(0)
	v_lshl_add_u64 v[4:5], s[94:95], 0, v[4:5]
	v_and_b32_e32 v20, 0x70, v9
	v_lshlrev_b32_e32 v8, 4, v8
	s_add_i32 s65, s54, 0
	v_lshl_add_u64 v[4:5], v[4:5], 0, v[20:21]
	v_lshl_add_u64 v[6:7], s[92:93], 0, v[6:7]
	v_and_b32_e32 v20, 0x70, v8
	s_add_i32 s67, s65, s54
	v_lshl_add_u64 v[2:3], s[94:95], 0, v[2:3]
	v_lshl_add_u64 v[6:7], v[6:7], 0, v[20:21]
	s_barrier
	s_nop 0
	s_add_i32 s54, s67, 0x2000
	s_mov_b32 m0, s65
	v_lshl_add_u64 v[2:3], v[2:3], 0, v[18:19]
	global_load_lds_dwordx4 v[6:7], off
	s_mov_b32 m0, s54
	s_add_i32 s55, s67, 0x2400
	global_load_lds_dwordx4 v[2:3], off
	s_mov_b32 m0, s55
	s_add_i32 s71, s65, 0x6000
	global_load_lds_dwordx4 v[4:5], off
	s_add_i32 s69, s67, 0x8000
	v_lshl_add_u64 v[8:9], v[6:7], 0, s[12:13]
	s_mov_b32 m0, s71
	s_add_i32 s70, s67, 0x8400
	global_load_lds_dwordx4 v[8:9], off
	v_lshl_add_u64 v[8:9], v[2:3], 0, s[12:13]
	s_mov_b32 m0, s69
	s_add_i32 s68, s65, 0xc000
	global_load_lds_dwordx4 v[8:9], off
	v_lshl_add_u64 v[8:9], v[4:5], 0, s[12:13]
	s_mov_b32 m0, s70
	s_add_i32 s66, s67, 0xe000
	global_load_lds_dwordx4 v[8:9], off
	s_waitcnt vmcnt(3)
	v_lshl_add_u64 v[8:9], v[6:7], 0, s[14:15]
	s_mov_b32 m0, s68
	s_waitcnt lgkmcnt(0)
	s_barrier
	global_load_lds_dwordx4 v[8:9], off
	v_lshl_add_u64 v[8:9], v[2:3], 0, s[14:15]
	s_mov_b32 m0, s66
	s_add_i32 s67, s67, 0xe400
	global_load_lds_dwordx4 v[8:9], off
	v_lshl_add_u64 v[8:9], v[4:5], 0, s[14:15]
	s_mov_b32 m0, s67
	s_and_b32 s64, s3, 64
	global_load_lds_dwordx4 v[8:9], off
	s_lshr_b32 s3, s3, 3
	s_and_b32 s3, s3, 0x1ffffff0
	v_or_b32_e32 v8, s3, v195
	v_or_b32_e32 v9, s64, v195
	v_lshl_add_u32 v11, v8, 7, 0
	v_lshlrev_b32_e32 v10, 7, v9
	v_add_u32_e32 v8, v11, v67
	v_add_u32_e32 v9, v87, v10
	ds_read_b128 v[12:15], v8
	ds_read_b128 v[22:25], v9 offset:8192
	ds_read_b128 v[26:29], v9 offset:10240
	ds_read_b128 v[30:33], v9 offset:12288
	ds_read_b128 v[34:37], v9 offset:14336
	v_add_u32_e32 v11, v11, v86
	v_add_u32_e32 v10, v88, v10
	ds_read_b128 v[38:41], v11
	ds_read_b128 v[42:45], v10 offset:8192
	ds_read_b128 v[46:49], v10 offset:10240
	ds_read_b128 v[50:53], v10 offset:12288
	ds_read_b128 v[54:57], v10 offset:14336
	s_waitcnt lgkmcnt(0)
	v_mfma_f32_16x16x32_bf16 v[22:25], v[22:25], v[12:15], 0
	v_mfma_f32_16x16x32_bf16 v[26:29], v[26:29], v[12:15], 0
	v_mfma_f32_16x16x32_bf16 v[30:33], v[30:33], v[12:15], 0
	v_mfma_f32_16x16x32_bf16 v[12:15], v[34:37], v[12:15], 0
	v_mfma_f32_16x16x32_bf16 v[22:25], v[42:45], v[38:41], v[22:25]
	v_mfma_f32_16x16x32_bf16 v[12:15], v[54:57], v[38:41], v[12:15]
	v_mfma_f32_16x16x32_bf16 v[26:29], v[46:49], v[38:41], v[26:29]
	v_mfma_f32_16x16x32_bf16 v[30:33], v[50:53], v[38:41], v[30:33]
	s_mov_b32 m0, s65
	s_waitcnt vmcnt(3)
	v_lshl_add_u64 v[16:17], v[6:7], 0, s[16:17]
	s_waitcnt lgkmcnt(0)
	s_barrier
	global_load_lds_dwordx4 v[16:17], off
	v_lshl_add_u64 v[16:17], v[2:3], 0, s[16:17]
	s_mov_b32 m0, s54
	s_nop 0
	global_load_lds_dwordx4 v[16:17], off
	v_lshl_add_u64 v[16:17], v[4:5], 0, s[16:17]
	s_mov_b32 m0, s55
	s_nop 0
	global_load_lds_dwordx4 v[16:17], off
	ds_read_b128 v[34:37], v8 offset:24576
	ds_read_b128 v[38:41], v9 offset:32768
	ds_read_b128 v[42:45], v9 offset:34816
	ds_read_b128 v[46:49], v9 offset:36864
	ds_read_b128 v[50:53], v9 offset:38912
	ds_read_b128 v[54:57], v11 offset:24576
	ds_read_b128 v[58:61], v10 offset:32768
	ds_read_b128 v[62:65], v10 offset:34816
	ds_read_b128 v[68:71], v10 offset:36864
	ds_read_b128 v[72:75], v10 offset:38912
	s_waitcnt lgkmcnt(0)
	v_mfma_f32_16x16x32_bf16 v[22:25], v[38:41], v[34:37], v[22:25]
	v_mfma_f32_16x16x32_bf16 v[12:15], v[50:53], v[34:37], v[12:15]
	v_mfma_f32_16x16x32_bf16 v[26:29], v[42:45], v[34:37], v[26:29]
	v_mfma_f32_16x16x32_bf16 v[30:33], v[46:49], v[34:37], v[30:33]
	v_mfma_f32_16x16x32_bf16 v[22:25], v[58:61], v[54:57], v[22:25]
	v_mfma_f32_16x16x32_bf16 v[12:15], v[72:75], v[54:57], v[12:15]
	v_mfma_f32_16x16x32_bf16 v[26:29], v[62:65], v[54:57], v[26:29]
	v_mfma_f32_16x16x32_bf16 v[30:33], v[68:71], v[54:57], v[30:33]
	s_mov_b32 m0, s71
	s_waitcnt vmcnt(3)
	v_lshl_add_u64 v[16:17], v[6:7], 0, s[18:19]
	s_waitcnt lgkmcnt(0)
	s_barrier
	global_load_lds_dwordx4 v[16:17], off
	v_lshl_add_u64 v[16:17], v[2:3], 0, s[18:19]
	s_mov_b32 m0, s69
	s_nop 0
	global_load_lds_dwordx4 v[16:17], off
	v_lshl_add_u64 v[16:17], v[4:5], 0, s[18:19]
	s_mov_b32 m0, s70
	s_nop 0
	global_load_lds_dwordx4 v[16:17], off
	ds_read_b128 v[34:37], v8 offset:49152
	ds_read_b128 v[38:41], v9 offset:57344
	ds_read_b128 v[42:45], v9 offset:59392
	ds_read_b128 v[46:49], v9 offset:61440
	ds_read_b128 v[50:53], v9 offset:63488
	ds_read_b128 v[54:57], v11 offset:49152
	ds_read_b128 v[58:61], v10 offset:57344
	ds_read_b128 v[62:65], v10 offset:59392
	ds_read_b128 v[68:71], v10 offset:61440
	ds_read_b128 v[72:75], v10 offset:63488
	s_waitcnt lgkmcnt(0)
	v_mfma_f32_16x16x32_bf16 v[22:25], v[38:41], v[34:37], v[22:25]
	v_mfma_f32_16x16x32_bf16 v[12:15], v[50:53], v[34:37], v[12:15]
	v_mfma_f32_16x16x32_bf16 v[26:29], v[42:45], v[34:37], v[26:29]
	v_mfma_f32_16x16x32_bf16 v[30:33], v[46:49], v[34:37], v[30:33]
	v_mfma_f32_16x16x32_bf16 v[22:25], v[58:61], v[54:57], v[22:25]
	v_mfma_f32_16x16x32_bf16 v[12:15], v[72:75], v[54:57], v[12:15]
	v_mfma_f32_16x16x32_bf16 v[26:29], v[62:65], v[54:57], v[26:29]
	v_mfma_f32_16x16x32_bf16 v[30:33], v[68:71], v[54:57], v[30:33]
	s_mov_b32 m0, s68
	s_waitcnt vmcnt(3)
	v_lshl_add_u64 v[16:17], v[6:7], 0, s[28:29]
	s_waitcnt lgkmcnt(0)
	s_barrier
; DI f32x4 mfma16(bf16x8 a, bf16x8 b, f32x4 c) { return __builtin_amdgcn_mfma_f32_16x16x32_bf16(a, b, c, 0, 0, 0); }
; #define RAW_BARRIER() do { asm volatile("s_waitcnt lgkmcnt(0)" ::: "memory"); __builtin_amdgcn_s_barrier(); } while (0)
; template <int N> DI void wait_vmcnt() { asm volatile("s_waitcnt vmcnt(%0)" ::"n"(N) : "memory"); }
;     ...
;   for (int kt = 0; kt < 16; kt++) {
;     if (NST == 3) { if (kt + 1 < 16) wait_vmcnt<NI>(); else wait_vmcnt<0>(); }
;     else wait_vmcnt<0>();
;     RAW_BARRIER();
;     if (NST == 3) { if (kt + 2 < 16) glds(kt + 2, (kt + 2) % 3); }
;     else { if (kt + 1 < 16) glds(kt + 1, (kt + 1) & 1); }
;     const char* As = smem + (NST == 3 ? kt % 3 : kt & 1) * STAGE;
;     const char* Bs = As + BM * 128;
;     bf16x8 af[2][TM], bfr[2][NJ];
; #pragma unroll
;     for (int kk = 0; kk < 2; kk++) {
;       const int coff = ((kk * 4 + l4) ^ swz) << 4;
; #pragma unroll
;       for (int i = 0; i < TM; i++) af[kk][i] = *(const bf16x8*)(As + (wm * (TM * 16) + i * 16 + l15) * 128 + coff);
; #pragma unroll
;       for (int j = 0; j < NJ; j++) {
;         int nrow = MERGE ? ((j >> 1) * 64 + wn * 32 + (j & 1) * 16) : (wn * 64 + j * 16);
;         bfr[kk][j] = *(const bf16x8*)(Bs + (nrow + l15) * 128 + coff);
;       }
;       __builtin_amdgcn_sched_barrier(0);
;     }
; #pragma unroll
;     for (int kk = 0; kk < 2; kk++) {
; #pragma unroll
;       for (int i = 0; i < TM; i++)
; #pragma unroll
;         for (int j = 0; j < NJ; j++) acc[i][j] = SWAP ? mfma16(bfr[kk][j], af[kk][i], acc[i][j]) : mfma16(af[kk][i], bfr[kk][j], acc[i][j]);
;       __builtin_amdgcn_sched_barrier(0);
;     }
	global_load_lds_dwordx4 v[16:17], off
	v_lshl_add_u64 v[16:17], v[2:3], 0, s[28:29]
	s_mov_b32 m0, s66
	s_nop 0
	global_load_lds_dwordx4 v[16:17], off
	v_lshl_add_u64 v[16:17], v[4:5], 0, s[28:29]
	s_mov_b32 m0, s67
	s_nop 0
	global_load_lds_dwordx4 v[16:17], off
	ds_read_b128 v[34:37], v8
	ds_read_b128 v[38:41], v9 offset:8192
	ds_read_b128 v[42:45], v9 offset:10240
	ds_read_b128 v[46:49], v9 offset:12288
	ds_read_b128 v[50:53], v9 offset:14336
	ds_read_b128 v[54:57], v11
	ds_read_b128 v[58:61], v10 offset:8192
	ds_read_b128 v[62:65], v10 offset:10240
	ds_read_b128 v[68:71], v10 offset:12288
	ds_read_b128 v[72:75], v10 offset:14336
	s_waitcnt lgkmcnt(0)
	v_mfma_f32_16x16x32_bf16 v[22:25], v[38:41], v[34:37], v[22:25]
	v_mfma_f32_16x16x32_bf16 v[12:15], v[50:53], v[34:37], v[12:15]
	v_mfma_f32_16x16x32_bf16 v[26:29], v[42:45], v[34:37], v[26:29]
	v_mfma_f32_16x16x32_bf16 v[30:33], v[46:49], v[34:37], v[30:33]
	v_mfma_f32_16x16x32_bf16 v[22:25], v[58:61], v[54:57], v[22:25]
	v_mfma_f32_16x16x32_bf16 v[12:15], v[72:75], v[54:57], v[12:15]
	v_mfma_f32_16x16x32_bf16 v[26:29], v[62:65], v[54:57], v[26:29]
	v_mfma_f32_16x16x32_bf16 v[30:33], v[68:71], v[54:57], v[30:33]
	s_mov_b32 m0, s65
	s_waitcnt vmcnt(3)
	v_lshl_add_u64 v[16:17], v[6:7], 0, s[34:35]
	s_waitcnt lgkmcnt(0)
	s_barrier
	global_load_lds_dwordx4 v[16:17], off
	v_lshl_add_u64 v[16:17], v[2:3], 0, s[34:35]
	s_mov_b32 m0, s54
	s_nop 0
	global_load_lds_dwordx4 v[16:17], off
	v_lshl_add_u64 v[16:17], v[4:5], 0, s[34:35]
	s_mov_b32 m0, s55
	s_nop 0
	global_load_lds_dwordx4 v[16:17], off
	ds_read_b128 v[34:37], v8 offset:24576
	ds_read_b128 v[38:41], v9 offset:32768
	ds_read_b128 v[42:45], v9 offset:34816
	ds_read_b128 v[46:49], v9 offset:36864
	ds_read_b128 v[50:53], v9 offset:38912
	ds_read_b128 v[54:57], v11 offset:24576
	ds_read_b128 v[58:61], v10 offset:32768
	ds_read_b128 v[62:65], v10 offset:34816
	ds_read_b128 v[68:71], v10 offset:36864
	ds_read_b128 v[72:75], v10 offset:38912
	s_waitcnt lgkmcnt(0)
	v_mfma_f32_16x16x32_bf16 v[22:25], v[38:41], v[34:37], v[22:25]
	v_mfma_f32_16x16x32_bf16 v[12:15], v[50:53], v[34:37], v[12:15]
	v_mfma_f32_16x16x32_bf16 v[26:29], v[42:45], v[34:37], v[26:29]
	v_mfma_f32_16x16x32_bf16 v[30:33], v[46:49], v[34:37], v[30:33]
	v_mfma_f32_16x16x32_bf16 v[22:25], v[58:61], v[54:57], v[22:25]
	v_mfma_f32_16x16x32_bf16 v[12:15], v[72:75], v[54:57], v[12:15]
	v_mfma_f32_16x16x32_bf16 v[26:29], v[62:65], v[54:57], v[26:29]
	v_mfma_f32_16x16x32_bf16 v[30:33], v[68:71], v[54:57], v[30:33]
	s_mov_b32 m0, s71
	s_waitcnt vmcnt(3)
	v_lshl_add_u64 v[16:17], v[6:7], 0, s[36:37]
	s_waitcnt lgkmcnt(0)
	s_barrier
	global_load_lds_dwordx4 v[16:17], off
	v_lshl_add_u64 v[16:17], v[2:3], 0, s[36:37]
	s_mov_b32 m0, s69
	s_nop 0
	global_load_lds_dwordx4 v[16:17], off
	v_lshl_add_u64 v[16:17], v[4:5], 0, s[36:37]
	s_mov_b32 m0, s70
	s_nop 0
	global_load_lds_dwordx4 v[16:17], off
	ds_read_b128 v[34:37], v8 offset:49152
	ds_read_b128 v[38:41], v9 offset:57344
	ds_read_b128 v[42:45], v9 offset:59392
	ds_read_b128 v[46:49], v9 offset:61440
	ds_read_b128 v[50:53], v9 offset:63488
	ds_read_b128 v[54:57], v11 offset:49152
	ds_read_b128 v[58:61], v10 offset:57344
	ds_read_b128 v[62:65], v10 offset:59392
	ds_read_b128 v[68:71], v10 offset:61440
	ds_read_b128 v[72:75], v10 offset:63488
	s_waitcnt lgkmcnt(0)
	v_mfma_f32_16x16x32_bf16 v[22:25], v[38:41], v[34:37], v[22:25]
	v_mfma_f32_16x16x32_bf16 v[12:15], v[50:53], v[34:37], v[12:15]
	v_mfma_f32_16x16x32_bf16 v[26:29], v[42:45], v[34:37], v[26:29]
	v_mfma_f32_16x16x32_bf16 v[30:33], v[46:49], v[34:37], v[30:33]
	v_mfma_f32_16x16x32_bf16 v[22:25], v[58:61], v[54:57], v[22:25]
	v_mfma_f32_16x16x32_bf16 v[12:15], v[72:75], v[54:57], v[12:15]
	v_mfma_f32_16x16x32_bf16 v[26:29], v[62:65], v[54:57], v[26:29]
	v_mfma_f32_16x16x32_bf16 v[30:33], v[68:71], v[54:57], v[30:33]
	s_mov_b32 m0, s68
	s_waitcnt vmcnt(3)
	v_lshl_add_u64 v[16:17], v[6:7], 0, s[38:39]
	s_waitcnt lgkmcnt(0)
	s_barrier
	global_load_lds_dwordx4 v[16:17], off
	v_lshl_add_u64 v[16:17], v[2:3], 0, s[38:39]
	s_mov_b32 m0, s66
	s_nop 0
	global_load_lds_dwordx4 v[16:17], off
	v_lshl_add_u64 v[16:17], v[4:5], 0, s[38:39]
	s_mov_b32 m0, s67
	s_nop 0
	global_load_lds_dwordx4 v[16:17], off
	ds_read_b128 v[34:37], v8
	ds_read_b128 v[38:41], v9 offset:8192
	ds_read_b128 v[42:45], v9 offset:10240
	ds_read_b128 v[46:49], v9 offset:12288
	ds_read_b128 v[50:53], v9 offset:14336
	ds_read_b128 v[54:57], v11
	ds_read_b128 v[58:61], v10 offset:8192
	ds_read_b128 v[62:65], v10 offset:10240
	ds_read_b128 v[68:71], v10 offset:12288
	ds_read_b128 v[72:75], v10 offset:14336
	s_waitcnt lgkmcnt(0)
	v_mfma_f32_16x16x32_bf16 v[22:25], v[38:41], v[34:37], v[22:25]
	v_mfma_f32_16x16x32_bf16 v[12:15], v[50:53], v[34:37], v[12:15]
	v_mfma_f32_16x16x32_bf16 v[26:29], v[42:45], v[34:37], v[26:29]
	v_mfma_f32_16x16x32_bf16 v[30:33], v[46:49], v[34:37], v[30:33]
	v_mfma_f32_16x16x32_bf16 v[22:25], v[58:61], v[54:57], v[22:25]
	v_mfma_f32_16x16x32_bf16 v[12:15], v[72:75], v[54:57], v[12:15]
	v_mfma_f32_16x16x32_bf16 v[26:29], v[62:65], v[54:57], v[26:29]
	v_mfma_f32_16x16x32_bf16 v[30:33], v[68:71], v[54:57], v[30:33]
	s_mov_b32 m0, s65
	s_waitcnt vmcnt(3)
	v_lshl_add_u64 v[16:17], v[6:7], 0, s[40:41]
	s_waitcnt lgkmcnt(0)
	s_barrier
; DI f32x4 mfma16(bf16x8 a, bf16x8 b, f32x4 c) { return __builtin_amdgcn_mfma_f32_16x16x32_bf16(a, b, c, 0, 0, 0); }
; #define RAW_BARRIER() do { asm volatile("s_waitcnt lgkmcnt(0)" ::: "memory"); __builtin_amdgcn_s_barrier(); } while (0)
; template <int N> DI void wait_vmcnt() { asm volatile("s_waitcnt vmcnt(%0)" ::"n"(N) : "memory"); }
;     ...
;   for (int kt = 0; kt < 16; kt++) {
;     if (NST == 3) { if (kt + 1 < 16) wait_vmcnt<NI>(); else wait_vmcnt<0>(); }
;     else wait_vmcnt<0>();
;     RAW_BARRIER();
;     if (NST == 3) { if (kt + 2 < 16) glds(kt + 2, (kt + 2) % 3); }
;     else { if (kt + 1 < 16) glds(kt + 1, (kt + 1) & 1); }
;     const char* As = smem + (NST == 3 ? kt % 3 : kt & 1) * STAGE;
;     const char* Bs = As + BM * 128;
;     bf16x8 af[2][TM], bfr[2][NJ];
; #pragma unroll
;     for (int kk = 0; kk < 2; kk++) {
;       const int coff = ((kk * 4 + l4) ^ swz) << 4;
; #pragma unroll
;       for (int i = 0; i < TM; i++) af[kk][i] = *(const bf16x8*)(As + (wm * (TM * 16) + i * 16 + l15) * 128 + coff);
; #pragma unroll
;       for (int j = 0; j < NJ; j++) {
;         int nrow = MERGE ? ((j >> 1) * 64 + wn * 32 + (j & 1) * 16) : (wn * 64 + j * 16);
;         bfr[kk][j] = *(const bf16x8*)(Bs + (nrow + l15) * 128 + coff);
;       }
;       __builtin_amdgcn_sched_barrier(0);
;     }
; #pragma unroll
;     for (int kk = 0; kk < 2; kk++) {
; #pragma unroll
;       for (int i = 0; i < TM; i++)
; #pragma unroll
;         for (int j = 0; j < NJ; j++) acc[i][j] = SWAP ? mfma16(bfr[kk][j], af[kk][i], acc[i][j]) : mfma16(af[kk][i], bfr[kk][j], acc[i][j]);
;       __builtin_amdgcn_sched_barrier(0);
;     }
	global_load_lds_dwordx4 v[16:17], off
	v_lshl_add_u64 v[16:17], v[2:3], 0, s[40:41]
	s_mov_b32 m0, s54
	s_nop 0
	global_load_lds_dwordx4 v[16:17], off
	v_lshl_add_u64 v[16:17], v[4:5], 0, s[40:41]
	s_mov_b32 m0, s55
	s_nop 0
	global_load_lds_dwordx4 v[16:17], off
	ds_read_b128 v[34:37], v8 offset:24576
	ds_read_b128 v[38:41], v9 offset:32768
	ds_read_b128 v[42:45], v9 offset:34816
	ds_read_b128 v[46:49], v9 offset:36864
	ds_read_b128 v[50:53], v9 offset:38912
	ds_read_b128 v[54:57], v11 offset:24576
	ds_read_b128 v[58:61], v10 offset:32768
	ds_read_b128 v[62:65], v10 offset:34816
	ds_read_b128 v[68:71], v10 offset:36864
	ds_read_b128 v[72:75], v10 offset:38912
	s_waitcnt lgkmcnt(0)
	v_mfma_f32_16x16x32_bf16 v[22:25], v[38:41], v[34:37], v[22:25]
	v_mfma_f32_16x16x32_bf16 v[12:15], v[50:53], v[34:37], v[12:15]
	v_mfma_f32_16x16x32_bf16 v[26:29], v[42:45], v[34:37], v[26:29]
	v_mfma_f32_16x16x32_bf16 v[30:33], v[46:49], v[34:37], v[30:33]
	v_mfma_f32_16x16x32_bf16 v[22:25], v[58:61], v[54:57], v[22:25]
	v_mfma_f32_16x16x32_bf16 v[12:15], v[72:75], v[54:57], v[12:15]
	v_mfma_f32_16x16x32_bf16 v[26:29], v[62:65], v[54:57], v[26:29]
	v_mfma_f32_16x16x32_bf16 v[30:33], v[68:71], v[54:57], v[30:33]
	s_mov_b32 m0, s71
	s_waitcnt vmcnt(3)
	v_lshl_add_u64 v[16:17], v[6:7], 0, s[42:43]
	s_waitcnt lgkmcnt(0)
	s_barrier
	global_load_lds_dwordx4 v[16:17], off
	v_lshl_add_u64 v[16:17], v[2:3], 0, s[42:43]
	s_mov_b32 m0, s69
	s_nop 0
	global_load_lds_dwordx4 v[16:17], off
	v_lshl_add_u64 v[16:17], v[4:5], 0, s[42:43]
	s_mov_b32 m0, s70
	s_nop 0
	global_load_lds_dwordx4 v[16:17], off
	ds_read_b128 v[34:37], v8 offset:49152
	ds_read_b128 v[38:41], v9 offset:57344
	ds_read_b128 v[42:45], v9 offset:59392
	ds_read_b128 v[46:49], v9 offset:61440
	ds_read_b128 v[50:53], v9 offset:63488
	ds_read_b128 v[54:57], v11 offset:49152
	ds_read_b128 v[58:61], v10 offset:57344
	ds_read_b128 v[62:65], v10 offset:59392
	ds_read_b128 v[68:71], v10 offset:61440
	ds_read_b128 v[72:75], v10 offset:63488
	s_waitcnt lgkmcnt(0)
	v_mfma_f32_16x16x32_bf16 v[22:25], v[38:41], v[34:37], v[22:25]
	v_mfma_f32_16x16x32_bf16 v[12:15], v[50:53], v[34:37], v[12:15]
	v_mfma_f32_16x16x32_bf16 v[26:29], v[42:45], v[34:37], v[26:29]
	v_mfma_f32_16x16x32_bf16 v[30:33], v[46:49], v[34:37], v[30:33]
	v_mfma_f32_16x16x32_bf16 v[22:25], v[58:61], v[54:57], v[22:25]
	v_mfma_f32_16x16x32_bf16 v[12:15], v[72:75], v[54:57], v[12:15]
	v_mfma_f32_16x16x32_bf16 v[26:29], v[62:65], v[54:57], v[26:29]
	v_mfma_f32_16x16x32_bf16 v[30:33], v[68:71], v[54:57], v[30:33]
	s_mov_b32 m0, s68
	s_waitcnt vmcnt(3)
	v_lshl_add_u64 v[16:17], v[6:7], 0, s[44:45]
	s_waitcnt lgkmcnt(0)
	s_barrier
	global_load_lds_dwordx4 v[16:17], off
	v_lshl_add_u64 v[16:17], v[2:3], 0, s[44:45]
	s_mov_b32 m0, s66
	s_nop 0
	global_load_lds_dwordx4 v[16:17], off
	v_lshl_add_u64 v[16:17], v[4:5], 0, s[44:45]
	s_mov_b32 m0, s67
	s_nop 0
	global_load_lds_dwordx4 v[16:17], off
	ds_read_b128 v[34:37], v8
	ds_read_b128 v[38:41], v9 offset:8192
	ds_read_b128 v[42:45], v9 offset:10240
	ds_read_b128 v[46:49], v9 offset:12288
	ds_read_b128 v[50:53], v9 offset:14336
	ds_read_b128 v[54:57], v11
	ds_read_b128 v[58:61], v10 offset:8192
	ds_read_b128 v[62:65], v10 offset:10240
	ds_read_b128 v[68:71], v10 offset:12288
	ds_read_b128 v[72:75], v10 offset:14336
	s_waitcnt lgkmcnt(0)
	v_mfma_f32_16x16x32_bf16 v[22:25], v[38:41], v[34:37], v[22:25]
	v_mfma_f32_16x16x32_bf16 v[12:15], v[50:53], v[34:37], v[12:15]
	v_mfma_f32_16x16x32_bf16 v[26:29], v[42:45], v[34:37], v[26:29]
	v_mfma_f32_16x16x32_bf16 v[30:33], v[46:49], v[34:37], v[30:33]
	v_mfma_f32_16x16x32_bf16 v[22:25], v[58:61], v[54:57], v[22:25]
	v_mfma_f32_16x16x32_bf16 v[12:15], v[72:75], v[54:57], v[12:15]
	v_mfma_f32_16x16x32_bf16 v[26:29], v[62:65], v[54:57], v[26:29]
	v_mfma_f32_16x16x32_bf16 v[30:33], v[68:71], v[54:57], v[30:33]
	s_mov_b32 m0, s65
	s_waitcnt vmcnt(3)
	v_lshl_add_u64 v[16:17], v[6:7], 0, s[46:47]
	s_waitcnt lgkmcnt(0)
	s_barrier
	global_load_lds_dwordx4 v[16:17], off
	v_lshl_add_u64 v[16:17], v[2:3], 0, s[46:47]
	s_mov_b32 m0, s54
	s_nop 0
	global_load_lds_dwordx4 v[16:17], off
	v_lshl_add_u64 v[16:17], v[4:5], 0, s[46:47]
	s_mov_b32 m0, s55
	s_nop 0
	global_load_lds_dwordx4 v[16:17], off
	ds_read_b128 v[34:37], v8 offset:24576
	ds_read_b128 v[38:41], v9 offset:32768
	ds_read_b128 v[42:45], v9 offset:34816
	ds_read_b128 v[46:49], v9 offset:36864
	ds_read_b128 v[50:53], v9 offset:38912
	ds_read_b128 v[54:57], v11 offset:24576
	ds_read_b128 v[58:61], v10 offset:32768
	ds_read_b128 v[62:65], v10 offset:34816
	ds_read_b128 v[68:71], v10 offset:36864
	ds_read_b128 v[72:75], v10 offset:38912
	s_waitcnt lgkmcnt(0)
	v_mfma_f32_16x16x32_bf16 v[22:25], v[38:41], v[34:37], v[22:25]
	v_mfma_f32_16x16x32_bf16 v[12:15], v[50:53], v[34:37], v[12:15]
	v_mfma_f32_16x16x32_bf16 v[26:29], v[42:45], v[34:37], v[26:29]
	v_mfma_f32_16x16x32_bf16 v[30:33], v[46:49], v[34:37], v[30:33]
	v_mfma_f32_16x16x32_bf16 v[22:25], v[58:61], v[54:57], v[22:25]
	v_mfma_f32_16x16x32_bf16 v[12:15], v[72:75], v[54:57], v[12:15]
	v_mfma_f32_16x16x32_bf16 v[26:29], v[62:65], v[54:57], v[26:29]
	v_mfma_f32_16x16x32_bf16 v[30:33], v[68:71], v[54:57], v[30:33]
	s_mov_b32 m0, s71
	s_waitcnt vmcnt(3)
	v_lshl_add_u64 v[16:17], v[6:7], 0, s[48:49]
	s_waitcnt lgkmcnt(0)
	s_barrier
; DI f32x4 mfma16(bf16x8 a, bf16x8 b, f32x4 c) { return __builtin_amdgcn_mfma_f32_16x16x32_bf16(a, b, c, 0, 0, 0); }
; #define RAW_BARRIER() do { asm volatile("s_waitcnt lgkmcnt(0)" ::: "memory"); __builtin_amdgcn_s_barrier(); } while (0)
; template <int N> DI void wait_vmcnt() { asm volatile("s_waitcnt vmcnt(%0)" ::"n"(N) : "memory"); }
;     ...
;   for (int kt = 0; kt < 16; kt++) {
;     if (NST == 3) { if (kt + 1 < 16) wait_vmcnt<NI>(); else wait_vmcnt<0>(); }
;     else wait_vmcnt<0>();
;     RAW_BARRIER();
;     if (NST == 3) { if (kt + 2 < 16) glds(kt + 2, (kt + 2) % 3); }
;     else { if (kt + 1 < 16) glds(kt + 1, (kt + 1) & 1); }
;     const char* As = smem + (NST == 3 ? kt % 3 : kt & 1) * STAGE;
;     const char* Bs = As + BM * 128;
;     bf16x8 af[2][TM], bfr[2][NJ];
; #pragma unroll
;     for (int kk = 0; kk < 2; kk++) {
;       const int coff = ((kk * 4 + l4) ^ swz) << 4;
; #pragma unroll
;       for (int i = 0; i < TM; i++) af[kk][i] = *(const bf16x8*)(As + (wm * (TM * 16) + i * 16 + l15) * 128 + coff);
; #pragma unroll
;       for (int j = 0; j < NJ; j++) {
;         int nrow = MERGE ? ((j >> 1) * 64 + wn * 32 + (j & 1) * 16) : (wn * 64 + j * 16);
;         bfr[kk][j] = *(const bf16x8*)(Bs + (nrow + l15) * 128 + coff);
;       }
;       __builtin_amdgcn_sched_barrier(0);
;     }
; #pragma unroll
;     for (int kk = 0; kk < 2; kk++) {
; #pragma unroll
;       for (int i = 0; i < TM; i++)
; #pragma unroll
;         for (int j = 0; j < NJ; j++) acc[i][j] = SWAP ? mfma16(bfr[kk][j], af[kk][i], acc[i][j]) : mfma16(af[kk][i], bfr[kk][j], acc[i][j]);
;       __builtin_amdgcn_sched_barrier(0);
;     }
	global_load_lds_dwordx4 v[16:17], off
	v_lshl_add_u64 v[16:17], v[2:3], 0, s[48:49]
	s_mov_b32 m0, s69
	s_nop 0
	global_load_lds_dwordx4 v[16:17], off
	v_lshl_add_u64 v[16:17], v[4:5], 0, s[48:49]
	s_mov_b32 m0, s70
	s_nop 0
	global_load_lds_dwordx4 v[16:17], off
	ds_read_b128 v[34:37], v8 offset:49152
	ds_read_b128 v[38:41], v9 offset:57344
	ds_read_b128 v[42:45], v9 offset:59392
	ds_read_b128 v[46:49], v9 offset:61440
	ds_read_b128 v[50:53], v9 offset:63488
	ds_read_b128 v[54:57], v11 offset:49152
	ds_read_b128 v[58:61], v10 offset:57344
	ds_read_b128 v[62:65], v10 offset:59392
	ds_read_b128 v[68:71], v10 offset:61440
	ds_read_b128 v[72:75], v10 offset:63488
	s_waitcnt lgkmcnt(0)
	v_mfma_f32_16x16x32_bf16 v[22:25], v[38:41], v[34:37], v[22:25]
	v_mfma_f32_16x16x32_bf16 v[12:15], v[50:53], v[34:37], v[12:15]
	v_mfma_f32_16x16x32_bf16 v[26:29], v[42:45], v[34:37], v[26:29]
	v_mfma_f32_16x16x32_bf16 v[30:33], v[46:49], v[34:37], v[30:33]
	v_mfma_f32_16x16x32_bf16 v[22:25], v[58:61], v[54:57], v[22:25]
	v_mfma_f32_16x16x32_bf16 v[12:15], v[72:75], v[54:57], v[12:15]
	v_mfma_f32_16x16x32_bf16 v[26:29], v[62:65], v[54:57], v[26:29]
	v_mfma_f32_16x16x32_bf16 v[30:33], v[68:71], v[54:57], v[30:33]
	s_mov_b32 m0, s68
	s_waitcnt vmcnt(3)
	v_lshl_add_u64 v[16:17], v[6:7], 0, s[50:51]
	s_waitcnt lgkmcnt(0)
	s_barrier
	global_load_lds_dwordx4 v[16:17], off
	v_lshl_add_u64 v[16:17], v[2:3], 0, s[50:51]
	s_mov_b32 m0, s66
	s_nop 0
	global_load_lds_dwordx4 v[16:17], off
	v_lshl_add_u64 v[16:17], v[4:5], 0, s[50:51]
	s_mov_b32 m0, s67
	s_nop 0
	global_load_lds_dwordx4 v[16:17], off
	ds_read_b128 v[34:37], v8
	ds_read_b128 v[38:41], v9 offset:8192
	ds_read_b128 v[42:45], v9 offset:10240
	ds_read_b128 v[46:49], v9 offset:12288
	ds_read_b128 v[50:53], v9 offset:14336
	ds_read_b128 v[54:57], v11
	ds_read_b128 v[58:61], v10 offset:8192
	ds_read_b128 v[62:65], v10 offset:10240
	ds_read_b128 v[68:71], v10 offset:12288
	ds_read_b128 v[72:75], v10 offset:14336
	s_waitcnt lgkmcnt(0)
	v_mfma_f32_16x16x32_bf16 v[22:25], v[38:41], v[34:37], v[22:25]
	v_mfma_f32_16x16x32_bf16 v[12:15], v[50:53], v[34:37], v[12:15]
	v_mfma_f32_16x16x32_bf16 v[26:29], v[42:45], v[34:37], v[26:29]
	v_mfma_f32_16x16x32_bf16 v[30:33], v[46:49], v[34:37], v[30:33]
	v_mfma_f32_16x16x32_bf16 v[22:25], v[58:61], v[54:57], v[22:25]
	v_mfma_f32_16x16x32_bf16 v[12:15], v[72:75], v[54:57], v[12:15]
	v_mfma_f32_16x16x32_bf16 v[26:29], v[62:65], v[54:57], v[26:29]
	v_mfma_f32_16x16x32_bf16 v[30:33], v[68:71], v[54:57], v[30:33]
	s_mov_b32 m0, s65
	s_waitcnt vmcnt(3)
	v_lshl_add_u64 v[6:7], v[6:7], 0, s[52:53]
	s_waitcnt lgkmcnt(0)
	s_barrier
	global_load_lds_dwordx4 v[6:7], off
	v_lshl_add_u64 v[2:3], v[2:3], 0, s[52:53]
	s_mov_b32 m0, s54
	s_nop 0
	global_load_lds_dwordx4 v[2:3], off
	v_lshl_add_u64 v[2:3], v[4:5], 0, s[52:53]
	s_mov_b32 m0, s55
	s_nop 0
	global_load_lds_dwordx4 v[2:3], off
	ds_read_b128 v[2:5], v8 offset:24576
	ds_read_b128 v[34:37], v9 offset:32768
	ds_read_b128 v[38:41], v9 offset:34816
	ds_read_b128 v[42:45], v9 offset:36864
	ds_read_b128 v[46:49], v9 offset:38912
	ds_read_b128 v[50:53], v11 offset:24576
	ds_read_b128 v[54:57], v10 offset:32768
	ds_read_b128 v[58:61], v10 offset:34816
	ds_read_b128 v[62:65], v10 offset:36864
	ds_read_b128 v[68:71], v10 offset:38912
	s_waitcnt lgkmcnt(0)
	v_mfma_f32_16x16x32_bf16 v[22:25], v[34:37], v[2:5], v[22:25]
	v_mfma_f32_16x16x32_bf16 v[26:29], v[38:41], v[2:5], v[26:29]
	v_mfma_f32_16x16x32_bf16 v[30:33], v[42:45], v[2:5], v[30:33]
	v_mfma_f32_16x16x32_bf16 v[2:5], v[46:49], v[2:5], v[12:15]
	v_mfma_f32_16x16x32_bf16 v[12:15], v[54:57], v[50:53], v[22:25]
	v_mfma_f32_16x16x32_bf16 v[22:25], v[58:61], v[50:53], v[26:29]
	v_mfma_f32_16x16x32_bf16 v[2:5], v[68:71], v[50:53], v[2:5]
	v_mfma_f32_16x16x32_bf16 v[26:29], v[62:65], v[50:53], v[30:33]
	s_waitcnt vmcnt(3)
	s_waitcnt lgkmcnt(0)
	s_barrier
; DI u32 pack2(float a, float b) { f32x2 v = {a, b}; bfx2 r = __builtin_convertvector(v, bfx2); return __builtin_bit_cast(u32, r); }
; DI f32x4 mfma16(bf16x8 a, bf16x8 b, f32x4 c) { return __builtin_amdgcn_mfma_f32_16x16x32_bf16(a, b, c, 0, 0, 0); }
;     ...
;   for (int kt = 0; kt < 16; kt++) {
;     if (NST == 3) { if (kt + 1 < 16) wait_vmcnt<NI>(); else wait_vmcnt<0>(); }
;     else wait_vmcnt<0>();
;     RAW_BARRIER();
;     if (NST == 3) { if (kt + 2 < 16) glds(kt + 2, (kt + 2) % 3); }
;     else { if (kt + 1 < 16) glds(kt + 1, (kt + 1) & 1); }
;     const char* As = smem + (NST == 3 ? kt % 3 : kt & 1) * STAGE;
;     const char* Bs = As + BM * 128;
;     bf16x8 af[2][TM], bfr[2][NJ];
; #pragma unroll
;     for (int kk = 0; kk < 2; kk++) {
;       const int coff = ((kk * 4 + l4) ^ swz) << 4;
; #pragma unroll
;       for (int i = 0; i < TM; i++) af[kk][i] = *(const bf16x8*)(As + (wm * (TM * 16) + i * 16 + l15) * 128 + coff);
; #pragma unroll
;       for (int j = 0; j < NJ; j++) {
;         int nrow = MERGE ? ((j >> 1) * 64 + wn * 32 + (j & 1) * 16) : (wn * 64 + j * 16);
;         bfr[kk][j] = *(const bf16x8*)(Bs + (nrow + l15) * 128 + coff);
;       }
;       __builtin_amdgcn_sched_barrier(0);
;     }
; #pragma unroll
;     for (int kk = 0; kk < 2; kk++) {
; #pragma unroll
;       for (int i = 0; i < TM; i++)
; #pragma unroll
;         for (int j = 0; j < NJ; j++) acc[i][j] = SWAP ? mfma16(bfr[kk][j], af[kk][i], acc[i][j]) : mfma16(af[kk][i], bfr[kk][j], acc[i][j]);
;       __builtin_amdgcn_sched_barrier(0);
;     }
;   }
;   __syncthreads();
; template <int TM>
; DI void phase1_tile(const P& p, char* smem, int m0, int n0) {
;     ...
; #pragma unroll
;   for (int i = 0; i < TM; i++) {
;     int tok = m0 + wm * (TM * 16) + i * 16 + (lane & 15);
;     float* cdst = nullptr;
;     if (tok < TP) { int b = tok >> 14, tt = tok & 16383; if (tt >= 16381) cdst = p.out + O_CP + (size_t)(b * 3 + tt - 16381) * 3072; }
;     else { int s = (tok - TP) >> 4, tt = tok & 15; if (tt >= 13) cdst = p.out + O_CS + (size_t)(s * 3 + tt - 13) * 3072; }
; #pragma unroll
;     for (int j = 0; j < 4; j++) {
;       int n = n0 + wn * 64 + j * 16 + 4 * (lane >> 4);
;       f32x4 a = acc[i][j];
;       u32x2 o = {pack2(a[0], a[1]), pack2(a[2], a[3])};
;       *(u32x2*)(QKV + (size_t)tok * 3072 + n) = o;
;       if (cdst) *(float4*)(cdst + n) = make_float4(a[0], a[1], a[2], a[3]);
	s_nop 1
	ds_read_b128 v[30:33], v9 offset:63488
	ds_read_b128 v[34:37], v9 offset:61440
	ds_read_b128 v[38:41], v9 offset:59392
	ds_read_b128 v[42:45], v9 offset:57344
	ds_read_b128 v[46:49], v8 offset:49152
	ds_read_b128 v[50:53], v11 offset:49152
	ds_read_b128 v[54:57], v10 offset:57344
	ds_read_b128 v[58:61], v10 offset:59392
	ds_read_b128 v[62:65], v10 offset:61440
	ds_read_b128 v[68:71], v10 offset:63488
	s_waitcnt lgkmcnt(0)
	v_mfma_f32_16x16x32_bf16 v[12:15], v[42:45], v[46:49], v[12:15]
	v_mfma_f32_16x16x32_bf16 v[22:25], v[38:41], v[46:49], v[22:25]
	v_mfma_f32_16x16x32_bf16 v[2:5], v[30:33], v[46:49], v[2:5]
	v_mfma_f32_16x16x32_bf16 v[26:29], v[34:37], v[46:49], v[26:29]
	v_mfma_f32_16x16x32_bf16 v[12:15], v[54:57], v[50:53], v[12:15]
	v_mfma_f32_16x16x32_bf16 v[22:25], v[58:61], v[50:53], v[22:25]
	v_mfma_f32_16x16x32_bf16 v[2:5], v[68:71], v[50:53], v[2:5]
	v_mfma_f32_16x16x32_bf16 v[26:29], v[62:65], v[50:53], v[26:29]
	s_waitcnt vmcnt(0)
	s_waitcnt lgkmcnt(0)
	s_barrier
	ds_read_b128 v[30:33], v9 offset:14336
	ds_read_b128 v[34:37], v9 offset:12288
	ds_read_b128 v[38:41], v9 offset:10240
	ds_read_b128 v[42:45], v9 offset:8192
	ds_read_b128 v[6:9], v8
	ds_read_b128 v[46:49], v11
	ds_read_b128 v[50:53], v10 offset:8192
	ds_read_b128 v[54:57], v10 offset:10240
	ds_read_b128 v[58:61], v10 offset:12288
	ds_read_b128 v[62:65], v10 offset:14336
	s_waitcnt lgkmcnt(0)
	v_mfma_f32_16x16x32_bf16 v[10:13], v[42:45], v[6:9], v[12:15]
	v_mfma_f32_16x16x32_bf16 v[22:25], v[38:41], v[6:9], v[22:25]
	v_mfma_f32_16x16x32_bf16 v[2:5], v[30:33], v[6:9], v[2:5]
	v_mfma_f32_16x16x32_bf16 v[26:29], v[34:37], v[6:9], v[26:29]
	v_mfma_f32_16x16x32_bf16 v[14:17], v[50:53], v[46:49], v[10:13]
	v_mfma_f32_16x16x32_bf16 v[10:13], v[54:57], v[46:49], v[22:25]
	v_mfma_f32_16x16x32_bf16 v[6:9], v[58:61], v[46:49], v[26:29]
	v_mfma_f32_16x16x32_bf16 v[2:5], v[62:65], v[46:49], v[2:5]
	v_or_b32_e32 v20, s2, v195
	v_add_u32_e32 v20, s3, v20
	v_cmp_lt_i32_e64 s[2:3], s57, v20
	s_waitcnt vmcnt(0)
	s_barrier
	s_and_saveexec_b64 s[54:55], s[2:3]
	s_xor_b64 s[2:3], exec, s[54:55]
	v_add_u32_e32 v22, 0xffff8000, v20
	v_lshrrev_b32_e32 v22, 4, v22
	v_mad_u64_u32 v[22:23], s[54:55], v22, 3, v[66:67]
	v_mov_b64_e32 v[24:25], s[8:9]
	v_mad_u64_u32 v[22:23], s[54:55], v22, s58, v[24:25]
	v_cndmask_b32_e32 v23, 0, v23, vcc
	v_cndmask_b32_e32 v22, 0, v22, vcc
	s_andn2_saveexec_b64 s[54:55], s[2:3]
	v_ashrrev_i32_e32 v22, 14, v20
	v_and_b32_e32 v24, 0x3fff, v20
	v_mul_i32_i24_e32 v22, 3, v22
	v_add3_u32 v25, v24, v22, s59
	v_mov_b64_e32 v[22:23], s[10:11]
	v_mad_i64_i32 v[22:23], s[2:3], v25, s58, v[22:23]
	v_cmp_lt_u32_e64 s[2:3], s60, v24
	s_nop 1
	v_cndmask_b32_e64 v23, 0, v23, s[2:3]
	v_cndmask_b32_e64 v22, 0, v22, s[2:3]
	s_or_b64 exec, exec, s[54:55]
	s_sub_i32 s2, s64, s63
	s_add_i32 s2, s2, s33
	v_add_u32_e32 v26, s2, v89
	v_mov_b64_e32 v[24:25], s[6:7]
	v_mad_i64_i32 v[24:25], s[2:3], v20, s61, v[24:25]
	v_ashrrev_i32_e32 v27, 31, v26
	v_cmp_ne_u64_e64 s[2:3], 0, v[22:23]
	v_cvt_pk_bf16_f32 v28, v14, v15
	v_cvt_pk_bf16_f32 v29, v16, v17
	v_lshl_add_u64 v[24:25], v[26:27], 1, v[24:25]
	v_lshl_add_u64 v[22:23], v[26:27], 2, v[22:23]
	global_store_dwordx2 v[24:25], v[28:29], off
	s_and_saveexec_b64 s[54:55], s[2:3]
	s_cbranch_execz .LBB0_102
	global_store_dwordx4 v[22:23], v[14:17], off

;     ...
;   const int tid = threadIdx.x, lane = tid & 63, w = __builtin_amdgcn_readfirstlane(tid >> 6), wm = w >> 1, wn = w & 1;
; #pragma unroll
;   for (int i = 0; i < TM; i++)
; #pragma unroll
;     for (int j = 0; j < NJ; j++) acc[i][j] = f32x4{0.f, 0.f, 0.f, 0.f};
;   const u16* ga[NIA];
;   const u16* gb[NIB];
; #pragma unroll
;   for (int ii = 0; ii < NIA; ii++) {
;     int r = (w * NIA + ii) * 8 + (lane >> 3), c = (lane & 7) ^ ((r >> 1) & 7);
;     ga[ii] = A + (size_t)(m0 + r) * 1024 + c * 8;
;   }
; #pragma unroll
;   for (int ii = 0; ii < NIB; ii++) {
;     int r = (w * NIB + ii) * 8 + (lane >> 3), c = (lane & 7) ^ ((r >> 1) & 7);
;     gb[ii] = brow(r) + c * 8;
;   }
;   auto glds = [&](int kt, int st) {
;     char* da = smem + st * STAGE + w * (NIA * 1024);
;     char* db = smem + st * STAGE + BM * 128 + w * (NIB * 1024);
; #pragma unroll
;     for (int ii = 0; ii < NIA; ii++) __builtin_amdgcn_global_load_lds((const unsigned*)(ga[ii] + kt * 64), (unsigned*)(da + ii * 1024), 16, 0, 0);
; #pragma unroll
;     for (int ii = 0; ii < NIB; ii++) __builtin_amdgcn_global_load_lds((const unsigned*)(gb[ii] + kt * 64), (unsigned*)(db + ii * 1024), 16, 0, 0);
;   };
;   const int l15 = lane & 15, l4 = lane >> 4;
;   const int swz = (l15 >> 1) & 7;
;   __syncthreads();
;   wait_vmcnt<0>();
;   glds(0, 0);
;   if (NST == 3) glds(1, 1);
;   for (int kt = 0; kt < 16; kt++) {
;     if (NST == 3) { if (kt + 1 < 16) wait_vmcnt<NI>(); else wait_vmcnt<0>(); }
;     else wait_vmcnt<0>();
;     RAW_BARRIER();
;     if (NST == 3) { if (kt + 2 < 16) glds(kt + 2, (kt + 2) % 3); }
;     else { if (kt + 1 < 16) glds(kt + 1, (kt + 1) & 1); }
;     const char* As = smem + (NST == 3 ? kt % 3 : kt & 1) * STAGE;
;     const char* Bs = As + BM * 128;
;     bf16x8 af[2][TM], bfr[2][NJ];
; #pragma unroll
;     for (int kk = 0; kk < 2; kk++) {
;       const int coff = ((kk * 4 + l4) ^ swz) << 4;
; #pragma unroll
;       for (int i = 0; i < TM; i++) af[kk][i] = *(const bf16x8*)(As + (wm * (TM * 16) + i * 16 + l15) * 128 + coff);
; #pragma unroll
;       for (int j = 0; j < NJ; j++) {
;         int nrow = MERGE ? ((j >> 1) * 64 + wn * 32 + (j & 1) * 16) : (wn * 64 + j * 16);
;         bfr[kk][j] = *(const bf16x8*)(Bs + (nrow + l15) * 128 + coff);
;       }
;       __builtin_amdgcn_sched_barrier(0);
;     }
; #pragma unroll
;     for (int kk = 0; kk < 2; kk++) {
; #pragma unroll
.LBB0_526:
	s_ashr_i32 s0, s2, 31
	s_lshr_b32 s0, s0, 29
	s_add_i32 s0, s2, s0
	v_readfirstlane_b32 s79, v188
	s_ashr_i32 s0, s0, 3
	s_lshr_b32 s69, s79, 6
	s_lshl_b32 s68, s0, 6
	v_lshl_or_b32 v2, s69, 3, v1
	s_add_i32 s68, s68, 0x8000
	v_lshrrev_b32_e32 v6, 1, v2
	s_lshl_b32 s0, s0, 10
	v_xor_b32_e32 v17, v6, v188
	v_add_u32_e32 v6, s68, v2
	s_sub_i32 s67, s3, s0
	v_ashrrev_i32_e32 v7, 31, v6
	v_lshl_or_b32 v2, s69, 4, v1
	s_add_i32 s0, s67, 0x1010
	v_lshlrev_b64 v[10:11], 11, v[6:7]
	v_lshlrev_b64 v[6:7], 11, v[2:3]
	v_or_b32_e32 v2, 8, v2
	s_lshl_b64 s[70:71], s[0:1], 11
	v_lshrrev_b32_e32 v8, 1, v2
	s_add_u32 s70, s82, s70
	v_xor_b32_e32 v18, v8, v188
	s_addc_u32 s71, s83, s71
	v_lshlrev_b64 v[8:9], 11, v[2:3]
	v_lshlrev_b32_e32 v2, 4, v18
	v_lshl_add_u64 v[8:9], s[70:71], 0, v[8:9]
	v_and_b32_e32 v2, 0x70, v2
	s_lshl_b32 s0, s69, 10
	v_lshl_add_u64 v[8:9], v[8:9], 0, v[2:3]
	v_lshlrev_b32_e32 v2, 4, v17
	s_add_i32 s72, s0, 0
	v_lshl_add_u64 v[10:11], s[80:81], 0, v[10:11]
	v_and_b32_e32 v2, 0x70, v2
	s_add_i32 s74, s72, s0
	v_lshl_add_u64 v[6:7], s[70:71], 0, v[6:7]
	v_lshl_add_u64 v[10:11], v[10:11], 0, v[2:3]
	s_barrier
	s_nop 0
	s_add_i32 s70, s74, 0x2000
	s_mov_b32 m0, s72
	v_lshl_add_u64 v[6:7], v[6:7], 0, v[4:5]
	global_load_lds_dwordx4 v[10:11], off
	s_mov_b32 m0, s70
	s_add_i32 s71, s74, 0x2400
	global_load_lds_dwordx4 v[6:7], off
	s_mov_b32 m0, s71
	s_add_i32 s78, s72, 0x6000
	global_load_lds_dwordx4 v[8:9], off
	s_add_i32 s76, s74, 0x8000
	v_lshl_add_u64 v[18:19], v[10:11], 0, s[6:7]
	s_mov_b32 m0, s78
	s_add_i32 s77, s74, 0x8400
	global_load_lds_dwordx4 v[18:19], off
	v_lshl_add_u64 v[18:19], v[6:7], 0, s[6:7]
	s_mov_b32 m0, s76
	s_add_i32 s75, s72, 0xc000
	global_load_lds_dwordx4 v[18:19], off
	v_lshl_add_u64 v[18:19], v[8:9], 0, s[6:7]
	s_mov_b32 m0, s77
	s_add_i32 s73, s74, 0xe000
	global_load_lds_dwordx4 v[18:19], off
	s_waitcnt vmcnt(3)
	v_lshl_add_u64 v[18:19], v[10:11], 0, s[8:9]
	s_mov_b32 m0, s75
	s_waitcnt lgkmcnt(0)
	s_barrier
	global_load_lds_dwordx4 v[18:19], off
	v_lshl_add_u64 v[18:19], v[6:7], 0, s[8:9]
	s_mov_b32 m0, s73
	s_add_i32 s74, s74, 0xe400
	global_load_lds_dwordx4 v[18:19], off
	v_lshl_add_u64 v[18:19], v[8:9], 0, s[8:9]
	s_mov_b32 m0, s74
	s_lshr_b32 s0, s79, 3
	global_load_lds_dwordx4 v[18:19], off
	s_and_b32 s69, s0, 0x1ffffff0
	v_or_b32_e32 v2, s69, v195
	s_and_b32 s0, s79, 64
	v_or_b32_e32 v17, s0, v195
	v_lshl_add_u32 v19, v2, 7, 0
	v_lshlrev_b32_e32 v18, 7, v17
	v_add_u32_e32 v2, v19, v86
	v_add_u32_e32 v17, v88, v18
	ds_read_b128 v[20:23], v2
	ds_read_b128 v[24:27], v17 offset:8192
	ds_read_b128 v[28:31], v17 offset:10240
	ds_read_b128 v[32:35], v17 offset:12288
	ds_read_b128 v[36:39], v17 offset:14336
	v_add_u32_e32 v19, v19, v87
	v_add_u32_e32 v18, v89, v18
	ds_read_b128 v[40:43], v19
	ds_read_b128 v[44:47], v18 offset:8192
	ds_read_b128 v[48:51], v18 offset:10240
	ds_read_b128 v[52:55], v18 offset:12288
	ds_read_b128 v[56:59], v18 offset:14336
	s_waitcnt lgkmcnt(0)
	v_mfma_f32_16x16x32_bf16 v[24:27], v[24:27], v[20:23], 0
	v_mfma_f32_16x16x32_bf16 v[28:31], v[28:31], v[20:23], 0
	v_mfma_f32_16x16x32_bf16 v[32:35], v[32:35], v[20:23], 0
	v_mfma_f32_16x16x32_bf16 v[20:23], v[36:39], v[20:23], 0
	v_mfma_f32_16x16x32_bf16 v[24:27], v[44:47], v[40:43], v[24:27]
	v_mfma_f32_16x16x32_bf16 v[28:31], v[48:51], v[40:43], v[28:31]
	v_mfma_f32_16x16x32_bf16 v[32:35], v[52:55], v[40:43], v[32:35]
	v_mfma_f32_16x16x32_bf16 v[20:23], v[56:59], v[40:43], v[20:23]
	s_mov_b32 m0, s72
	s_waitcnt vmcnt(3)
	v_lshl_add_u64 v[36:37], v[10:11], 0, s[10:11]
	s_waitcnt lgkmcnt(0)
	s_barrier
	global_load_lds_dwordx4 v[36:37], off
	v_lshl_add_u64 v[36:37], v[6:7], 0, s[10:11]
	s_mov_b32 m0, s70
	s_nop 0
	global_load_lds_dwordx4 v[36:37], off
	v_lshl_add_u64 v[36:37], v[8:9], 0, s[10:11]
	s_mov_b32 m0, s71
	s_nop 0
	global_load_lds_dwordx4 v[36:37], off
	ds_read_b128 v[36:39], v2 offset:24576
	ds_read_b128 v[40:43], v17 offset:32768
	ds_read_b128 v[44:47], v17 offset:34816
	ds_read_b128 v[48:51], v17 offset:36864
	ds_read_b128 v[52:55], v17 offset:38912
	ds_read_b128 v[56:59], v19 offset:24576
	ds_read_b128 v[60:63], v18 offset:32768
	ds_read_b128 v[68:71], v18 offset:34816
	ds_read_b128 v[72:75], v18 offset:36864
	ds_read_b128 v[76:79], v18 offset:38912
	s_waitcnt lgkmcnt(0)
	v_mfma_f32_16x16x32_bf16 v[24:27], v[40:43], v[36:39], v[24:27]
	v_mfma_f32_16x16x32_bf16 v[28:31], v[44:47], v[36:39], v[28:31]
	v_mfma_f32_16x16x32_bf16 v[32:35], v[48:51], v[36:39], v[32:35]
	v_mfma_f32_16x16x32_bf16 v[20:23], v[52:55], v[36:39], v[20:23]
	v_mfma_f32_16x16x32_bf16 v[24:27], v[60:63], v[56:59], v[24:27]
	v_mfma_f32_16x16x32_bf16 v[28:31], v[68:71], v[56:59], v[28:31]
	v_mfma_f32_16x16x32_bf16 v[32:35], v[72:75], v[56:59], v[32:35]
	v_mfma_f32_16x16x32_bf16 v[20:23], v[76:79], v[56:59], v[20:23]
	s_mov_b32 m0, s78
	s_waitcnt vmcnt(3)
	v_lshl_add_u64 v[36:37], v[10:11], 0, s[12:13]
	s_waitcnt lgkmcnt(0)
	s_barrier
	global_load_lds_dwordx4 v[36:37], off
	v_lshl_add_u64 v[36:37], v[6:7], 0, s[12:13]
	s_mov_b32 m0, s76
	s_nop 0
	global_load_lds_dwordx4 v[36:37], off
	v_lshl_add_u64 v[36:37], v[8:9], 0, s[12:13]
	s_mov_b32 m0, s77
	s_nop 0
	global_load_lds_dwordx4 v[36:37], off
	ds_read_b128 v[36:39], v2 offset:49152
	ds_read_b128 v[40:43], v17 offset:57344
	ds_read_b128 v[44:47], v17 offset:59392
	ds_read_b128 v[48:51], v17 offset:61440
	ds_read_b128 v[52:55], v17 offset:63488
	ds_read_b128 v[56:59], v19 offset:49152
	ds_read_b128 v[60:63], v18 offset:57344
	ds_read_b128 v[68:71], v18 offset:59392
	ds_read_b128 v[72:75], v18 offset:61440
	ds_read_b128 v[76:79], v18 offset:63488
	s_waitcnt lgkmcnt(0)
	v_mfma_f32_16x16x32_bf16 v[24:27], v[40:43], v[36:39], v[24:27]
	v_mfma_f32_16x16x32_bf16 v[28:31], v[44:47], v[36:39], v[28:31]
	v_mfma_f32_16x16x32_bf16 v[32:35], v[48:51], v[36:39], v[32:35]
	v_mfma_f32_16x16x32_bf16 v[20:23], v[52:55], v[36:39], v[20:23]
	v_mfma_f32_16x16x32_bf16 v[24:27], v[60:63], v[56:59], v[24:27]
	v_mfma_f32_16x16x32_bf16 v[28:31], v[68:71], v[56:59], v[28:31]
	v_mfma_f32_16x16x32_bf16 v[32:35], v[72:75], v[56:59], v[32:35]
	v_mfma_f32_16x16x32_bf16 v[20:23], v[76:79], v[56:59], v[20:23]
	s_mov_b32 m0, s75
	s_waitcnt vmcnt(3)
	v_lshl_add_u64 v[36:37], v[10:11], 0, s[14:15]
	s_waitcnt lgkmcnt(0)
	s_barrier
; DI f32x4 mfma16(bf16x8 a, bf16x8 b, f32x4 c) { return __builtin_amdgcn_mfma_f32_16x16x32_bf16(a, b, c, 0, 0, 0); }
; #define RAW_BARRIER() do { asm volatile("s_waitcnt lgkmcnt(0)" ::: "memory"); __builtin_amdgcn_s_barrier(); } while (0)
; template <int N> DI void wait_vmcnt() { asm volatile("s_waitcnt vmcnt(%0)" ::"n"(N) : "memory"); }
;     ...
;   for (int kt = 0; kt < 16; kt++) {
;     if (NST == 3) { if (kt + 1 < 16) wait_vmcnt<NI>(); else wait_vmcnt<0>(); }
;     else wait_vmcnt<0>();
;     RAW_BARRIER();
;     if (NST == 3) { if (kt + 2 < 16) glds(kt + 2, (kt + 2) % 3); }
;     else { if (kt + 1 < 16) glds(kt + 1, (kt + 1) & 1); }
;     const char* As = smem + (NST == 3 ? kt % 3 : kt & 1) * STAGE;
;     const char* Bs = As + BM * 128;
;     bf16x8 af[2][TM], bfr[2][NJ];
; #pragma unroll
;     for (int kk = 0; kk < 2; kk++) {
;       const int coff = ((kk * 4 + l4) ^ swz) << 4;
; #pragma unroll
;       for (int i = 0; i < TM; i++) af[kk][i] = *(const bf16x8*)(As + (wm * (TM * 16) + i * 16 + l15) * 128 + coff);
; #pragma unroll
;       for (int j = 0; j < NJ; j++) {
;         int nrow = MERGE ? ((j >> 1) * 64 + wn * 32 + (j & 1) * 16) : (wn * 64 + j * 16);
;         bfr[kk][j] = *(const bf16x8*)(Bs + (nrow + l15) * 128 + coff);
;       }
;       __builtin_amdgcn_sched_barrier(0);
;     }
; #pragma unroll
;     for (int kk = 0; kk < 2; kk++) {
; #pragma unroll
;       for (int i = 0; i < TM; i++)
; #pragma unroll
;         for (int j = 0; j < NJ; j++) acc[i][j] = SWAP ? mfma16(bfr[kk][j], af[kk][i], acc[i][j]) : mfma16(af[kk][i], bfr[kk][j], acc[i][j]);
;       __builtin_amdgcn_sched_barrier(0);
;     }
	global_load_lds_dwordx4 v[36:37], off
	v_lshl_add_u64 v[36:37], v[6:7], 0, s[14:15]
	s_mov_b32 m0, s73
	s_nop 0
	global_load_lds_dwordx4 v[36:37], off
	v_lshl_add_u64 v[36:37], v[8:9], 0, s[14:15]
	s_mov_b32 m0, s74
	s_nop 0
	global_load_lds_dwordx4 v[36:37], off
	ds_read_b128 v[36:39], v2
	ds_read_b128 v[40:43], v17 offset:8192
	ds_read_b128 v[44:47], v17 offset:10240
	ds_read_b128 v[48:51], v17 offset:12288
	ds_read_b128 v[52:55], v17 offset:14336
	ds_read_b128 v[56:59], v19
	ds_read_b128 v[60:63], v18 offset:8192
	ds_read_b128 v[68:71], v18 offset:10240
	ds_read_b128 v[72:75], v18 offset:12288
	ds_read_b128 v[76:79], v18 offset:14336
	s_waitcnt lgkmcnt(0)
	v_mfma_f32_16x16x32_bf16 v[24:27], v[40:43], v[36:39], v[24:27]
	v_mfma_f32_16x16x32_bf16 v[28:31], v[44:47], v[36:39], v[28:31]
	v_mfma_f32_16x16x32_bf16 v[32:35], v[48:51], v[36:39], v[32:35]
	v_mfma_f32_16x16x32_bf16 v[20:23], v[52:55], v[36:39], v[20:23]
	v_mfma_f32_16x16x32_bf16 v[24:27], v[60:63], v[56:59], v[24:27]
	v_mfma_f32_16x16x32_bf16 v[28:31], v[68:71], v[56:59], v[28:31]
	v_mfma_f32_16x16x32_bf16 v[32:35], v[72:75], v[56:59], v[32:35]
	v_mfma_f32_16x16x32_bf16 v[20:23], v[76:79], v[56:59], v[20:23]
	s_mov_b32 m0, s72
	s_waitcnt vmcnt(3)
	v_lshl_add_u64 v[36:37], v[10:11], 0, s[16:17]
	s_waitcnt lgkmcnt(0)
	s_barrier
	global_load_lds_dwordx4 v[36:37], off
	v_lshl_add_u64 v[36:37], v[6:7], 0, s[16:17]
	s_mov_b32 m0, s70
	s_nop 0
	global_load_lds_dwordx4 v[36:37], off
	v_lshl_add_u64 v[36:37], v[8:9], 0, s[16:17]
	s_mov_b32 m0, s71
	s_nop 0
	global_load_lds_dwordx4 v[36:37], off
	ds_read_b128 v[36:39], v2 offset:24576
	ds_read_b128 v[40:43], v17 offset:32768
	ds_read_b128 v[44:47], v17 offset:34816
	ds_read_b128 v[48:51], v17 offset:36864
	ds_read_b128 v[52:55], v17 offset:38912
	ds_read_b128 v[56:59], v19 offset:24576
	ds_read_b128 v[60:63], v18 offset:32768
	ds_read_b128 v[68:71], v18 offset:34816
	ds_read_b128 v[72:75], v18 offset:36864
	ds_read_b128 v[76:79], v18 offset:38912
	s_waitcnt lgkmcnt(0)
	v_mfma_f32_16x16x32_bf16 v[24:27], v[40:43], v[36:39], v[24:27]
	v_mfma_f32_16x16x32_bf16 v[28:31], v[44:47], v[36:39], v[28:31]
	v_mfma_f32_16x16x32_bf16 v[32:35], v[48:51], v[36:39], v[32:35]
	v_mfma_f32_16x16x32_bf16 v[20:23], v[52:55], v[36:39], v[20:23]
	v_mfma_f32_16x16x32_bf16 v[24:27], v[60:63], v[56:59], v[24:27]
	v_mfma_f32_16x16x32_bf16 v[28:31], v[68:71], v[56:59], v[28:31]
	v_mfma_f32_16x16x32_bf16 v[32:35], v[72:75], v[56:59], v[32:35]
	v_mfma_f32_16x16x32_bf16 v[20:23], v[76:79], v[56:59], v[20:23]
	s_mov_b32 m0, s78
	s_waitcnt vmcnt(3)
	v_lshl_add_u64 v[36:37], v[10:11], 0, s[30:31]
	s_waitcnt lgkmcnt(0)
	s_barrier
	global_load_lds_dwordx4 v[36:37], off
	v_lshl_add_u64 v[36:37], v[6:7], 0, s[30:31]
	s_mov_b32 m0, s76
	s_nop 0
	global_load_lds_dwordx4 v[36:37], off
	v_lshl_add_u64 v[36:37], v[8:9], 0, s[30:31]
	s_mov_b32 m0, s77
	s_nop 0
	global_load_lds_dwordx4 v[36:37], off
	ds_read_b128 v[36:39], v2 offset:49152
	ds_read_b128 v[40:43], v17 offset:57344
	ds_read_b128 v[44:47], v17 offset:59392
	ds_read_b128 v[48:51], v17 offset:61440
	ds_read_b128 v[52:55], v17 offset:63488
	ds_read_b128 v[56:59], v19 offset:49152
	ds_read_b128 v[60:63], v18 offset:57344
	ds_read_b128 v[68:71], v18 offset:59392
	ds_read_b128 v[72:75], v18 offset:61440
	ds_read_b128 v[76:79], v18 offset:63488
	s_waitcnt lgkmcnt(0)
	v_mfma_f32_16x16x32_bf16 v[24:27], v[40:43], v[36:39], v[24:27]
	v_mfma_f32_16x16x32_bf16 v[28:31], v[44:47], v[36:39], v[28:31]
	v_mfma_f32_16x16x32_bf16 v[32:35], v[48:51], v[36:39], v[32:35]
	v_mfma_f32_16x16x32_bf16 v[20:23], v[52:55], v[36:39], v[20:23]
	v_mfma_f32_16x16x32_bf16 v[24:27], v[60:63], v[56:59], v[24:27]
	v_mfma_f32_16x16x32_bf16 v[28:31], v[68:71], v[56:59], v[28:31]
	v_mfma_f32_16x16x32_bf16 v[32:35], v[72:75], v[56:59], v[32:35]
	v_mfma_f32_16x16x32_bf16 v[20:23], v[76:79], v[56:59], v[20:23]
	s_mov_b32 m0, s75
	s_waitcnt vmcnt(3)
	v_lshl_add_u64 v[36:37], v[10:11], 0, s[34:35]
	s_waitcnt lgkmcnt(0)
	s_barrier
	global_load_lds_dwordx4 v[36:37], off
	v_lshl_add_u64 v[36:37], v[6:7], 0, s[34:35]
	s_mov_b32 m0, s73
	s_nop 0
	global_load_lds_dwordx4 v[36:37], off
	v_lshl_add_u64 v[36:37], v[8:9], 0, s[34:35]
	s_mov_b32 m0, s74
	s_nop 0
	global_load_lds_dwordx4 v[36:37], off
	ds_read_b128 v[36:39], v2
	ds_read_b128 v[40:43], v17 offset:8192
	ds_read_b128 v[44:47], v17 offset:10240
	ds_read_b128 v[48:51], v17 offset:12288
	ds_read_b128 v[52:55], v17 offset:14336
	ds_read_b128 v[56:59], v19
	ds_read_b128 v[60:63], v18 offset:8192
	ds_read_b128 v[68:71], v18 offset:10240
	ds_read_b128 v[72:75], v18 offset:12288
	ds_read_b128 v[76:79], v18 offset:14336
	s_waitcnt lgkmcnt(0)
	v_mfma_f32_16x16x32_bf16 v[24:27], v[40:43], v[36:39], v[24:27]
	v_mfma_f32_16x16x32_bf16 v[28:31], v[44:47], v[36:39], v[28:31]
	v_mfma_f32_16x16x32_bf16 v[32:35], v[48:51], v[36:39], v[32:35]
	v_mfma_f32_16x16x32_bf16 v[20:23], v[52:55], v[36:39], v[20:23]
	v_mfma_f32_16x16x32_bf16 v[24:27], v[60:63], v[56:59], v[24:27]
	v_mfma_f32_16x16x32_bf16 v[28:31], v[68:71], v[56:59], v[28:31]
	v_mfma_f32_16x16x32_bf16 v[32:35], v[72:75], v[56:59], v[32:35]
	v_mfma_f32_16x16x32_bf16 v[20:23], v[76:79], v[56:59], v[20:23]
	s_mov_b32 m0, s72
	s_waitcnt vmcnt(3)
	v_lshl_add_u64 v[36:37], v[10:11], 0, s[52:53]
	s_waitcnt lgkmcnt(0)
	s_barrier
; DI f32x4 mfma16(bf16x8 a, bf16x8 b, f32x4 c) { return __builtin_amdgcn_mfma_f32_16x16x32_bf16(a, b, c, 0, 0, 0); }
; #define RAW_BARRIER() do { asm volatile("s_waitcnt lgkmcnt(0)" ::: "memory"); __builtin_amdgcn_s_barrier(); } while (0)
; template <int N> DI void wait_vmcnt() { asm volatile("s_waitcnt vmcnt(%0)" ::"n"(N) : "memory"); }
;     ...
;   for (int kt = 0; kt < 16; kt++) {
;     if (NST == 3) { if (kt + 1 < 16) wait_vmcnt<NI>(); else wait_vmcnt<0>(); }
;     else wait_vmcnt<0>();
;     RAW_BARRIER();
;     if (NST == 3) { if (kt + 2 < 16) glds(kt + 2, (kt + 2) % 3); }
;     else { if (kt + 1 < 16) glds(kt + 1, (kt + 1) & 1); }
;     const char* As = smem + (NST == 3 ? kt % 3 : kt & 1) * STAGE;
;     const char* Bs = As + BM * 128;
;     bf16x8 af[2][TM], bfr[2][NJ];
; #pragma unroll
;     for (int kk = 0; kk < 2; kk++) {
;       const int coff = ((kk * 4 + l4) ^ swz) << 4;
; #pragma unroll
;       for (int i = 0; i < TM; i++) af[kk][i] = *(const bf16x8*)(As + (wm * (TM * 16) + i * 16 + l15) * 128 + coff);
; #pragma unroll
;       for (int j = 0; j < NJ; j++) {
;         int nrow = MERGE ? ((j >> 1) * 64 + wn * 32 + (j & 1) * 16) : (wn * 64 + j * 16);
;         bfr[kk][j] = *(const bf16x8*)(Bs + (nrow + l15) * 128 + coff);
;       }
;       __builtin_amdgcn_sched_barrier(0);
;     }
; #pragma unroll
;     for (int kk = 0; kk < 2; kk++) {
; #pragma unroll
;       for (int i = 0; i < TM; i++)
; #pragma unroll
;         for (int j = 0; j < NJ; j++) acc[i][j] = SWAP ? mfma16(bfr[kk][j], af[kk][i], acc[i][j]) : mfma16(af[kk][i], bfr[kk][j], acc[i][j]);
;       __builtin_amdgcn_sched_barrier(0);
;     }
;   }
	global_load_lds_dwordx4 v[36:37], off
	v_lshl_add_u64 v[36:37], v[6:7], 0, s[52:53]
	s_mov_b32 m0, s70
	s_nop 0
	global_load_lds_dwordx4 v[36:37], off
	v_lshl_add_u64 v[36:37], v[8:9], 0, s[52:53]
	s_mov_b32 m0, s71
	s_nop 0
	global_load_lds_dwordx4 v[36:37], off
	ds_read_b128 v[36:39], v2 offset:24576
	ds_read_b128 v[40:43], v17 offset:32768
	ds_read_b128 v[44:47], v17 offset:34816
	ds_read_b128 v[48:51], v17 offset:36864
	ds_read_b128 v[52:55], v17 offset:38912
	ds_read_b128 v[56:59], v19 offset:24576
	ds_read_b128 v[60:63], v18 offset:32768
	ds_read_b128 v[68:71], v18 offset:34816
	ds_read_b128 v[72:75], v18 offset:36864
	ds_read_b128 v[76:79], v18 offset:38912
	s_waitcnt lgkmcnt(0)
	v_mfma_f32_16x16x32_bf16 v[24:27], v[40:43], v[36:39], v[24:27]
	v_mfma_f32_16x16x32_bf16 v[28:31], v[44:47], v[36:39], v[28:31]
	v_mfma_f32_16x16x32_bf16 v[32:35], v[48:51], v[36:39], v[32:35]
	v_mfma_f32_16x16x32_bf16 v[20:23], v[52:55], v[36:39], v[20:23]
	v_mfma_f32_16x16x32_bf16 v[24:27], v[60:63], v[56:59], v[24:27]
	v_mfma_f32_16x16x32_bf16 v[28:31], v[68:71], v[56:59], v[28:31]
	v_mfma_f32_16x16x32_bf16 v[32:35], v[72:75], v[56:59], v[32:35]
	v_mfma_f32_16x16x32_bf16 v[20:23], v[76:79], v[56:59], v[20:23]
	s_mov_b32 m0, s78
	s_waitcnt vmcnt(3)
	v_lshl_add_u64 v[36:37], v[10:11], 0, s[54:55]
	s_waitcnt lgkmcnt(0)
	s_barrier
	global_load_lds_dwordx4 v[36:37], off
	v_lshl_add_u64 v[36:37], v[6:7], 0, s[54:55]
	s_mov_b32 m0, s76
	s_nop 0
	global_load_lds_dwordx4 v[36:37], off
	v_lshl_add_u64 v[36:37], v[8:9], 0, s[54:55]
	s_mov_b32 m0, s77
	s_nop 0
	global_load_lds_dwordx4 v[36:37], off
	ds_read_b128 v[36:39], v2 offset:49152
	ds_read_b128 v[40:43], v17 offset:57344
	ds_read_b128 v[44:47], v17 offset:59392
	ds_read_b128 v[48:51], v17 offset:61440
	ds_read_b128 v[52:55], v17 offset:63488
	ds_read_b128 v[56:59], v19 offset:49152
	ds_read_b128 v[60:63], v18 offset:57344
	ds_read_b128 v[68:71], v18 offset:59392
	ds_read_b128 v[72:75], v18 offset:61440
	ds_read_b128 v[76:79], v18 offset:63488
	s_waitcnt lgkmcnt(0)
	v_mfma_f32_16x16x32_bf16 v[24:27], v[40:43], v[36:39], v[24:27]
	v_mfma_f32_16x16x32_bf16 v[28:31], v[44:47], v[36:39], v[28:31]
	v_mfma_f32_16x16x32_bf16 v[32:35], v[48:51], v[36:39], v[32:35]
	v_mfma_f32_16x16x32_bf16 v[20:23], v[52:55], v[36:39], v[20:23]
	v_mfma_f32_16x16x32_bf16 v[24:27], v[60:63], v[56:59], v[24:27]
	v_mfma_f32_16x16x32_bf16 v[28:31], v[68:71], v[56:59], v[28:31]
	v_mfma_f32_16x16x32_bf16 v[32:35], v[72:75], v[56:59], v[32:35]
	v_mfma_f32_16x16x32_bf16 v[20:23], v[76:79], v[56:59], v[20:23]
	s_mov_b32 m0, s75
	s_waitcnt vmcnt(3)
	v_lshl_add_u64 v[36:37], v[10:11], 0, s[56:57]
	s_waitcnt lgkmcnt(0)
	s_barrier
	global_load_lds_dwordx4 v[36:37], off
	v_lshl_add_u64 v[36:37], v[6:7], 0, s[56:57]
	s_mov_b32 m0, s73
	s_nop 0
	global_load_lds_dwordx4 v[36:37], off
	v_lshl_add_u64 v[36:37], v[8:9], 0, s[56:57]
	s_mov_b32 m0, s74
	s_nop 0
	global_load_lds_dwordx4 v[36:37], off
	ds_read_b128 v[36:39], v2
	ds_read_b128 v[40:43], v17 offset:8192
	ds_read_b128 v[44:47], v17 offset:10240
	ds_read_b128 v[48:51], v17 offset:12288
	ds_read_b128 v[52:55], v17 offset:14336
	ds_read_b128 v[56:59], v19
	ds_read_b128 v[60:63], v18 offset:8192
	ds_read_b128 v[68:71], v18 offset:10240
	ds_read_b128 v[72:75], v18 offset:12288
	ds_read_b128 v[76:79], v18 offset:14336
	s_waitcnt lgkmcnt(0)
	v_mfma_f32_16x16x32_bf16 v[24:27], v[40:43], v[36:39], v[24:27]
	v_mfma_f32_16x16x32_bf16 v[28:31], v[44:47], v[36:39], v[28:31]
	v_mfma_f32_16x16x32_bf16 v[32:35], v[48:51], v[36:39], v[32:35]
	v_mfma_f32_16x16x32_bf16 v[20:23], v[52:55], v[36:39], v[20:23]
	v_mfma_f32_16x16x32_bf16 v[24:27], v[60:63], v[56:59], v[24:27]
	v_mfma_f32_16x16x32_bf16 v[28:31], v[68:71], v[56:59], v[28:31]
	v_mfma_f32_16x16x32_bf16 v[32:35], v[72:75], v[56:59], v[32:35]
	v_mfma_f32_16x16x32_bf16 v[20:23], v[76:79], v[56:59], v[20:23]
	s_mov_b32 m0, s72
	s_waitcnt vmcnt(3)
	v_lshl_add_u64 v[36:37], v[10:11], 0, s[58:59]
	s_waitcnt lgkmcnt(0)
	s_barrier
	global_load_lds_dwordx4 v[36:37], off
	v_lshl_add_u64 v[36:37], v[6:7], 0, s[58:59]
	s_mov_b32 m0, s70
	s_nop 0
	global_load_lds_dwordx4 v[36:37], off
	v_lshl_add_u64 v[36:37], v[8:9], 0, s[58:59]
	s_mov_b32 m0, s71
	s_nop 0
	global_load_lds_dwordx4 v[36:37], off
	ds_read_b128 v[36:39], v2 offset:24576
	ds_read_b128 v[40:43], v17 offset:32768
	ds_read_b128 v[44:47], v17 offset:34816
	ds_read_b128 v[48:51], v17 offset:36864
	ds_read_b128 v[52:55], v17 offset:38912
	ds_read_b128 v[56:59], v19 offset:24576
	ds_read_b128 v[60:63], v18 offset:32768
	ds_read_b128 v[68:71], v18 offset:34816
	ds_read_b128 v[72:75], v18 offset:36864
	ds_read_b128 v[76:79], v18 offset:38912
	s_waitcnt lgkmcnt(0)
	v_mfma_f32_16x16x32_bf16 v[24:27], v[40:43], v[36:39], v[24:27]
	v_mfma_f32_16x16x32_bf16 v[28:31], v[44:47], v[36:39], v[28:31]
	v_mfma_f32_16x16x32_bf16 v[32:35], v[48:51], v[36:39], v[32:35]
	v_mfma_f32_16x16x32_bf16 v[20:23], v[52:55], v[36:39], v[20:23]
	v_mfma_f32_16x16x32_bf16 v[24:27], v[60:63], v[56:59], v[24:27]
	v_mfma_f32_16x16x32_bf16 v[28:31], v[68:71], v[56:59], v[28:31]
	v_mfma_f32_16x16x32_bf16 v[32:35], v[72:75], v[56:59], v[32:35]
	v_mfma_f32_16x16x32_bf16 v[20:23], v[76:79], v[56:59], v[20:23]
	s_mov_b32 m0, s78
	s_waitcnt vmcnt(3)
	v_lshl_add_u64 v[36:37], v[10:11], 0, s[60:61]
	s_waitcnt lgkmcnt(0)
	s_barrier
; DI f32x4 mfma16(bf16x8 a, bf16x8 b, f32x4 c) { return __builtin_amdgcn_mfma_f32_16x16x32_bf16(a, b, c, 0, 0, 0); }
; #define RAW_BARRIER() do { asm volatile("s_waitcnt lgkmcnt(0)" ::: "memory"); __builtin_amdgcn_s_barrier(); } while (0)
; template <int N> DI void wait_vmcnt() { asm volatile("s_waitcnt vmcnt(%0)" ::"n"(N) : "memory"); }
;     ...
;   for (int kt = 0; kt < 16; kt++) {
;     if (NST == 3) { if (kt + 1 < 16) wait_vmcnt<NI>(); else wait_vmcnt<0>(); }
;     else wait_vmcnt<0>();
;     RAW_BARRIER();
;     if (NST == 3) { if (kt + 2 < 16) glds(kt + 2, (kt + 2) % 3); }
;     else { if (kt + 1 < 16) glds(kt + 1, (kt + 1) & 1); }
;     const char* As = smem + (NST == 3 ? kt % 3 : kt & 1) * STAGE;
;     const char* Bs = As + BM * 128;
;     bf16x8 af[2][TM], bfr[2][NJ];
; #pragma unroll
;     for (int kk = 0; kk < 2; kk++) {
;       const int coff = ((kk * 4 + l4) ^ swz) << 4;
; #pragma unroll
;       for (int i = 0; i < TM; i++) af[kk][i] = *(const bf16x8*)(As + (wm * (TM * 16) + i * 16 + l15) * 128 + coff);
; #pragma unroll
;       for (int j = 0; j < NJ; j++) {
;         int nrow = MERGE ? ((j >> 1) * 64 + wn * 32 + (j & 1) * 16) : (wn * 64 + j * 16);
;         bfr[kk][j] = *(const bf16x8*)(Bs + (nrow + l15) * 128 + coff);
;       }
;       __builtin_amdgcn_sched_barrier(0);
;     }
; #pragma unroll
;     for (int kk = 0; kk < 2; kk++) {
; #pragma unroll
;       for (int i = 0; i < TM; i++)
; #pragma unroll
;         for (int j = 0; j < NJ; j++) acc[i][j] = SWAP ? mfma16(bfr[kk][j], af[kk][i], acc[i][j]) : mfma16(af[kk][i], bfr[kk][j], acc[i][j]);
;       __builtin_amdgcn_sched_barrier(0);
;     }
;   }
	global_load_lds_dwordx4 v[36:37], off
	v_lshl_add_u64 v[36:37], v[6:7], 0, s[60:61]
	s_mov_b32 m0, s76
	s_nop 0
	global_load_lds_dwordx4 v[36:37], off
	v_lshl_add_u64 v[36:37], v[8:9], 0, s[60:61]
	s_mov_b32 m0, s77
	s_nop 0
	global_load_lds_dwordx4 v[36:37], off
	ds_read_b128 v[36:39], v2 offset:49152
	ds_read_b128 v[40:43], v17 offset:57344
	ds_read_b128 v[44:47], v17 offset:59392
	ds_read_b128 v[48:51], v17 offset:61440
	ds_read_b128 v[52:55], v17 offset:63488
	ds_read_b128 v[56:59], v19 offset:49152
	ds_read_b128 v[60:63], v18 offset:57344
	ds_read_b128 v[68:71], v18 offset:59392
	ds_read_b128 v[72:75], v18 offset:61440
	ds_read_b128 v[76:79], v18 offset:63488
	s_waitcnt lgkmcnt(0)
	v_mfma_f32_16x16x32_bf16 v[24:27], v[40:43], v[36:39], v[24:27]
	v_mfma_f32_16x16x32_bf16 v[28:31], v[44:47], v[36:39], v[28:31]
	v_mfma_f32_16x16x32_bf16 v[32:35], v[48:51], v[36:39], v[32:35]
	v_mfma_f32_16x16x32_bf16 v[20:23], v[52:55], v[36:39], v[20:23]
	v_mfma_f32_16x16x32_bf16 v[24:27], v[60:63], v[56:59], v[24:27]
	v_mfma_f32_16x16x32_bf16 v[28:31], v[68:71], v[56:59], v[28:31]
	v_mfma_f32_16x16x32_bf16 v[32:35], v[72:75], v[56:59], v[32:35]
	v_mfma_f32_16x16x32_bf16 v[20:23], v[76:79], v[56:59], v[20:23]
	s_mov_b32 m0, s75
	s_waitcnt vmcnt(3)
	v_lshl_add_u64 v[36:37], v[10:11], 0, s[62:63]
	s_waitcnt lgkmcnt(0)
	s_barrier
	global_load_lds_dwordx4 v[36:37], off
	v_lshl_add_u64 v[36:37], v[6:7], 0, s[62:63]
	s_mov_b32 m0, s73
	s_nop 0
	global_load_lds_dwordx4 v[36:37], off
	v_lshl_add_u64 v[36:37], v[8:9], 0, s[62:63]
	s_mov_b32 m0, s74
	s_nop 0
	global_load_lds_dwordx4 v[36:37], off
	ds_read_b128 v[36:39], v2
	ds_read_b128 v[40:43], v17 offset:8192
	ds_read_b128 v[44:47], v17 offset:10240
	ds_read_b128 v[48:51], v17 offset:12288
	ds_read_b128 v[52:55], v17 offset:14336
	ds_read_b128 v[56:59], v19
	ds_read_b128 v[60:63], v18 offset:8192
	ds_read_b128 v[68:71], v18 offset:10240
	ds_read_b128 v[72:75], v18 offset:12288
	ds_read_b128 v[76:79], v18 offset:14336
	s_waitcnt lgkmcnt(0)
	v_mfma_f32_16x16x32_bf16 v[24:27], v[40:43], v[36:39], v[24:27]
	v_mfma_f32_16x16x32_bf16 v[28:31], v[44:47], v[36:39], v[28:31]
	v_mfma_f32_16x16x32_bf16 v[32:35], v[48:51], v[36:39], v[32:35]
	v_mfma_f32_16x16x32_bf16 v[20:23], v[52:55], v[36:39], v[20:23]
	v_mfma_f32_16x16x32_bf16 v[24:27], v[60:63], v[56:59], v[24:27]
	v_mfma_f32_16x16x32_bf16 v[28:31], v[68:71], v[56:59], v[28:31]
	v_mfma_f32_16x16x32_bf16 v[32:35], v[72:75], v[56:59], v[32:35]
	v_mfma_f32_16x16x32_bf16 v[20:23], v[76:79], v[56:59], v[20:23]
	s_mov_b32 m0, s72
	s_waitcnt vmcnt(3)
	v_lshl_add_u64 v[10:11], v[10:11], 0, s[64:65]
	s_waitcnt lgkmcnt(0)
	s_barrier
	global_load_lds_dwordx4 v[10:11], off
	v_lshl_add_u64 v[6:7], v[6:7], 0, s[64:65]
	s_mov_b32 m0, s70
	s_nop 0
	global_load_lds_dwordx4 v[6:7], off
	v_lshl_add_u64 v[6:7], v[8:9], 0, s[64:65]
	s_mov_b32 m0, s71
	s_nop 0
	global_load_lds_dwordx4 v[6:7], off
	ds_read_b128 v[6:9], v2 offset:24576
	ds_read_b128 v[36:39], v17 offset:32768
	ds_read_b128 v[40:43], v17 offset:34816
	ds_read_b128 v[44:47], v17 offset:36864
	ds_read_b128 v[48:51], v17 offset:38912
	ds_read_b128 v[52:55], v19 offset:24576
	ds_read_b128 v[56:59], v18 offset:32768
	ds_read_b128 v[60:63], v18 offset:34816
	ds_read_b128 v[68:71], v18 offset:36864
	ds_read_b128 v[72:75], v18 offset:38912
	s_waitcnt lgkmcnt(0)
	v_mfma_f32_16x16x32_bf16 v[24:27], v[36:39], v[6:9], v[24:27]
	v_mfma_f32_16x16x32_bf16 v[28:31], v[40:43], v[6:9], v[28:31]
	v_mfma_f32_16x16x32_bf16 v[32:35], v[44:47], v[6:9], v[32:35]
	v_mfma_f32_16x16x32_bf16 v[6:9], v[48:51], v[6:9], v[20:23]
	v_mfma_f32_16x16x32_bf16 v[20:23], v[56:59], v[52:55], v[24:27]
	v_mfma_f32_16x16x32_bf16 v[24:27], v[60:63], v[52:55], v[28:31]
	v_mfma_f32_16x16x32_bf16 v[28:31], v[68:71], v[52:55], v[32:35]
	v_mfma_f32_16x16x32_bf16 v[6:9], v[72:75], v[52:55], v[6:9]
	s_waitcnt vmcnt(3)
	s_waitcnt lgkmcnt(0)
	s_barrier
	s_nop 1
	ds_read_b128 v[32:35], v17 offset:63488
	ds_read_b128 v[36:39], v17 offset:61440
	ds_read_b128 v[40:43], v17 offset:59392
	ds_read_b128 v[44:47], v17 offset:57344
	ds_read_b128 v[48:51], v2 offset:49152
	ds_read_b128 v[52:55], v19 offset:49152
	ds_read_b128 v[56:59], v18 offset:57344
	ds_read_b128 v[60:63], v18 offset:59392
	ds_read_b128 v[68:71], v18 offset:61440
	ds_read_b128 v[72:75], v18 offset:63488
	s_waitcnt lgkmcnt(0)
	v_mfma_f32_16x16x32_bf16 v[20:23], v[44:47], v[48:51], v[20:23]
	v_mfma_f32_16x16x32_bf16 v[24:27], v[40:43], v[48:51], v[24:27]
	v_mfma_f32_16x16x32_bf16 v[28:31], v[36:39], v[48:51], v[28:31]
	v_mfma_f32_16x16x32_bf16 v[6:9], v[32:35], v[48:51], v[6:9]
	v_mfma_f32_16x16x32_bf16 v[20:23], v[56:59], v[52:55], v[20:23]
	v_mfma_f32_16x16x32_bf16 v[24:27], v[60:63], v[52:55], v[24:27]
	v_mfma_f32_16x16x32_bf16 v[28:31], v[68:71], v[52:55], v[28:31]
	v_mfma_f32_16x16x32_bf16 v[6:9], v[72:75], v[52:55], v[6:9]
	s_waitcnt vmcnt(0)
	s_waitcnt lgkmcnt(0)
	s_barrier
; DI u32 pack2(float a, float b) { f32x2 v = {a, b}; bfx2 r = __builtin_convertvector(v, bfx2); return __builtin_bit_cast(u32, r); }
; DI f32x4 mfma16(bf16x8 a, bf16x8 b, f32x4 c) { return __builtin_amdgcn_mfma_f32_16x16x32_bf16(a, b, c, 0, 0, 0); }
;     ...
; #pragma unroll
;     for (int kk = 0; kk < 2; kk++) {
; #pragma unroll
;       for (int i = 0; i < TM; i++)
; #pragma unroll
;         for (int j = 0; j < NJ; j++) acc[i][j] = SWAP ? mfma16(bfr[kk][j], af[kk][i], acc[i][j]) : mfma16(af[kk][i], bfr[kk][j], acc[i][j]);
;       __builtin_amdgcn_sched_barrier(0);
;     }
;   }
;   __syncthreads();
; template <int TM>
; DI void phase4_tile(const P& p, char* smem, int m0, int nt) {
;     ...
;       for (int i = 0; i < TM; i++) {
;         int tok = m0 + wm * (TM * 16) + i * 16 + (lane & 15);
;         float ss = 0.f;
; #pragma unroll
;         for (int j = 0; j < 4; j++)
; #pragma unroll
;           for (int rr = 0; rr < 4; rr++) ss += acc[i][j][rr] * acc[i][j][rr];
;         ss += __shfl_xor(ss, 16); ss += __shfl_xor(ss, 32);
;         float rinv = rsqrtf(ss * (1.f / 64.f) + RMS_EPS);
; #pragma unroll
;         for (int j = 0; j < 4; j++) {
;           int dd = j * 16 + 4 * (lane >> 4);
;           float4 g4 = *(const float4*)(gain + dd);
;           float o0 = acc[i][j][0] * rinv * g4.x, o1 = acc[i][j][1] * rinv * g4.y, o2 = acc[i][j][2] * rinv * g4.z, o3 = acc[i][j][3] * rinv * g4.w;
;           int col = hh * 128 + m * 64 + dd;
;           if (isq) {
;             u32x2 ov = {pack2(o0 * QSCALE, o1 * QSCALE), pack2(o2 * QSCALE, o3 * QSCALE)};
;             *(u32x2*)(Qn + (size_t)tok * 1024 + col) = ov;
;           } else {
	ds_read_b128 v[32:35], v17 offset:14336
	ds_read_b128 v[36:39], v17 offset:12288
	ds_read_b128 v[40:43], v17 offset:10240
	ds_read_b128 v[44:47], v17 offset:8192
	ds_read_b128 v[48:51], v2
	ds_read_b128 v[52:55], v19
	ds_read_b128 v[56:59], v18 offset:8192
	ds_read_b128 v[60:63], v18 offset:10240
	ds_read_b128 v[68:71], v18 offset:12288
	ds_read_b128 v[72:75], v18 offset:14336
	s_waitcnt lgkmcnt(0)
	v_mfma_f32_16x16x32_bf16 v[18:21], v[44:47], v[48:51], v[20:23]
	v_mfma_f32_16x16x32_bf16 v[22:25], v[40:43], v[48:51], v[24:27]
	v_mfma_f32_16x16x32_bf16 v[26:29], v[36:39], v[48:51], v[28:31]
	v_mfma_f32_16x16x32_bf16 v[6:9], v[32:35], v[48:51], v[6:9]
	v_mfma_f32_16x16x32_bf16 v[18:21], v[56:59], v[52:55], v[18:21]
	v_mfma_f32_16x16x32_bf16 v[22:25], v[60:63], v[52:55], v[22:25]
	v_mfma_f32_16x16x32_bf16 v[26:29], v[68:71], v[52:55], v[26:29]
	v_mfma_f32_16x16x32_bf16 v[6:9], v[72:75], v[52:55], v[6:9]
	s_waitcnt vmcnt(0)
	s_barrier
	global_load_dwordx4 v[30:33], v[66:67], off
	s_nop 1
	v_mul_f32_e32 v40, v19, v19
	v_fmac_f32_e32 v40, v18, v18
	v_fmac_f32_e32 v40, v20, v20
	v_fmac_f32_e32 v40, v21, v21
	v_fmac_f32_e32 v40, v22, v22
	v_fmac_f32_e32 v40, v23, v23
	v_fmac_f32_e32 v40, v24, v24
	v_pk_mul_f32 v[34:35], v[26:27], v[26:27]
	v_fmac_f32_e32 v40, v25, v25
	v_add_f32_e32 v34, v34, v40
	v_pk_mul_f32 v[10:11], v[28:29], v[28:29]
	v_add_f32_e32 v34, v35, v34
	v_add_f32_e32 v10, v10, v34
	v_pk_mul_f32 v[38:39], v[6:7], v[6:7]
	v_add_f32_e32 v10, v11, v10
	v_add_f32_e32 v10, v38, v10
	v_cmp_lt_i32_e32 vcc, v13, v14
	v_pk_mul_f32 v[36:37], v[8:9], v[8:9]
	v_add_f32_e32 v10, v39, v10
	v_cndmask_b32_e32 v17, v12, v13, vcc
	v_add_f32_e32 v10, v36, v10
	v_lshlrev_b32_e32 v17, 2, v17
	v_add_f32_e32 v11, v37, v10
	ds_bpermute_b32 v17, v17, v11
	v_cmp_lt_i32_e32 vcc, v15, v14
	v_or_b32_e32 v2, s68, v195
	v_add_u32_e32 v10, s69, v2
	v_cndmask_b32_e32 v34, v12, v15, vcc
	v_lshlrev_b32_e32 v2, 2, v34
	s_waitcnt lgkmcnt(0)
	v_add_f32_e32 v17, v11, v17
	ds_bpermute_b32 v2, v2, v17
	s_and_b32 s67, s67, 0x380
	s_or_b32 s0, s67, s0
	v_ashrrev_i32_e32 v11, 31, v10
	v_or_b32_e32 v34, s0, v214
	s_waitcnt lgkmcnt(0)
	v_add_f32_e32 v2, v17, v2
	v_fmamk_f32 v2, v2, 0x3c800000, v16
	v_mul_f32_e32 v17, 0x4b800000, v2
	v_cmp_gt_f32_e32 vcc, s33, v2
	v_lshlrev_b64 v[10:11], 11, v[10:11]
	v_lshl_add_u64 v[10:11], s[28:29], 0, v[10:11]
	v_cndmask_b32_e32 v2, v2, v17, vcc
	v_rsq_f32_e32 v17, v2
	v_lshlrev_b32_e32 v2, 1, v34
	v_lshl_add_u64 v[10:11], v[10:11], 0, v[2:3]
	s_add_i32 s2, s2, s4
	v_mul_f32_e32 v2, 0x45800000, v17
	v_cndmask_b32_e32 v2, v17, v2, vcc
	v_pk_mul_f32 v[18:19], v[18:19], v[2:3] op_sel_hi:[1,0]
	v_pk_mul_f32 v[20:21], v[20:21], v[2:3] op_sel_hi:[1,0]
	v_pk_mul_f32 v[22:23], v[22:23], v[2:3] op_sel_hi:[1,0]
	v_pk_mul_f32 v[24:25], v[24:25], v[2:3] op_sel_hi:[1,0]
	v_pk_mul_f32 v[6:7], v[6:7], v[2:3] op_sel_hi:[1,0]
	v_pk_mul_f32 v[8:9], v[8:9], v[2:3] op_sel_hi:[1,0]
	s_add_i32 s3, s3, s5
	s_cmp_gt_i32 s2, 31
	s_waitcnt vmcnt(0)
	v_pk_mul_f32 v[18:19], v[30:31], v[18:19]
	v_pk_mul_f32 v[20:21], v[32:33], v[20:21]
	v_pk_mul_f32 v[18:19], v[18:19], s[66:67] op_sel_hi:[1,0]
	v_pk_mul_f32 v[20:21], v[20:21], s[66:67] op_sel_hi:[1,0]
	v_cvt_pk_bf16_f32 v18, v18, v19
	v_cvt_pk_bf16_f32 v19, v20, v21
	global_store_dwordx2 v[10:11], v[18:19], off
	global_load_dwordx4 v[18:21], v[66:67], off offset:64
	s_waitcnt vmcnt(0)
	v_pk_mul_f32 v[18:19], v[18:19], v[22:23]
	v_pk_mul_f32 v[20:21], v[20:21], v[24:25]
	v_pk_mul_f32 v[18:19], v[18:19], s[66:67] op_sel_hi:[1,0]
	v_pk_mul_f32 v[20:21], v[20:21], s[66:67] op_sel_hi:[1,0]
	v_cvt_pk_bf16_f32 v18, v18, v19
	v_cvt_pk_bf16_f32 v19, v20, v21
	global_store_dwordx2 v[10:11], v[18:19], off offset:32
	global_load_dwordx4 v[18:21], v[66:67], off offset:128
	v_pk_mul_f32 v[22:23], v[26:27], v[2:3] op_sel_hi:[1,0]
	v_pk_mul_f32 v[24:25], v[28:29], v[2:3] op_sel_hi:[1,0]
	s_waitcnt vmcnt(0)
	v_pk_mul_f32 v[18:19], v[18:19], v[22:23]
	v_pk_mul_f32 v[20:21], v[20:21], v[24:25]
	v_pk_mul_f32 v[18:19], v[18:19], s[66:67] op_sel_hi:[1,0]
	v_pk_mul_f32 v[20:21], v[20:21], s[66:67] op_sel_hi:[1,0]
	v_cvt_pk_bf16_f32 v18, v18, v19
	v_cvt_pk_bf16_f32 v19, v20, v21
	global_store_dwordx2 v[10:11], v[18:19], off offset:64
	global_load_dwordx4 v[18:21], v[66:67], off offset:192
	s_waitcnt vmcnt(0)
	v_pk_mul_f32 v[6:7], v[6:7], v[18:19]
	v_pk_mul_f32 v[8:9], v[8:9], v[20:21]
	v_pk_mul_f32 v[6:7], v[6:7], s[66:67] op_sel_hi:[1,0]
	v_pk_mul_f32 v[8:9], v[8:9], s[66:67] op_sel_hi:[1,0]
	v_cvt_pk_bf16_f32 v6, v6, v7
	v_cvt_pk_bf16_f32 v7, v8, v9
	global_store_dwordx2 v[10:11], v[6:7], off offset:96
	s_cbranch_scc0 .LBB0_526

; DI f32x4 mfma16(bf16x8 a, bf16x8 b, f32x4 c) { return __builtin_amdgcn_mfma_f32_16x16x32_bf16(a, b, c, 0, 0, 0); }
; #define RAW_BARRIER() do { asm volatile("s_waitcnt lgkmcnt(0)" ::: "memory"); __builtin_amdgcn_s_barrier(); } while (0)
; template <int N> DI void wait_vmcnt() { asm volatile("s_waitcnt vmcnt(%0)" ::"n"(N) : "memory"); }
;     ...
;   __syncthreads();
;   wait_vmcnt<0>();
;   glds(0, 0);
;   if (NST == 3) glds(1, 1);
;   for (int kt = 0; kt < 16; kt++) {
;     if (NST == 3) { if (kt + 1 < 16) wait_vmcnt<NI>(); else wait_vmcnt<0>(); }
;     else wait_vmcnt<0>();
;     RAW_BARRIER();
;     if (NST == 3) { if (kt + 2 < 16) glds(kt + 2, (kt + 2) % 3); }
;     else { if (kt + 1 < 16) glds(kt + 1, (kt + 1) & 1); }
;     const char* As = smem + (NST == 3 ? kt % 3 : kt & 1) * STAGE;
;     const char* Bs = As + BM * 128;
;     bf16x8 af[2][TM], bfr[2][NJ];
; #pragma unroll
;     for (int kk = 0; kk < 2; kk++) {
;       const int coff = ((kk * 4 + l4) ^ swz) << 4;
; #pragma unroll
;       for (int i = 0; i < TM; i++) af[kk][i] = *(const bf16x8*)(As + (wm * (TM * 16) + i * 16 + l15) * 128 + coff);
; #pragma unroll
;       for (int j = 0; j < NJ; j++) {
;         int nrow = MERGE ? ((j >> 1) * 64 + wn * 32 + (j & 1) * 16) : (wn * 64 + j * 16);
;         bfr[kk][j] = *(const bf16x8*)(Bs + (nrow + l15) * 128 + coff);
;       }
;       __builtin_amdgcn_sched_barrier(0);
;     }
; #pragma unroll
;     for (int kk = 0; kk < 2; kk++) {
; #pragma unroll
;       for (int i = 0; i < TM; i++)
; #pragma unroll
;         for (int j = 0; j < NJ; j++) acc[i][j] = SWAP ? mfma16(bfr[kk][j], af[kk][i], acc[i][j]) : mfma16(af[kk][i], bfr[kk][j], acc[i][j]);
;       __builtin_amdgcn_sched_barrier(0);
;     }
;   }
.LBB0_682:
	s_ashr_i32 s0, s82, 31
	s_lshr_b32 s0, s0, 28
	s_add_i32 s0, s82, s0
	s_ashr_i32 s75, s0, 4
	s_and_b32 s0, s0, -16
	s_sub_i32 s76, s82, s0
	v_readfirstlane_b32 s0, v1
	s_lshr_b32 s79, s0, 7
	s_bfe_u32 s84, s0, 0x10006
	s_lshl_b32 s0, s75, 11
	s_sub_i32 s83, s33, s0
	s_lshl_b32 s74, s75, 6
	s_add_i32 s4, s83, 0x1410
	v_readlane_b32 s36, v251, 1
	s_add_i32 s78, s74, 0x8000
	s_lshl_b64 s[0:1], s[4:5], 11
	v_readlane_b32 s50, v251, 15
	v_readlane_b32 s51, v251, 16
	s_add_u32 s2, s50, s0
	s_addc_u32 s3, s51, s1
	s_cmp_gt_i32 s76, 7
	s_mov_b64 s[0:1], -1
	v_readlane_b32 s37, v251, 2
	v_readlane_b32 s38, v251, 3
	v_readlane_b32 s39, v251, 4
	v_readlane_b32 s40, v251, 5
	v_readlane_b32 s41, v251, 6
	v_readlane_b32 s42, v251, 7
	v_readlane_b32 s43, v251, 8
	v_readlane_b32 s44, v251, 9
	v_readlane_b32 s45, v251, 10
	v_readlane_b32 s46, v251, 11
	v_readlane_b32 s47, v251, 12
	v_readlane_b32 s48, v251, 13
	v_readlane_b32 s49, v251, 14
	s_cbranch_scc0 .LBB0_700
	v_readfirstlane_b32 s86, v1
	s_lshr_b32 s0, s86, 6
	v_lshl_or_b32 v2, s0, 3, v187
	v_lshrrev_b32_e32 v3, 1, v2
	v_add_u32_e32 v2, s78, v2
	v_xor_b32_e32 v8, v3, v1
	v_ashrrev_i32_e32 v3, 31, v2
	v_lshl_or_b32 v18, s0, 4, v187
	v_lshlrev_b64 v[6:7], 11, v[2:3]
	v_lshlrev_b64 v[2:3], 11, v[18:19]
	v_or_b32_e32 v18, 8, v18
	v_lshrrev_b32_e32 v4, 1, v18
	v_xor_b32_e32 v9, v4, v1
	v_lshlrev_b64 v[4:5], 11, v[18:19]
	v_lshlrev_b32_e32 v9, 4, v9
	v_readlane_b32 s36, v251, 1
	s_lshl_b32 s0, s0, 10
	v_lshl_add_u64 v[4:5], s[2:3], 0, v[4:5]
	v_and_b32_e32 v18, 0x70, v9
	v_readlane_b32 s48, v251, 13
	v_readlane_b32 s49, v251, 14
	v_lshlrev_b32_e32 v8, 4, v8
	s_add_i32 s4, s0, 0
	v_lshl_add_u64 v[4:5], v[4:5], 0, v[18:19]
	v_lshl_add_u64 v[6:7], s[48:49], 0, v[6:7]
	v_and_b32_e32 v18, 0x70, v8
	s_add_i32 s88, s4, s0
	v_lshl_add_u64 v[2:3], s[2:3], 0, v[2:3]
	v_mov_b32_e32 v21, v19
	v_lshl_add_u64 v[6:7], v[6:7], 0, v[18:19]
	s_waitcnt vmcnt(63) expcnt(7) lgkmcnt(15)
	s_barrier
	s_nop 0
	s_add_i32 s0, s88, 0x2000
	s_mov_b32 m0, s4
	v_lshl_add_u64 v[2:3], v[2:3], 0, v[20:21]
	global_load_lds_dwordx4 v[6:7], off
	s_mov_b32 m0, s0
	s_add_i32 s1, s88, 0x2400
	global_load_lds_dwordx4 v[2:3], off
	s_mov_b32 m0, s1
	s_add_i32 s87, s4, 0x6000
	s_lshl_b32 s77, s75, 4
	global_load_lds_dwordx4 v[4:5], off
	s_add_i32 s75, s88, 0x8000
	v_lshl_add_u64 v[8:9], v[6:7], 0, s[16:17]
	s_mov_b32 m0, s87
	s_add_i32 s85, s88, 0x8400
	global_load_lds_dwordx4 v[8:9], off
	v_lshl_add_u64 v[8:9], v[2:3], 0, s[16:17]
	s_mov_b32 m0, s75
	s_lshr_b32 s89, s86, 3
	global_load_lds_dwordx4 v[8:9], off
	v_lshl_add_u64 v[8:9], v[4:5], 0, s[16:17]
	s_mov_b32 m0, s85
	s_and_b32 s89, s89, 0x1fffff0
	global_load_lds_dwordx4 v[8:9], off
	v_or_b32_e32 v10, s89, v195
	v_and_or_b32 v8, s86, 64, v195
	s_add_i32 s89, s4, 0xc000
	v_lshlrev_b32_e32 v16, 7, v8
	s_waitcnt vmcnt(3)
	s_add_i32 s86, s88, 0xe000
	v_lshl_add_u64 v[8:9], v[6:7], 0, s[18:19]
	s_mov_b32 m0, s89
	s_waitcnt lgkmcnt(0)
	s_barrier
	global_load_lds_dwordx4 v[8:9], off
	v_lshl_add_u64 v[8:9], v[2:3], 0, s[18:19]
	s_mov_b32 m0, s86
	s_add_i32 s88, s88, 0xe400
	global_load_lds_dwordx4 v[8:9], off
	v_lshl_add_u64 v[8:9], v[4:5], 0, s[18:19]
	s_mov_b32 m0, s88
	v_lshl_add_u32 v10, v10, 7, 0
	global_load_lds_dwordx4 v[8:9], off
	v_add_u32_e32 v8, v10, v109
	v_add_u32_e32 v9, v111, v16
	ds_read_b128 v[12:15], v8
	ds_read_b128 v[22:25], v9 offset:8192
	ds_read_b128 v[26:29], v9 offset:10240
	s_waitcnt vmcnt(0)
	ds_read_b128 v[30:33], v9 offset:12288
	ds_read_b128 v[34:37], v9 offset:14336
	v_readlane_b32 s37, v251, 2
	v_readlane_b32 s38, v251, 3
	v_readlane_b32 s39, v251, 4
	v_readlane_b32 s40, v251, 5
	v_readlane_b32 s41, v251, 6
	v_readlane_b32 s42, v251, 7
	v_readlane_b32 s43, v251, 8
	v_readlane_b32 s44, v251, 9
	v_readlane_b32 s45, v251, 10
	v_readlane_b32 s46, v251, 11
	v_readlane_b32 s47, v251, 12
	v_readlane_b32 s50, v251, 15
	v_readlane_b32 s51, v251, 16
	v_add_u32_e32 v11, v10, v110
	v_add_u32_e32 v10, v112, v16
	ds_read_b128 v[38:41], v11
	ds_read_b128 v[42:45], v10 offset:8192
	ds_read_b128 v[46:49], v10 offset:10240
	ds_read_b128 v[52:55], v10 offset:12288
	ds_read_b128 v[56:59], v10 offset:14336
	s_waitcnt lgkmcnt(0)
	v_mfma_f32_16x16x32_bf16 v[22:25], v[12:15], v[22:25], 0
	v_mfma_f32_16x16x32_bf16 v[26:29], v[12:15], v[26:29], 0
	v_mfma_f32_16x16x32_bf16 v[30:33], v[12:15], v[30:33], 0
	v_mfma_f32_16x16x32_bf16 v[12:15], v[12:15], v[34:37], 0
	v_mfma_f32_16x16x32_bf16 v[22:25], v[38:41], v[42:45], v[22:25]
	v_mfma_f32_16x16x32_bf16 v[26:29], v[38:41], v[46:49], v[26:29]
	v_mfma_f32_16x16x32_bf16 v[30:33], v[38:41], v[52:55], v[30:33]
	v_mfma_f32_16x16x32_bf16 v[12:15], v[38:41], v[56:59], v[12:15]
	s_mov_b32 m0, s4
	s_waitcnt vmcnt(3)
	v_lshl_add_u64 v[16:17], v[6:7], 0, s[28:29]
	s_waitcnt lgkmcnt(0)
	s_barrier
	global_load_lds_dwordx4 v[16:17], off
	v_lshl_add_u64 v[16:17], v[2:3], 0, s[28:29]
	s_mov_b32 m0, s0
	s_nop 0
	global_load_lds_dwordx4 v[16:17], off
	v_lshl_add_u64 v[16:17], v[4:5], 0, s[28:29]
	s_mov_b32 m0, s1
	s_nop 0
	global_load_lds_dwordx4 v[16:17], off
	ds_read_b128 v[34:37], v8 offset:24576
	ds_read_b128 v[38:41], v9 offset:32768
	ds_read_b128 v[42:45], v9 offset:34816
	ds_read_b128 v[46:49], v9 offset:36864
	ds_read_b128 v[52:55], v9 offset:38912
	ds_read_b128 v[56:59], v11 offset:24576
	ds_read_b128 v[60:63], v10 offset:32768
	ds_read_b128 v[70:73], v10 offset:34816
	ds_read_b128 v[74:77], v10 offset:36864
	ds_read_b128 v[78:81], v10 offset:38912
	s_waitcnt lgkmcnt(0)
	v_mfma_f32_16x16x32_bf16 v[22:25], v[34:37], v[38:41], v[22:25]
	v_mfma_f32_16x16x32_bf16 v[26:29], v[34:37], v[42:45], v[26:29]
	v_mfma_f32_16x16x32_bf16 v[30:33], v[34:37], v[46:49], v[30:33]
	v_mfma_f32_16x16x32_bf16 v[12:15], v[34:37], v[52:55], v[12:15]
	v_mfma_f32_16x16x32_bf16 v[22:25], v[56:59], v[60:63], v[22:25]
	v_mfma_f32_16x16x32_bf16 v[26:29], v[56:59], v[70:73], v[26:29]
	v_mfma_f32_16x16x32_bf16 v[30:33], v[56:59], v[74:77], v[30:33]
	v_mfma_f32_16x16x32_bf16 v[12:15], v[56:59], v[78:81], v[12:15]
	s_mov_b32 m0, s87
	s_waitcnt vmcnt(3)
	v_lshl_add_u64 v[16:17], v[6:7], 0, s[30:31]
	s_waitcnt lgkmcnt(0)
	s_barrier
; DI f32x4 mfma16(bf16x8 a, bf16x8 b, f32x4 c) { return __builtin_amdgcn_mfma_f32_16x16x32_bf16(a, b, c, 0, 0, 0); }
; #define RAW_BARRIER() do { asm volatile("s_waitcnt lgkmcnt(0)" ::: "memory"); __builtin_amdgcn_s_barrier(); } while (0)
; template <int N> DI void wait_vmcnt() { asm volatile("s_waitcnt vmcnt(%0)" ::"n"(N) : "memory"); }
;     ...
;   for (int kt = 0; kt < 16; kt++) {
;     if (NST == 3) { if (kt + 1 < 16) wait_vmcnt<NI>(); else wait_vmcnt<0>(); }
;     else wait_vmcnt<0>();
;     RAW_BARRIER();
;     if (NST == 3) { if (kt + 2 < 16) glds(kt + 2, (kt + 2) % 3); }
;     else { if (kt + 1 < 16) glds(kt + 1, (kt + 1) & 1); }
;     const char* As = smem + (NST == 3 ? kt % 3 : kt & 1) * STAGE;
;     const char* Bs = As + BM * 128;
;     bf16x8 af[2][TM], bfr[2][NJ];
; #pragma unroll
;     for (int kk = 0; kk < 2; kk++) {
;       const int coff = ((kk * 4 + l4) ^ swz) << 4;
; #pragma unroll
;       for (int i = 0; i < TM; i++) af[kk][i] = *(const bf16x8*)(As + (wm * (TM * 16) + i * 16 + l15) * 128 + coff);
; #pragma unroll
;       for (int j = 0; j < NJ; j++) {
;         int nrow = MERGE ? ((j >> 1) * 64 + wn * 32 + (j & 1) * 16) : (wn * 64 + j * 16);
;         bfr[kk][j] = *(const bf16x8*)(Bs + (nrow + l15) * 128 + coff);
;       }
;       __builtin_amdgcn_sched_barrier(0);
;     }
; #pragma unroll
;     for (int kk = 0; kk < 2; kk++) {
; #pragma unroll
;       for (int i = 0; i < TM; i++)
; #pragma unroll
;         for (int j = 0; j < NJ; j++) acc[i][j] = SWAP ? mfma16(bfr[kk][j], af[kk][i], acc[i][j]) : mfma16(af[kk][i], bfr[kk][j], acc[i][j]);
;       __builtin_amdgcn_sched_barrier(0);
;     }
;   }
	global_load_lds_dwordx4 v[16:17], off
	v_lshl_add_u64 v[16:17], v[2:3], 0, s[30:31]
	s_mov_b32 m0, s75
	s_nop 0
	global_load_lds_dwordx4 v[16:17], off
	v_lshl_add_u64 v[16:17], v[4:5], 0, s[30:31]
	s_mov_b32 m0, s85
	s_nop 0
	global_load_lds_dwordx4 v[16:17], off
	ds_read_b128 v[34:37], v8 offset:49152
	ds_read_b128 v[38:41], v9 offset:57344
	ds_read_b128 v[42:45], v9 offset:59392
	ds_read_b128 v[46:49], v9 offset:61440
	ds_read_b128 v[52:55], v9 offset:63488
	ds_read_b128 v[56:59], v11 offset:49152
	ds_read_b128 v[60:63], v10 offset:57344
	ds_read_b128 v[70:73], v10 offset:59392
	ds_read_b128 v[74:77], v10 offset:61440
	ds_read_b128 v[78:81], v10 offset:63488
	s_waitcnt lgkmcnt(0)
	v_mfma_f32_16x16x32_bf16 v[22:25], v[34:37], v[38:41], v[22:25]
	v_mfma_f32_16x16x32_bf16 v[26:29], v[34:37], v[42:45], v[26:29]
	v_mfma_f32_16x16x32_bf16 v[30:33], v[34:37], v[46:49], v[30:33]
	v_mfma_f32_16x16x32_bf16 v[12:15], v[34:37], v[52:55], v[12:15]
	v_mfma_f32_16x16x32_bf16 v[22:25], v[56:59], v[60:63], v[22:25]
	v_mfma_f32_16x16x32_bf16 v[26:29], v[56:59], v[70:73], v[26:29]
	v_mfma_f32_16x16x32_bf16 v[30:33], v[56:59], v[74:77], v[30:33]
	v_mfma_f32_16x16x32_bf16 v[12:15], v[56:59], v[78:81], v[12:15]
	s_mov_b32 m0, s89
	s_waitcnt vmcnt(3)
	v_lshl_add_u64 v[16:17], v[6:7], 0, s[34:35]
	s_waitcnt lgkmcnt(0)
	s_barrier
	global_load_lds_dwordx4 v[16:17], off
	v_lshl_add_u64 v[16:17], v[2:3], 0, s[34:35]
	s_mov_b32 m0, s86
	s_nop 0
	global_load_lds_dwordx4 v[16:17], off
	v_lshl_add_u64 v[16:17], v[4:5], 0, s[34:35]
	s_mov_b32 m0, s88
	s_nop 0
	global_load_lds_dwordx4 v[16:17], off
	ds_read_b128 v[34:37], v8
	ds_read_b128 v[38:41], v9 offset:8192
	ds_read_b128 v[42:45], v9 offset:10240
	ds_read_b128 v[46:49], v9 offset:12288
	ds_read_b128 v[52:55], v9 offset:14336
	ds_read_b128 v[56:59], v11
	ds_read_b128 v[60:63], v10 offset:8192
	ds_read_b128 v[70:73], v10 offset:10240
	ds_read_b128 v[74:77], v10 offset:12288
	ds_read_b128 v[78:81], v10 offset:14336
	s_waitcnt lgkmcnt(0)
	v_mfma_f32_16x16x32_bf16 v[22:25], v[34:37], v[38:41], v[22:25]
	v_mfma_f32_16x16x32_bf16 v[26:29], v[34:37], v[42:45], v[26:29]
	v_mfma_f32_16x16x32_bf16 v[30:33], v[34:37], v[46:49], v[30:33]
	v_mfma_f32_16x16x32_bf16 v[12:15], v[34:37], v[52:55], v[12:15]
	v_mfma_f32_16x16x32_bf16 v[22:25], v[56:59], v[60:63], v[22:25]
	v_mfma_f32_16x16x32_bf16 v[26:29], v[56:59], v[70:73], v[26:29]
	v_mfma_f32_16x16x32_bf16 v[30:33], v[56:59], v[74:77], v[30:33]
	v_mfma_f32_16x16x32_bf16 v[12:15], v[56:59], v[78:81], v[12:15]
	s_mov_b32 m0, s4
	s_waitcnt vmcnt(3)
	v_lshl_add_u64 v[16:17], v[6:7], 0, s[52:53]
	s_waitcnt lgkmcnt(0)
	s_barrier
	global_load_lds_dwordx4 v[16:17], off
	v_lshl_add_u64 v[16:17], v[2:3], 0, s[52:53]
	s_mov_b32 m0, s0
	s_nop 0
	global_load_lds_dwordx4 v[16:17], off
	v_lshl_add_u64 v[16:17], v[4:5], 0, s[52:53]
	s_mov_b32 m0, s1
	s_nop 0
	global_load_lds_dwordx4 v[16:17], off
	ds_read_b128 v[34:37], v8 offset:24576
	ds_read_b128 v[38:41], v9 offset:32768
	ds_read_b128 v[42:45], v9 offset:34816
	ds_read_b128 v[46:49], v9 offset:36864
	ds_read_b128 v[52:55], v9 offset:38912
	ds_read_b128 v[56:59], v11 offset:24576
	ds_read_b128 v[60:63], v10 offset:32768
	ds_read_b128 v[70:73], v10 offset:34816
	ds_read_b128 v[74:77], v10 offset:36864
	ds_read_b128 v[78:81], v10 offset:38912
	s_waitcnt lgkmcnt(0)
	v_mfma_f32_16x16x32_bf16 v[22:25], v[34:37], v[38:41], v[22:25]
	v_mfma_f32_16x16x32_bf16 v[26:29], v[34:37], v[42:45], v[26:29]
	v_mfma_f32_16x16x32_bf16 v[30:33], v[34:37], v[46:49], v[30:33]
	v_mfma_f32_16x16x32_bf16 v[12:15], v[34:37], v[52:55], v[12:15]
	v_mfma_f32_16x16x32_bf16 v[22:25], v[56:59], v[60:63], v[22:25]
	v_mfma_f32_16x16x32_bf16 v[26:29], v[56:59], v[70:73], v[26:29]
	v_mfma_f32_16x16x32_bf16 v[30:33], v[56:59], v[74:77], v[30:33]
	v_mfma_f32_16x16x32_bf16 v[12:15], v[56:59], v[78:81], v[12:15]
	s_mov_b32 m0, s87
	s_waitcnt vmcnt(3)
	v_lshl_add_u64 v[16:17], v[6:7], 0, s[54:55]
	s_waitcnt lgkmcnt(0)
	s_barrier
	global_load_lds_dwordx4 v[16:17], off
	v_lshl_add_u64 v[16:17], v[2:3], 0, s[54:55]
	s_mov_b32 m0, s75
	s_nop 0
	global_load_lds_dwordx4 v[16:17], off
	v_lshl_add_u64 v[16:17], v[4:5], 0, s[54:55]
	s_mov_b32 m0, s85
	s_nop 0
	global_load_lds_dwordx4 v[16:17], off
	ds_read_b128 v[34:37], v8 offset:49152
	ds_read_b128 v[38:41], v9 offset:57344
	ds_read_b128 v[42:45], v9 offset:59392
	ds_read_b128 v[46:49], v9 offset:61440
	ds_read_b128 v[52:55], v9 offset:63488
	ds_read_b128 v[56:59], v11 offset:49152
	ds_read_b128 v[60:63], v10 offset:57344
	ds_read_b128 v[70:73], v10 offset:59392
	ds_read_b128 v[74:77], v10 offset:61440
	ds_read_b128 v[78:81], v10 offset:63488
	s_waitcnt lgkmcnt(0)
	v_mfma_f32_16x16x32_bf16 v[22:25], v[34:37], v[38:41], v[22:25]
	v_mfma_f32_16x16x32_bf16 v[26:29], v[34:37], v[42:45], v[26:29]
	v_mfma_f32_16x16x32_bf16 v[30:33], v[34:37], v[46:49], v[30:33]
	v_mfma_f32_16x16x32_bf16 v[12:15], v[34:37], v[52:55], v[12:15]
	v_mfma_f32_16x16x32_bf16 v[22:25], v[56:59], v[60:63], v[22:25]
	v_mfma_f32_16x16x32_bf16 v[26:29], v[56:59], v[70:73], v[26:29]
	v_mfma_f32_16x16x32_bf16 v[30:33], v[56:59], v[74:77], v[30:33]
	v_mfma_f32_16x16x32_bf16 v[12:15], v[56:59], v[78:81], v[12:15]
	s_mov_b32 m0, s89
	s_waitcnt vmcnt(3)
	v_lshl_add_u64 v[16:17], v[6:7], 0, s[56:57]
	s_waitcnt lgkmcnt(0)
	s_barrier
; DI f32x4 mfma16(bf16x8 a, bf16x8 b, f32x4 c) { return __builtin_amdgcn_mfma_f32_16x16x32_bf16(a, b, c, 0, 0, 0); }
; #define RAW_BARRIER() do { asm volatile("s_waitcnt lgkmcnt(0)" ::: "memory"); __builtin_amdgcn_s_barrier(); } while (0)
; template <int N> DI void wait_vmcnt() { asm volatile("s_waitcnt vmcnt(%0)" ::"n"(N) : "memory"); }
;     ...
;   for (int kt = 0; kt < 16; kt++) {
;     if (NST == 3) { if (kt + 1 < 16) wait_vmcnt<NI>(); else wait_vmcnt<0>(); }
;     else wait_vmcnt<0>();
;     RAW_BARRIER();
;     if (NST == 3) { if (kt + 2 < 16) glds(kt + 2, (kt + 2) % 3); }
;     else { if (kt + 1 < 16) glds(kt + 1, (kt + 1) & 1); }
;     const char* As = smem + (NST == 3 ? kt % 3 : kt & 1) * STAGE;
;     const char* Bs = As + BM * 128;
;     bf16x8 af[2][TM], bfr[2][NJ];
; #pragma unroll
;     for (int kk = 0; kk < 2; kk++) {
;       const int coff = ((kk * 4 + l4) ^ swz) << 4;
; #pragma unroll
;       for (int i = 0; i < TM; i++) af[kk][i] = *(const bf16x8*)(As + (wm * (TM * 16) + i * 16 + l15) * 128 + coff);
; #pragma unroll
;       for (int j = 0; j < NJ; j++) {
;         int nrow = MERGE ? ((j >> 1) * 64 + wn * 32 + (j & 1) * 16) : (wn * 64 + j * 16);
;         bfr[kk][j] = *(const bf16x8*)(Bs + (nrow + l15) * 128 + coff);
;       }
;       __builtin_amdgcn_sched_barrier(0);
;     }
; #pragma unroll
;     for (int kk = 0; kk < 2; kk++) {
; #pragma unroll
;       for (int i = 0; i < TM; i++)
; #pragma unroll
;         for (int j = 0; j < NJ; j++) acc[i][j] = SWAP ? mfma16(bfr[kk][j], af[kk][i], acc[i][j]) : mfma16(af[kk][i], bfr[kk][j], acc[i][j]);
;       __builtin_amdgcn_sched_barrier(0);
;     }
;   }
	global_load_lds_dwordx4 v[16:17], off
	v_lshl_add_u64 v[16:17], v[2:3], 0, s[56:57]
	s_mov_b32 m0, s86
	s_nop 0
	global_load_lds_dwordx4 v[16:17], off
	v_lshl_add_u64 v[16:17], v[4:5], 0, s[56:57]
	s_mov_b32 m0, s88
	s_nop 0
	global_load_lds_dwordx4 v[16:17], off
	ds_read_b128 v[34:37], v8
	ds_read_b128 v[38:41], v9 offset:8192
	ds_read_b128 v[42:45], v9 offset:10240
	ds_read_b128 v[46:49], v9 offset:12288
	ds_read_b128 v[52:55], v9 offset:14336
	ds_read_b128 v[56:59], v11
	ds_read_b128 v[60:63], v10 offset:8192
	ds_read_b128 v[70:73], v10 offset:10240
	ds_read_b128 v[74:77], v10 offset:12288
	ds_read_b128 v[78:81], v10 offset:14336
	s_waitcnt lgkmcnt(0)
	v_mfma_f32_16x16x32_bf16 v[22:25], v[34:37], v[38:41], v[22:25]
	v_mfma_f32_16x16x32_bf16 v[26:29], v[34:37], v[42:45], v[26:29]
	v_mfma_f32_16x16x32_bf16 v[30:33], v[34:37], v[46:49], v[30:33]
	v_mfma_f32_16x16x32_bf16 v[12:15], v[34:37], v[52:55], v[12:15]
	v_mfma_f32_16x16x32_bf16 v[22:25], v[56:59], v[60:63], v[22:25]
	v_mfma_f32_16x16x32_bf16 v[26:29], v[56:59], v[70:73], v[26:29]
	v_mfma_f32_16x16x32_bf16 v[30:33], v[56:59], v[74:77], v[30:33]
	v_mfma_f32_16x16x32_bf16 v[12:15], v[56:59], v[78:81], v[12:15]
	s_mov_b32 m0, s4
	s_waitcnt vmcnt(3)
	v_lshl_add_u64 v[16:17], v[6:7], 0, s[58:59]
	s_waitcnt lgkmcnt(0)
	s_barrier
	global_load_lds_dwordx4 v[16:17], off
	v_lshl_add_u64 v[16:17], v[2:3], 0, s[58:59]
	s_mov_b32 m0, s0
	s_nop 0
	global_load_lds_dwordx4 v[16:17], off
	v_lshl_add_u64 v[16:17], v[4:5], 0, s[58:59]
	s_mov_b32 m0, s1
	s_nop 0
	global_load_lds_dwordx4 v[16:17], off
	ds_read_b128 v[34:37], v8 offset:24576
	ds_read_b128 v[38:41], v9 offset:32768
	ds_read_b128 v[42:45], v9 offset:34816
	ds_read_b128 v[46:49], v9 offset:36864
	ds_read_b128 v[52:55], v9 offset:38912
	ds_read_b128 v[56:59], v11 offset:24576
	ds_read_b128 v[60:63], v10 offset:32768
	ds_read_b128 v[70:73], v10 offset:34816
	ds_read_b128 v[74:77], v10 offset:36864
	ds_read_b128 v[78:81], v10 offset:38912
	s_waitcnt lgkmcnt(0)
	v_mfma_f32_16x16x32_bf16 v[22:25], v[34:37], v[38:41], v[22:25]
	v_mfma_f32_16x16x32_bf16 v[26:29], v[34:37], v[42:45], v[26:29]
	v_mfma_f32_16x16x32_bf16 v[30:33], v[34:37], v[46:49], v[30:33]
	v_mfma_f32_16x16x32_bf16 v[12:15], v[34:37], v[52:55], v[12:15]
	v_mfma_f32_16x16x32_bf16 v[22:25], v[56:59], v[60:63], v[22:25]
	v_mfma_f32_16x16x32_bf16 v[26:29], v[56:59], v[70:73], v[26:29]
	v_mfma_f32_16x16x32_bf16 v[30:33], v[56:59], v[74:77], v[30:33]
	v_mfma_f32_16x16x32_bf16 v[12:15], v[56:59], v[78:81], v[12:15]
	s_mov_b32 m0, s87
	s_waitcnt vmcnt(3)
	v_lshl_add_u64 v[16:17], v[6:7], 0, s[60:61]
	s_waitcnt lgkmcnt(0)
	s_barrier
	global_load_lds_dwordx4 v[16:17], off
	v_lshl_add_u64 v[16:17], v[2:3], 0, s[60:61]
	s_mov_b32 m0, s75
	s_nop 0
	global_load_lds_dwordx4 v[16:17], off
	v_lshl_add_u64 v[16:17], v[4:5], 0, s[60:61]
	s_mov_b32 m0, s85
	s_nop 0
	global_load_lds_dwordx4 v[16:17], off
	ds_read_b128 v[34:37], v8 offset:49152
	ds_read_b128 v[38:41], v9 offset:57344
	ds_read_b128 v[42:45], v9 offset:59392
	ds_read_b128 v[46:49], v9 offset:61440
	ds_read_b128 v[52:55], v9 offset:63488
	ds_read_b128 v[56:59], v11 offset:49152
	ds_read_b128 v[60:63], v10 offset:57344
	ds_read_b128 v[70:73], v10 offset:59392
	ds_read_b128 v[74:77], v10 offset:61440
	ds_read_b128 v[78:81], v10 offset:63488
	s_waitcnt lgkmcnt(0)
	v_mfma_f32_16x16x32_bf16 v[22:25], v[34:37], v[38:41], v[22:25]
	v_mfma_f32_16x16x32_bf16 v[26:29], v[34:37], v[42:45], v[26:29]
	v_mfma_f32_16x16x32_bf16 v[30:33], v[34:37], v[46:49], v[30:33]
	v_mfma_f32_16x16x32_bf16 v[12:15], v[34:37], v[52:55], v[12:15]
	v_mfma_f32_16x16x32_bf16 v[22:25], v[56:59], v[60:63], v[22:25]
	v_mfma_f32_16x16x32_bf16 v[26:29], v[56:59], v[70:73], v[26:29]
	v_mfma_f32_16x16x32_bf16 v[30:33], v[56:59], v[74:77], v[30:33]
	v_mfma_f32_16x16x32_bf16 v[12:15], v[56:59], v[78:81], v[12:15]
	s_mov_b32 m0, s89
	s_waitcnt vmcnt(3)
	v_lshl_add_u64 v[16:17], v[6:7], 0, s[62:63]
	s_waitcnt lgkmcnt(0)
	s_barrier
	global_load_lds_dwordx4 v[16:17], off
	v_lshl_add_u64 v[16:17], v[2:3], 0, s[62:63]
	s_mov_b32 m0, s86
	s_nop 0
	global_load_lds_dwordx4 v[16:17], off
	v_lshl_add_u64 v[16:17], v[4:5], 0, s[62:63]
	s_mov_b32 m0, s88
	s_nop 0
	global_load_lds_dwordx4 v[16:17], off
	ds_read_b128 v[34:37], v8
	ds_read_b128 v[38:41], v9 offset:8192
	ds_read_b128 v[42:45], v9 offset:10240
	ds_read_b128 v[46:49], v9 offset:12288
	ds_read_b128 v[52:55], v9 offset:14336
	ds_read_b128 v[56:59], v11
	ds_read_b128 v[60:63], v10 offset:8192
	ds_read_b128 v[70:73], v10 offset:10240
	ds_read_b128 v[74:77], v10 offset:12288
	ds_read_b128 v[78:81], v10 offset:14336
	s_waitcnt lgkmcnt(0)
	v_mfma_f32_16x16x32_bf16 v[22:25], v[34:37], v[38:41], v[22:25]
	v_mfma_f32_16x16x32_bf16 v[26:29], v[34:37], v[42:45], v[26:29]
	v_mfma_f32_16x16x32_bf16 v[30:33], v[34:37], v[46:49], v[30:33]
	v_mfma_f32_16x16x32_bf16 v[12:15], v[34:37], v[52:55], v[12:15]
	v_mfma_f32_16x16x32_bf16 v[22:25], v[56:59], v[60:63], v[22:25]
	v_mfma_f32_16x16x32_bf16 v[26:29], v[56:59], v[70:73], v[26:29]
	v_mfma_f32_16x16x32_bf16 v[30:33], v[56:59], v[74:77], v[30:33]
	v_mfma_f32_16x16x32_bf16 v[12:15], v[56:59], v[78:81], v[12:15]
	s_mov_b32 m0, s4
	s_waitcnt vmcnt(3)
	v_lshl_add_u64 v[16:17], v[6:7], 0, s[64:65]
	s_waitcnt lgkmcnt(0)
	s_barrier
; DI f32x4 mfma16(bf16x8 a, bf16x8 b, f32x4 c) { return __builtin_amdgcn_mfma_f32_16x16x32_bf16(a, b, c, 0, 0, 0); }
; #define RAW_BARRIER() do { asm volatile("s_waitcnt lgkmcnt(0)" ::: "memory"); __builtin_amdgcn_s_barrier(); } while (0)
; template <int N> DI void wait_vmcnt() { asm volatile("s_waitcnt vmcnt(%0)" ::"n"(N) : "memory"); }
;     ...
;   for (int kt = 0; kt < 16; kt++) {
;     if (NST == 3) { if (kt + 1 < 16) wait_vmcnt<NI>(); else wait_vmcnt<0>(); }
;     else wait_vmcnt<0>();
;     RAW_BARRIER();
;     if (NST == 3) { if (kt + 2 < 16) glds(kt + 2, (kt + 2) % 3); }
;     else { if (kt + 1 < 16) glds(kt + 1, (kt + 1) & 1); }
;     const char* As = smem + (NST == 3 ? kt % 3 : kt & 1) * STAGE;
;     const char* Bs = As + BM * 128;
;     bf16x8 af[2][TM], bfr[2][NJ];
; #pragma unroll
;     for (int kk = 0; kk < 2; kk++) {
;       const int coff = ((kk * 4 + l4) ^ swz) << 4;
; #pragma unroll
;       for (int i = 0; i < TM; i++) af[kk][i] = *(const bf16x8*)(As + (wm * (TM * 16) + i * 16 + l15) * 128 + coff);
; #pragma unroll
;       for (int j = 0; j < NJ; j++) {
;         int nrow = MERGE ? ((j >> 1) * 64 + wn * 32 + (j & 1) * 16) : (wn * 64 + j * 16);
;         bfr[kk][j] = *(const bf16x8*)(Bs + (nrow + l15) * 128 + coff);
;       }
;       __builtin_amdgcn_sched_barrier(0);
;     }
; #pragma unroll
;     for (int kk = 0; kk < 2; kk++) {
; #pragma unroll
;       for (int i = 0; i < TM; i++)
; #pragma unroll
;         for (int j = 0; j < NJ; j++) acc[i][j] = SWAP ? mfma16(bfr[kk][j], af[kk][i], acc[i][j]) : mfma16(af[kk][i], bfr[kk][j], acc[i][j]);
;       __builtin_amdgcn_sched_barrier(0);
;     }
;   }
	global_load_lds_dwordx4 v[16:17], off
	v_lshl_add_u64 v[16:17], v[2:3], 0, s[64:65]
	s_mov_b32 m0, s0
	s_nop 0
	global_load_lds_dwordx4 v[16:17], off
	v_lshl_add_u64 v[16:17], v[4:5], 0, s[64:65]
	s_mov_b32 m0, s1
	s_nop 0
	global_load_lds_dwordx4 v[16:17], off
	ds_read_b128 v[34:37], v8 offset:24576
	ds_read_b128 v[38:41], v9 offset:32768
	ds_read_b128 v[42:45], v9 offset:34816
	ds_read_b128 v[46:49], v9 offset:36864
	ds_read_b128 v[52:55], v9 offset:38912
	ds_read_b128 v[56:59], v11 offset:24576
	ds_read_b128 v[60:63], v10 offset:32768
	ds_read_b128 v[70:73], v10 offset:34816
	ds_read_b128 v[74:77], v10 offset:36864
	ds_read_b128 v[78:81], v10 offset:38912
	s_waitcnt lgkmcnt(0)
	v_mfma_f32_16x16x32_bf16 v[22:25], v[34:37], v[38:41], v[22:25]
	v_mfma_f32_16x16x32_bf16 v[26:29], v[34:37], v[42:45], v[26:29]
	v_mfma_f32_16x16x32_bf16 v[30:33], v[34:37], v[46:49], v[30:33]
	v_mfma_f32_16x16x32_bf16 v[12:15], v[34:37], v[52:55], v[12:15]
	v_mfma_f32_16x16x32_bf16 v[22:25], v[56:59], v[60:63], v[22:25]
	v_mfma_f32_16x16x32_bf16 v[26:29], v[56:59], v[70:73], v[26:29]
	v_mfma_f32_16x16x32_bf16 v[30:33], v[56:59], v[74:77], v[30:33]
	v_mfma_f32_16x16x32_bf16 v[12:15], v[56:59], v[78:81], v[12:15]
	s_mov_b32 m0, s87
	s_waitcnt vmcnt(3)
	v_lshl_add_u64 v[16:17], v[6:7], 0, s[66:67]
	s_waitcnt lgkmcnt(0)
	s_barrier
	global_load_lds_dwordx4 v[16:17], off
	v_lshl_add_u64 v[16:17], v[2:3], 0, s[66:67]
	s_mov_b32 m0, s75
	s_nop 0
	global_load_lds_dwordx4 v[16:17], off
	v_lshl_add_u64 v[16:17], v[4:5], 0, s[66:67]
	s_mov_b32 m0, s85
	s_nop 0
	global_load_lds_dwordx4 v[16:17], off
	ds_read_b128 v[34:37], v8 offset:49152
	ds_read_b128 v[38:41], v9 offset:57344
	ds_read_b128 v[42:45], v9 offset:59392
	ds_read_b128 v[46:49], v9 offset:61440
	ds_read_b128 v[52:55], v9 offset:63488
	ds_read_b128 v[56:59], v11 offset:49152
	ds_read_b128 v[60:63], v10 offset:57344
	ds_read_b128 v[70:73], v10 offset:59392
	ds_read_b128 v[74:77], v10 offset:61440
	ds_read_b128 v[78:81], v10 offset:63488
	s_waitcnt lgkmcnt(0)
	v_mfma_f32_16x16x32_bf16 v[22:25], v[34:37], v[38:41], v[22:25]
	v_mfma_f32_16x16x32_bf16 v[26:29], v[34:37], v[42:45], v[26:29]
	v_mfma_f32_16x16x32_bf16 v[30:33], v[34:37], v[46:49], v[30:33]
	v_mfma_f32_16x16x32_bf16 v[12:15], v[34:37], v[52:55], v[12:15]
	v_mfma_f32_16x16x32_bf16 v[22:25], v[56:59], v[60:63], v[22:25]
	v_mfma_f32_16x16x32_bf16 v[26:29], v[56:59], v[70:73], v[26:29]
	v_mfma_f32_16x16x32_bf16 v[30:33], v[56:59], v[74:77], v[30:33]
	v_mfma_f32_16x16x32_bf16 v[12:15], v[56:59], v[78:81], v[12:15]
	s_mov_b32 m0, s89
	s_waitcnt vmcnt(3)
	v_lshl_add_u64 v[16:17], v[6:7], 0, s[68:69]
	s_waitcnt lgkmcnt(0)
	s_barrier
	global_load_lds_dwordx4 v[16:17], off
	v_lshl_add_u64 v[16:17], v[2:3], 0, s[68:69]
	s_mov_b32 m0, s86
	s_nop 0
	global_load_lds_dwordx4 v[16:17], off
	v_lshl_add_u64 v[16:17], v[4:5], 0, s[68:69]
	s_mov_b32 m0, s88
	s_nop 0
	global_load_lds_dwordx4 v[16:17], off
	ds_read_b128 v[34:37], v8
	ds_read_b128 v[38:41], v9 offset:8192
	ds_read_b128 v[42:45], v9 offset:10240
	ds_read_b128 v[46:49], v9 offset:12288
	ds_read_b128 v[52:55], v9 offset:14336
	ds_read_b128 v[56:59], v11
	ds_read_b128 v[60:63], v10 offset:8192
	ds_read_b128 v[70:73], v10 offset:10240
	ds_read_b128 v[74:77], v10 offset:12288
	ds_read_b128 v[78:81], v10 offset:14336
	s_waitcnt lgkmcnt(0)
	v_mfma_f32_16x16x32_bf16 v[22:25], v[34:37], v[38:41], v[22:25]
	v_mfma_f32_16x16x32_bf16 v[26:29], v[34:37], v[42:45], v[26:29]
	v_mfma_f32_16x16x32_bf16 v[30:33], v[34:37], v[46:49], v[30:33]
	v_mfma_f32_16x16x32_bf16 v[12:15], v[34:37], v[52:55], v[12:15]
	v_mfma_f32_16x16x32_bf16 v[22:25], v[56:59], v[60:63], v[22:25]
	v_mfma_f32_16x16x32_bf16 v[26:29], v[56:59], v[70:73], v[26:29]
	v_mfma_f32_16x16x32_bf16 v[30:33], v[56:59], v[74:77], v[30:33]
	v_mfma_f32_16x16x32_bf16 v[12:15], v[56:59], v[78:81], v[12:15]
	s_mov_b32 m0, s4
	s_waitcnt vmcnt(3)
	v_lshl_add_u64 v[6:7], v[6:7], 0, s[70:71]
	s_waitcnt lgkmcnt(0)
	s_barrier
	global_load_lds_dwordx4 v[6:7], off
	v_lshl_add_u64 v[2:3], v[2:3], 0, s[70:71]
	s_mov_b32 m0, s0
	s_nop 0
	global_load_lds_dwordx4 v[2:3], off
	v_lshl_add_u64 v[2:3], v[4:5], 0, s[70:71]
	s_mov_b32 m0, s1
	s_nop 0
	global_load_lds_dwordx4 v[2:3], off
	ds_read_b128 v[2:5], v8 offset:24576
	ds_read_b128 v[34:37], v9 offset:32768
	ds_read_b128 v[38:41], v9 offset:34816
	ds_read_b128 v[42:45], v9 offset:36864
	ds_read_b128 v[46:49], v9 offset:38912
	ds_read_b128 v[52:55], v11 offset:24576
	ds_read_b128 v[56:59], v10 offset:32768
	ds_read_b128 v[60:63], v10 offset:34816
	ds_read_b128 v[70:73], v10 offset:36864
	ds_read_b128 v[74:77], v10 offset:38912
	s_waitcnt lgkmcnt(0)
	v_mfma_f32_16x16x32_bf16 v[22:25], v[2:5], v[34:37], v[22:25]
	v_mfma_f32_16x16x32_bf16 v[26:29], v[2:5], v[38:41], v[26:29]
	v_mfma_f32_16x16x32_bf16 v[30:33], v[2:5], v[42:45], v[30:33]
	v_mfma_f32_16x16x32_bf16 v[2:5], v[2:5], v[46:49], v[12:15]
	v_mfma_f32_16x16x32_bf16 v[12:15], v[52:55], v[56:59], v[22:25]
	v_mfma_f32_16x16x32_bf16 v[22:25], v[52:55], v[60:63], v[26:29]
	v_mfma_f32_16x16x32_bf16 v[26:29], v[52:55], v[70:73], v[30:33]
	v_mfma_f32_16x16x32_bf16 v[2:5], v[52:55], v[74:77], v[2:5]
	s_waitcnt vmcnt(3)
	s_waitcnt lgkmcnt(0)
	s_barrier
; DI u32 pack2(float a, float b) { f32x2 v = {a, b}; bfx2 r = __builtin_convertvector(v, bfx2); return __builtin_bit_cast(u32, r); }
; DI f32x4 mfma16(bf16x8 a, bf16x8 b, f32x4 c) { return __builtin_amdgcn_mfma_f32_16x16x32_bf16(a, b, c, 0, 0, 0); }
;     ...
; #pragma unroll
;     for (int kk = 0; kk < 2; kk++) {
; #pragma unroll
;       for (int i = 0; i < TM; i++)
; #pragma unroll
;         for (int j = 0; j < NJ; j++) acc[i][j] = SWAP ? mfma16(bfr[kk][j], af[kk][i], acc[i][j]) : mfma16(af[kk][i], bfr[kk][j], acc[i][j]);
;       __builtin_amdgcn_sched_barrier(0);
;     }
;   }
;   __syncthreads();
; template <int TM>
; DI void phase4_tile(const P& p, char* smem, int m0, int nt) {
;     ...
;       for (int i = 0; i < TM; i++) {
;         int tok = m0 + wm * (TM * 16) + i * 16 + 4 * (lane >> 4);
; #pragma unroll
;         for (int j = 0; j < 4; j++) {
;           int dv = wn * 64 + j * 16 + (lane & 15);
;           f32x4 a = acc[i][j];
;           u32x2 ov = {pack2(a[0], a[1]), pack2(a[2], a[3])};
;           if (tok < TP) {
;             int b = tok >> 14, tt = tok & 16383;
;             *(u32x2*)(Vt + ((size_t)(b * 8 + hh) * 128 + dv) * SEQ + (tt & ~15) + 4 * VPERM((tt >> 2) & 3)) = ov;
; #pragma unroll
;             for (int rr = 0; rr < 4; rr++) __builtin_nontemporal_store(a[rr], &p.out[O_VP + (size_t)(tok + rr) * 1024 + hh * 128 + dv]);
;           } else {
;             int s = (tok - TP) >> 4, tt = tok & 15;
;             *(u32x2*)(Vt + (size_t)33554432 + ((size_t)(s * 8 + hh) * 128 + dv) * 16 + 4 * VPERM((tt >> 2) & 3)) = ov;
; #pragma unroll
;             for (int rr = 0; rr < 4; rr++) __builtin_nontemporal_store(a[rr], &p.out[O_VS + (size_t)(tok - TP + rr) * 1024 + hh * 128 + dv]);
;           }
	s_nop 1
	ds_read_b128 v[30:33], v9 offset:63488
	ds_read_b128 v[34:37], v9 offset:61440
	ds_read_b128 v[38:41], v9 offset:59392
	ds_read_b128 v[42:45], v9 offset:57344
	ds_read_b128 v[46:49], v8 offset:49152
	ds_read_b128 v[52:55], v11 offset:49152
	ds_read_b128 v[56:59], v10 offset:57344
	ds_read_b128 v[60:63], v10 offset:59392
	ds_read_b128 v[70:73], v10 offset:61440
	ds_read_b128 v[74:77], v10 offset:63488
	s_waitcnt lgkmcnt(0)
	v_mfma_f32_16x16x32_bf16 v[12:15], v[46:49], v[42:45], v[12:15]
	v_mfma_f32_16x16x32_bf16 v[22:25], v[46:49], v[38:41], v[22:25]
	v_mfma_f32_16x16x32_bf16 v[26:29], v[46:49], v[34:37], v[26:29]
	v_mfma_f32_16x16x32_bf16 v[2:5], v[46:49], v[30:33], v[2:5]
	v_mfma_f32_16x16x32_bf16 v[12:15], v[52:55], v[56:59], v[12:15]
	v_mfma_f32_16x16x32_bf16 v[22:25], v[52:55], v[60:63], v[22:25]
	v_mfma_f32_16x16x32_bf16 v[26:29], v[52:55], v[70:73], v[26:29]
	v_mfma_f32_16x16x32_bf16 v[2:5], v[52:55], v[74:77], v[2:5]
	s_waitcnt vmcnt(0)
	s_waitcnt lgkmcnt(0)
	s_barrier
	ds_read_b128 v[30:33], v9 offset:14336
	ds_read_b128 v[34:37], v9 offset:12288
	ds_read_b128 v[38:41], v9 offset:10240
	ds_read_b128 v[42:45], v9 offset:8192
	ds_read_b128 v[6:9], v8
	ds_read_b128 v[46:49], v11
	ds_read_b128 v[52:55], v10 offset:8192
	ds_read_b128 v[56:59], v10 offset:10240
	ds_read_b128 v[60:63], v10 offset:12288
	ds_read_b128 v[70:73], v10 offset:14336
	s_waitcnt lgkmcnt(0)
	v_mfma_f32_16x16x32_bf16 v[10:13], v[6:9], v[42:45], v[12:15]
	v_mfma_f32_16x16x32_bf16 v[22:25], v[6:9], v[38:41], v[22:25]
	v_mfma_f32_16x16x32_bf16 v[26:29], v[6:9], v[34:37], v[26:29]
	v_mfma_f32_16x16x32_bf16 v[2:5], v[6:9], v[30:33], v[2:5]
	v_mfma_f32_16x16x32_bf16 v[14:17], v[46:49], v[52:55], v[10:13]
	v_mfma_f32_16x16x32_bf16 v[10:13], v[46:49], v[56:59], v[22:25]
	v_mfma_f32_16x16x32_bf16 v[6:9], v[46:49], v[60:63], v[26:29]
	v_mfma_f32_16x16x32_bf16 v[2:5], v[46:49], v[70:73], v[2:5]
	s_lshl_b32 s4, s79, 4
	v_or_b32_e32 v18, s78, v113
	v_add_u32_e32 v24, s4, v18
	s_add_i32 s4, s4, s74
	v_add_u32_e32 v18, s4, v113
	v_lshrrev_b32_e32 v18, 1, v18
	v_and_b32_e32 v18, 0x7ffffff8, v18
	v_subrev_u32_e32 v18, s77, v18
	v_lshl_or_b32 v21, s84, 6, v195
	v_add3_u32 v18, s82, v18, -8
	v_cmp_lt_i32_e64 s[0:1], s80, v24
	v_add_u32_e32 v30, 0xffff8000, v24
	v_lshlrev_b64 v[38:39], 11, v[18:19]
	s_add_i32 s4, s83, 0xfffffc00
	v_cvt_pk_bf16_f32 v44, v14, v15
	v_cvt_pk_bf16_f32 v45, v16, v17
	v_add_u32_e32 v28, 0xffff8001, v24
	v_add_u32_e32 v26, 0xffff8002, v24
	v_add_u32_e32 v22, 0xffff8003, v24
	v_lshlrev_b32_e32 v18, 2, v21
	s_waitcnt vmcnt(0)
	s_barrier
	s_and_saveexec_b64 s[74:75], s[0:1]
	s_xor_b64 s[74:75], exec, s[74:75]
	s_cbranch_execz .LBB0_685
	v_lshlrev_b32_e32 v32, 5, v21
	v_mov_b32_e32 v33, v19
	v_lshl_add_u64 v[32:33], v[68:69], 0, v[32:33]
	v_lshl_add_u64 v[32:33], v[38:39], 1, v[32:33]
	v_mov_b32_e32 v31, v19
	v_readlane_b32 s36, v251, 1
	global_store_dwordx2 v[32:33], v[44:45], off
	v_lshlrev_b64 v[32:33], 12, v[30:31]
	v_readlane_b32 s48, v251, 13
	v_readlane_b32 s49, v251, 14
	s_lshl_b64 s[86:87], s[4:5], 2
	v_mov_b32_e32 v29, v19
	v_lshl_add_u64 v[32:33], s[48:49], 0, v[32:33]
	v_lshl_add_u64 v[32:33], v[32:33], 0, s[86:87]
	v_lshl_add_u64 v[32:33], v[32:33], 0, v[18:19]
	v_add_co_u32_e32 v32, vcc, 0x18312000, v32
	v_mov_b32_e32 v27, v19
	s_nop 0
	v_addc_co_u32_e32 v33, vcc, 0, v33, vcc
	global_store_dword v[32:33], v14, off nt
	v_lshlrev_b64 v[32:33], 12, v[28:29]
	v_lshl_add_u64 v[32:33], s[48:49], 0, v[32:33]
	v_lshl_add_u64 v[32:33], v[32:33], 0, s[86:87]
	v_lshl_add_u64 v[32:33], v[32:33], 0, v[18:19]
	v_add_co_u32_e32 v32, vcc, 0x18312000, v32
	v_mov_b32_e32 v23, v19
	s_nop 0
	v_addc_co_u32_e32 v33, vcc, 0, v33, vcc
	global_store_dword v[32:33], v15, off nt
	v_lshlrev_b64 v[32:33], 12, v[26:27]
	v_lshl_add_u64 v[32:33], s[48:49], 0, v[32:33]
	v_lshl_add_u64 v[32:33], v[32:33], 0, s[86:87]
	v_lshl_add_u64 v[32:33], v[32:33], 0, v[18:19]
	v_add_co_u32_e32 v32, vcc, 0x18312000, v32
	v_readlane_b32 s37, v251, 2
	s_nop 0
	v_addc_co_u32_e32 v33, vcc, 0, v33, vcc
	v_readlane_b32 s38, v251, 3
	v_readlane_b32 s39, v251, 4
	v_readlane_b32 s40, v251, 5
	v_readlane_b32 s41, v251, 6
	v_readlane_b32 s42, v251, 7
	v_readlane_b32 s43, v251, 8
	v_readlane_b32 s44, v251, 9
	v_readlane_b32 s45, v251, 10
	v_readlane_b32 s46, v251, 11
	v_readlane_b32 s47, v251, 12
	v_readlane_b32 s50, v251, 15
	v_readlane_b32 s51, v251, 16
	global_store_dword v[32:33], v16, off nt
	v_mov_b64_e32 v[46:47], v[22:23]

; DI f32x4 mfma16(bf16x8 a, bf16x8 b, f32x4 c) { return __builtin_amdgcn_mfma_f32_16x16x32_bf16(a, b, c, 0, 0, 0); }
; #define RAW_BARRIER() do { asm volatile("s_waitcnt lgkmcnt(0)" ::: "memory"); __builtin_amdgcn_s_barrier(); } while (0)
; template <int N> DI void wait_vmcnt() { asm volatile("s_waitcnt vmcnt(%0)" ::"n"(N) : "memory"); }
;     ...
;   __syncthreads();
;   wait_vmcnt<0>();
;   glds(0, 0);
;   if (NST == 3) glds(1, 1);
;   for (int kt = 0; kt < 16; kt++) {
;     if (NST == 3) { if (kt + 1 < 16) wait_vmcnt<NI>(); else wait_vmcnt<0>(); }
;     else wait_vmcnt<0>();
;     RAW_BARRIER();
;     if (NST == 3) { if (kt + 2 < 16) glds(kt + 2, (kt + 2) % 3); }
;     else { if (kt + 1 < 16) glds(kt + 1, (kt + 1) & 1); }
;     const char* As = smem + (NST == 3 ? kt % 3 : kt & 1) * STAGE;
;     const char* Bs = As + BM * 128;
;     bf16x8 af[2][TM], bfr[2][NJ];
; #pragma unroll
;     for (int kk = 0; kk < 2; kk++) {
;       const int coff = ((kk * 4 + l4) ^ swz) << 4;
; #pragma unroll
;       for (int i = 0; i < TM; i++) af[kk][i] = *(const bf16x8*)(As + (wm * (TM * 16) + i * 16 + l15) * 128 + coff);
; #pragma unroll
;       for (int j = 0; j < NJ; j++) {
;         int nrow = MERGE ? ((j >> 1) * 64 + wn * 32 + (j & 1) * 16) : (wn * 64 + j * 16);
;         bfr[kk][j] = *(const bf16x8*)(Bs + (nrow + l15) * 128 + coff);
;       }
;       __builtin_amdgcn_sched_barrier(0);
;     }
; #pragma unroll
;     for (int kk = 0; kk < 2; kk++) {
; #pragma unroll
;       for (int i = 0; i < TM; i++)
; #pragma unroll
;         for (int j = 0; j < NJ; j++) acc[i][j] = SWAP ? mfma16(bfr[kk][j], af[kk][i], acc[i][j]) : mfma16(af[kk][i], bfr[kk][j], acc[i][j]);
;       __builtin_amdgcn_sched_barrier(0);
;     }
;   }
.LBB0_700:
	s_and_b64 vcc, exec, s[0:1]
	s_cbranch_vccz .LBB0_681
	v_readfirstlane_b32 s86, v1
	s_lshr_b32 s0, s86, 6
	v_lshl_or_b32 v2, s0, 3, v187
	v_lshrrev_b32_e32 v3, 1, v2
	v_add_u32_e32 v2, s78, v2
	v_xor_b32_e32 v8, v3, v1
	v_ashrrev_i32_e32 v3, 31, v2
	v_lshl_or_b32 v18, s0, 4, v187
	v_lshlrev_b64 v[6:7], 11, v[2:3]
	v_lshlrev_b64 v[2:3], 11, v[18:19]
	v_or_b32_e32 v18, 8, v18
	v_lshrrev_b32_e32 v4, 1, v18
	v_xor_b32_e32 v9, v4, v1
	v_lshlrev_b64 v[4:5], 11, v[18:19]
	v_lshlrev_b32_e32 v9, 4, v9
	v_readlane_b32 s36, v251, 1
	s_lshl_b32 s0, s0, 10
	v_lshl_add_u64 v[2:3], s[2:3], 0, v[2:3]
	v_lshl_add_u64 v[4:5], s[2:3], 0, v[4:5]
	v_and_b32_e32 v18, 0x70, v9
	v_readlane_b32 s48, v251, 13
	v_readlane_b32 s49, v251, 14
	v_lshlrev_b32_e32 v8, 4, v8
	s_add_i32 s2, s0, 0
	v_lshl_add_u64 v[4:5], v[4:5], 0, v[18:19]
	v_lshl_add_u64 v[6:7], s[48:49], 0, v[6:7]
	v_and_b32_e32 v18, 0x70, v8
	s_add_i32 s4, s2, s0
	v_mov_b32_e32 v21, v19
	v_lshl_add_u64 v[6:7], v[6:7], 0, v[18:19]
	s_waitcnt vmcnt(63) expcnt(7) lgkmcnt(15)
	s_barrier
	s_nop 0
	s_add_i32 s0, s4, 0x2000
	s_mov_b32 m0, s2
	v_lshl_add_u64 v[2:3], v[2:3], 0, v[20:21]
	global_load_lds_dwordx4 v[6:7], off
	s_mov_b32 m0, s0
	s_add_i32 s1, s4, 0x2400
	global_load_lds_dwordx4 v[2:3], off
	s_mov_b32 m0, s1
	s_add_i32 s85, s2, 0x6000
	global_load_lds_dwordx4 v[4:5], off
	s_add_i32 s75, s4, 0x8000
	v_lshl_add_u64 v[8:9], v[6:7], 0, s[16:17]
	s_mov_b32 m0, s85
	s_add_i32 s77, s4, 0x8400
	global_load_lds_dwordx4 v[8:9], off
	v_lshl_add_u64 v[8:9], v[2:3], 0, s[16:17]
	s_mov_b32 m0, s75
	s_add_i32 s74, s2, 0xc000
	global_load_lds_dwordx4 v[8:9], off
	v_lshl_add_u64 v[8:9], v[4:5], 0, s[16:17]
	s_mov_b32 m0, s77
	s_add_i32 s3, s4, 0xe000
	global_load_lds_dwordx4 v[8:9], off
	s_waitcnt vmcnt(3)
	v_lshl_add_u64 v[8:9], v[6:7], 0, s[18:19]
	s_mov_b32 m0, s74
	s_waitcnt lgkmcnt(0)
	s_barrier
	global_load_lds_dwordx4 v[8:9], off
	v_lshl_add_u64 v[8:9], v[2:3], 0, s[18:19]
	s_mov_b32 m0, s3
	s_add_i32 s4, s4, 0xe400
	global_load_lds_dwordx4 v[8:9], off
	v_lshl_add_u64 v[8:9], v[4:5], 0, s[18:19]
	s_mov_b32 m0, s4
	s_lshr_b32 s87, s86, 3
	global_load_lds_dwordx4 v[8:9], off
	s_and_b32 s87, s87, 0x1fffff0
	v_or_b32_e32 v8, s87, v195
	v_and_or_b32 v9, s86, 64, v195
	v_lshl_add_u32 v11, v8, 7, 0
	v_lshlrev_b32_e32 v10, 7, v9
	v_add_u32_e32 v8, v11, v109
	v_add_u32_e32 v9, v111, v10
	ds_read_b128 v[12:15], v8
	ds_read_b128 v[22:25], v9 offset:8192
	ds_read_b128 v[26:29], v9 offset:10240
	s_waitcnt vmcnt(0)
	ds_read_b128 v[30:33], v9 offset:12288
	ds_read_b128 v[34:37], v9 offset:14336
	v_readlane_b32 s37, v251, 2
	v_readlane_b32 s38, v251, 3
	v_readlane_b32 s39, v251, 4
	v_readlane_b32 s40, v251, 5
	v_readlane_b32 s41, v251, 6
	v_readlane_b32 s42, v251, 7
	v_readlane_b32 s43, v251, 8
	v_readlane_b32 s44, v251, 9
	v_readlane_b32 s45, v251, 10
	v_readlane_b32 s46, v251, 11
	v_readlane_b32 s47, v251, 12
	v_readlane_b32 s50, v251, 15
	v_readlane_b32 s51, v251, 16
	v_add_u32_e32 v11, v11, v110
	v_add_u32_e32 v10, v112, v10
	ds_read_b128 v[38:41], v11
	ds_read_b128 v[42:45], v10 offset:8192
	ds_read_b128 v[46:49], v10 offset:10240
	ds_read_b128 v[52:55], v10 offset:12288
	ds_read_b128 v[56:59], v10 offset:14336
	s_waitcnt lgkmcnt(0)
	v_mfma_f32_16x16x32_bf16 v[22:25], v[22:25], v[12:15], 0
	v_mfma_f32_16x16x32_bf16 v[26:29], v[26:29], v[12:15], 0
	v_mfma_f32_16x16x32_bf16 v[30:33], v[30:33], v[12:15], 0
	v_mfma_f32_16x16x32_bf16 v[12:15], v[34:37], v[12:15], 0
	v_mfma_f32_16x16x32_bf16 v[22:25], v[42:45], v[38:41], v[22:25]
	v_mfma_f32_16x16x32_bf16 v[26:29], v[46:49], v[38:41], v[26:29]
	v_mfma_f32_16x16x32_bf16 v[30:33], v[52:55], v[38:41], v[30:33]
	v_mfma_f32_16x16x32_bf16 v[12:15], v[56:59], v[38:41], v[12:15]
	s_mov_b32 m0, s2
	s_waitcnt vmcnt(3)
	v_lshl_add_u64 v[16:17], v[6:7], 0, s[28:29]
	s_waitcnt lgkmcnt(0)
	s_barrier
	global_load_lds_dwordx4 v[16:17], off
	v_lshl_add_u64 v[16:17], v[2:3], 0, s[28:29]
	s_mov_b32 m0, s0
	s_nop 0
	global_load_lds_dwordx4 v[16:17], off
	v_lshl_add_u64 v[16:17], v[4:5], 0, s[28:29]
	s_mov_b32 m0, s1
	s_nop 0
	global_load_lds_dwordx4 v[16:17], off
	ds_read_b128 v[34:37], v8 offset:24576
	ds_read_b128 v[38:41], v9 offset:32768
	ds_read_b128 v[42:45], v9 offset:34816
	ds_read_b128 v[46:49], v9 offset:36864
	ds_read_b128 v[52:55], v9 offset:38912
	ds_read_b128 v[56:59], v11 offset:24576
	ds_read_b128 v[60:63], v10 offset:32768
	ds_read_b128 v[70:73], v10 offset:34816
	ds_read_b128 v[74:77], v10 offset:36864
	ds_read_b128 v[78:81], v10 offset:38912
	s_waitcnt lgkmcnt(0)
	v_mfma_f32_16x16x32_bf16 v[22:25], v[38:41], v[34:37], v[22:25]
	v_mfma_f32_16x16x32_bf16 v[26:29], v[42:45], v[34:37], v[26:29]
	v_mfma_f32_16x16x32_bf16 v[30:33], v[46:49], v[34:37], v[30:33]
	v_mfma_f32_16x16x32_bf16 v[12:15], v[52:55], v[34:37], v[12:15]
	v_mfma_f32_16x16x32_bf16 v[22:25], v[60:63], v[56:59], v[22:25]
	v_mfma_f32_16x16x32_bf16 v[26:29], v[70:73], v[56:59], v[26:29]
	v_mfma_f32_16x16x32_bf16 v[30:33], v[74:77], v[56:59], v[30:33]
	v_mfma_f32_16x16x32_bf16 v[12:15], v[78:81], v[56:59], v[12:15]
	s_mov_b32 m0, s85
	s_waitcnt vmcnt(3)
	v_lshl_add_u64 v[16:17], v[6:7], 0, s[30:31]
	s_waitcnt lgkmcnt(0)
	s_barrier
; DI f32x4 mfma16(bf16x8 a, bf16x8 b, f32x4 c) { return __builtin_amdgcn_mfma_f32_16x16x32_bf16(a, b, c, 0, 0, 0); }
; #define RAW_BARRIER() do { asm volatile("s_waitcnt lgkmcnt(0)" ::: "memory"); __builtin_amdgcn_s_barrier(); } while (0)
; template <int N> DI void wait_vmcnt() { asm volatile("s_waitcnt vmcnt(%0)" ::"n"(N) : "memory"); }
;     ...
;   for (int kt = 0; kt < 16; kt++) {
;     if (NST == 3) { if (kt + 1 < 16) wait_vmcnt<NI>(); else wait_vmcnt<0>(); }
;     else wait_vmcnt<0>();
;     RAW_BARRIER();
;     if (NST == 3) { if (kt + 2 < 16) glds(kt + 2, (kt + 2) % 3); }
;     else { if (kt + 1 < 16) glds(kt + 1, (kt + 1) & 1); }
;     const char* As = smem + (NST == 3 ? kt % 3 : kt & 1) * STAGE;
;     const char* Bs = As + BM * 128;
;     bf16x8 af[2][TM], bfr[2][NJ];
; #pragma unroll
;     for (int kk = 0; kk < 2; kk++) {
;       const int coff = ((kk * 4 + l4) ^ swz) << 4;
; #pragma unroll
;       for (int i = 0; i < TM; i++) af[kk][i] = *(const bf16x8*)(As + (wm * (TM * 16) + i * 16 + l15) * 128 + coff);
; #pragma unroll
;       for (int j = 0; j < NJ; j++) {
;         int nrow = MERGE ? ((j >> 1) * 64 + wn * 32 + (j & 1) * 16) : (wn * 64 + j * 16);
;         bfr[kk][j] = *(const bf16x8*)(Bs + (nrow + l15) * 128 + coff);
;       }
;       __builtin_amdgcn_sched_barrier(0);
;     }
; #pragma unroll
;     for (int kk = 0; kk < 2; kk++) {
; #pragma unroll
;       for (int i = 0; i < TM; i++)
; #pragma unroll
;         for (int j = 0; j < NJ; j++) acc[i][j] = SWAP ? mfma16(bfr[kk][j], af[kk][i], acc[i][j]) : mfma16(af[kk][i], bfr[kk][j], acc[i][j]);
;       __builtin_amdgcn_sched_barrier(0);
;     }
;   }
	global_load_lds_dwordx4 v[16:17], off
	v_lshl_add_u64 v[16:17], v[2:3], 0, s[30:31]
	s_mov_b32 m0, s75
	s_nop 0
	global_load_lds_dwordx4 v[16:17], off
	v_lshl_add_u64 v[16:17], v[4:5], 0, s[30:31]
	s_mov_b32 m0, s77
	s_nop 0
	global_load_lds_dwordx4 v[16:17], off
	ds_read_b128 v[34:37], v8 offset:49152
	ds_read_b128 v[38:41], v9 offset:57344
	ds_read_b128 v[42:45], v9 offset:59392
	ds_read_b128 v[46:49], v9 offset:61440
	ds_read_b128 v[52:55], v9 offset:63488
	ds_read_b128 v[56:59], v11 offset:49152
	ds_read_b128 v[60:63], v10 offset:57344
	ds_read_b128 v[70:73], v10 offset:59392
	ds_read_b128 v[74:77], v10 offset:61440
	ds_read_b128 v[78:81], v10 offset:63488
	s_waitcnt lgkmcnt(0)
	v_mfma_f32_16x16x32_bf16 v[22:25], v[38:41], v[34:37], v[22:25]
	v_mfma_f32_16x16x32_bf16 v[26:29], v[42:45], v[34:37], v[26:29]
	v_mfma_f32_16x16x32_bf16 v[30:33], v[46:49], v[34:37], v[30:33]
	v_mfma_f32_16x16x32_bf16 v[12:15], v[52:55], v[34:37], v[12:15]
	v_mfma_f32_16x16x32_bf16 v[22:25], v[60:63], v[56:59], v[22:25]
	v_mfma_f32_16x16x32_bf16 v[26:29], v[70:73], v[56:59], v[26:29]
	v_mfma_f32_16x16x32_bf16 v[30:33], v[74:77], v[56:59], v[30:33]
	v_mfma_f32_16x16x32_bf16 v[12:15], v[78:81], v[56:59], v[12:15]
	s_mov_b32 m0, s74
	s_waitcnt vmcnt(3)
	v_lshl_add_u64 v[16:17], v[6:7], 0, s[34:35]
	s_waitcnt lgkmcnt(0)
	s_barrier
	global_load_lds_dwordx4 v[16:17], off
	v_lshl_add_u64 v[16:17], v[2:3], 0, s[34:35]
	s_mov_b32 m0, s3
	s_nop 0
	global_load_lds_dwordx4 v[16:17], off
	v_lshl_add_u64 v[16:17], v[4:5], 0, s[34:35]
	s_mov_b32 m0, s4
	s_nop 0
	global_load_lds_dwordx4 v[16:17], off
	ds_read_b128 v[34:37], v8
	ds_read_b128 v[38:41], v9 offset:8192
	ds_read_b128 v[42:45], v9 offset:10240
	ds_read_b128 v[46:49], v9 offset:12288
	ds_read_b128 v[52:55], v9 offset:14336
	ds_read_b128 v[56:59], v11
	ds_read_b128 v[60:63], v10 offset:8192
	ds_read_b128 v[70:73], v10 offset:10240
	ds_read_b128 v[74:77], v10 offset:12288
	ds_read_b128 v[78:81], v10 offset:14336
	s_waitcnt lgkmcnt(0)
	v_mfma_f32_16x16x32_bf16 v[22:25], v[38:41], v[34:37], v[22:25]
	v_mfma_f32_16x16x32_bf16 v[26:29], v[42:45], v[34:37], v[26:29]
	v_mfma_f32_16x16x32_bf16 v[30:33], v[46:49], v[34:37], v[30:33]
	v_mfma_f32_16x16x32_bf16 v[12:15], v[52:55], v[34:37], v[12:15]
	v_mfma_f32_16x16x32_bf16 v[22:25], v[60:63], v[56:59], v[22:25]
	v_mfma_f32_16x16x32_bf16 v[26:29], v[70:73], v[56:59], v[26:29]
	v_mfma_f32_16x16x32_bf16 v[30:33], v[74:77], v[56:59], v[30:33]
	v_mfma_f32_16x16x32_bf16 v[12:15], v[78:81], v[56:59], v[12:15]
	s_mov_b32 m0, s2
	s_waitcnt vmcnt(3)
	v_lshl_add_u64 v[16:17], v[6:7], 0, s[52:53]
	s_waitcnt lgkmcnt(0)
	s_barrier
	global_load_lds_dwordx4 v[16:17], off
	v_lshl_add_u64 v[16:17], v[2:3], 0, s[52:53]
	s_mov_b32 m0, s0
	s_nop 0
	global_load_lds_dwordx4 v[16:17], off
	v_lshl_add_u64 v[16:17], v[4:5], 0, s[52:53]
	s_mov_b32 m0, s1
	s_nop 0
	global_load_lds_dwordx4 v[16:17], off
	ds_read_b128 v[34:37], v8 offset:24576
	ds_read_b128 v[38:41], v9 offset:32768
	ds_read_b128 v[42:45], v9 offset:34816
	ds_read_b128 v[46:49], v9 offset:36864
	ds_read_b128 v[52:55], v9 offset:38912
	ds_read_b128 v[56:59], v11 offset:24576
	ds_read_b128 v[60:63], v10 offset:32768
	ds_read_b128 v[70:73], v10 offset:34816
	ds_read_b128 v[74:77], v10 offset:36864
	ds_read_b128 v[78:81], v10 offset:38912
	s_waitcnt lgkmcnt(0)
	v_mfma_f32_16x16x32_bf16 v[22:25], v[38:41], v[34:37], v[22:25]
	v_mfma_f32_16x16x32_bf16 v[26:29], v[42:45], v[34:37], v[26:29]
	v_mfma_f32_16x16x32_bf16 v[30:33], v[46:49], v[34:37], v[30:33]
	v_mfma_f32_16x16x32_bf16 v[12:15], v[52:55], v[34:37], v[12:15]
	v_mfma_f32_16x16x32_bf16 v[22:25], v[60:63], v[56:59], v[22:25]
	v_mfma_f32_16x16x32_bf16 v[26:29], v[70:73], v[56:59], v[26:29]
	v_mfma_f32_16x16x32_bf16 v[30:33], v[74:77], v[56:59], v[30:33]
	v_mfma_f32_16x16x32_bf16 v[12:15], v[78:81], v[56:59], v[12:15]
	s_mov_b32 m0, s85
	s_waitcnt vmcnt(3)
	v_lshl_add_u64 v[16:17], v[6:7], 0, s[54:55]
	s_waitcnt lgkmcnt(0)
	s_barrier
	global_load_lds_dwordx4 v[16:17], off
	v_lshl_add_u64 v[16:17], v[2:3], 0, s[54:55]
	s_mov_b32 m0, s75
	s_nop 0
	global_load_lds_dwordx4 v[16:17], off
	v_lshl_add_u64 v[16:17], v[4:5], 0, s[54:55]
	s_mov_b32 m0, s77
	s_nop 0
	global_load_lds_dwordx4 v[16:17], off
	ds_read_b128 v[34:37], v8 offset:49152
	ds_read_b128 v[38:41], v9 offset:57344
	ds_read_b128 v[42:45], v9 offset:59392
	ds_read_b128 v[46:49], v9 offset:61440
	ds_read_b128 v[52:55], v9 offset:63488
	ds_read_b128 v[56:59], v11 offset:49152
	ds_read_b128 v[60:63], v10 offset:57344
	ds_read_b128 v[70:73], v10 offset:59392
	ds_read_b128 v[74:77], v10 offset:61440
	ds_read_b128 v[78:81], v10 offset:63488
	s_waitcnt lgkmcnt(0)
	v_mfma_f32_16x16x32_bf16 v[22:25], v[38:41], v[34:37], v[22:25]
	v_mfma_f32_16x16x32_bf16 v[26:29], v[42:45], v[34:37], v[26:29]
	v_mfma_f32_16x16x32_bf16 v[30:33], v[46:49], v[34:37], v[30:33]
	v_mfma_f32_16x16x32_bf16 v[12:15], v[52:55], v[34:37], v[12:15]
	v_mfma_f32_16x16x32_bf16 v[22:25], v[60:63], v[56:59], v[22:25]
	v_mfma_f32_16x16x32_bf16 v[26:29], v[70:73], v[56:59], v[26:29]
	v_mfma_f32_16x16x32_bf16 v[30:33], v[74:77], v[56:59], v[30:33]
	v_mfma_f32_16x16x32_bf16 v[12:15], v[78:81], v[56:59], v[12:15]
	s_mov_b32 m0, s74
	s_waitcnt vmcnt(3)
	v_lshl_add_u64 v[16:17], v[6:7], 0, s[56:57]
	s_waitcnt lgkmcnt(0)
	s_barrier
; DI f32x4 mfma16(bf16x8 a, bf16x8 b, f32x4 c) { return __builtin_amdgcn_mfma_f32_16x16x32_bf16(a, b, c, 0, 0, 0); }
; #define RAW_BARRIER() do { asm volatile("s_waitcnt lgkmcnt(0)" ::: "memory"); __builtin_amdgcn_s_barrier(); } while (0)
; template <int N> DI void wait_vmcnt() { asm volatile("s_waitcnt vmcnt(%0)" ::"n"(N) : "memory"); }
;     ...
;   for (int kt = 0; kt < 16; kt++) {
;     if (NST == 3) { if (kt + 1 < 16) wait_vmcnt<NI>(); else wait_vmcnt<0>(); }
;     else wait_vmcnt<0>();
;     RAW_BARRIER();
;     if (NST == 3) { if (kt + 2 < 16) glds(kt + 2, (kt + 2) % 3); }
;     else { if (kt + 1 < 16) glds(kt + 1, (kt + 1) & 1); }
;     const char* As = smem + (NST == 3 ? kt % 3 : kt & 1) * STAGE;
;     const char* Bs = As + BM * 128;
;     bf16x8 af[2][TM], bfr[2][NJ];
; #pragma unroll
;     for (int kk = 0; kk < 2; kk++) {
;       const int coff = ((kk * 4 + l4) ^ swz) << 4;
; #pragma unroll
;       for (int i = 0; i < TM; i++) af[kk][i] = *(const bf16x8*)(As + (wm * (TM * 16) + i * 16 + l15) * 128 + coff);
; #pragma unroll
;       for (int j = 0; j < NJ; j++) {
;         int nrow = MERGE ? ((j >> 1) * 64 + wn * 32 + (j & 1) * 16) : (wn * 64 + j * 16);
;         bfr[kk][j] = *(const bf16x8*)(Bs + (nrow + l15) * 128 + coff);
;       }
;       __builtin_amdgcn_sched_barrier(0);
;     }
; #pragma unroll
;     for (int kk = 0; kk < 2; kk++) {
; #pragma unroll
;       for (int i = 0; i < TM; i++)
; #pragma unroll
;         for (int j = 0; j < NJ; j++) acc[i][j] = SWAP ? mfma16(bfr[kk][j], af[kk][i], acc[i][j]) : mfma16(af[kk][i], bfr[kk][j], acc[i][j]);
;       __builtin_amdgcn_sched_barrier(0);
;     }
;   }
	global_load_lds_dwordx4 v[16:17], off
	v_lshl_add_u64 v[16:17], v[2:3], 0, s[56:57]
	s_mov_b32 m0, s3
	s_nop 0
	global_load_lds_dwordx4 v[16:17], off
	v_lshl_add_u64 v[16:17], v[4:5], 0, s[56:57]
	s_mov_b32 m0, s4
	s_nop 0
	global_load_lds_dwordx4 v[16:17], off
	ds_read_b128 v[34:37], v8
	ds_read_b128 v[38:41], v9 offset:8192
	ds_read_b128 v[42:45], v9 offset:10240
	ds_read_b128 v[46:49], v9 offset:12288
	ds_read_b128 v[52:55], v9 offset:14336
	ds_read_b128 v[56:59], v11
	ds_read_b128 v[60:63], v10 offset:8192
	ds_read_b128 v[70:73], v10 offset:10240
	ds_read_b128 v[74:77], v10 offset:12288
	ds_read_b128 v[78:81], v10 offset:14336
	s_waitcnt lgkmcnt(0)
	v_mfma_f32_16x16x32_bf16 v[22:25], v[38:41], v[34:37], v[22:25]
	v_mfma_f32_16x16x32_bf16 v[26:29], v[42:45], v[34:37], v[26:29]
	v_mfma_f32_16x16x32_bf16 v[30:33], v[46:49], v[34:37], v[30:33]
	v_mfma_f32_16x16x32_bf16 v[12:15], v[52:55], v[34:37], v[12:15]
	v_mfma_f32_16x16x32_bf16 v[22:25], v[60:63], v[56:59], v[22:25]
	v_mfma_f32_16x16x32_bf16 v[26:29], v[70:73], v[56:59], v[26:29]
	v_mfma_f32_16x16x32_bf16 v[30:33], v[74:77], v[56:59], v[30:33]
	v_mfma_f32_16x16x32_bf16 v[12:15], v[78:81], v[56:59], v[12:15]
	s_mov_b32 m0, s2
	s_waitcnt vmcnt(3)
	v_lshl_add_u64 v[16:17], v[6:7], 0, s[58:59]
	s_waitcnt lgkmcnt(0)
	s_barrier
	global_load_lds_dwordx4 v[16:17], off
	v_lshl_add_u64 v[16:17], v[2:3], 0, s[58:59]
	s_mov_b32 m0, s0
	s_nop 0
	global_load_lds_dwordx4 v[16:17], off
	v_lshl_add_u64 v[16:17], v[4:5], 0, s[58:59]
	s_mov_b32 m0, s1
	s_nop 0
	global_load_lds_dwordx4 v[16:17], off
	ds_read_b128 v[34:37], v8 offset:24576
	ds_read_b128 v[38:41], v9 offset:32768
	ds_read_b128 v[42:45], v9 offset:34816
	ds_read_b128 v[46:49], v9 offset:36864
	ds_read_b128 v[52:55], v9 offset:38912
	ds_read_b128 v[56:59], v11 offset:24576
	ds_read_b128 v[60:63], v10 offset:32768
	ds_read_b128 v[70:73], v10 offset:34816
	ds_read_b128 v[74:77], v10 offset:36864
	ds_read_b128 v[78:81], v10 offset:38912
	s_waitcnt lgkmcnt(0)
	v_mfma_f32_16x16x32_bf16 v[22:25], v[38:41], v[34:37], v[22:25]
	v_mfma_f32_16x16x32_bf16 v[26:29], v[42:45], v[34:37], v[26:29]
	v_mfma_f32_16x16x32_bf16 v[30:33], v[46:49], v[34:37], v[30:33]
	v_mfma_f32_16x16x32_bf16 v[12:15], v[52:55], v[34:37], v[12:15]
	v_mfma_f32_16x16x32_bf16 v[22:25], v[60:63], v[56:59], v[22:25]
	v_mfma_f32_16x16x32_bf16 v[26:29], v[70:73], v[56:59], v[26:29]
	v_mfma_f32_16x16x32_bf16 v[30:33], v[74:77], v[56:59], v[30:33]
	v_mfma_f32_16x16x32_bf16 v[12:15], v[78:81], v[56:59], v[12:15]
	s_mov_b32 m0, s85
	s_waitcnt vmcnt(3)
	v_lshl_add_u64 v[16:17], v[6:7], 0, s[60:61]
	s_waitcnt lgkmcnt(0)
	s_barrier
	global_load_lds_dwordx4 v[16:17], off
	v_lshl_add_u64 v[16:17], v[2:3], 0, s[60:61]
	s_mov_b32 m0, s75
	s_nop 0
	global_load_lds_dwordx4 v[16:17], off
	v_lshl_add_u64 v[16:17], v[4:5], 0, s[60:61]
	s_mov_b32 m0, s77
	s_nop 0
	global_load_lds_dwordx4 v[16:17], off
	ds_read_b128 v[34:37], v8 offset:49152
	ds_read_b128 v[38:41], v9 offset:57344
	ds_read_b128 v[42:45], v9 offset:59392
	ds_read_b128 v[46:49], v9 offset:61440
	ds_read_b128 v[52:55], v9 offset:63488
	ds_read_b128 v[56:59], v11 offset:49152
	ds_read_b128 v[60:63], v10 offset:57344
	ds_read_b128 v[70:73], v10 offset:59392
	ds_read_b128 v[74:77], v10 offset:61440
	ds_read_b128 v[78:81], v10 offset:63488
	s_waitcnt lgkmcnt(0)
	v_mfma_f32_16x16x32_bf16 v[22:25], v[38:41], v[34:37], v[22:25]
	v_mfma_f32_16x16x32_bf16 v[26:29], v[42:45], v[34:37], v[26:29]
	v_mfma_f32_16x16x32_bf16 v[30:33], v[46:49], v[34:37], v[30:33]
	v_mfma_f32_16x16x32_bf16 v[12:15], v[52:55], v[34:37], v[12:15]
	v_mfma_f32_16x16x32_bf16 v[22:25], v[60:63], v[56:59], v[22:25]
	v_mfma_f32_16x16x32_bf16 v[26:29], v[70:73], v[56:59], v[26:29]
	v_mfma_f32_16x16x32_bf16 v[30:33], v[74:77], v[56:59], v[30:33]
	v_mfma_f32_16x16x32_bf16 v[12:15], v[78:81], v[56:59], v[12:15]
	s_mov_b32 m0, s74
	s_waitcnt vmcnt(3)
	v_lshl_add_u64 v[16:17], v[6:7], 0, s[62:63]
	s_waitcnt lgkmcnt(0)
	s_barrier
	global_load_lds_dwordx4 v[16:17], off
	v_lshl_add_u64 v[16:17], v[2:3], 0, s[62:63]
	s_mov_b32 m0, s3
	s_nop 0
	global_load_lds_dwordx4 v[16:17], off
	v_lshl_add_u64 v[16:17], v[4:5], 0, s[62:63]
	s_mov_b32 m0, s4
	s_nop 0
	global_load_lds_dwordx4 v[16:17], off
	ds_read_b128 v[34:37], v8
	ds_read_b128 v[38:41], v9 offset:8192
	ds_read_b128 v[42:45], v9 offset:10240
	ds_read_b128 v[46:49], v9 offset:12288
	ds_read_b128 v[52:55], v9 offset:14336
	ds_read_b128 v[56:59], v11
	ds_read_b128 v[60:63], v10 offset:8192
	ds_read_b128 v[70:73], v10 offset:10240
	ds_read_b128 v[74:77], v10 offset:12288
	ds_read_b128 v[78:81], v10 offset:14336
	s_waitcnt lgkmcnt(0)
	v_mfma_f32_16x16x32_bf16 v[22:25], v[38:41], v[34:37], v[22:25]
	v_mfma_f32_16x16x32_bf16 v[26:29], v[42:45], v[34:37], v[26:29]
	v_mfma_f32_16x16x32_bf16 v[30:33], v[46:49], v[34:37], v[30:33]
	v_mfma_f32_16x16x32_bf16 v[12:15], v[52:55], v[34:37], v[12:15]
	v_mfma_f32_16x16x32_bf16 v[22:25], v[60:63], v[56:59], v[22:25]
	v_mfma_f32_16x16x32_bf16 v[26:29], v[70:73], v[56:59], v[26:29]
	v_mfma_f32_16x16x32_bf16 v[30:33], v[74:77], v[56:59], v[30:33]
	v_mfma_f32_16x16x32_bf16 v[12:15], v[78:81], v[56:59], v[12:15]
	s_mov_b32 m0, s2
	s_waitcnt vmcnt(3)
	v_lshl_add_u64 v[16:17], v[6:7], 0, s[64:65]
	s_waitcnt lgkmcnt(0)
	s_barrier
; DI f32x4 mfma16(bf16x8 a, bf16x8 b, f32x4 c) { return __builtin_amdgcn_mfma_f32_16x16x32_bf16(a, b, c, 0, 0, 0); }
; #define RAW_BARRIER() do { asm volatile("s_waitcnt lgkmcnt(0)" ::: "memory"); __builtin_amdgcn_s_barrier(); } while (0)
; template <int N> DI void wait_vmcnt() { asm volatile("s_waitcnt vmcnt(%0)" ::"n"(N) : "memory"); }
;     ...
;   for (int kt = 0; kt < 16; kt++) {
;     if (NST == 3) { if (kt + 1 < 16) wait_vmcnt<NI>(); else wait_vmcnt<0>(); }
;     else wait_vmcnt<0>();
;     RAW_BARRIER();
;     if (NST == 3) { if (kt + 2 < 16) glds(kt + 2, (kt + 2) % 3); }
;     else { if (kt + 1 < 16) glds(kt + 1, (kt + 1) & 1); }
;     const char* As = smem + (NST == 3 ? kt % 3 : kt & 1) * STAGE;
;     const char* Bs = As + BM * 128;
;     bf16x8 af[2][TM], bfr[2][NJ];
; #pragma unroll
;     for (int kk = 0; kk < 2; kk++) {
;       const int coff = ((kk * 4 + l4) ^ swz) << 4;
; #pragma unroll
;       for (int i = 0; i < TM; i++) af[kk][i] = *(const bf16x8*)(As + (wm * (TM * 16) + i * 16 + l15) * 128 + coff);
; #pragma unroll
;       for (int j = 0; j < NJ; j++) {
;         int nrow = MERGE ? ((j >> 1) * 64 + wn * 32 + (j & 1) * 16) : (wn * 64 + j * 16);
;         bfr[kk][j] = *(const bf16x8*)(Bs + (nrow + l15) * 128 + coff);
;       }
;       __builtin_amdgcn_sched_barrier(0);
;     }
; #pragma unroll
;     for (int kk = 0; kk < 2; kk++) {
; #pragma unroll
;       for (int i = 0; i < TM; i++)
; #pragma unroll
;         for (int j = 0; j < NJ; j++) acc[i][j] = SWAP ? mfma16(bfr[kk][j], af[kk][i], acc[i][j]) : mfma16(af[kk][i], bfr[kk][j], acc[i][j]);
;       __builtin_amdgcn_sched_barrier(0);
;     }
;   }
	global_load_lds_dwordx4 v[16:17], off
	v_lshl_add_u64 v[16:17], v[2:3], 0, s[64:65]
	s_mov_b32 m0, s0
	s_nop 0
	global_load_lds_dwordx4 v[16:17], off
	v_lshl_add_u64 v[16:17], v[4:5], 0, s[64:65]
	s_mov_b32 m0, s1
	s_nop 0
	global_load_lds_dwordx4 v[16:17], off
	ds_read_b128 v[34:37], v8 offset:24576
	ds_read_b128 v[38:41], v9 offset:32768
	ds_read_b128 v[42:45], v9 offset:34816
	ds_read_b128 v[46:49], v9 offset:36864
	ds_read_b128 v[52:55], v9 offset:38912
	ds_read_b128 v[56:59], v11 offset:24576
	ds_read_b128 v[60:63], v10 offset:32768
	ds_read_b128 v[70:73], v10 offset:34816
	ds_read_b128 v[74:77], v10 offset:36864
	ds_read_b128 v[78:81], v10 offset:38912
	s_waitcnt lgkmcnt(0)
	v_mfma_f32_16x16x32_bf16 v[22:25], v[38:41], v[34:37], v[22:25]
	v_mfma_f32_16x16x32_bf16 v[26:29], v[42:45], v[34:37], v[26:29]
	v_mfma_f32_16x16x32_bf16 v[30:33], v[46:49], v[34:37], v[30:33]
	v_mfma_f32_16x16x32_bf16 v[12:15], v[52:55], v[34:37], v[12:15]
	v_mfma_f32_16x16x32_bf16 v[22:25], v[60:63], v[56:59], v[22:25]
	v_mfma_f32_16x16x32_bf16 v[26:29], v[70:73], v[56:59], v[26:29]
	v_mfma_f32_16x16x32_bf16 v[30:33], v[74:77], v[56:59], v[30:33]
	v_mfma_f32_16x16x32_bf16 v[12:15], v[78:81], v[56:59], v[12:15]
	s_mov_b32 m0, s85
	s_waitcnt vmcnt(3)
	v_lshl_add_u64 v[16:17], v[6:7], 0, s[66:67]
	s_waitcnt lgkmcnt(0)
	s_barrier
	global_load_lds_dwordx4 v[16:17], off
	v_lshl_add_u64 v[16:17], v[2:3], 0, s[66:67]
	s_mov_b32 m0, s75
	s_nop 0
	global_load_lds_dwordx4 v[16:17], off
	v_lshl_add_u64 v[16:17], v[4:5], 0, s[66:67]
	s_mov_b32 m0, s77
	s_nop 0
	global_load_lds_dwordx4 v[16:17], off
	ds_read_b128 v[34:37], v8 offset:49152
	ds_read_b128 v[38:41], v9 offset:57344
	ds_read_b128 v[42:45], v9 offset:59392
	ds_read_b128 v[46:49], v9 offset:61440
	ds_read_b128 v[52:55], v9 offset:63488
	ds_read_b128 v[56:59], v11 offset:49152
	ds_read_b128 v[60:63], v10 offset:57344
	ds_read_b128 v[70:73], v10 offset:59392
	ds_read_b128 v[74:77], v10 offset:61440
	ds_read_b128 v[78:81], v10 offset:63488
	s_waitcnt lgkmcnt(0)
	v_mfma_f32_16x16x32_bf16 v[22:25], v[38:41], v[34:37], v[22:25]
	v_mfma_f32_16x16x32_bf16 v[26:29], v[42:45], v[34:37], v[26:29]
	v_mfma_f32_16x16x32_bf16 v[30:33], v[46:49], v[34:37], v[30:33]
	v_mfma_f32_16x16x32_bf16 v[12:15], v[52:55], v[34:37], v[12:15]
	v_mfma_f32_16x16x32_bf16 v[22:25], v[60:63], v[56:59], v[22:25]
	v_mfma_f32_16x16x32_bf16 v[26:29], v[70:73], v[56:59], v[26:29]
	v_mfma_f32_16x16x32_bf16 v[30:33], v[74:77], v[56:59], v[30:33]
	v_mfma_f32_16x16x32_bf16 v[12:15], v[78:81], v[56:59], v[12:15]
	s_mov_b32 m0, s74
	s_waitcnt vmcnt(3)
	v_lshl_add_u64 v[16:17], v[6:7], 0, s[68:69]
	s_waitcnt lgkmcnt(0)
	s_barrier
	global_load_lds_dwordx4 v[16:17], off
	v_lshl_add_u64 v[16:17], v[2:3], 0, s[68:69]
	s_mov_b32 m0, s3
	s_nop 0
	global_load_lds_dwordx4 v[16:17], off
	v_lshl_add_u64 v[16:17], v[4:5], 0, s[68:69]
	s_mov_b32 m0, s4
	s_nop 0
	global_load_lds_dwordx4 v[16:17], off
	ds_read_b128 v[34:37], v8
	ds_read_b128 v[38:41], v9 offset:8192
	ds_read_b128 v[42:45], v9 offset:10240
	ds_read_b128 v[46:49], v9 offset:12288
	ds_read_b128 v[52:55], v9 offset:14336
	ds_read_b128 v[56:59], v11
	ds_read_b128 v[60:63], v10 offset:8192
	ds_read_b128 v[70:73], v10 offset:10240
	ds_read_b128 v[74:77], v10 offset:12288
	ds_read_b128 v[78:81], v10 offset:14336
	s_waitcnt lgkmcnt(0)
	v_mfma_f32_16x16x32_bf16 v[22:25], v[38:41], v[34:37], v[22:25]
	v_mfma_f32_16x16x32_bf16 v[26:29], v[42:45], v[34:37], v[26:29]
	v_mfma_f32_16x16x32_bf16 v[30:33], v[46:49], v[34:37], v[30:33]
	v_mfma_f32_16x16x32_bf16 v[12:15], v[52:55], v[34:37], v[12:15]
	v_mfma_f32_16x16x32_bf16 v[22:25], v[60:63], v[56:59], v[22:25]
	v_mfma_f32_16x16x32_bf16 v[26:29], v[70:73], v[56:59], v[26:29]
	v_mfma_f32_16x16x32_bf16 v[30:33], v[74:77], v[56:59], v[30:33]
	v_mfma_f32_16x16x32_bf16 v[12:15], v[78:81], v[56:59], v[12:15]
	s_mov_b32 m0, s2
	s_waitcnt vmcnt(3)
	v_lshl_add_u64 v[6:7], v[6:7], 0, s[70:71]
	s_waitcnt lgkmcnt(0)
	s_barrier
	global_load_lds_dwordx4 v[6:7], off
	v_lshl_add_u64 v[2:3], v[2:3], 0, s[70:71]
	s_mov_b32 m0, s0
	s_nop 0
	global_load_lds_dwordx4 v[2:3], off
	v_lshl_add_u64 v[2:3], v[4:5], 0, s[70:71]
	s_mov_b32 m0, s1
	s_nop 0
	global_load_lds_dwordx4 v[2:3], off
	ds_read_b128 v[2:5], v8 offset:24576
	ds_read_b128 v[34:37], v9 offset:32768
	ds_read_b128 v[38:41], v9 offset:34816
	ds_read_b128 v[42:45], v9 offset:36864
	ds_read_b128 v[46:49], v9 offset:38912
	ds_read_b128 v[52:55], v11 offset:24576
	ds_read_b128 v[56:59], v10 offset:32768
	ds_read_b128 v[60:63], v10 offset:34816
	ds_read_b128 v[70:73], v10 offset:36864
	ds_read_b128 v[74:77], v10 offset:38912
	s_waitcnt lgkmcnt(0)
	v_mfma_f32_16x16x32_bf16 v[22:25], v[34:37], v[2:5], v[22:25]
	v_mfma_f32_16x16x32_bf16 v[26:29], v[38:41], v[2:5], v[26:29]
	v_mfma_f32_16x16x32_bf16 v[30:33], v[42:45], v[2:5], v[30:33]
	v_mfma_f32_16x16x32_bf16 v[2:5], v[46:49], v[2:5], v[12:15]
	v_mfma_f32_16x16x32_bf16 v[12:15], v[56:59], v[52:55], v[22:25]
	v_mfma_f32_16x16x32_bf16 v[22:25], v[60:63], v[52:55], v[26:29]
	v_mfma_f32_16x16x32_bf16 v[26:29], v[70:73], v[52:55], v[30:33]
	v_mfma_f32_16x16x32_bf16 v[2:5], v[74:77], v[52:55], v[2:5]
	s_waitcnt vmcnt(3)
	s_waitcnt lgkmcnt(0)
	s_barrier
; DI u32 pack2(float a, float b) { f32x2 v = {a, b}; bfx2 r = __builtin_convertvector(v, bfx2); return __builtin_bit_cast(u32, r); }
; DI f32x4 mfma16(bf16x8 a, bf16x8 b, f32x4 c) { return __builtin_amdgcn_mfma_f32_16x16x32_bf16(a, b, c, 0, 0, 0); }
;     ...
; #pragma unroll
;     for (int kk = 0; kk < 2; kk++) {
; #pragma unroll
;       for (int i = 0; i < TM; i++)
; #pragma unroll
;         for (int j = 0; j < NJ; j++) acc[i][j] = SWAP ? mfma16(bfr[kk][j], af[kk][i], acc[i][j]) : mfma16(af[kk][i], bfr[kk][j], acc[i][j]);
;       __builtin_amdgcn_sched_barrier(0);
;     }
;   }
;   __syncthreads();
; template <int TM>
; DI void phase4_tile(const P& p, char* smem, int m0, int nt) {
;     ...
;       for (int i = 0; i < TM; i++) {
;         int tok = m0 + wm * (TM * 16) + i * 16 + (lane & 15);
;         float ss = 0.f;
; #pragma unroll
;         for (int j = 0; j < 4; j++)
; #pragma unroll
;           for (int rr = 0; rr < 4; rr++) ss += acc[i][j][rr] * acc[i][j][rr];
;         ss += __shfl_xor(ss, 16); ss += __shfl_xor(ss, 32);
;         float rinv = rsqrtf(ss * (1.f / 64.f) + RMS_EPS);
; #pragma unroll
;         for (int j = 0; j < 4; j++) {
;           int dd = j * 16 + 4 * (lane >> 4);
;           float4 g4 = *(const float4*)(gain + dd);
;           float o0 = acc[i][j][0] * rinv * g4.x, o1 = acc[i][j][1] * rinv * g4.y, o2 = acc[i][j][2] * rinv * g4.z, o3 = acc[i][j][3] * rinv * g4.w;
;           int col = hh * 128 + m * 64 + dd;
;           if (isq) {
;             u32x2 ov = {pack2(o0 * QSCALE, o1 * QSCALE), pack2(o2 * QSCALE, o3 * QSCALE)};
;             *(u32x2*)(Qn + (size_t)tok * 1024 + col) = ov;
;           } else {
;             u32x2 ov = {pack2(o0, o1), pack2(o2, o3)};
;             *(u32x2*)(Kn + (size_t)tok * 1024 + col) = ov;
;             float* kd = tok < TP ? p.out + O_KP + (size_t)tok * 1024 + col : p.out + O_KS + (size_t)(tok - TP) * 1024 + col;
;             __builtin_nontemporal_store(f32x4{o0, o1, o2, o3}, (f32x4*)kd);
;           }
;         }
	s_nop 1
	ds_read_b128 v[30:33], v9 offset:63488
	ds_read_b128 v[34:37], v9 offset:61440
	ds_read_b128 v[38:41], v9 offset:59392
	ds_read_b128 v[42:45], v9 offset:57344
	ds_read_b128 v[46:49], v8 offset:49152
	ds_read_b128 v[52:55], v11 offset:49152
	ds_read_b128 v[56:59], v10 offset:57344
	ds_read_b128 v[60:63], v10 offset:59392
	ds_read_b128 v[70:73], v10 offset:61440
	ds_read_b128 v[74:77], v10 offset:63488
	s_waitcnt lgkmcnt(0)
	v_mfma_f32_16x16x32_bf16 v[12:15], v[42:45], v[46:49], v[12:15]
	v_mfma_f32_16x16x32_bf16 v[22:25], v[38:41], v[46:49], v[22:25]
	v_mfma_f32_16x16x32_bf16 v[26:29], v[34:37], v[46:49], v[26:29]
	v_mfma_f32_16x16x32_bf16 v[2:5], v[30:33], v[46:49], v[2:5]
	v_mfma_f32_16x16x32_bf16 v[12:15], v[56:59], v[52:55], v[12:15]
	v_mfma_f32_16x16x32_bf16 v[22:25], v[60:63], v[52:55], v[22:25]
	v_mfma_f32_16x16x32_bf16 v[26:29], v[70:73], v[52:55], v[26:29]
	v_mfma_f32_16x16x32_bf16 v[2:5], v[74:77], v[52:55], v[2:5]
	s_waitcnt vmcnt(0)
	s_waitcnt lgkmcnt(0)
	s_barrier
	ds_read_b128 v[30:33], v9 offset:14336
	ds_read_b128 v[34:37], v9 offset:12288
	ds_read_b128 v[38:41], v9 offset:10240
	ds_read_b128 v[42:45], v9 offset:8192
	ds_read_b128 v[6:9], v8
	ds_read_b128 v[46:49], v11
	ds_read_b128 v[52:55], v10 offset:8192
	ds_read_b128 v[56:59], v10 offset:10240
	ds_read_b128 v[60:63], v10 offset:12288
	ds_read_b128 v[70:73], v10 offset:14336
	s_waitcnt lgkmcnt(0)
	v_mfma_f32_16x16x32_bf16 v[10:13], v[42:45], v[6:9], v[12:15]
	v_mfma_f32_16x16x32_bf16 v[14:17], v[38:41], v[6:9], v[22:25]
	v_mfma_f32_16x16x32_bf16 v[22:25], v[34:37], v[6:9], v[26:29]
	v_mfma_f32_16x16x32_bf16 v[2:5], v[30:33], v[6:9], v[2:5]
	v_mfma_f32_16x16x32_bf16 v[34:37], v[52:55], v[46:49], v[10:13]
	v_mfma_f32_16x16x32_bf16 v[10:13], v[56:59], v[46:49], v[14:17]
	v_mfma_f32_16x16x32_bf16 v[6:9], v[60:63], v[46:49], v[22:25]
	v_mfma_f32_16x16x32_bf16 v[2:5], v[70:73], v[46:49], v[2:5]
	s_nop 1
	v_or_b32_e32 v14, s78, v195
	s_cmp_gt_i32 s76, -1
	v_readlane_b32 s36, v251, 29
	v_lshl_add_u32 v22, s79, 4, v14
	s_cselect_b64 s[74:75], -1, 0
	s_cmp_lt_i32 s76, 0
	v_readlane_b32 s38, v251, 31
	v_readlane_b32 s39, v251, 32
	v_readlane_b32 s40, v251, 33
	v_readlane_b32 s41, v251, 34
	v_add_u32_e32 v18, 0xffff8000, v22
	s_cselect_b32 s77, s39, s41
	s_cselect_b32 s76, s38, s40
	v_lshlrev_b64 v[24:25], 12, v[18:19]
	v_lshlrev_b32_e32 v18, 2, v113
	s_waitcnt vmcnt(0)
	s_barrier
	global_load_dwordx4 v[14:17], v18, s[76:77]
	v_mul_f32_e32 v39, v35, v35
	v_fmac_f32_e32 v39, v34, v34
	v_fmac_f32_e32 v39, v36, v36
	v_fmac_f32_e32 v39, v37, v37
	v_fmac_f32_e32 v39, v10, v10
	v_fmac_f32_e32 v39, v11, v11
	v_fmac_f32_e32 v39, v12, v12
	v_pk_mul_f32 v[28:29], v[6:7], v[6:7]
	v_fmac_f32_e32 v39, v13, v13
	v_add_f32_e32 v28, v28, v39
	v_pk_mul_f32 v[26:27], v[8:9], v[8:9]
	v_add_f32_e32 v28, v29, v28
	v_add_f32_e32 v26, v26, v28
	v_and_b32_e32 v23, 64, v51
	v_pk_mul_f32 v[32:33], v[2:3], v[2:3]
	v_add_f32_e32 v26, v27, v26
	v_xor_b32_e32 v21, 16, v51
	v_add_u32_e32 v23, 64, v23
	v_add_f32_e32 v26, v32, v26
	v_pk_mul_f32 v[30:31], v[4:5], v[4:5]
	v_cmp_lt_i32_e32 vcc, v21, v23
	v_add_f32_e32 v26, v33, v26
	v_add_f32_e32 v26, v30, v26
	v_cndmask_b32_e32 v21, v51, v21, vcc
	v_lshlrev_b32_e32 v21, 2, v21
	v_add_f32_e32 v28, v31, v26
	ds_bpermute_b32 v21, v21, v28
	v_xor_b32_e32 v38, 32, v51
	v_cmp_lt_i32_e32 vcc, v38, v23
	s_lshl_b32 s2, s84, 6
	s_and_b32 s3, s83, 0x380
	v_cndmask_b32_e32 v38, v51, v38, vcc
	v_lshlrev_b32_e32 v29, 2, v38
	s_waitcnt lgkmcnt(0)
	v_add_f32_e32 v30, v28, v21
	ds_bpermute_b32 v31, v29, v30
	s_or_b32 s4, s2, s3
	v_ashrrev_i32_e32 v23, 31, v22
	s_mov_b32 s0, 0x8000
	v_lshlrev_b64 v[26:27], 10, v[22:23]
	s_waitcnt lgkmcnt(0)
	v_add_f32_e32 v30, v30, v31
	v_fmamk_f32 v30, v30, 0x3c800000, v50
	v_mul_f32_e32 v31, 0x4b800000, v30
	v_cmp_gt_f32_e64 s[2:3], s81, v30
	v_lshlrev_b64 v[28:29], 11, v[22:23]
	v_or_b32_e32 v21, s4, v113
	v_cndmask_b32_e64 v30, v30, v31, s[2:3]
	v_rsq_f32_e32 v30, v30
	s_mov_b64 s[78:79], -1
	v_cmp_gt_i32_e64 s[0:1], s0, v22
	s_and_b64 vcc, exec, s[74:75]
	v_mul_f32_e32 v31, 0x45800000, v30
	v_cndmask_b32_e64 v30, v30, v31, s[2:3]
	v_pk_mul_f32 v[34:35], v[34:35], v[30:31] op_sel_hi:[1,0]
	v_pk_mul_f32 v[36:37], v[36:37], v[30:31] op_sel_hi:[1,0]
	v_lshl_add_u64 v[22:23], s[10:11], 0, v[28:29]
	v_lshl_add_u64 v[24:25], s[14:15], 0, v[24:25]
	v_lshl_add_u64 v[26:27], v[26:27], 2, s[12:13]
	v_lshlrev_b32_e32 v32, 1, v21
	v_readlane_b32 s37, v251, 30
	v_readlane_b32 s42, v251, 35
	v_readlane_b32 s43, v251, 36
	v_readlane_b32 s44, v251, 37
	v_readlane_b32 s45, v251, 38
	v_readlane_b32 s46, v251, 39
	v_readlane_b32 s47, v251, 40
	v_readlane_b32 s48, v251, 41
	v_readlane_b32 s49, v251, 42
	v_readlane_b32 s50, v251, 43
	v_readlane_b32 s51, v251, 44
	s_waitcnt vmcnt(0)
	v_pk_mul_f32 v[14:15], v[14:15], v[34:35]
	v_pk_mul_f32 v[16:17], v[16:17], v[36:37]
	s_cbranch_vccz .LBB0_703
	v_mov_b32_e32 v33, v19
	v_cvt_pk_bf16_f32 v34, v14, v15
	v_cvt_pk_bf16_f32 v35, v16, v17
	v_lshl_add_u64 v[36:37], v[22:23], 0, v[32:33]
	global_store_dwordx2 v[36:37], v[34:35], off
	v_cndmask_b32_e64 v35, v25, v27, s[0:1]
	v_cndmask_b32_e64 v34, v24, v26, s[0:1]
	v_lshlrev_b32_e32 v36, 2, v21
	v_mov_b32_e32 v37, v19
	v_lshl_add_u64 v[34:35], v[34:35], 0, v[36:37]
	global_store_dwordx4 v[34:35], v[14:17], off nt
	s_mov_b64 s[78:79], 0

; DI f32x4 mfma16(bf16x8 a, bf16x8 b, f32x4 c) { return __builtin_amdgcn_mfma_f32_16x16x32_bf16(a, b, c, 0, 0, 0); }
; #define RAW_BARRIER() do { asm volatile("s_waitcnt lgkmcnt(0)" ::: "memory"); __builtin_amdgcn_s_barrier(); } while (0)
; template <int N> DI void wait_vmcnt() { asm volatile("s_waitcnt vmcnt(%0)" ::"n"(N) : "memory"); }
;     ...
;   __syncthreads();
;   wait_vmcnt<0>();
;   glds(0, 0);
;   if (NST == 3) glds(1, 1);
;   for (int kt = 0; kt < 16; kt++) {
;     if (NST == 3) { if (kt + 1 < 16) wait_vmcnt<NI>(); else wait_vmcnt<0>(); }
;     else wait_vmcnt<0>();
;     RAW_BARRIER();
;     if (NST == 3) { if (kt + 2 < 16) glds(kt + 2, (kt + 2) % 3); }
;     else { if (kt + 1 < 16) glds(kt + 1, (kt + 1) & 1); }
;     const char* As = smem + (NST == 3 ? kt % 3 : kt & 1) * STAGE;
;     const char* Bs = As + BM * 128;
;     bf16x8 af[2][TM], bfr[2][NJ];
; #pragma unroll
;     for (int kk = 0; kk < 2; kk++) {
;       const int coff = ((kk * 4 + l4) ^ swz) << 4;
; #pragma unroll
;       for (int i = 0; i < TM; i++) af[kk][i] = *(const bf16x8*)(As + (wm * (TM * 16) + i * 16 + l15) * 128 + coff);
; #pragma unroll
;       for (int j = 0; j < NJ; j++) {
;         int nrow = MERGE ? ((j >> 1) * 64 + wn * 32 + (j & 1) * 16) : (wn * 64 + j * 16);
;         bfr[kk][j] = *(const bf16x8*)(Bs + (nrow + l15) * 128 + coff);
;       }
;       __builtin_amdgcn_sched_barrier(0);
;     }
; #pragma unroll
;     for (int kk = 0; kk < 2; kk++) {
; #pragma unroll
;       for (int i = 0; i < TM; i++)
; #pragma unroll
;         for (int j = 0; j < NJ; j++) acc[i][j] = SWAP ? mfma16(bfr[kk][j], af[kk][i], acc[i][j]) : mfma16(af[kk][i], bfr[kk][j], acc[i][j]);
;       __builtin_amdgcn_sched_barrier(0);
;     }
;   }
.LBB0_809:
	s_ashr_i32 s53, s52, 31
	s_lshr_b32 s53, s53, 28
	s_add_i32 s53, s52, s53
	v_readfirstlane_b32 s56, v136
	s_ashr_i32 s54, s53, 4
	s_lshr_b32 s57, s56, 6
	s_lshl_b32 s53, s54, 6
	s_mul_i32 s58, s57, 3
	s_add_i32 s55, s53, 0x8000
	s_and_b32 s60, s58, 0xffffff8
	v_lshl_or_b32 v2, s57, 3, v187
	s_cmp_eq_u32 s60, 8
	v_lshrrev_b32_e32 v3, 1, v2
	v_add_u32_e32 v2, s55, v2
	s_cselect_b32 s60, s49, 0x2010
	s_add_i32 s61, s58, 1
	v_xor_b32_e32 v10, v3, v136
	v_ashrrev_i32_e32 v3, 31, v2
	s_mul_i32 s59, s57, 24
	s_lshl_b32 s54, s54, 10
	s_and_b32 s62, s61, 0xffffff8
	v_lshlrev_b64 v[8:9], 11, v[2:3]
	v_or_b32_e32 v2, s59, v187
	s_cmp_eq_u32 s62, 8
	v_lshrrev_b32_e32 v2, 1, v2
	s_cselect_b32 s62, s49, 0x2010
	s_cmpk_lt_u32 s56, 0xc0
	v_xor_b32_e32 v4, v2, v136
	s_cselect_b32 s60, 0xc00, s60
	v_bitop3_b32 v2, v142, 63, s59 bitop3:0xc8
	v_add_u32_e32 v2, s60, v2
	v_subrev_u32_e32 v2, s54, v2
	v_add_u32_e32 v30, s33, v2
	v_lshlrev_b32_e32 v4, 4, v4
	v_lshlrev_b64 v[2:3], 11, v[30:31]
	v_and_b32_e32 v30, 0x70, v4
	v_lshl_or_b32 v4, s61, 3, v187
	v_lshrrev_b32_e32 v4, 1, v4
	v_xor_b32_e32 v6, v4, v136
	v_add_u16_e32 v4, s59, v45
	s_cselect_b32 s60, 0xc00, s62
	v_and_b32_e32 v4, 63, v4
	v_add_u32_e32 v4, s60, v4
	v_lshl_add_u64 v[2:3], s[74:75], 0, v[2:3]
	v_subrev_u32_e32 v4, s54, v4
	v_lshl_add_u64 v[2:3], v[2:3], 0, v[30:31]
	v_add_u32_e32 v30, s33, v4
	v_lshlrev_b32_e32 v6, 4, v6
	s_add_i32 s58, s58, 2
	v_lshlrev_b64 v[4:5], 11, v[30:31]
	v_and_b32_e32 v30, 0x70, v6
	v_lshl_or_b32 v6, s58, 3, v187
	s_and_b32 s58, s58, 0xffffff8
	v_lshrrev_b32_e32 v6, 1, v6
	s_cmp_eq_u32 s58, 8
	v_xor_b32_e32 v11, v6, v136
	s_cselect_b32 s58, s49, 0x2010
	s_cmpk_gt_u32 s56, 0x7f
	v_add_u16_e32 v6, s59, v44
	s_cselect_b32 s58, s58, 0xc00
	v_and_b32_e32 v6, 63, v6
	v_add_u32_e32 v6, s58, v6
	v_lshl_add_u64 v[4:5], s[74:75], 0, v[4:5]
	v_subrev_u32_e32 v6, s54, v6
	v_lshl_add_u64 v[4:5], v[4:5], 0, v[30:31]
	v_add_u32_e32 v30, s33, v6
	v_lshlrev_b64 v[6:7], 11, v[30:31]
	v_lshlrev_b32_e32 v11, 4, v11
	s_lshl_b32 s62, s57, 10
	v_lshl_add_u64 v[6:7], s[74:75], 0, v[6:7]
	v_and_b32_e32 v30, 0x70, v11
	v_lshlrev_b32_e32 v10, 4, v10
	s_add_i32 s61, s62, 0
	s_mul_i32 s63, s57, 0xc00
	s_lshl_b32 s57, s57, 11
	v_lshl_add_u64 v[6:7], v[6:7], 0, v[30:31]
	v_lshl_add_u64 v[8:9], s[72:73], 0, v[8:9]
	v_and_b32_e32 v30, 0x70, v10
	s_add_i32 s68, s61, s57
	v_lshl_add_u64 v[8:9], v[8:9], 0, v[30:31]
	s_barrier
	s_nop 0
	s_add_i32 s58, s68, 0x2000
	s_mov_b32 m0, s61
	s_add_i32 s59, s68, 0x2400
	global_load_lds_dwordx4 v[8:9], off
	s_mov_b32 m0, s58
	s_add_i32 s60, s68, 0x2800
	global_load_lds_dwordx4 v[2:3], off
	s_mov_b32 m0, s59
	s_add_i32 s69, s61, 0x8000
	global_load_lds_dwordx4 v[4:5], off
	s_mov_b32 m0, s60
	s_add_i32 s66, s68, 0xa000
	global_load_lds_dwordx4 v[6:7], off
	v_lshl_add_u64 v[10:11], v[8:9], 0, s[0:1]
	s_mov_b32 m0, s69
	s_add_i32 s67, s68, 0xa400
	global_load_lds_dwordx4 v[10:11], off
	v_lshl_add_u64 v[10:11], v[2:3], 0, s[0:1]
	s_mov_b32 m0, s66
	s_add_i32 s68, s68, 0xa800
	global_load_lds_dwordx4 v[10:11], off
	v_lshl_add_u64 v[10:11], v[4:5], 0, s[0:1]
	s_mov_b32 m0, s67
	s_add_i32 s64, s50, s62
	global_load_lds_dwordx4 v[10:11], off
	v_lshl_add_u64 v[10:11], v[6:7], 0, s[0:1]
	s_mov_b32 m0, s68
	s_add_i32 s65, s63, 0
	global_load_lds_dwordx4 v[10:11], off
	s_waitcnt vmcnt(4)
	s_add_i32 s62, s65, 0x12000
	v_lshl_add_u64 v[10:11], v[8:9], 0, s[2:3]
	s_mov_b32 m0, s64
	s_waitcnt lgkmcnt(0)
	s_barrier
	global_load_lds_dwordx4 v[10:11], off
	v_lshl_add_u64 v[10:11], v[2:3], 0, s[2:3]
	s_mov_b32 m0, s62
	s_add_i32 s63, s65, 0x12400
	global_load_lds_dwordx4 v[10:11], off
	v_lshl_add_u64 v[10:11], v[4:5], 0, s[2:3]
	s_mov_b32 m0, s63
	s_add_i32 s65, s65, 0x12800
	global_load_lds_dwordx4 v[10:11], off
	v_lshl_add_u64 v[10:11], v[6:7], 0, s[2:3]
	s_mov_b32 m0, s65
	s_lshr_b32 s57, s56, 3
	global_load_lds_dwordx4 v[10:11], off
	s_and_b32 s57, s57, 0x1ffffff0
	v_or_b32_e32 v10, s57, v195
	s_lshr_b32 s56, s56, 1
	v_lshlrev_b32_e32 v30, 7, v10
	s_and_b32 s56, s56, 32
	v_or_b32_e32 v10, s56, v195
	v_add_u32_e32 v12, 0, v30
	v_lshlrev_b32_e32 v47, 7, v10
	v_add_u32_e32 v10, v12, v137
	v_add_u32_e32 v11, v139, v47
	ds_read_b128 v[14:17], v10
	ds_read_b128 v[18:21], v11 offset:8192
	ds_read_b128 v[22:25], v11 offset:10240
	ds_read_b128 v[26:29], v11 offset:16384
	ds_read_b128 v[32:35], v11 offset:18432
	ds_read_b128 v[36:39], v11 offset:24576
	ds_read_b128 v[48:51], v11 offset:26624
	v_add_u32_e32 v13, v12, v138
	v_add_u32_e32 v12, v140, v47
	ds_read_b128 v[52:55], v13
	ds_read_b128 v[56:59], v12 offset:8192
	ds_read_b128 v[60:63], v12 offset:10240
	ds_read_b128 v[64:67], v12 offset:16384
	ds_read_b128 v[68:71], v12 offset:18432
	ds_read_b128 v[72:75], v12 offset:24576
	ds_read_b128 v[76:79], v12 offset:26624
	s_waitcnt lgkmcnt(0)
	v_mfma_f32_16x16x32_bf16 v[18:21], v[18:21], v[14:17], 0
	v_mfma_f32_16x16x32_bf16 v[22:25], v[22:25], v[14:17], 0
	v_mfma_f32_16x16x32_bf16 v[26:29], v[26:29], v[14:17], 0
	v_mfma_f32_16x16x32_bf16 v[32:35], v[32:35], v[14:17], 0
	v_mfma_f32_16x16x32_bf16 v[36:39], v[36:39], v[14:17], 0
	v_mfma_f32_16x16x32_bf16 v[14:17], v[48:51], v[14:17], 0
	v_mfma_f32_16x16x32_bf16 v[18:21], v[56:59], v[52:55], v[18:21]
	v_mfma_f32_16x16x32_bf16 v[22:25], v[60:63], v[52:55], v[22:25]
	v_mfma_f32_16x16x32_bf16 v[26:29], v[64:67], v[52:55], v[26:29]
	v_mfma_f32_16x16x32_bf16 v[32:35], v[68:71], v[52:55], v[32:35]
	v_mfma_f32_16x16x32_bf16 v[36:39], v[72:75], v[52:55], v[36:39]
	v_mfma_f32_16x16x32_bf16 v[14:17], v[76:79], v[52:55], v[14:17]
	s_mov_b32 m0, s61
	s_waitcnt vmcnt(4)
	v_lshl_add_u64 v[40:41], v[8:9], 0, s[12:13]
	s_waitcnt lgkmcnt(0)
	s_barrier
; DI f32x4 mfma16(bf16x8 a, bf16x8 b, f32x4 c) { return __builtin_amdgcn_mfma_f32_16x16x32_bf16(a, b, c, 0, 0, 0); }
; #define RAW_BARRIER() do { asm volatile("s_waitcnt lgkmcnt(0)" ::: "memory"); __builtin_amdgcn_s_barrier(); } while (0)
; template <int N> DI void wait_vmcnt() { asm volatile("s_waitcnt vmcnt(%0)" ::"n"(N) : "memory"); }
;     ...
;   for (int kt = 0; kt < 16; kt++) {
;     if (NST == 3) { if (kt + 1 < 16) wait_vmcnt<NI>(); else wait_vmcnt<0>(); }
;     else wait_vmcnt<0>();
;     RAW_BARRIER();
;     if (NST == 3) { if (kt + 2 < 16) glds(kt + 2, (kt + 2) % 3); }
;     else { if (kt + 1 < 16) glds(kt + 1, (kt + 1) & 1); }
;     const char* As = smem + (NST == 3 ? kt % 3 : kt & 1) * STAGE;
;     const char* Bs = As + BM * 128;
;     bf16x8 af[2][TM], bfr[2][NJ];
; #pragma unroll
;     for (int kk = 0; kk < 2; kk++) {
;       const int coff = ((kk * 4 + l4) ^ swz) << 4;
; #pragma unroll
;       for (int i = 0; i < TM; i++) af[kk][i] = *(const bf16x8*)(As + (wm * (TM * 16) + i * 16 + l15) * 128 + coff);
; #pragma unroll
;       for (int j = 0; j < NJ; j++) {
;         int nrow = MERGE ? ((j >> 1) * 64 + wn * 32 + (j & 1) * 16) : (wn * 64 + j * 16);
;         bfr[kk][j] = *(const bf16x8*)(Bs + (nrow + l15) * 128 + coff);
;       }
;       __builtin_amdgcn_sched_barrier(0);
;     }
; #pragma unroll
;     for (int kk = 0; kk < 2; kk++) {
; #pragma unroll
;       for (int i = 0; i < TM; i++)
; #pragma unroll
;         for (int j = 0; j < NJ; j++) acc[i][j] = SWAP ? mfma16(bfr[kk][j], af[kk][i], acc[i][j]) : mfma16(af[kk][i], bfr[kk][j], acc[i][j]);
;       __builtin_amdgcn_sched_barrier(0);
;     }
;   }
	global_load_lds_dwordx4 v[40:41], off
	v_lshl_add_u64 v[40:41], v[2:3], 0, s[12:13]
	s_mov_b32 m0, s58
	s_nop 0
	global_load_lds_dwordx4 v[40:41], off
	v_lshl_add_u64 v[40:41], v[4:5], 0, s[12:13]
	s_mov_b32 m0, s59
	s_nop 0
	global_load_lds_dwordx4 v[40:41], off
	v_lshl_add_u64 v[40:41], v[6:7], 0, s[12:13]
	s_mov_b32 m0, s60
	s_nop 0
	global_load_lds_dwordx4 v[40:41], off
	ds_read_b128 v[48:51], v10 offset:32768
	ds_read_b128 v[52:55], v11 offset:40960
	ds_read_b128 v[56:59], v11 offset:43008
	ds_read_b128 v[60:63], v11 offset:49152
	ds_read_b128 v[64:67], v11 offset:51200
	ds_read_b128 v[68:71], v11 offset:57344
	ds_read_b128 v[72:75], v11 offset:59392
	ds_read_b128 v[76:79], v13 offset:32768
	ds_read_b128 v[80:83], v12 offset:40960
	s_waitcnt vmcnt(0)
	ds_read_b128 v[84:87], v12 offset:43008
	ds_read_b128 v[88:91], v12 offset:49152
	ds_read_b128 v[92:95], v12 offset:51200
	ds_read_b128 v[96:99], v12 offset:57344
	ds_read_b128 v[100:103], v12 offset:59392
	s_waitcnt lgkmcnt(0)
	v_mfma_f32_16x16x32_bf16 v[18:21], v[52:55], v[48:51], v[18:21]
	v_mfma_f32_16x16x32_bf16 v[22:25], v[56:59], v[48:51], v[22:25]
	v_mfma_f32_16x16x32_bf16 v[26:29], v[60:63], v[48:51], v[26:29]
	v_mfma_f32_16x16x32_bf16 v[32:35], v[64:67], v[48:51], v[32:35]
	v_mfma_f32_16x16x32_bf16 v[36:39], v[68:71], v[48:51], v[36:39]
	v_mfma_f32_16x16x32_bf16 v[14:17], v[72:75], v[48:51], v[14:17]
	v_mfma_f32_16x16x32_bf16 v[18:21], v[80:83], v[76:79], v[18:21]
	v_mfma_f32_16x16x32_bf16 v[22:25], v[84:87], v[76:79], v[22:25]
	v_mfma_f32_16x16x32_bf16 v[26:29], v[88:91], v[76:79], v[26:29]
	v_mfma_f32_16x16x32_bf16 v[32:35], v[92:95], v[76:79], v[32:35]
	v_mfma_f32_16x16x32_bf16 v[36:39], v[96:99], v[76:79], v[36:39]
	v_mfma_f32_16x16x32_bf16 v[48:51], v[100:103], v[76:79], v[14:17]
	s_mov_b32 m0, s69
	s_waitcnt vmcnt(4)
	s_nop 1
	v_lshl_add_u64 v[14:15], v[8:9], 0, s[14:15]
	s_waitcnt lgkmcnt(0)
	s_barrier
	global_load_lds_dwordx4 v[14:15], off
	v_lshl_add_u64 v[14:15], v[2:3], 0, s[14:15]
	s_mov_b32 m0, s66
	v_add_u32_e32 v16, s50, v30
	global_load_lds_dwordx4 v[14:15], off
	v_lshl_add_u64 v[14:15], v[4:5], 0, s[14:15]
	s_mov_b32 m0, s67
	s_nop 0
	global_load_lds_dwordx4 v[14:15], off
	v_lshl_add_u64 v[14:15], v[6:7], 0, s[14:15]
	s_mov_b32 m0, s68
	s_nop 0
	global_load_lds_dwordx4 v[14:15], off
	v_add_u32_e32 v14, v16, v137
	v_add_u32_e32 v15, v42, v47
	ds_read_b128 v[52:55], v14
	ds_read_b128 v[56:59], v15
	ds_read_b128 v[60:63], v15 offset:2048
	ds_read_b128 v[64:67], v15 offset:8192
	ds_read_b128 v[68:71], v15 offset:10240
	ds_read_b128 v[72:75], v15 offset:16384
	ds_read_b128 v[76:79], v15 offset:18432
	v_add_u32_e32 v17, v16, v138
	v_add_u32_e32 v16, v43, v47
	ds_read_b128 v[80:83], v17
	ds_read_b128 v[84:87], v16
	ds_read_b128 v[88:91], v16 offset:2048
	ds_read_b128 v[92:95], v16 offset:8192
	ds_read_b128 v[96:99], v16 offset:10240
	ds_read_b128 v[100:103], v16 offset:16384
	ds_read_b128 v[104:107], v16 offset:18432
	s_waitcnt lgkmcnt(0)
	v_mfma_f32_16x16x32_bf16 v[18:21], v[56:59], v[52:55], v[18:21]
	v_mfma_f32_16x16x32_bf16 v[22:25], v[60:63], v[52:55], v[22:25]
	v_mfma_f32_16x16x32_bf16 v[26:29], v[64:67], v[52:55], v[26:29]
	v_mfma_f32_16x16x32_bf16 v[32:35], v[68:71], v[52:55], v[32:35]
	v_mfma_f32_16x16x32_bf16 v[36:39], v[72:75], v[52:55], v[36:39]
	v_mfma_f32_16x16x32_bf16 v[48:51], v[76:79], v[52:55], v[48:51]
	v_mfma_f32_16x16x32_bf16 v[18:21], v[84:87], v[80:83], v[18:21]
	v_mfma_f32_16x16x32_bf16 v[22:25], v[88:91], v[80:83], v[22:25]
	v_mfma_f32_16x16x32_bf16 v[26:29], v[92:95], v[80:83], v[26:29]
	v_mfma_f32_16x16x32_bf16 v[32:35], v[96:99], v[80:83], v[32:35]
	v_mfma_f32_16x16x32_bf16 v[36:39], v[100:103], v[80:83], v[36:39]
	v_mfma_f32_16x16x32_bf16 v[48:51], v[104:107], v[80:83], v[48:51]
	s_mov_b32 m0, s64
	s_waitcnt vmcnt(4)
	v_lshl_add_u64 v[40:41], v[8:9], 0, s[16:17]
	s_waitcnt lgkmcnt(0)
	s_barrier
	global_load_lds_dwordx4 v[40:41], off
	v_lshl_add_u64 v[40:41], v[2:3], 0, s[16:17]
	s_mov_b32 m0, s62
	s_nop 0
	global_load_lds_dwordx4 v[40:41], off
	v_lshl_add_u64 v[40:41], v[4:5], 0, s[16:17]
	s_mov_b32 m0, s63
	s_nop 0
	global_load_lds_dwordx4 v[40:41], off
	v_lshl_add_u64 v[40:41], v[6:7], 0, s[16:17]
	s_mov_b32 m0, s65
	s_nop 0
	global_load_lds_dwordx4 v[40:41], off
	ds_read_b128 v[52:55], v10
	ds_read_b128 v[56:59], v11 offset:8192
	ds_read_b128 v[60:63], v11 offset:10240
	ds_read_b128 v[64:67], v11 offset:16384
	ds_read_b128 v[68:71], v11 offset:18432
	ds_read_b128 v[72:75], v11 offset:24576
	ds_read_b128 v[76:79], v11 offset:26624
	ds_read_b128 v[80:83], v13
	ds_read_b128 v[84:87], v12 offset:8192
	ds_read_b128 v[88:91], v12 offset:10240
	ds_read_b128 v[92:95], v12 offset:16384
	ds_read_b128 v[96:99], v12 offset:18432
	ds_read_b128 v[100:103], v12 offset:24576
	ds_read_b128 v[104:107], v12 offset:26624
	s_waitcnt lgkmcnt(0)
	v_mfma_f32_16x16x32_bf16 v[18:21], v[56:59], v[52:55], v[18:21]
	v_mfma_f32_16x16x32_bf16 v[22:25], v[60:63], v[52:55], v[22:25]
	v_mfma_f32_16x16x32_bf16 v[26:29], v[64:67], v[52:55], v[26:29]
	v_mfma_f32_16x16x32_bf16 v[32:35], v[68:71], v[52:55], v[32:35]
	v_mfma_f32_16x16x32_bf16 v[36:39], v[72:75], v[52:55], v[36:39]
	v_mfma_f32_16x16x32_bf16 v[48:51], v[76:79], v[52:55], v[48:51]
	v_mfma_f32_16x16x32_bf16 v[18:21], v[84:87], v[80:83], v[18:21]
	v_mfma_f32_16x16x32_bf16 v[22:25], v[88:91], v[80:83], v[22:25]
	v_mfma_f32_16x16x32_bf16 v[26:29], v[92:95], v[80:83], v[26:29]
	v_mfma_f32_16x16x32_bf16 v[32:35], v[96:99], v[80:83], v[32:35]
	v_mfma_f32_16x16x32_bf16 v[36:39], v[100:103], v[80:83], v[36:39]
	v_mfma_f32_16x16x32_bf16 v[48:51], v[104:107], v[80:83], v[48:51]
	s_mov_b32 m0, s61
	s_waitcnt vmcnt(4)
	v_lshl_add_u64 v[40:41], v[8:9], 0, s[18:19]
	s_waitcnt lgkmcnt(0)
	s_barrier
; DI f32x4 mfma16(bf16x8 a, bf16x8 b, f32x4 c) { return __builtin_amdgcn_mfma_f32_16x16x32_bf16(a, b, c, 0, 0, 0); }
; #define RAW_BARRIER() do { asm volatile("s_waitcnt lgkmcnt(0)" ::: "memory"); __builtin_amdgcn_s_barrier(); } while (0)
; template <int N> DI void wait_vmcnt() { asm volatile("s_waitcnt vmcnt(%0)" ::"n"(N) : "memory"); }
;     ...
;   for (int kt = 0; kt < 16; kt++) {
;     if (NST == 3) { if (kt + 1 < 16) wait_vmcnt<NI>(); else wait_vmcnt<0>(); }
;     else wait_vmcnt<0>();
;     RAW_BARRIER();
;     if (NST == 3) { if (kt + 2 < 16) glds(kt + 2, (kt + 2) % 3); }
;     else { if (kt + 1 < 16) glds(kt + 1, (kt + 1) & 1); }
;     const char* As = smem + (NST == 3 ? kt % 3 : kt & 1) * STAGE;
;     const char* Bs = As + BM * 128;
;     bf16x8 af[2][TM], bfr[2][NJ];
; #pragma unroll
;     for (int kk = 0; kk < 2; kk++) {
;       const int coff = ((kk * 4 + l4) ^ swz) << 4;
; #pragma unroll
;       for (int i = 0; i < TM; i++) af[kk][i] = *(const bf16x8*)(As + (wm * (TM * 16) + i * 16 + l15) * 128 + coff);
; #pragma unroll
;       for (int j = 0; j < NJ; j++) {
;         int nrow = MERGE ? ((j >> 1) * 64 + wn * 32 + (j & 1) * 16) : (wn * 64 + j * 16);
;         bfr[kk][j] = *(const bf16x8*)(Bs + (nrow + l15) * 128 + coff);
;       }
;       __builtin_amdgcn_sched_barrier(0);
;     }
; #pragma unroll
;     for (int kk = 0; kk < 2; kk++) {
; #pragma unroll
;       for (int i = 0; i < TM; i++)
; #pragma unroll
;         for (int j = 0; j < NJ; j++) acc[i][j] = SWAP ? mfma16(bfr[kk][j], af[kk][i], acc[i][j]) : mfma16(af[kk][i], bfr[kk][j], acc[i][j]);
;       __builtin_amdgcn_sched_barrier(0);
;     }
;   }
	global_load_lds_dwordx4 v[40:41], off
	v_lshl_add_u64 v[40:41], v[2:3], 0, s[18:19]
	s_mov_b32 m0, s58
	s_nop 0
	global_load_lds_dwordx4 v[40:41], off
	v_lshl_add_u64 v[40:41], v[4:5], 0, s[18:19]
	s_mov_b32 m0, s59
	s_nop 0
	global_load_lds_dwordx4 v[40:41], off
	v_lshl_add_u64 v[40:41], v[6:7], 0, s[18:19]
	s_mov_b32 m0, s60
	s_nop 0
	global_load_lds_dwordx4 v[40:41], off
	ds_read_b128 v[52:55], v10 offset:32768
	ds_read_b128 v[56:59], v11 offset:40960
	ds_read_b128 v[60:63], v11 offset:43008
	ds_read_b128 v[64:67], v11 offset:49152
	ds_read_b128 v[68:71], v11 offset:51200
	ds_read_b128 v[72:75], v11 offset:57344
	ds_read_b128 v[76:79], v11 offset:59392
	ds_read_b128 v[80:83], v13 offset:32768
	ds_read_b128 v[84:87], v12 offset:40960
	ds_read_b128 v[88:91], v12 offset:43008
	ds_read_b128 v[92:95], v12 offset:49152
	ds_read_b128 v[96:99], v12 offset:51200
	ds_read_b128 v[100:103], v12 offset:57344
	ds_read_b128 v[104:107], v12 offset:59392
	s_waitcnt lgkmcnt(0)
	v_mfma_f32_16x16x32_bf16 v[18:21], v[56:59], v[52:55], v[18:21]
	v_mfma_f32_16x16x32_bf16 v[22:25], v[60:63], v[52:55], v[22:25]
	v_mfma_f32_16x16x32_bf16 v[26:29], v[64:67], v[52:55], v[26:29]
	v_mfma_f32_16x16x32_bf16 v[32:35], v[68:71], v[52:55], v[32:35]
	v_mfma_f32_16x16x32_bf16 v[36:39], v[72:75], v[52:55], v[36:39]
	v_mfma_f32_16x16x32_bf16 v[48:51], v[76:79], v[52:55], v[48:51]
	v_mfma_f32_16x16x32_bf16 v[18:21], v[84:87], v[80:83], v[18:21]
	v_mfma_f32_16x16x32_bf16 v[22:25], v[88:91], v[80:83], v[22:25]
	v_mfma_f32_16x16x32_bf16 v[26:29], v[92:95], v[80:83], v[26:29]
	v_mfma_f32_16x16x32_bf16 v[32:35], v[96:99], v[80:83], v[32:35]
	v_mfma_f32_16x16x32_bf16 v[36:39], v[100:103], v[80:83], v[36:39]
	v_mfma_f32_16x16x32_bf16 v[48:51], v[104:107], v[80:83], v[48:51]
	s_mov_b32 m0, s69
	s_waitcnt vmcnt(4)
	v_lshl_add_u64 v[40:41], v[8:9], 0, s[24:25]
	s_waitcnt lgkmcnt(0)
	s_barrier
	global_load_lds_dwordx4 v[40:41], off
	v_lshl_add_u64 v[40:41], v[2:3], 0, s[24:25]
	s_mov_b32 m0, s66
	s_nop 0
	global_load_lds_dwordx4 v[40:41], off
	v_lshl_add_u64 v[40:41], v[4:5], 0, s[24:25]
	s_mov_b32 m0, s67
	s_nop 0
	global_load_lds_dwordx4 v[40:41], off
	v_lshl_add_u64 v[40:41], v[6:7], 0, s[24:25]
	s_mov_b32 m0, s68
	s_nop 0
	global_load_lds_dwordx4 v[40:41], off
	ds_read_b128 v[52:55], v14
	ds_read_b128 v[56:59], v15
	ds_read_b128 v[60:63], v15 offset:2048
	ds_read_b128 v[64:67], v15 offset:8192
	ds_read_b128 v[68:71], v15 offset:10240
	ds_read_b128 v[72:75], v15 offset:16384
	ds_read_b128 v[76:79], v15 offset:18432
	ds_read_b128 v[80:83], v17
	ds_read_b128 v[84:87], v16
	ds_read_b128 v[88:91], v16 offset:2048
	ds_read_b128 v[92:95], v16 offset:8192
	ds_read_b128 v[96:99], v16 offset:10240
	ds_read_b128 v[100:103], v16 offset:16384
	ds_read_b128 v[104:107], v16 offset:18432
	s_waitcnt lgkmcnt(0)
	v_mfma_f32_16x16x32_bf16 v[18:21], v[56:59], v[52:55], v[18:21]
	v_mfma_f32_16x16x32_bf16 v[22:25], v[60:63], v[52:55], v[22:25]
	v_mfma_f32_16x16x32_bf16 v[26:29], v[64:67], v[52:55], v[26:29]
	v_mfma_f32_16x16x32_bf16 v[32:35], v[68:71], v[52:55], v[32:35]
	v_mfma_f32_16x16x32_bf16 v[36:39], v[72:75], v[52:55], v[36:39]
	v_mfma_f32_16x16x32_bf16 v[48:51], v[76:79], v[52:55], v[48:51]
	v_mfma_f32_16x16x32_bf16 v[18:21], v[84:87], v[80:83], v[18:21]
	v_mfma_f32_16x16x32_bf16 v[22:25], v[88:91], v[80:83], v[22:25]
	v_mfma_f32_16x16x32_bf16 v[26:29], v[92:95], v[80:83], v[26:29]
	v_mfma_f32_16x16x32_bf16 v[32:35], v[96:99], v[80:83], v[32:35]
	v_mfma_f32_16x16x32_bf16 v[36:39], v[100:103], v[80:83], v[36:39]
	v_mfma_f32_16x16x32_bf16 v[48:51], v[104:107], v[80:83], v[48:51]
	s_mov_b32 m0, s64
	s_waitcnt vmcnt(4)
	v_lshl_add_u64 v[40:41], v[8:9], 0, s[26:27]
	s_waitcnt lgkmcnt(0)
	s_barrier
	global_load_lds_dwordx4 v[40:41], off
	v_lshl_add_u64 v[40:41], v[2:3], 0, s[26:27]
	s_mov_b32 m0, s62
	s_nop 0
	global_load_lds_dwordx4 v[40:41], off
	v_lshl_add_u64 v[40:41], v[4:5], 0, s[26:27]
	s_mov_b32 m0, s63
	s_nop 0
	global_load_lds_dwordx4 v[40:41], off
	v_lshl_add_u64 v[40:41], v[6:7], 0, s[26:27]
	s_mov_b32 m0, s65
	s_nop 0
	global_load_lds_dwordx4 v[40:41], off
	ds_read_b128 v[52:55], v10
	ds_read_b128 v[56:59], v11 offset:8192
	ds_read_b128 v[60:63], v11 offset:10240
	ds_read_b128 v[64:67], v11 offset:16384
	ds_read_b128 v[68:71], v11 offset:18432
	ds_read_b128 v[72:75], v11 offset:24576
	ds_read_b128 v[76:79], v11 offset:26624
	ds_read_b128 v[80:83], v13
	ds_read_b128 v[84:87], v12 offset:8192
	ds_read_b128 v[88:91], v12 offset:10240
	ds_read_b128 v[92:95], v12 offset:16384
	ds_read_b128 v[96:99], v12 offset:18432
	ds_read_b128 v[100:103], v12 offset:24576
	ds_read_b128 v[104:107], v12 offset:26624
	s_waitcnt lgkmcnt(0)
	v_mfma_f32_16x16x32_bf16 v[18:21], v[56:59], v[52:55], v[18:21]
	v_mfma_f32_16x16x32_bf16 v[22:25], v[60:63], v[52:55], v[22:25]
	v_mfma_f32_16x16x32_bf16 v[26:29], v[64:67], v[52:55], v[26:29]
	v_mfma_f32_16x16x32_bf16 v[32:35], v[68:71], v[52:55], v[32:35]
	v_mfma_f32_16x16x32_bf16 v[36:39], v[72:75], v[52:55], v[36:39]
	v_mfma_f32_16x16x32_bf16 v[48:51], v[76:79], v[52:55], v[48:51]
	v_mfma_f32_16x16x32_bf16 v[18:21], v[84:87], v[80:83], v[18:21]
	v_mfma_f32_16x16x32_bf16 v[22:25], v[88:91], v[80:83], v[22:25]
	v_mfma_f32_16x16x32_bf16 v[26:29], v[92:95], v[80:83], v[26:29]
	v_mfma_f32_16x16x32_bf16 v[32:35], v[96:99], v[80:83], v[32:35]
	v_mfma_f32_16x16x32_bf16 v[36:39], v[100:103], v[80:83], v[36:39]
	v_mfma_f32_16x16x32_bf16 v[48:51], v[104:107], v[80:83], v[48:51]
	s_mov_b32 m0, s61
	s_waitcnt vmcnt(4)
	v_lshl_add_u64 v[40:41], v[8:9], 0, s[28:29]
	s_waitcnt lgkmcnt(0)
	s_barrier
; DI f32x4 mfma16(bf16x8 a, bf16x8 b, f32x4 c) { return __builtin_amdgcn_mfma_f32_16x16x32_bf16(a, b, c, 0, 0, 0); }
; #define RAW_BARRIER() do { asm volatile("s_waitcnt lgkmcnt(0)" ::: "memory"); __builtin_amdgcn_s_barrier(); } while (0)
; template <int N> DI void wait_vmcnt() { asm volatile("s_waitcnt vmcnt(%0)" ::"n"(N) : "memory"); }
;     ...
;   for (int kt = 0; kt < 16; kt++) {
;     if (NST == 3) { if (kt + 1 < 16) wait_vmcnt<NI>(); else wait_vmcnt<0>(); }
;     else wait_vmcnt<0>();
;     RAW_BARRIER();
;     if (NST == 3) { if (kt + 2 < 16) glds(kt + 2, (kt + 2) % 3); }
;     else { if (kt + 1 < 16) glds(kt + 1, (kt + 1) & 1); }
;     const char* As = smem + (NST == 3 ? kt % 3 : kt & 1) * STAGE;
;     const char* Bs = As + BM * 128;
;     bf16x8 af[2][TM], bfr[2][NJ];
; #pragma unroll
;     for (int kk = 0; kk < 2; kk++) {
;       const int coff = ((kk * 4 + l4) ^ swz) << 4;
; #pragma unroll
;       for (int i = 0; i < TM; i++) af[kk][i] = *(const bf16x8*)(As + (wm * (TM * 16) + i * 16 + l15) * 128 + coff);
; #pragma unroll
;       for (int j = 0; j < NJ; j++) {
;         int nrow = MERGE ? ((j >> 1) * 64 + wn * 32 + (j & 1) * 16) : (wn * 64 + j * 16);
;         bfr[kk][j] = *(const bf16x8*)(Bs + (nrow + l15) * 128 + coff);
;       }
;       __builtin_amdgcn_sched_barrier(0);
;     }
; #pragma unroll
;     for (int kk = 0; kk < 2; kk++) {
; #pragma unroll
;       for (int i = 0; i < TM; i++)
; #pragma unroll
;         for (int j = 0; j < NJ; j++) acc[i][j] = SWAP ? mfma16(bfr[kk][j], af[kk][i], acc[i][j]) : mfma16(af[kk][i], bfr[kk][j], acc[i][j]);
;       __builtin_amdgcn_sched_barrier(0);
;     }
;   }
	global_load_lds_dwordx4 v[40:41], off
	v_lshl_add_u64 v[40:41], v[2:3], 0, s[28:29]
	s_mov_b32 m0, s58
	s_nop 0
	global_load_lds_dwordx4 v[40:41], off
	v_lshl_add_u64 v[40:41], v[4:5], 0, s[28:29]
	s_mov_b32 m0, s59
	s_nop 0
	global_load_lds_dwordx4 v[40:41], off
	v_lshl_add_u64 v[40:41], v[6:7], 0, s[28:29]
	s_mov_b32 m0, s60
	s_nop 0
	global_load_lds_dwordx4 v[40:41], off
	ds_read_b128 v[52:55], v10 offset:32768
	ds_read_b128 v[56:59], v11 offset:40960
	ds_read_b128 v[60:63], v11 offset:43008
	ds_read_b128 v[64:67], v11 offset:49152
	ds_read_b128 v[68:71], v11 offset:51200
	ds_read_b128 v[72:75], v11 offset:57344
	ds_read_b128 v[76:79], v11 offset:59392
	ds_read_b128 v[80:83], v13 offset:32768
	ds_read_b128 v[84:87], v12 offset:40960
	ds_read_b128 v[88:91], v12 offset:43008
	ds_read_b128 v[92:95], v12 offset:49152
	ds_read_b128 v[96:99], v12 offset:51200
	ds_read_b128 v[100:103], v12 offset:57344
	ds_read_b128 v[104:107], v12 offset:59392
	s_waitcnt lgkmcnt(0)
	v_mfma_f32_16x16x32_bf16 v[18:21], v[56:59], v[52:55], v[18:21]
	v_mfma_f32_16x16x32_bf16 v[22:25], v[60:63], v[52:55], v[22:25]
	v_mfma_f32_16x16x32_bf16 v[26:29], v[64:67], v[52:55], v[26:29]
	v_mfma_f32_16x16x32_bf16 v[32:35], v[68:71], v[52:55], v[32:35]
	v_mfma_f32_16x16x32_bf16 v[36:39], v[72:75], v[52:55], v[36:39]
	v_mfma_f32_16x16x32_bf16 v[48:51], v[76:79], v[52:55], v[48:51]
	v_mfma_f32_16x16x32_bf16 v[18:21], v[84:87], v[80:83], v[18:21]
	v_mfma_f32_16x16x32_bf16 v[22:25], v[88:91], v[80:83], v[22:25]
	v_mfma_f32_16x16x32_bf16 v[26:29], v[92:95], v[80:83], v[26:29]
	v_mfma_f32_16x16x32_bf16 v[32:35], v[96:99], v[80:83], v[32:35]
	v_mfma_f32_16x16x32_bf16 v[36:39], v[100:103], v[80:83], v[36:39]
	v_mfma_f32_16x16x32_bf16 v[48:51], v[104:107], v[80:83], v[48:51]
	s_mov_b32 m0, s69
	s_waitcnt vmcnt(4)
	v_lshl_add_u64 v[40:41], v[8:9], 0, s[30:31]
	s_waitcnt lgkmcnt(0)
	s_barrier
	global_load_lds_dwordx4 v[40:41], off
	v_lshl_add_u64 v[40:41], v[2:3], 0, s[30:31]
	s_mov_b32 m0, s66
	s_nop 0
	global_load_lds_dwordx4 v[40:41], off
	v_lshl_add_u64 v[40:41], v[4:5], 0, s[30:31]
	s_mov_b32 m0, s67
	s_nop 0
	global_load_lds_dwordx4 v[40:41], off
	v_lshl_add_u64 v[40:41], v[6:7], 0, s[30:31]
	s_mov_b32 m0, s68
	s_nop 0
	global_load_lds_dwordx4 v[40:41], off
	ds_read_b128 v[52:55], v14
	ds_read_b128 v[56:59], v15
	ds_read_b128 v[60:63], v15 offset:2048
	ds_read_b128 v[64:67], v15 offset:8192
	ds_read_b128 v[68:71], v15 offset:10240
	ds_read_b128 v[72:75], v15 offset:16384
	ds_read_b128 v[76:79], v15 offset:18432
	ds_read_b128 v[80:83], v17
	ds_read_b128 v[84:87], v16
	ds_read_b128 v[88:91], v16 offset:2048
	ds_read_b128 v[92:95], v16 offset:8192
	ds_read_b128 v[96:99], v16 offset:10240
	ds_read_b128 v[100:103], v16 offset:16384
	ds_read_b128 v[104:107], v16 offset:18432
	s_waitcnt lgkmcnt(0)
	v_mfma_f32_16x16x32_bf16 v[18:21], v[56:59], v[52:55], v[18:21]
	v_mfma_f32_16x16x32_bf16 v[22:25], v[60:63], v[52:55], v[22:25]
	v_mfma_f32_16x16x32_bf16 v[26:29], v[64:67], v[52:55], v[26:29]
	v_mfma_f32_16x16x32_bf16 v[32:35], v[68:71], v[52:55], v[32:35]
	v_mfma_f32_16x16x32_bf16 v[36:39], v[72:75], v[52:55], v[36:39]
	v_mfma_f32_16x16x32_bf16 v[48:51], v[76:79], v[52:55], v[48:51]
	v_mfma_f32_16x16x32_bf16 v[18:21], v[84:87], v[80:83], v[18:21]
	v_mfma_f32_16x16x32_bf16 v[22:25], v[88:91], v[80:83], v[22:25]
	v_mfma_f32_16x16x32_bf16 v[26:29], v[92:95], v[80:83], v[26:29]
	v_mfma_f32_16x16x32_bf16 v[32:35], v[96:99], v[80:83], v[32:35]
	v_mfma_f32_16x16x32_bf16 v[36:39], v[100:103], v[80:83], v[36:39]
	v_mfma_f32_16x16x32_bf16 v[48:51], v[104:107], v[80:83], v[48:51]
	s_mov_b32 m0, s64
	s_waitcnt vmcnt(4)
	v_lshl_add_u64 v[40:41], v[8:9], 0, s[34:35]
	s_waitcnt lgkmcnt(0)
	s_barrier
	global_load_lds_dwordx4 v[40:41], off
	v_lshl_add_u64 v[40:41], v[2:3], 0, s[34:35]
	s_mov_b32 m0, s62
	s_nop 0
	global_load_lds_dwordx4 v[40:41], off
	v_lshl_add_u64 v[40:41], v[4:5], 0, s[34:35]
	s_mov_b32 m0, s63
	s_nop 0
	global_load_lds_dwordx4 v[40:41], off
	v_lshl_add_u64 v[40:41], v[6:7], 0, s[34:35]
	s_mov_b32 m0, s65
	s_nop 0
	global_load_lds_dwordx4 v[40:41], off
	ds_read_b128 v[52:55], v10
	ds_read_b128 v[56:59], v11 offset:8192
	ds_read_b128 v[60:63], v11 offset:10240
	ds_read_b128 v[64:67], v11 offset:16384
	ds_read_b128 v[68:71], v11 offset:18432
	ds_read_b128 v[72:75], v11 offset:24576
	ds_read_b128 v[76:79], v11 offset:26624
	ds_read_b128 v[80:83], v13
	ds_read_b128 v[84:87], v12 offset:8192
	ds_read_b128 v[88:91], v12 offset:10240
	ds_read_b128 v[92:95], v12 offset:16384
	ds_read_b128 v[96:99], v12 offset:18432
	ds_read_b128 v[100:103], v12 offset:24576
	ds_read_b128 v[104:107], v12 offset:26624
	s_waitcnt lgkmcnt(0)
	v_mfma_f32_16x16x32_bf16 v[18:21], v[56:59], v[52:55], v[18:21]
	v_mfma_f32_16x16x32_bf16 v[22:25], v[60:63], v[52:55], v[22:25]
	v_mfma_f32_16x16x32_bf16 v[26:29], v[64:67], v[52:55], v[26:29]
	v_mfma_f32_16x16x32_bf16 v[32:35], v[68:71], v[52:55], v[32:35]
	v_mfma_f32_16x16x32_bf16 v[36:39], v[72:75], v[52:55], v[36:39]
	v_mfma_f32_16x16x32_bf16 v[48:51], v[76:79], v[52:55], v[48:51]
	v_mfma_f32_16x16x32_bf16 v[18:21], v[84:87], v[80:83], v[18:21]
	v_mfma_f32_16x16x32_bf16 v[22:25], v[88:91], v[80:83], v[22:25]
	v_mfma_f32_16x16x32_bf16 v[26:29], v[92:95], v[80:83], v[26:29]
	v_mfma_f32_16x16x32_bf16 v[32:35], v[96:99], v[80:83], v[32:35]
	v_mfma_f32_16x16x32_bf16 v[36:39], v[100:103], v[80:83], v[36:39]
	v_mfma_f32_16x16x32_bf16 v[48:51], v[104:107], v[80:83], v[48:51]
	s_mov_b32 m0, s61
	s_waitcnt vmcnt(4)
	v_lshl_add_u64 v[40:41], v[8:9], 0, s[38:39]
	s_waitcnt lgkmcnt(0)
	s_barrier
; DI f32x4 mfma16(bf16x8 a, bf16x8 b, f32x4 c) { return __builtin_amdgcn_mfma_f32_16x16x32_bf16(a, b, c, 0, 0, 0); }
; #define RAW_BARRIER() do { asm volatile("s_waitcnt lgkmcnt(0)" ::: "memory"); __builtin_amdgcn_s_barrier(); } while (0)
; template <int N> DI void wait_vmcnt() { asm volatile("s_waitcnt vmcnt(%0)" ::"n"(N) : "memory"); }
;     ...
;   for (int kt = 0; kt < 16; kt++) {
;     if (NST == 3) { if (kt + 1 < 16) wait_vmcnt<NI>(); else wait_vmcnt<0>(); }
;     else wait_vmcnt<0>();
;     RAW_BARRIER();
;     if (NST == 3) { if (kt + 2 < 16) glds(kt + 2, (kt + 2) % 3); }
;     else { if (kt + 1 < 16) glds(kt + 1, (kt + 1) & 1); }
;     const char* As = smem + (NST == 3 ? kt % 3 : kt & 1) * STAGE;
;     const char* Bs = As + BM * 128;
;     bf16x8 af[2][TM], bfr[2][NJ];
; #pragma unroll
;     for (int kk = 0; kk < 2; kk++) {
;       const int coff = ((kk * 4 + l4) ^ swz) << 4;
; #pragma unroll
;       for (int i = 0; i < TM; i++) af[kk][i] = *(const bf16x8*)(As + (wm * (TM * 16) + i * 16 + l15) * 128 + coff);
; #pragma unroll
;       for (int j = 0; j < NJ; j++) {
;         int nrow = MERGE ? ((j >> 1) * 64 + wn * 32 + (j & 1) * 16) : (wn * 64 + j * 16);
;         bfr[kk][j] = *(const bf16x8*)(Bs + (nrow + l15) * 128 + coff);
;       }
;       __builtin_amdgcn_sched_barrier(0);
;     }
; #pragma unroll
;     for (int kk = 0; kk < 2; kk++) {
; #pragma unroll
;       for (int i = 0; i < TM; i++)
; #pragma unroll
;         for (int j = 0; j < NJ; j++) acc[i][j] = SWAP ? mfma16(bfr[kk][j], af[kk][i], acc[i][j]) : mfma16(af[kk][i], bfr[kk][j], acc[i][j]);
;       __builtin_amdgcn_sched_barrier(0);
;     }
;   }
	global_load_lds_dwordx4 v[40:41], off
	v_lshl_add_u64 v[40:41], v[2:3], 0, s[38:39]
	s_mov_b32 m0, s58
	s_nop 0
	global_load_lds_dwordx4 v[40:41], off
	v_lshl_add_u64 v[40:41], v[4:5], 0, s[38:39]
	s_mov_b32 m0, s59
	s_nop 0
	global_load_lds_dwordx4 v[40:41], off
	v_lshl_add_u64 v[40:41], v[6:7], 0, s[38:39]
	s_mov_b32 m0, s60
	s_nop 0
	global_load_lds_dwordx4 v[40:41], off
	ds_read_b128 v[52:55], v10 offset:32768
	ds_read_b128 v[56:59], v11 offset:40960
	ds_read_b128 v[60:63], v11 offset:43008
	ds_read_b128 v[64:67], v11 offset:49152
	ds_read_b128 v[68:71], v11 offset:51200
	ds_read_b128 v[72:75], v11 offset:57344
	ds_read_b128 v[76:79], v11 offset:59392
	ds_read_b128 v[80:83], v13 offset:32768
	ds_read_b128 v[84:87], v12 offset:40960
	ds_read_b128 v[88:91], v12 offset:43008
	ds_read_b128 v[92:95], v12 offset:49152
	ds_read_b128 v[96:99], v12 offset:51200
	ds_read_b128 v[100:103], v12 offset:57344
	ds_read_b128 v[104:107], v12 offset:59392
	s_waitcnt lgkmcnt(0)
	v_mfma_f32_16x16x32_bf16 v[18:21], v[56:59], v[52:55], v[18:21]
	v_mfma_f32_16x16x32_bf16 v[22:25], v[60:63], v[52:55], v[22:25]
	v_mfma_f32_16x16x32_bf16 v[26:29], v[64:67], v[52:55], v[26:29]
	v_mfma_f32_16x16x32_bf16 v[32:35], v[68:71], v[52:55], v[32:35]
	v_mfma_f32_16x16x32_bf16 v[36:39], v[72:75], v[52:55], v[36:39]
	v_mfma_f32_16x16x32_bf16 v[48:51], v[76:79], v[52:55], v[48:51]
	v_mfma_f32_16x16x32_bf16 v[18:21], v[84:87], v[80:83], v[18:21]
	v_mfma_f32_16x16x32_bf16 v[22:25], v[88:91], v[80:83], v[22:25]
	v_mfma_f32_16x16x32_bf16 v[26:29], v[92:95], v[80:83], v[26:29]
	v_mfma_f32_16x16x32_bf16 v[32:35], v[96:99], v[80:83], v[32:35]
	v_mfma_f32_16x16x32_bf16 v[36:39], v[100:103], v[80:83], v[36:39]
	v_mfma_f32_16x16x32_bf16 v[48:51], v[104:107], v[80:83], v[48:51]
	s_mov_b32 m0, s69
	s_waitcnt vmcnt(4)
	v_lshl_add_u64 v[40:41], v[8:9], 0, s[40:41]
	s_waitcnt lgkmcnt(0)
	s_barrier
	global_load_lds_dwordx4 v[40:41], off
	v_lshl_add_u64 v[40:41], v[2:3], 0, s[40:41]
	s_mov_b32 m0, s66
	s_nop 0
	global_load_lds_dwordx4 v[40:41], off
	v_lshl_add_u64 v[40:41], v[4:5], 0, s[40:41]
	s_mov_b32 m0, s67
	s_nop 0
	global_load_lds_dwordx4 v[40:41], off
	v_lshl_add_u64 v[40:41], v[6:7], 0, s[40:41]
	s_mov_b32 m0, s68
	s_nop 0
	global_load_lds_dwordx4 v[40:41], off
	ds_read_b128 v[52:55], v14
	ds_read_b128 v[56:59], v15
	ds_read_b128 v[60:63], v15 offset:2048
	ds_read_b128 v[64:67], v15 offset:8192
	ds_read_b128 v[68:71], v15 offset:10240
	ds_read_b128 v[72:75], v15 offset:16384
	ds_read_b128 v[76:79], v15 offset:18432
	ds_read_b128 v[80:83], v17
	ds_read_b128 v[84:87], v16
	ds_read_b128 v[88:91], v16 offset:2048
	ds_read_b128 v[92:95], v16 offset:8192
	ds_read_b128 v[96:99], v16 offset:10240
	ds_read_b128 v[100:103], v16 offset:16384
	ds_read_b128 v[104:107], v16 offset:18432
	s_waitcnt lgkmcnt(0)
	v_mfma_f32_16x16x32_bf16 v[18:21], v[56:59], v[52:55], v[18:21]
	v_mfma_f32_16x16x32_bf16 v[22:25], v[60:63], v[52:55], v[22:25]
	v_mfma_f32_16x16x32_bf16 v[26:29], v[64:67], v[52:55], v[26:29]
	v_mfma_f32_16x16x32_bf16 v[32:35], v[68:71], v[52:55], v[32:35]
	v_mfma_f32_16x16x32_bf16 v[36:39], v[72:75], v[52:55], v[36:39]
	v_mfma_f32_16x16x32_bf16 v[48:51], v[76:79], v[52:55], v[48:51]
	v_mfma_f32_16x16x32_bf16 v[18:21], v[84:87], v[80:83], v[18:21]
	v_mfma_f32_16x16x32_bf16 v[22:25], v[88:91], v[80:83], v[22:25]
	v_mfma_f32_16x16x32_bf16 v[26:29], v[92:95], v[80:83], v[26:29]
	v_mfma_f32_16x16x32_bf16 v[32:35], v[96:99], v[80:83], v[32:35]
	v_mfma_f32_16x16x32_bf16 v[36:39], v[100:103], v[80:83], v[36:39]
	v_mfma_f32_16x16x32_bf16 v[48:51], v[104:107], v[80:83], v[48:51]
	s_mov_b32 m0, s64
	s_waitcnt vmcnt(4)
	v_lshl_add_u64 v[40:41], v[8:9], 0, s[42:43]
	s_waitcnt lgkmcnt(0)
	s_barrier
	global_load_lds_dwordx4 v[40:41], off
	v_lshl_add_u64 v[40:41], v[2:3], 0, s[42:43]
	s_mov_b32 m0, s62
	s_nop 0
	global_load_lds_dwordx4 v[40:41], off
	v_lshl_add_u64 v[40:41], v[4:5], 0, s[42:43]
	s_mov_b32 m0, s63
	s_nop 0
	global_load_lds_dwordx4 v[40:41], off
	v_lshl_add_u64 v[40:41], v[6:7], 0, s[42:43]
	s_mov_b32 m0, s65
	s_nop 0
	global_load_lds_dwordx4 v[40:41], off
	ds_read_b128 v[52:55], v10
	ds_read_b128 v[56:59], v11 offset:8192
	ds_read_b128 v[60:63], v11 offset:10240
	ds_read_b128 v[64:67], v11 offset:16384
	ds_read_b128 v[68:71], v11 offset:18432
	ds_read_b128 v[72:75], v11 offset:24576
	ds_read_b128 v[76:79], v11 offset:26624
	ds_read_b128 v[80:83], v13
	ds_read_b128 v[84:87], v12 offset:8192
	ds_read_b128 v[88:91], v12 offset:10240
	ds_read_b128 v[92:95], v12 offset:16384
	ds_read_b128 v[96:99], v12 offset:18432
	ds_read_b128 v[100:103], v12 offset:24576
	ds_read_b128 v[104:107], v12 offset:26624
	s_waitcnt lgkmcnt(0)
	v_mfma_f32_16x16x32_bf16 v[18:21], v[56:59], v[52:55], v[18:21]
	v_mfma_f32_16x16x32_bf16 v[22:25], v[60:63], v[52:55], v[22:25]
	v_mfma_f32_16x16x32_bf16 v[26:29], v[64:67], v[52:55], v[26:29]
	v_mfma_f32_16x16x32_bf16 v[32:35], v[68:71], v[52:55], v[32:35]
	v_mfma_f32_16x16x32_bf16 v[36:39], v[72:75], v[52:55], v[36:39]
	v_mfma_f32_16x16x32_bf16 v[48:51], v[76:79], v[52:55], v[48:51]
	v_mfma_f32_16x16x32_bf16 v[18:21], v[84:87], v[80:83], v[18:21]
	v_mfma_f32_16x16x32_bf16 v[22:25], v[88:91], v[80:83], v[22:25]
	v_mfma_f32_16x16x32_bf16 v[26:29], v[92:95], v[80:83], v[26:29]
	v_mfma_f32_16x16x32_bf16 v[32:35], v[96:99], v[80:83], v[32:35]
	v_mfma_f32_16x16x32_bf16 v[36:39], v[100:103], v[80:83], v[36:39]
	v_mfma_f32_16x16x32_bf16 v[48:51], v[104:107], v[80:83], v[48:51]
	s_mov_b32 m0, s61
	s_waitcnt vmcnt(4)
	v_lshl_add_u64 v[8:9], v[8:9], 0, s[44:45]
	s_waitcnt lgkmcnt(0)
	s_barrier
; DI f32x4 mfma16(bf16x8 a, bf16x8 b, f32x4 c) { return __builtin_amdgcn_mfma_f32_16x16x32_bf16(a, b, c, 0, 0, 0); }
;     ...
; #pragma unroll
;     for (int kk = 0; kk < 2; kk++) {
; #pragma unroll
;       for (int i = 0; i < TM; i++)
; #pragma unroll
;         for (int j = 0; j < NJ; j++) acc[i][j] = SWAP ? mfma16(bfr[kk][j], af[kk][i], acc[i][j]) : mfma16(af[kk][i], bfr[kk][j], acc[i][j]);
;       __builtin_amdgcn_sched_barrier(0);
;     }
;   }
;   __syncthreads();
; template <int TM>
; DI void phase6_tile(const P& p, char* smem, int m0, int n0) {
;     ...
;     const int head = n0 >> 7;
; #pragma unroll
;     for (int i = 0; i < TM; i++) {
;       int tok = m0 + wm * (TM * 16) + i * 16 + (lane & 15);
;       const float4* sp = (const float4*)(SSQ + (size_t)tok * 64 + head * 8);
;       float4 s0 = sp[0], s1 = sp[1];
;       float ssq = s0.x + s0.y + s0.z + s0.w + s1.x + s1.y + s1.z + s1.w;
;       float rinv = rsqrtf(ssq * (1.f / 128.f) + RMS_EPS);
	global_load_lds_dwordx4 v[8:9], off
	v_lshl_add_u64 v[2:3], v[2:3], 0, s[44:45]
	s_mov_b32 m0, s58
	s_nop 0
	global_load_lds_dwordx4 v[2:3], off
	v_lshl_add_u64 v[2:3], v[4:5], 0, s[44:45]
	s_mov_b32 m0, s59
	s_nop 0
	global_load_lds_dwordx4 v[2:3], off
	v_lshl_add_u64 v[2:3], v[6:7], 0, s[44:45]
	s_mov_b32 m0, s60
	s_nop 0
	global_load_lds_dwordx4 v[2:3], off
	ds_read_b128 v[2:5], v10 offset:32768
	ds_read_b128 v[6:9], v11 offset:40960
	ds_read_b128 v[52:55], v11 offset:43008
	ds_read_b128 v[56:59], v11 offset:49152
	ds_read_b128 v[60:63], v11 offset:51200
	ds_read_b128 v[64:67], v11 offset:57344
	ds_read_b128 v[68:71], v11 offset:59392
	ds_read_b128 v[72:75], v13 offset:32768
	ds_read_b128 v[76:79], v12 offset:40960
	ds_read_b128 v[80:83], v12 offset:43008
	ds_read_b128 v[84:87], v12 offset:49152
	ds_read_b128 v[88:91], v12 offset:51200
	ds_read_b128 v[92:95], v12 offset:57344
	ds_read_b128 v[96:99], v12 offset:59392
	s_waitcnt lgkmcnt(0)
	v_mfma_f32_16x16x32_bf16 v[6:9], v[6:9], v[2:5], v[18:21]
	v_mfma_f32_16x16x32_bf16 v[18:21], v[52:55], v[2:5], v[22:25]
	v_mfma_f32_16x16x32_bf16 v[22:25], v[56:59], v[2:5], v[26:29]
	v_mfma_f32_16x16x32_bf16 v[26:29], v[60:63], v[2:5], v[32:35]
	v_mfma_f32_16x16x32_bf16 v[32:35], v[64:67], v[2:5], v[36:39]
	v_mfma_f32_16x16x32_bf16 v[2:5], v[68:71], v[2:5], v[48:51]
	v_mfma_f32_16x16x32_bf16 v[6:9], v[76:79], v[72:75], v[6:9]
	v_mfma_f32_16x16x32_bf16 v[18:21], v[80:83], v[72:75], v[18:21]
	v_mfma_f32_16x16x32_bf16 v[22:25], v[84:87], v[72:75], v[22:25]
	v_mfma_f32_16x16x32_bf16 v[26:29], v[88:91], v[72:75], v[26:29]
	v_mfma_f32_16x16x32_bf16 v[32:35], v[92:95], v[72:75], v[32:35]
	v_mfma_f32_16x16x32_bf16 v[2:5], v[96:99], v[72:75], v[2:5]
	s_waitcnt vmcnt(4)
	s_waitcnt lgkmcnt(0)
	s_barrier
	ds_read_b128 v[36:39], v15 offset:18432
	ds_read_b128 v[48:51], v15 offset:16384
	ds_read_b128 v[52:55], v15 offset:10240
	ds_read_b128 v[56:59], v15 offset:8192
	ds_read_b128 v[60:63], v15 offset:2048
	ds_read_b128 v[64:67], v15
	ds_read_b128 v[68:71], v14
	ds_read_b128 v[72:75], v17
	ds_read_b128 v[76:79], v16
	ds_read_b128 v[80:83], v16 offset:2048
	ds_read_b128 v[84:87], v16 offset:8192
	ds_read_b128 v[88:91], v16 offset:10240
	ds_read_b128 v[92:95], v16 offset:16384
	ds_read_b128 v[14:17], v16 offset:18432
	s_waitcnt lgkmcnt(0)
	v_mfma_f32_16x16x32_bf16 v[6:9], v[64:67], v[68:71], v[6:9]
	v_mfma_f32_16x16x32_bf16 v[18:21], v[60:63], v[68:71], v[18:21]
	v_mfma_f32_16x16x32_bf16 v[22:25], v[56:59], v[68:71], v[22:25]
	v_mfma_f32_16x16x32_bf16 v[26:29], v[52:55], v[68:71], v[26:29]
	v_mfma_f32_16x16x32_bf16 v[32:35], v[48:51], v[68:71], v[32:35]
	v_mfma_f32_16x16x32_bf16 v[2:5], v[36:39], v[68:71], v[2:5]
	v_mfma_f32_16x16x32_bf16 v[6:9], v[76:79], v[72:75], v[6:9]
	v_mfma_f32_16x16x32_bf16 v[18:21], v[80:83], v[72:75], v[18:21]
	v_mfma_f32_16x16x32_bf16 v[22:25], v[84:87], v[72:75], v[22:25]
	v_mfma_f32_16x16x32_bf16 v[26:29], v[88:91], v[72:75], v[26:29]
	v_mfma_f32_16x16x32_bf16 v[32:35], v[92:95], v[72:75], v[32:35]
	v_mfma_f32_16x16x32_bf16 v[2:5], v[14:17], v[72:75], v[2:5]
	s_waitcnt vmcnt(0)
	s_waitcnt lgkmcnt(0)
	s_barrier
	ds_read_b128 v[14:17], v11 offset:26624
	ds_read_b128 v[36:39], v11 offset:24576
	ds_read_b128 v[48:51], v11 offset:18432
	ds_read_b128 v[52:55], v11 offset:16384
	ds_read_b128 v[56:59], v11 offset:10240
	ds_read_b128 v[60:63], v11 offset:8192
	ds_read_b128 v[64:67], v10
	ds_read_b128 v[68:71], v13
	ds_read_b128 v[72:75], v12 offset:8192
	ds_read_b128 v[76:79], v12 offset:10240
	ds_read_b128 v[80:83], v12 offset:16384
	ds_read_b128 v[84:87], v12 offset:18432
	ds_read_b128 v[88:91], v12 offset:24576
	ds_read_b128 v[92:95], v12 offset:26624
	s_waitcnt lgkmcnt(0)
	v_mfma_f32_16x16x32_bf16 v[6:9], v[60:63], v[64:67], v[6:9]
	v_mfma_f32_16x16x32_bf16 v[10:13], v[56:59], v[64:67], v[18:21]
	v_mfma_f32_16x16x32_bf16 v[18:21], v[52:55], v[64:67], v[22:25]
	v_mfma_f32_16x16x32_bf16 v[26:29], v[48:51], v[64:67], v[26:29]
	v_mfma_f32_16x16x32_bf16 v[32:35], v[36:39], v[64:67], v[32:35]
	v_mfma_f32_16x16x32_bf16 v[36:39], v[14:17], v[64:67], v[2:5]
	v_mfma_f32_16x16x32_bf16 v[14:17], v[72:75], v[68:71], v[6:9]
	v_mfma_f32_16x16x32_bf16 v[2:5], v[76:79], v[68:71], v[10:13]
	v_mfma_f32_16x16x32_bf16 v[22:25], v[80:83], v[68:71], v[18:21]
	v_mfma_f32_16x16x32_bf16 v[10:13], v[84:87], v[68:71], v[26:29]
	v_mfma_f32_16x16x32_bf16 v[18:21], v[88:91], v[68:71], v[32:35]
	v_mfma_f32_16x16x32_bf16 v[6:9], v[92:95], v[68:71], v[36:39]
	s_nop 0
	v_or_b32_e32 v26, s55, v195
	v_add_u32_e32 v26, s57, v26
	v_ashrrev_i32_e32 v27, 31, v26
	s_sub_i32 s53, s47, s53
	v_lshlrev_b64 v[28:29], 8, v[26:27]
	s_and_b32 s58, s53, -8
	v_lshl_add_u64 v[28:29], s[10:11], 0, v[28:29]
	s_ashr_i32 s59, s58, 31
	v_lshl_add_u64 v[32:33], s[58:59], 2, v[28:29]
	v_lshlrev_b64 v[26:27], 11, v[26:27]
	s_waitcnt vmcnt(0)
	s_barrier
; DI float bflo(u32 w) { return __uint_as_float(w << 16); }
; DI float bfhi(u32 w) { return __uint_as_float(w & 0xffff0000u); }
; DI float sigmoidf_(float x) { return 1.f / (1.f + __expf(-x)); }
; template <int TM>
; DI void phase6_tile(const P& p, char* smem, int m0, int n0) {
;     ...
;       int tok = m0 + wm * (TM * 16) + i * 16 + (lane & 15);
;       const float4* sp = (const float4*)(SSQ + (size_t)tok * 64 + head * 8);
;       float4 s0 = sp[0], s1 = sp[1];
;       float ssq = s0.x + s0.y + s0.z + s0.w + s1.x + s1.y + s1.z + s1.w;
;       float rinv = rsqrtf(ssq * (1.f / 128.f) + RMS_EPS);
; #pragma unroll
;       for (int jj = 0; jj < 2; jj++) {
;         int ch = n0 + wn * 32 + jj * 16 + 4 * (lane >> 4);
;         u32x2 oa = *(const u32x2*)(OA + (size_t)tok * 1024 + ch);
;         u32x2 ob = *(const u32x2*)(OB + (size_t)tok * 1024 + ch);
;         float4 g4 = *(const float4*)(p.delta_norm_g + (ch & 127));
;         float av[4] = {bflo(oa[0]), bfhi(oa[0]), bflo(oa[1]), bfhi(oa[1])};
;         float bv[4] = {bflo(ob[0]), bfhi(ob[0]), bflo(ob[1]), bfhi(ob[1])};
;         float gv[4] = {g4.x, g4.y, g4.z, g4.w};
;         float o[4];
; #pragma unroll
;         for (int rr = 0; rr < 4; rr++) {
;           float z = acc[i][jj][rr], ga = acc[i][2 + jj][rr], gb = acc[i][4 + jj][rr];
;           float oan = av[rr] * rinv * gv[rr] * (z / (1.f + __expf(-z)));
;           o[rr] = sigmoidf_(ga) * oan + sigmoidf_(gb) * bv[rr];
;         }
	v_lshl_add_u64 v[40:41], s[8:9], 0, v[26:27]
	v_lshl_add_u64 v[48:49], s[6:7], 0, v[26:27]
	global_load_dwordx4 v[26:29], v[32:33], off offset:16
	global_load_dwordx4 v[36:39], v[32:33], off
	s_sub_i32 s53, s56, s54
	s_add_i32 s53, s53, s33
	v_add_u32_e32 v34, s53, v141
	v_ashrrev_i32_e32 v35, 31, v34
	v_mul_f32_e32 v22, 0xbfb8aa3b, v22
	v_mul_f32_e32 v23, 0xbfb8aa3b, v23
	v_exp_f32_e32 v22, v22
	v_exp_f32_e32 v23, v23
	v_mul_f32_e32 v18, 0xbfb8aa3b, v18
	v_mul_f32_e32 v19, 0xbfb8aa3b, v19
	v_exp_f32_e32 v18, v18
	v_pk_add_f32 v[22:23], v[22:23], 1.0 op_sel_hi:[1,0]
	v_exp_f32_e32 v19, v19
	v_mul_f32_e32 v21, 0xbfb8aa3b, v21
	v_exp_f32_e32 v21, v21
	v_mul_f32_e32 v10, 0xbfb8aa3b, v10
	v_pk_add_f32 v[18:19], v[18:19], 1.0 op_sel_hi:[1,0]
	v_mul_f32_e32 v11, 0xbfb8aa3b, v11
	v_exp_f32_e32 v10, v10
	v_exp_f32_e32 v11, v11
	v_mul_f32_e32 v6, 0xbfb8aa3b, v6
	v_mul_f32_e32 v7, 0xbfb8aa3b, v7
	v_exp_f32_e32 v6, v6
	v_pk_add_f32 v[10:11], v[10:11], 1.0 op_sel_hi:[1,0]
	v_exp_f32_e32 v7, v7
	v_mul_f32_e32 v9, 0xbfb8aa3b, v9
	v_exp_f32_e32 v9, v9
	s_add_i32 s52, s52, s76
	v_pk_add_f32 v[6:7], v[6:7], 1.0 op_sel_hi:[1,0]
	s_add_i32 s33, s33, s46
	s_add_i32 s47, s47, s48
	s_cmp_lt_i32 s52, 64
	s_waitcnt vmcnt(0)
	v_add_f32_e32 v30, v36, v37
	v_add_f32_e32 v30, v30, v38
	v_add_f32_e32 v30, v30, v39
	v_add_f32_e32 v26, v30, v26
	v_add_f32_e32 v26, v26, v27
	v_add_f32_e32 v26, v26, v28
	v_add_f32_e32 v26, v26, v29
	v_fmamk_f32 v26, v26, 0x3c000000, v46
	v_cmp_gt_f32_e32 vcc, s51, v26
	v_mul_f32_e32 v27, 0x4b800000, v26
	s_nop 0
	v_cndmask_b32_e32 v26, v26, v27, vcc
	v_rsq_f32_e32 v26, v26
	s_nop 0
	v_mul_f32_e32 v27, 0x45800000, v26
	v_cndmask_b32_e32 v30, v26, v27, vcc
	v_lshlrev_b64 v[26:27], 1, v[34:35]
	v_lshl_add_u64 v[32:33], v[40:41], 0, v[26:27]
	global_load_dwordx2 v[38:39], v[32:33], off
	v_lshl_add_u64 v[36:37], v[48:49], 0, v[26:27]
	global_load_dwordx2 v[40:41], v[36:37], off
	v_and_b32_e32 v26, 0x6c, v34
	v_mul_f32_e32 v27, 0xbfb8aa3b, v14
	v_lshlrev_b32_e32 v26, 2, v26
	v_exp_f32_e32 v48, v27
	v_mul_f32_e32 v27, 0xbfb8aa3b, v15
	v_exp_f32_e32 v49, v27
	global_load_dwordx4 v[26:29], v26, s[36:37]
	v_pk_add_f32 v[48:49], v[48:49], 1.0 op_sel_hi:[1,0]
	s_nop 0
	v_div_scale_f32 v35, s[54:55], v49, v49, v15
	s_waitcnt vmcnt(2)
	v_lshlrev_b32_e32 v50, 16, v38
	v_and_b32_e32 v51, 0xffff0000, v38
	v_rcp_f32_e32 v38, v35
	s_waitcnt vmcnt(1)
	v_lshlrev_b32_e32 v52, 16, v40
	v_and_b32_e32 v53, 0xffff0000, v40
	v_pk_mul_f32 v[50:51], v[30:31], v[50:51] op_sel_hi:[0,1]
	v_fma_f32 v40, -v35, v38, 1.0
	v_fmac_f32_e32 v38, v40, v38
	v_div_scale_f32 v40, vcc, v15, v49, v15
	v_mul_f32_e32 v47, v40, v38
	s_waitcnt vmcnt(0)
	v_pk_mul_f32 v[26:27], v[26:27], v[50:51]
	v_fma_f32 v50, -v35, v47, v40
	v_fmac_f32_e32 v47, v50, v38
	v_fma_f32 v35, -v35, v47, v40
	v_div_fmas_f32 v35, v35, v38, v47
	v_div_fixup_f32 v15, v35, v49, v15
	v_div_scale_f32 v35, s[54:55], v48, v48, v14
	v_rcp_f32_e32 v38, v35
	s_nop 0
	v_fma_f32 v40, -v35, v38, 1.0
	v_fmac_f32_e32 v38, v40, v38
	v_div_scale_f32 v40, vcc, v14, v48, v14
	v_mul_f32_e32 v47, v40, v38
	v_fma_f32 v49, -v35, v47, v40
	v_fmac_f32_e32 v47, v49, v38
	v_fma_f32 v35, -v35, v47, v40
	v_div_fmas_f32 v35, v35, v38, v47
	v_div_fixup_f32 v14, v35, v48, v14
	v_pk_mul_f32 v[14:15], v[14:15], v[26:27]
	v_div_scale_f32 v26, s[54:55], v23, v23, 1.0
	v_rcp_f32_e32 v27, v26
	s_nop 0
	v_fma_f32 v35, -v26, v27, 1.0
	v_fmac_f32_e32 v27, v35, v27
	v_div_scale_f32 v35, vcc, 1.0, v23, 1.0
	v_mul_f32_e32 v38, v35, v27
	v_fma_f32 v40, -v26, v38, v35
	v_fmac_f32_e32 v38, v40, v27
	v_fma_f32 v26, -v26, v38, v35
	v_div_fmas_f32 v26, v26, v27, v38
	v_div_fixup_f32 v23, v26, v23, 1.0
	v_div_scale_f32 v26, s[54:55], v22, v22, 1.0
	v_rcp_f32_e32 v27, v26
	s_nop 0
	v_fma_f32 v35, -v26, v27, 1.0
	v_fmac_f32_e32 v27, v35, v27
	v_div_scale_f32 v35, vcc, 1.0, v22, 1.0
	v_mul_f32_e32 v38, v35, v27
	v_fma_f32 v40, -v26, v38, v35
	v_fmac_f32_e32 v38, v40, v27
	v_fma_f32 v26, -v26, v38, v35
	v_div_fmas_f32 v26, v26, v27, v38
	v_div_fixup_f32 v22, v26, v22, 1.0
	v_pk_mul_f32 v[14:15], v[22:23], v[14:15]
	v_div_scale_f32 v22, s[54:55], v19, v19, 1.0
	v_rcp_f32_e32 v23, v22
	s_nop 0
	v_fma_f32 v26, -v22, v23, 1.0
	v_fmac_f32_e32 v23, v26, v23
	v_div_scale_f32 v26, vcc, 1.0, v19, 1.0
	v_mul_f32_e32 v27, v26, v23
	v_fma_f32 v35, -v22, v27, v26
	v_fmac_f32_e32 v27, v35, v23
	v_fma_f32 v22, -v22, v27, v26
	v_div_fmas_f32 v22, v22, v23, v27
	v_div_fixup_f32 v19, v22, v19, 1.0
	v_div_scale_f32 v22, s[54:55], v18, v18, 1.0
	v_rcp_f32_e32 v23, v22
	s_nop 0
	v_fma_f32 v26, -v22, v23, 1.0
	v_fmac_f32_e32 v23, v26, v23
	v_div_scale_f32 v26, vcc, 1.0, v18, 1.0
	v_mul_f32_e32 v27, v26, v23
	v_fma_f32 v35, -v22, v27, v26
	v_fmac_f32_e32 v27, v35, v23
	v_fma_f32 v22, -v22, v27, v26
	v_div_fmas_f32 v22, v22, v23, v27
	v_div_fixup_f32 v18, v22, v18, 1.0
	v_pk_fma_f32 v[14:15], v[18:19], v[52:53], v[14:15]
	v_mul_f32_e32 v19, 0xbfb8aa3b, v24
	v_exp_f32_e32 v22, v19
	v_mul_f32_e32 v19, 0xbfb8aa3b, v20
	v_mul_f32_e32 v18, 0xbfb8aa3b, v16
	v_exp_f32_e32 v20, v19
	v_mul_f32_e32 v19, 0xbfb8aa3b, v17
	v_exp_f32_e32 v18, v18
	v_exp_f32_e32 v19, v19
	v_mul_f32_e32 v23, 0xbfb8aa3b, v25
	v_lshlrev_b32_e32 v24, 16, v39
	v_and_b32_e32 v25, 0xffff0000, v39
	v_pk_mul_f32 v[24:25], v[30:31], v[24:25] op_sel_hi:[0,1]
	v_pk_add_f32 v[18:19], v[18:19], 1.0 op_sel_hi:[1,0]
	v_pk_mul_f32 v[24:25], v[28:29], v[24:25]
	v_div_scale_f32 v28, s[54:55], v19, v19, v17
	v_rcp_f32_e32 v29, v28
	v_exp_f32_e32 v23, v23
	v_lshlrev_b32_e32 v26, 16, v41
	v_and_b32_e32 v27, 0xffff0000, v41
	v_fma_f32 v35, -v28, v29, 1.0
	v_fmac_f32_e32 v29, v35, v29
	v_div_scale_f32 v35, vcc, v17, v19, v17
; DI u32 pack2(float a, float b) { f32x2 v = {a, b}; bfx2 r = __builtin_convertvector(v, bfx2); return __builtin_bit_cast(u32, r); }
; DI float sigmoidf_(float x) { return 1.f / (1.f + __expf(-x)); }
; template <int TM>
; DI void phase6_tile(const P& p, char* smem, int m0, int n0) {
;     ...
; #pragma unroll
;         for (int rr = 0; rr < 4; rr++) {
;           float z = acc[i][jj][rr], ga = acc[i][2 + jj][rr], gb = acc[i][4 + jj][rr];
;           float oan = av[rr] * rinv * gv[rr] * (z / (1.f + __expf(-z)));
;           o[rr] = sigmoidf_(ga) * oan + sigmoidf_(gb) * bv[rr];
;         }
;         u32x2 ov = {pack2(o[0], o[1]), pack2(o[2], o[3])};
;         *(u32x2*)(OA + (size_t)tok * 1024 + ch) = ov;
	v_mul_f32_e32 v38, v35, v29
	v_fma_f32 v39, -v28, v38, v35
	v_fmac_f32_e32 v38, v39, v29
	v_fma_f32 v28, -v28, v38, v35
	v_div_fmas_f32 v28, v28, v29, v38
	v_div_fixup_f32 v17, v28, v19, v17
	v_div_scale_f32 v19, s[54:55], v18, v18, v16
	v_rcp_f32_e32 v28, v19
	v_cvt_pk_bf16_f32 v14, v14, v15
	v_fma_f32 v29, -v19, v28, 1.0
	v_fmac_f32_e32 v28, v29, v28
	v_div_scale_f32 v29, vcc, v16, v18, v16
	v_mul_f32_e32 v35, v29, v28
	v_fma_f32 v38, -v19, v35, v29
	v_fmac_f32_e32 v35, v38, v28
	v_fma_f32 v19, -v19, v35, v29
	v_div_fmas_f32 v19, v19, v28, v35
	v_div_fixup_f32 v16, v19, v18, v16
	v_pk_add_f32 v[18:19], v[22:23], 1.0 op_sel_hi:[1,0]
	v_pk_mul_f32 v[16:17], v[16:17], v[24:25]
	v_div_scale_f32 v22, s[54:55], v19, v19, 1.0
	v_rcp_f32_e32 v23, v22
	s_nop 0
	v_fma_f32 v24, -v22, v23, 1.0
	v_fmac_f32_e32 v23, v24, v23
	v_div_scale_f32 v24, vcc, 1.0, v19, 1.0
	v_mul_f32_e32 v25, v24, v23
	v_fma_f32 v28, -v22, v25, v24
	v_fmac_f32_e32 v25, v28, v23
	v_fma_f32 v22, -v22, v25, v24
	v_div_fmas_f32 v22, v22, v23, v25
	v_div_fixup_f32 v19, v22, v19, 1.0
	v_div_scale_f32 v22, s[54:55], v18, v18, 1.0
	v_rcp_f32_e32 v23, v22
	s_nop 0
	v_fma_f32 v24, -v22, v23, 1.0
	v_fmac_f32_e32 v23, v24, v23
	v_div_scale_f32 v24, vcc, 1.0, v18, 1.0
	v_mul_f32_e32 v25, v24, v23
	v_fma_f32 v28, -v22, v25, v24
	v_fmac_f32_e32 v25, v28, v23
	v_fma_f32 v22, -v22, v25, v24
	v_div_fmas_f32 v22, v22, v23, v25
	v_div_fixup_f32 v18, v22, v18, 1.0
	v_pk_mul_f32 v[16:17], v[18:19], v[16:17]
	v_pk_add_f32 v[18:19], v[20:21], 1.0 op_sel_hi:[1,0]
	s_nop 0
	v_div_scale_f32 v20, s[54:55], v19, v19, 1.0
	v_rcp_f32_e32 v21, v20
	s_nop 0
	v_fma_f32 v22, -v20, v21, 1.0
	v_fmac_f32_e32 v21, v22, v21
	v_div_scale_f32 v22, vcc, 1.0, v19, 1.0
	v_mul_f32_e32 v23, v22, v21
	v_fma_f32 v24, -v20, v23, v22
	v_fmac_f32_e32 v23, v24, v21
	v_fma_f32 v20, -v20, v23, v22
	v_div_fmas_f32 v20, v20, v21, v23
	v_div_fixup_f32 v19, v20, v19, 1.0
	v_div_scale_f32 v20, s[54:55], v18, v18, 1.0
	v_rcp_f32_e32 v21, v20
	s_nop 0
	v_fma_f32 v22, -v20, v21, 1.0
	v_fmac_f32_e32 v21, v22, v21
	v_div_scale_f32 v22, vcc, 1.0, v18, 1.0
	v_mul_f32_e32 v23, v22, v21
	v_fma_f32 v24, -v20, v23, v22
	v_fmac_f32_e32 v23, v24, v21
	v_fma_f32 v20, -v20, v23, v22
	v_div_fmas_f32 v20, v20, v21, v23
	v_div_fixup_f32 v18, v20, v18, 1.0
	v_pk_fma_f32 v[16:17], v[18:19], v[26:27], v[16:17]
	s_nop 0
	v_cvt_pk_bf16_f32 v15, v16, v17
	global_store_dwordx2 v[32:33], v[14:15], off
	global_load_dwordx2 v[20:21], v[32:33], off offset:32
	global_load_dwordx2 v[18:19], v[36:37], off offset:32
	v_add_u32_e32 v14, 16, v34
	v_and_b32_e32 v14, 0x7c, v14
	v_mul_f32_e32 v15, 0xbfb8aa3b, v2
	v_lshlrev_b32_e32 v14, 2, v14
	v_exp_f32_e32 v22, v15
	v_mul_f32_e32 v15, 0xbfb8aa3b, v3
	v_exp_f32_e32 v23, v15
	global_load_dwordx4 v[14:17], v14, s[36:37]
	v_pk_add_f32 v[22:23], v[22:23], 1.0 op_sel_hi:[1,0]
	s_waitcnt vmcnt(2)
	v_lshlrev_b32_e32 v24, 16, v20
	s_waitcnt vmcnt(1)
	v_lshlrev_b32_e32 v26, 16, v18
	v_and_b32_e32 v27, 0xffff0000, v18
	v_div_scale_f32 v18, s[54:55], v23, v23, v3
	v_and_b32_e32 v25, 0xffff0000, v20
	v_rcp_f32_e32 v20, v18
	v_pk_mul_f32 v[24:25], v[30:31], v[24:25] op_sel_hi:[0,1]
	s_waitcnt vmcnt(0)
; DI u32 pack2(float a, float b) { f32x2 v = {a, b}; bfx2 r = __builtin_convertvector(v, bfx2); return __builtin_bit_cast(u32, r); }
; DI float sigmoidf_(float x) { return 1.f / (1.f + __expf(-x)); }
; template <int TM>
; DI void phase6_tile(const P& p, char* smem, int m0, int n0) {
;     ...
; #pragma unroll
;         for (int rr = 0; rr < 4; rr++) {
;           float z = acc[i][jj][rr], ga = acc[i][2 + jj][rr], gb = acc[i][4 + jj][rr];
;           float oan = av[rr] * rinv * gv[rr] * (z / (1.f + __expf(-z)));
;           o[rr] = sigmoidf_(ga) * oan + sigmoidf_(gb) * bv[rr];
;         }
;         u32x2 ov = {pack2(o[0], o[1]), pack2(o[2], o[3])};
;         *(u32x2*)(OA + (size_t)tok * 1024 + ch) = ov;
;       }
; DI void phase6(const P& p, char* smem, int bid, int nb) {
;     ...
;   for (int t = bid; t < 4 * 16; t += nb) phase6_tile<1>(p, smem, TP + (t / 16) * 64, (t % 16) * 64);
	v_pk_mul_f32 v[14:15], v[14:15], v[24:25]
	v_fma_f32 v24, -v18, v20, 1.0
	v_fmac_f32_e32 v20, v24, v20
	v_div_scale_f32 v24, vcc, v3, v23, v3
	v_mul_f32_e32 v25, v24, v20
	v_fma_f32 v28, -v18, v25, v24
	v_fmac_f32_e32 v25, v28, v20
	v_fma_f32 v18, -v18, v25, v24
	v_div_fmas_f32 v18, v18, v20, v25
	v_div_fixup_f32 v3, v18, v23, v3
	v_div_scale_f32 v18, s[54:55], v22, v22, v2
	v_rcp_f32_e32 v20, v18
	s_nop 0
	v_fma_f32 v23, -v18, v20, 1.0
	v_fmac_f32_e32 v20, v23, v20
	v_div_scale_f32 v23, vcc, v2, v22, v2
	v_mul_f32_e32 v24, v23, v20
	v_fma_f32 v25, -v18, v24, v23
	v_fmac_f32_e32 v24, v25, v20
	v_fma_f32 v18, -v18, v24, v23
	v_div_fmas_f32 v18, v18, v20, v24
	v_div_fixup_f32 v2, v18, v22, v2
	v_pk_mul_f32 v[2:3], v[2:3], v[14:15]
	v_div_scale_f32 v14, s[54:55], v11, v11, 1.0
	v_rcp_f32_e32 v15, v14
	s_nop 0
	v_fma_f32 v18, -v14, v15, 1.0
	v_fmac_f32_e32 v15, v18, v15
	v_div_scale_f32 v18, vcc, 1.0, v11, 1.0
	v_mul_f32_e32 v20, v18, v15
	v_fma_f32 v22, -v14, v20, v18
	v_fmac_f32_e32 v20, v22, v15
	v_fma_f32 v14, -v14, v20, v18
	v_div_fmas_f32 v14, v14, v15, v20
	v_div_fixup_f32 v11, v14, v11, 1.0
	v_div_scale_f32 v14, s[54:55], v10, v10, 1.0
	v_rcp_f32_e32 v15, v14
	s_nop 0
	v_fma_f32 v18, -v14, v15, 1.0
	v_fmac_f32_e32 v15, v18, v15
	v_div_scale_f32 v18, vcc, 1.0, v10, 1.0
	v_mul_f32_e32 v20, v18, v15
	v_fma_f32 v22, -v14, v20, v18
	v_fmac_f32_e32 v20, v22, v15
	v_fma_f32 v14, -v14, v20, v18
	v_div_fmas_f32 v14, v14, v15, v20
	v_div_fixup_f32 v10, v14, v10, 1.0
	v_pk_mul_f32 v[2:3], v[10:11], v[2:3]
	v_div_scale_f32 v10, s[54:55], v7, v7, 1.0
	v_rcp_f32_e32 v11, v10
	s_nop 0
	v_fma_f32 v14, -v10, v11, 1.0
	v_fmac_f32_e32 v11, v14, v11
	v_div_scale_f32 v14, vcc, 1.0, v7, 1.0
	v_mul_f32_e32 v15, v14, v11
	v_fma_f32 v18, -v10, v15, v14
	v_fmac_f32_e32 v15, v18, v11
	v_fma_f32 v10, -v10, v15, v14
	v_div_fmas_f32 v10, v10, v11, v15
	v_div_fixup_f32 v7, v10, v7, 1.0
	v_div_scale_f32 v10, s[54:55], v6, v6, 1.0
	v_rcp_f32_e32 v11, v10
	s_nop 0
	v_fma_f32 v14, -v10, v11, 1.0
	v_fmac_f32_e32 v11, v14, v11
	v_div_scale_f32 v14, vcc, 1.0, v6, 1.0
	v_mul_f32_e32 v15, v14, v11
	v_fma_f32 v18, -v10, v15, v14
	v_fmac_f32_e32 v15, v18, v11
	v_fma_f32 v10, -v10, v15, v14
	v_div_fmas_f32 v10, v10, v11, v15
	v_div_fixup_f32 v6, v10, v6, 1.0
	v_pk_fma_f32 v[2:3], v[6:7], v[26:27], v[2:3]
	v_mul_f32_e32 v7, 0xbfb8aa3b, v12
	v_exp_f32_e32 v10, v7
	v_mul_f32_e32 v7, 0xbfb8aa3b, v8
	v_mul_f32_e32 v6, 0xbfb8aa3b, v4
	v_exp_f32_e32 v8, v7
	v_mul_f32_e32 v7, 0xbfb8aa3b, v5
	v_exp_f32_e32 v6, v6
	v_exp_f32_e32 v7, v7
	v_mul_f32_e32 v11, 0xbfb8aa3b, v13
	v_lshlrev_b32_e32 v12, 16, v21
	v_and_b32_e32 v13, 0xffff0000, v21
	v_pk_mul_f32 v[12:13], v[30:31], v[12:13] op_sel_hi:[0,1]
	v_pk_add_f32 v[6:7], v[6:7], 1.0 op_sel_hi:[1,0]
	v_pk_mul_f32 v[12:13], v[12:13], v[16:17]
	v_div_scale_f32 v16, s[54:55], v7, v7, v5
	v_rcp_f32_e32 v17, v16
	v_lshlrev_b32_e32 v14, 16, v19
	v_and_b32_e32 v15, 0xffff0000, v19
	v_exp_f32_e32 v11, v11
	v_fma_f32 v18, -v16, v17, 1.0
	v_fmac_f32_e32 v17, v18, v17
	v_div_scale_f32 v18, vcc, v5, v7, v5
	v_mul_f32_e32 v19, v18, v17
	v_fma_f32 v20, -v16, v19, v18
	v_fmac_f32_e32 v19, v20, v17
	v_fma_f32 v16, -v16, v19, v18
	v_div_fmas_f32 v16, v16, v17, v19
	v_div_fixup_f32 v5, v16, v7, v5
	v_div_scale_f32 v7, s[54:55], v6, v6, v4
	v_rcp_f32_e32 v16, v7
	v_cvt_pk_bf16_f32 v2, v2, v3
	v_fma_f32 v17, -v7, v16, 1.0
	v_fmac_f32_e32 v16, v17, v16
	v_div_scale_f32 v17, vcc, v4, v6, v4
	v_mul_f32_e32 v18, v17, v16
	v_fma_f32 v19, -v7, v18, v17
	v_fmac_f32_e32 v18, v19, v16
	v_fma_f32 v7, -v7, v18, v17
	v_div_fmas_f32 v7, v7, v16, v18
	v_div_fixup_f32 v4, v7, v6, v4
	v_pk_add_f32 v[6:7], v[10:11], 1.0 op_sel_hi:[1,0]
	v_pk_mul_f32 v[4:5], v[4:5], v[12:13]
	v_div_scale_f32 v10, s[54:55], v7, v7, 1.0
	v_rcp_f32_e32 v11, v10
	s_nop 0
	v_fma_f32 v12, -v10, v11, 1.0
	v_fmac_f32_e32 v11, v12, v11
	v_div_scale_f32 v12, vcc, 1.0, v7, 1.0
	v_mul_f32_e32 v13, v12, v11
	v_fma_f32 v16, -v10, v13, v12
	v_fmac_f32_e32 v13, v16, v11
	v_fma_f32 v10, -v10, v13, v12
	v_div_fmas_f32 v10, v10, v11, v13
	v_div_fixup_f32 v7, v10, v7, 1.0
	v_div_scale_f32 v10, s[54:55], v6, v6, 1.0
	v_rcp_f32_e32 v11, v10
	s_nop 0
	v_fma_f32 v12, -v10, v11, 1.0
	v_fmac_f32_e32 v11, v12, v11
	v_div_scale_f32 v12, vcc, 1.0, v6, 1.0
	v_mul_f32_e32 v13, v12, v11
	v_fma_f32 v16, -v10, v13, v12
	v_fmac_f32_e32 v13, v16, v11
	v_fma_f32 v10, -v10, v13, v12
	v_div_fmas_f32 v10, v10, v11, v13
	v_div_fixup_f32 v6, v10, v6, 1.0
	v_pk_mul_f32 v[4:5], v[6:7], v[4:5]
	v_pk_add_f32 v[6:7], v[8:9], 1.0 op_sel_hi:[1,0]
	s_nop 0
	v_div_scale_f32 v8, s[54:55], v7, v7, 1.0
	v_rcp_f32_e32 v9, v8
	s_nop 0
	v_fma_f32 v10, -v8, v9, 1.0
	v_fmac_f32_e32 v9, v10, v9
	v_div_scale_f32 v10, vcc, 1.0, v7, 1.0
	v_mul_f32_e32 v11, v10, v9
	v_fma_f32 v12, -v8, v11, v10
	v_fmac_f32_e32 v11, v12, v9
	v_fma_f32 v8, -v8, v11, v10
	v_div_fmas_f32 v8, v8, v9, v11
	v_div_fixup_f32 v7, v8, v7, 1.0
	v_div_scale_f32 v8, s[54:55], v6, v6, 1.0
	v_rcp_f32_e32 v9, v8
	s_nop 0
	v_fma_f32 v10, -v8, v9, 1.0
	v_fmac_f32_e32 v9, v10, v9
	v_div_scale_f32 v10, vcc, 1.0, v6, 1.0
	v_mul_f32_e32 v11, v10, v9
	v_fma_f32 v12, -v8, v11, v10
	v_fmac_f32_e32 v11, v12, v9
	v_fma_f32 v8, -v8, v11, v10
	v_div_fmas_f32 v8, v8, v9, v11
	v_div_fixup_f32 v6, v8, v6, 1.0
	v_pk_fma_f32 v[4:5], v[6:7], v[14:15], v[4:5]
	s_nop 0
	v_cvt_pk_bf16_f32 v3, v4, v5
	global_store_dwordx2 v[32:33], v[2:3], off offset:32
	s_cbranch_scc1 .LBB0_809

; DI f32x4 mfma16(bf16x8 a, bf16x8 b, f32x4 c) { return __builtin_amdgcn_mfma_f32_16x16x32_bf16(a, b, c, 0, 0, 0); }
; #define RAW_BARRIER() do { asm volatile("s_waitcnt lgkmcnt(0)" ::: "memory"); __builtin_amdgcn_s_barrier(); } while (0)
; template <int N> DI void wait_vmcnt() { asm volatile("s_waitcnt vmcnt(%0)" ::"n"(N) : "memory"); }
;     ...
;   __syncthreads();
;   wait_vmcnt<0>();
;   glds(0, 0);
;   if (NST == 3) glds(1, 1);
;   for (int kt = 0; kt < 16; kt++) {
;     if (NST == 3) { if (kt + 1 < 16) wait_vmcnt<NI>(); else wait_vmcnt<0>(); }
;     else wait_vmcnt<0>();
;     RAW_BARRIER();
;     if (NST == 3) { if (kt + 2 < 16) glds(kt + 2, (kt + 2) % 3); }
;     else { if (kt + 1 < 16) glds(kt + 1, (kt + 1) & 1); }
;     const char* As = smem + (NST == 3 ? kt % 3 : kt & 1) * STAGE;
;     const char* Bs = As + BM * 128;
;     bf16x8 af[2][TM], bfr[2][NJ];
; #pragma unroll
;     for (int kk = 0; kk < 2; kk++) {
;       const int coff = ((kk * 4 + l4) ^ swz) << 4;
; #pragma unroll
;       for (int i = 0; i < TM; i++) af[kk][i] = *(const bf16x8*)(As + (wm * (TM * 16) + i * 16 + l15) * 128 + coff);
; #pragma unroll
;       for (int j = 0; j < NJ; j++) {
;         int nrow = MERGE ? ((j >> 1) * 64 + wn * 32 + (j & 1) * 16) : (wn * 64 + j * 16);
;         bfr[kk][j] = *(const bf16x8*)(Bs + (nrow + l15) * 128 + coff);
;       }
;       __builtin_amdgcn_sched_barrier(0);
;     }
; #pragma unroll
;     for (int kk = 0; kk < 2; kk++) {
; #pragma unroll
;       for (int i = 0; i < TM; i++)
; #pragma unroll
;         for (int j = 0; j < NJ; j++) acc[i][j] = SWAP ? mfma16(bfr[kk][j], af[kk][i], acc[i][j]) : mfma16(af[kk][i], bfr[kk][j], acc[i][j]);
;       __builtin_amdgcn_sched_barrier(0);
;     }
;   }
.LBB0_847:
	s_ashr_i32 s45, s44, 31
	s_lshr_b32 s45, s45, 29
	s_add_i32 s45, s44, s45
	v_readfirstlane_b32 s48, v84
	s_ashr_i32 s46, s45, 3
	s_lshr_b32 s47, s48, 6
	s_lshl_b32 s45, s46, 6
	s_lshl_b32 s49, s47, 4
	s_lshl_b32 s46, s46, 10
	v_lshl_or_b32 v4, s47, 3, v187
	s_sub_i32 s50, s49, s46
	s_add_i32 s45, s45, 0x8000
	v_lshrrev_b32_e32 v6, 1, v4
	s_add_i32 s50, s50, s33
	v_xor_b32_e32 v12, v6, v84
	v_add_u32_e32 v6, s45, v4
	v_add_u32_e32 v8, s50, v187
	v_ashrrev_i32_e32 v7, 31, v6
	v_ashrrev_i32_e32 v9, 31, v8
	v_or3_b32 v4, s49, v187, 8
	v_lshlrev_b64 v[10:11], 11, v[6:7]
	v_lshlrev_b64 v[6:7], 11, v[8:9]
	v_lshrrev_b32_e32 v4, 1, v4
	v_add_u32_e32 v8, 8, v8
	v_xor_b32_e32 v4, v4, v84
	v_ashrrev_i32_e32 v9, 31, v8
	v_lshlrev_b64 v[8:9], 11, v[8:9]
	v_lshlrev_b32_e32 v4, 4, v4
	v_lshl_add_u64 v[8:9], s[4:5], 0, v[8:9]
	v_and_b32_e32 v4, 0x70, v4
	s_lshl_b32 s47, s47, 10
	v_lshl_add_u64 v[8:9], v[8:9], 0, v[4:5]
	v_lshlrev_b32_e32 v4, 4, v12
	s_add_i32 s51, s47, 0
	v_lshl_add_u64 v[10:11], s[2:3], 0, v[10:11]
	v_and_b32_e32 v4, 0x70, v4
	s_add_i32 s53, s51, s47
	v_lshl_add_u64 v[6:7], s[4:5], 0, v[6:7]
	v_lshl_add_u64 v[10:11], v[10:11], 0, v[4:5]
	s_barrier
	s_nop 0
	s_add_i32 s49, s53, 0x2000
	s_mov_b32 m0, s51
	v_lshl_add_u64 v[6:7], v[6:7], 0, v[2:3]
	global_load_lds_dwordx4 v[10:11], off
	s_mov_b32 m0, s49
	s_add_i32 s50, s53, 0x2400
	global_load_lds_dwordx4 v[6:7], off
	s_mov_b32 m0, s50
	s_add_i32 s57, s51, 0x6000
	global_load_lds_dwordx4 v[8:9], off
	s_add_i32 s55, s53, 0x8000
	v_lshl_add_u64 v[12:13], v[10:11], 0, s[6:7]
	s_mov_b32 m0, s57
	s_add_i32 s56, s53, 0x8400
	global_load_lds_dwordx4 v[12:13], off
	v_lshl_add_u64 v[12:13], v[6:7], 0, s[6:7]
	s_mov_b32 m0, s55
	s_add_i32 s54, s51, 0xc000
	global_load_lds_dwordx4 v[12:13], off
	v_lshl_add_u64 v[12:13], v[8:9], 0, s[6:7]
	s_mov_b32 m0, s56
	s_add_i32 s52, s53, 0xe000
	global_load_lds_dwordx4 v[12:13], off
	s_waitcnt vmcnt(3)
	v_lshl_add_u64 v[12:13], v[10:11], 0, s[8:9]
	s_mov_b32 m0, s54
	s_waitcnt lgkmcnt(0)
	s_barrier
	global_load_lds_dwordx4 v[12:13], off
	v_lshl_add_u64 v[12:13], v[6:7], 0, s[8:9]
	s_mov_b32 m0, s52
	s_add_i32 s53, s53, 0xe400
	global_load_lds_dwordx4 v[12:13], off
	v_lshl_add_u64 v[12:13], v[8:9], 0, s[8:9]
	s_mov_b32 m0, s53
	s_and_b32 s47, s48, 64
	global_load_lds_dwordx4 v[12:13], off
	s_lshr_b32 s48, s48, 3
	s_and_b32 s48, s48, 0x1ffffff0
	v_or_b32_e32 v4, s48, v195
	v_or_b32_e32 v12, s47, v195
	v_lshl_add_u32 v14, v4, 7, 0
	v_lshlrev_b32_e32 v13, 7, v12
	v_add_u32_e32 v4, v14, v85
	v_add_u32_e32 v12, v87, v13
	ds_read_b128 v[16:19], v4
	ds_read_b128 v[20:23], v12 offset:8192
	ds_read_b128 v[24:27], v12 offset:10240
	ds_read_b128 v[28:31], v12 offset:12288
	ds_read_b128 v[32:35], v12 offset:14336
	v_add_u32_e32 v14, v14, v86
	v_add_u32_e32 v13, v88, v13
	ds_read_b128 v[36:39], v14
	ds_read_b128 v[40:43], v13 offset:8192
	ds_read_b128 v[44:47], v13 offset:10240
	ds_read_b128 v[48:51], v13 offset:12288
	ds_read_b128 v[52:55], v13 offset:14336
	s_waitcnt lgkmcnt(0)
	v_mfma_f32_16x16x32_bf16 v[20:23], v[20:23], v[16:19], 0
	v_mfma_f32_16x16x32_bf16 v[24:27], v[24:27], v[16:19], 0
	v_mfma_f32_16x16x32_bf16 v[28:31], v[28:31], v[16:19], 0
	v_mfma_f32_16x16x32_bf16 v[16:19], v[32:35], v[16:19], 0
	v_mfma_f32_16x16x32_bf16 v[20:23], v[40:43], v[36:39], v[20:23]
	v_mfma_f32_16x16x32_bf16 v[24:27], v[44:47], v[36:39], v[24:27]
	v_mfma_f32_16x16x32_bf16 v[28:31], v[48:51], v[36:39], v[28:31]
	v_mfma_f32_16x16x32_bf16 v[16:19], v[52:55], v[36:39], v[16:19]
	s_mov_b32 m0, s51
	s_waitcnt vmcnt(3)
	v_lshl_add_u64 v[32:33], v[10:11], 0, s[10:11]
	s_waitcnt lgkmcnt(0)
	s_barrier
	global_load_lds_dwordx4 v[32:33], off
	v_lshl_add_u64 v[32:33], v[6:7], 0, s[10:11]
	s_mov_b32 m0, s49
	s_nop 0
	global_load_lds_dwordx4 v[32:33], off
	v_lshl_add_u64 v[32:33], v[8:9], 0, s[10:11]
	s_mov_b32 m0, s50
	s_nop 0
	global_load_lds_dwordx4 v[32:33], off
	ds_read_b128 v[32:35], v4 offset:24576
	ds_read_b128 v[36:39], v12 offset:32768
	ds_read_b128 v[40:43], v12 offset:34816
	ds_read_b128 v[44:47], v12 offset:36864
	ds_read_b128 v[48:51], v12 offset:38912
	ds_read_b128 v[52:55], v14 offset:24576
	ds_read_b128 v[56:59], v13 offset:32768
	ds_read_b128 v[60:63], v13 offset:34816
	ds_read_b128 v[64:67], v13 offset:36864
	ds_read_b128 v[68:71], v13 offset:38912
	s_waitcnt lgkmcnt(0)
	v_mfma_f32_16x16x32_bf16 v[20:23], v[36:39], v[32:35], v[20:23]
	v_mfma_f32_16x16x32_bf16 v[24:27], v[40:43], v[32:35], v[24:27]
	v_mfma_f32_16x16x32_bf16 v[28:31], v[44:47], v[32:35], v[28:31]
	v_mfma_f32_16x16x32_bf16 v[16:19], v[48:51], v[32:35], v[16:19]
	v_mfma_f32_16x16x32_bf16 v[20:23], v[56:59], v[52:55], v[20:23]
	v_mfma_f32_16x16x32_bf16 v[24:27], v[60:63], v[52:55], v[24:27]
	v_mfma_f32_16x16x32_bf16 v[28:31], v[64:67], v[52:55], v[28:31]
	v_mfma_f32_16x16x32_bf16 v[16:19], v[68:71], v[52:55], v[16:19]
	s_mov_b32 m0, s57
	s_waitcnt vmcnt(3)
	v_lshl_add_u64 v[32:33], v[10:11], 0, s[12:13]
	s_waitcnt lgkmcnt(0)
	s_barrier
	global_load_lds_dwordx4 v[32:33], off
	v_lshl_add_u64 v[32:33], v[6:7], 0, s[12:13]
	s_mov_b32 m0, s55
	s_nop 0
	global_load_lds_dwordx4 v[32:33], off
	v_lshl_add_u64 v[32:33], v[8:9], 0, s[12:13]
	s_mov_b32 m0, s56
	s_nop 0
	global_load_lds_dwordx4 v[32:33], off
	ds_read_b128 v[32:35], v4 offset:49152
	ds_read_b128 v[36:39], v12 offset:57344
	ds_read_b128 v[40:43], v12 offset:59392
	ds_read_b128 v[44:47], v12 offset:61440
	ds_read_b128 v[48:51], v12 offset:63488
	ds_read_b128 v[52:55], v14 offset:49152
	ds_read_b128 v[56:59], v13 offset:57344
	ds_read_b128 v[60:63], v13 offset:59392
	ds_read_b128 v[64:67], v13 offset:61440
	ds_read_b128 v[68:71], v13 offset:63488
	s_waitcnt lgkmcnt(0)
	v_mfma_f32_16x16x32_bf16 v[20:23], v[36:39], v[32:35], v[20:23]
	v_mfma_f32_16x16x32_bf16 v[24:27], v[40:43], v[32:35], v[24:27]
	v_mfma_f32_16x16x32_bf16 v[28:31], v[44:47], v[32:35], v[28:31]
	v_mfma_f32_16x16x32_bf16 v[16:19], v[48:51], v[32:35], v[16:19]
	v_mfma_f32_16x16x32_bf16 v[20:23], v[56:59], v[52:55], v[20:23]
	v_mfma_f32_16x16x32_bf16 v[24:27], v[60:63], v[52:55], v[24:27]
	v_mfma_f32_16x16x32_bf16 v[28:31], v[64:67], v[52:55], v[28:31]
	v_mfma_f32_16x16x32_bf16 v[16:19], v[68:71], v[52:55], v[16:19]
	s_mov_b32 m0, s54
	s_waitcnt vmcnt(3)
	v_lshl_add_u64 v[32:33], v[10:11], 0, s[14:15]
	s_waitcnt lgkmcnt(0)
	s_barrier
; DI f32x4 mfma16(bf16x8 a, bf16x8 b, f32x4 c) { return __builtin_amdgcn_mfma_f32_16x16x32_bf16(a, b, c, 0, 0, 0); }
; #define RAW_BARRIER() do { asm volatile("s_waitcnt lgkmcnt(0)" ::: "memory"); __builtin_amdgcn_s_barrier(); } while (0)
; template <int N> DI void wait_vmcnt() { asm volatile("s_waitcnt vmcnt(%0)" ::"n"(N) : "memory"); }
;     ...
;   for (int kt = 0; kt < 16; kt++) {
;     if (NST == 3) { if (kt + 1 < 16) wait_vmcnt<NI>(); else wait_vmcnt<0>(); }
;     else wait_vmcnt<0>();
;     RAW_BARRIER();
;     if (NST == 3) { if (kt + 2 < 16) glds(kt + 2, (kt + 2) % 3); }
;     else { if (kt + 1 < 16) glds(kt + 1, (kt + 1) & 1); }
;     const char* As = smem + (NST == 3 ? kt % 3 : kt & 1) * STAGE;
;     const char* Bs = As + BM * 128;
;     bf16x8 af[2][TM], bfr[2][NJ];
; #pragma unroll
;     for (int kk = 0; kk < 2; kk++) {
;       const int coff = ((kk * 4 + l4) ^ swz) << 4;
; #pragma unroll
;       for (int i = 0; i < TM; i++) af[kk][i] = *(const bf16x8*)(As + (wm * (TM * 16) + i * 16 + l15) * 128 + coff);
; #pragma unroll
;       for (int j = 0; j < NJ; j++) {
;         int nrow = MERGE ? ((j >> 1) * 64 + wn * 32 + (j & 1) * 16) : (wn * 64 + j * 16);
;         bfr[kk][j] = *(const bf16x8*)(Bs + (nrow + l15) * 128 + coff);
;       }
;       __builtin_amdgcn_sched_barrier(0);
;     }
; #pragma unroll
;     for (int kk = 0; kk < 2; kk++) {
; #pragma unroll
;       for (int i = 0; i < TM; i++)
; #pragma unroll
;         for (int j = 0; j < NJ; j++) acc[i][j] = SWAP ? mfma16(bfr[kk][j], af[kk][i], acc[i][j]) : mfma16(af[kk][i], bfr[kk][j], acc[i][j]);
;       __builtin_amdgcn_sched_barrier(0);
;     }
;   }
	global_load_lds_dwordx4 v[32:33], off
	v_lshl_add_u64 v[32:33], v[6:7], 0, s[14:15]
	s_mov_b32 m0, s52
	s_nop 0
	global_load_lds_dwordx4 v[32:33], off
	v_lshl_add_u64 v[32:33], v[8:9], 0, s[14:15]
	s_mov_b32 m0, s53
	s_nop 0
	global_load_lds_dwordx4 v[32:33], off
	ds_read_b128 v[32:35], v4
	ds_read_b128 v[36:39], v12 offset:8192
	ds_read_b128 v[40:43], v12 offset:10240
	ds_read_b128 v[44:47], v12 offset:12288
	ds_read_b128 v[48:51], v12 offset:14336
	ds_read_b128 v[52:55], v14
	ds_read_b128 v[56:59], v13 offset:8192
	ds_read_b128 v[60:63], v13 offset:10240
	ds_read_b128 v[64:67], v13 offset:12288
	ds_read_b128 v[68:71], v13 offset:14336
	s_waitcnt lgkmcnt(0)
	v_mfma_f32_16x16x32_bf16 v[20:23], v[36:39], v[32:35], v[20:23]
	v_mfma_f32_16x16x32_bf16 v[24:27], v[40:43], v[32:35], v[24:27]
	v_mfma_f32_16x16x32_bf16 v[28:31], v[44:47], v[32:35], v[28:31]
	v_mfma_f32_16x16x32_bf16 v[16:19], v[48:51], v[32:35], v[16:19]
	v_mfma_f32_16x16x32_bf16 v[20:23], v[56:59], v[52:55], v[20:23]
	v_mfma_f32_16x16x32_bf16 v[24:27], v[60:63], v[52:55], v[24:27]
	v_mfma_f32_16x16x32_bf16 v[28:31], v[64:67], v[52:55], v[28:31]
	v_mfma_f32_16x16x32_bf16 v[16:19], v[68:71], v[52:55], v[16:19]
	s_mov_b32 m0, s51
	s_waitcnt vmcnt(3)
	v_lshl_add_u64 v[32:33], v[10:11], 0, s[16:17]
	s_waitcnt lgkmcnt(0)
	s_barrier
	global_load_lds_dwordx4 v[32:33], off
	v_lshl_add_u64 v[32:33], v[6:7], 0, s[16:17]
	s_mov_b32 m0, s49
	s_nop 0
	global_load_lds_dwordx4 v[32:33], off
	v_lshl_add_u64 v[32:33], v[8:9], 0, s[16:17]
	s_mov_b32 m0, s50
	s_nop 0
	global_load_lds_dwordx4 v[32:33], off
	ds_read_b128 v[32:35], v4 offset:24576
	ds_read_b128 v[36:39], v12 offset:32768
	ds_read_b128 v[40:43], v12 offset:34816
	ds_read_b128 v[44:47], v12 offset:36864
	ds_read_b128 v[48:51], v12 offset:38912
	ds_read_b128 v[52:55], v14 offset:24576
	ds_read_b128 v[56:59], v13 offset:32768
	ds_read_b128 v[60:63], v13 offset:34816
	ds_read_b128 v[64:67], v13 offset:36864
	ds_read_b128 v[68:71], v13 offset:38912
	s_waitcnt lgkmcnt(0)
	v_mfma_f32_16x16x32_bf16 v[20:23], v[36:39], v[32:35], v[20:23]
	v_mfma_f32_16x16x32_bf16 v[24:27], v[40:43], v[32:35], v[24:27]
	v_mfma_f32_16x16x32_bf16 v[28:31], v[44:47], v[32:35], v[28:31]
	v_mfma_f32_16x16x32_bf16 v[16:19], v[48:51], v[32:35], v[16:19]
	v_mfma_f32_16x16x32_bf16 v[20:23], v[56:59], v[52:55], v[20:23]
	v_mfma_f32_16x16x32_bf16 v[24:27], v[60:63], v[52:55], v[24:27]
	v_mfma_f32_16x16x32_bf16 v[28:31], v[64:67], v[52:55], v[28:31]
	v_mfma_f32_16x16x32_bf16 v[16:19], v[68:71], v[52:55], v[16:19]
	s_mov_b32 m0, s57
	s_waitcnt vmcnt(3)
	v_lshl_add_u64 v[32:33], v[10:11], 0, s[18:19]
	s_waitcnt lgkmcnt(0)
	s_barrier
	global_load_lds_dwordx4 v[32:33], off
	v_lshl_add_u64 v[32:33], v[6:7], 0, s[18:19]
	s_mov_b32 m0, s55
	s_nop 0
	global_load_lds_dwordx4 v[32:33], off
	v_lshl_add_u64 v[32:33], v[8:9], 0, s[18:19]
	s_mov_b32 m0, s56
	s_nop 0
	global_load_lds_dwordx4 v[32:33], off
	ds_read_b128 v[32:35], v4 offset:49152
	ds_read_b128 v[36:39], v12 offset:57344
	ds_read_b128 v[40:43], v12 offset:59392
	ds_read_b128 v[44:47], v12 offset:61440
	ds_read_b128 v[48:51], v12 offset:63488
	ds_read_b128 v[52:55], v14 offset:49152
	ds_read_b128 v[56:59], v13 offset:57344
	ds_read_b128 v[60:63], v13 offset:59392
	ds_read_b128 v[64:67], v13 offset:61440
	ds_read_b128 v[68:71], v13 offset:63488
	s_waitcnt lgkmcnt(0)
	v_mfma_f32_16x16x32_bf16 v[20:23], v[36:39], v[32:35], v[20:23]
	v_mfma_f32_16x16x32_bf16 v[24:27], v[40:43], v[32:35], v[24:27]
	v_mfma_f32_16x16x32_bf16 v[28:31], v[44:47], v[32:35], v[28:31]
	v_mfma_f32_16x16x32_bf16 v[16:19], v[48:51], v[32:35], v[16:19]
	v_mfma_f32_16x16x32_bf16 v[20:23], v[56:59], v[52:55], v[20:23]
	v_mfma_f32_16x16x32_bf16 v[24:27], v[60:63], v[52:55], v[24:27]
	v_mfma_f32_16x16x32_bf16 v[28:31], v[64:67], v[52:55], v[28:31]
	v_mfma_f32_16x16x32_bf16 v[16:19], v[68:71], v[52:55], v[16:19]
	s_mov_b32 m0, s54
	s_waitcnt vmcnt(3)
	v_lshl_add_u64 v[32:33], v[10:11], 0, s[24:25]
	s_waitcnt lgkmcnt(0)
	s_barrier
	global_load_lds_dwordx4 v[32:33], off
	v_lshl_add_u64 v[32:33], v[6:7], 0, s[24:25]
	s_mov_b32 m0, s52
	s_nop 0
	global_load_lds_dwordx4 v[32:33], off
	v_lshl_add_u64 v[32:33], v[8:9], 0, s[24:25]
	s_mov_b32 m0, s53
	s_nop 0
	global_load_lds_dwordx4 v[32:33], off
	ds_read_b128 v[32:35], v4
	ds_read_b128 v[36:39], v12 offset:8192
	ds_read_b128 v[40:43], v12 offset:10240
	ds_read_b128 v[44:47], v12 offset:12288
	ds_read_b128 v[48:51], v12 offset:14336
	ds_read_b128 v[52:55], v14
	ds_read_b128 v[56:59], v13 offset:8192
	ds_read_b128 v[60:63], v13 offset:10240
	ds_read_b128 v[64:67], v13 offset:12288
	ds_read_b128 v[68:71], v13 offset:14336
	s_waitcnt lgkmcnt(0)
	v_mfma_f32_16x16x32_bf16 v[20:23], v[36:39], v[32:35], v[20:23]
	v_mfma_f32_16x16x32_bf16 v[24:27], v[40:43], v[32:35], v[24:27]
	v_mfma_f32_16x16x32_bf16 v[28:31], v[44:47], v[32:35], v[28:31]
	v_mfma_f32_16x16x32_bf16 v[16:19], v[48:51], v[32:35], v[16:19]
	v_mfma_f32_16x16x32_bf16 v[20:23], v[56:59], v[52:55], v[20:23]
	v_mfma_f32_16x16x32_bf16 v[24:27], v[60:63], v[52:55], v[24:27]
	v_mfma_f32_16x16x32_bf16 v[28:31], v[64:67], v[52:55], v[28:31]
	v_mfma_f32_16x16x32_bf16 v[16:19], v[68:71], v[52:55], v[16:19]
	s_mov_b32 m0, s51
	s_waitcnt vmcnt(3)
	v_lshl_add_u64 v[32:33], v[10:11], 0, s[26:27]
	s_waitcnt lgkmcnt(0)
	s_barrier
; DI f32x4 mfma16(bf16x8 a, bf16x8 b, f32x4 c) { return __builtin_amdgcn_mfma_f32_16x16x32_bf16(a, b, c, 0, 0, 0); }
; #define RAW_BARRIER() do { asm volatile("s_waitcnt lgkmcnt(0)" ::: "memory"); __builtin_amdgcn_s_barrier(); } while (0)
; template <int N> DI void wait_vmcnt() { asm volatile("s_waitcnt vmcnt(%0)" ::"n"(N) : "memory"); }
;     ...
;   for (int kt = 0; kt < 16; kt++) {
;     if (NST == 3) { if (kt + 1 < 16) wait_vmcnt<NI>(); else wait_vmcnt<0>(); }
;     else wait_vmcnt<0>();
;     RAW_BARRIER();
;     if (NST == 3) { if (kt + 2 < 16) glds(kt + 2, (kt + 2) % 3); }
;     else { if (kt + 1 < 16) glds(kt + 1, (kt + 1) & 1); }
;     const char* As = smem + (NST == 3 ? kt % 3 : kt & 1) * STAGE;
;     const char* Bs = As + BM * 128;
;     bf16x8 af[2][TM], bfr[2][NJ];
; #pragma unroll
;     for (int kk = 0; kk < 2; kk++) {
;       const int coff = ((kk * 4 + l4) ^ swz) << 4;
; #pragma unroll
;       for (int i = 0; i < TM; i++) af[kk][i] = *(const bf16x8*)(As + (wm * (TM * 16) + i * 16 + l15) * 128 + coff);
; #pragma unroll
;       for (int j = 0; j < NJ; j++) {
;         int nrow = MERGE ? ((j >> 1) * 64 + wn * 32 + (j & 1) * 16) : (wn * 64 + j * 16);
;         bfr[kk][j] = *(const bf16x8*)(Bs + (nrow + l15) * 128 + coff);
;       }
;       __builtin_amdgcn_sched_barrier(0);
;     }
; #pragma unroll
;     for (int kk = 0; kk < 2; kk++) {
; #pragma unroll
;       for (int i = 0; i < TM; i++)
; #pragma unroll
;         for (int j = 0; j < NJ; j++) acc[i][j] = SWAP ? mfma16(bfr[kk][j], af[kk][i], acc[i][j]) : mfma16(af[kk][i], bfr[kk][j], acc[i][j]);
;       __builtin_amdgcn_sched_barrier(0);
;     }
;   }
	global_load_lds_dwordx4 v[32:33], off
	v_lshl_add_u64 v[32:33], v[6:7], 0, s[26:27]
	s_mov_b32 m0, s49
	s_nop 0
	global_load_lds_dwordx4 v[32:33], off
	v_lshl_add_u64 v[32:33], v[8:9], 0, s[26:27]
	s_mov_b32 m0, s50
	s_nop 0
	global_load_lds_dwordx4 v[32:33], off
	ds_read_b128 v[32:35], v4 offset:24576
	ds_read_b128 v[36:39], v12 offset:32768
	ds_read_b128 v[40:43], v12 offset:34816
	ds_read_b128 v[44:47], v12 offset:36864
	ds_read_b128 v[48:51], v12 offset:38912
	ds_read_b128 v[52:55], v14 offset:24576
	ds_read_b128 v[56:59], v13 offset:32768
	ds_read_b128 v[60:63], v13 offset:34816
	ds_read_b128 v[64:67], v13 offset:36864
	ds_read_b128 v[68:71], v13 offset:38912
	s_waitcnt lgkmcnt(0)
	v_mfma_f32_16x16x32_bf16 v[20:23], v[36:39], v[32:35], v[20:23]
	v_mfma_f32_16x16x32_bf16 v[24:27], v[40:43], v[32:35], v[24:27]
	v_mfma_f32_16x16x32_bf16 v[28:31], v[44:47], v[32:35], v[28:31]
	v_mfma_f32_16x16x32_bf16 v[16:19], v[48:51], v[32:35], v[16:19]
	v_mfma_f32_16x16x32_bf16 v[20:23], v[56:59], v[52:55], v[20:23]
	v_mfma_f32_16x16x32_bf16 v[24:27], v[60:63], v[52:55], v[24:27]
	v_mfma_f32_16x16x32_bf16 v[28:31], v[64:67], v[52:55], v[28:31]
	v_mfma_f32_16x16x32_bf16 v[16:19], v[68:71], v[52:55], v[16:19]
	s_mov_b32 m0, s57
	s_waitcnt vmcnt(3)
	v_lshl_add_u64 v[32:33], v[10:11], 0, s[28:29]
	s_waitcnt lgkmcnt(0)
	s_barrier
	global_load_lds_dwordx4 v[32:33], off
	v_lshl_add_u64 v[32:33], v[6:7], 0, s[28:29]
	s_mov_b32 m0, s55
	s_nop 0
	global_load_lds_dwordx4 v[32:33], off
	v_lshl_add_u64 v[32:33], v[8:9], 0, s[28:29]
	s_mov_b32 m0, s56
	s_nop 0
	global_load_lds_dwordx4 v[32:33], off
	ds_read_b128 v[32:35], v4 offset:49152
	ds_read_b128 v[36:39], v12 offset:57344
	ds_read_b128 v[40:43], v12 offset:59392
	ds_read_b128 v[44:47], v12 offset:61440
	ds_read_b128 v[48:51], v12 offset:63488
	ds_read_b128 v[52:55], v14 offset:49152
	ds_read_b128 v[56:59], v13 offset:57344
	ds_read_b128 v[60:63], v13 offset:59392
	ds_read_b128 v[64:67], v13 offset:61440
	ds_read_b128 v[68:71], v13 offset:63488
	s_waitcnt lgkmcnt(0)
	v_mfma_f32_16x16x32_bf16 v[20:23], v[36:39], v[32:35], v[20:23]
	v_mfma_f32_16x16x32_bf16 v[24:27], v[40:43], v[32:35], v[24:27]
	v_mfma_f32_16x16x32_bf16 v[28:31], v[44:47], v[32:35], v[28:31]
	v_mfma_f32_16x16x32_bf16 v[16:19], v[48:51], v[32:35], v[16:19]
	v_mfma_f32_16x16x32_bf16 v[20:23], v[56:59], v[52:55], v[20:23]
	v_mfma_f32_16x16x32_bf16 v[24:27], v[60:63], v[52:55], v[24:27]
	v_mfma_f32_16x16x32_bf16 v[28:31], v[64:67], v[52:55], v[28:31]
	v_mfma_f32_16x16x32_bf16 v[16:19], v[68:71], v[52:55], v[16:19]
	s_mov_b32 m0, s54
	s_waitcnt vmcnt(3)
	v_lshl_add_u64 v[32:33], v[10:11], 0, s[30:31]
	s_waitcnt lgkmcnt(0)
	s_barrier
	global_load_lds_dwordx4 v[32:33], off
	v_lshl_add_u64 v[32:33], v[6:7], 0, s[30:31]
	s_mov_b32 m0, s52
	s_nop 0
	global_load_lds_dwordx4 v[32:33], off
	v_lshl_add_u64 v[32:33], v[8:9], 0, s[30:31]
	s_mov_b32 m0, s53
	s_nop 0
	global_load_lds_dwordx4 v[32:33], off
	ds_read_b128 v[32:35], v4
	ds_read_b128 v[36:39], v12 offset:8192
	ds_read_b128 v[40:43], v12 offset:10240
	ds_read_b128 v[44:47], v12 offset:12288
	ds_read_b128 v[48:51], v12 offset:14336
	ds_read_b128 v[52:55], v14
	ds_read_b128 v[56:59], v13 offset:8192
	ds_read_b128 v[60:63], v13 offset:10240
	ds_read_b128 v[64:67], v13 offset:12288
	ds_read_b128 v[68:71], v13 offset:14336
	s_waitcnt lgkmcnt(0)
	v_mfma_f32_16x16x32_bf16 v[20:23], v[36:39], v[32:35], v[20:23]
	v_mfma_f32_16x16x32_bf16 v[24:27], v[40:43], v[32:35], v[24:27]
	v_mfma_f32_16x16x32_bf16 v[28:31], v[44:47], v[32:35], v[28:31]
	v_mfma_f32_16x16x32_bf16 v[16:19], v[48:51], v[32:35], v[16:19]
	v_mfma_f32_16x16x32_bf16 v[20:23], v[56:59], v[52:55], v[20:23]
	v_mfma_f32_16x16x32_bf16 v[24:27], v[60:63], v[52:55], v[24:27]
	v_mfma_f32_16x16x32_bf16 v[28:31], v[64:67], v[52:55], v[28:31]
	v_mfma_f32_16x16x32_bf16 v[16:19], v[68:71], v[52:55], v[16:19]
	s_mov_b32 m0, s51
	s_waitcnt vmcnt(3)
	v_lshl_add_u64 v[32:33], v[10:11], 0, s[34:35]
	s_waitcnt lgkmcnt(0)
	s_barrier
	global_load_lds_dwordx4 v[32:33], off
	v_lshl_add_u64 v[32:33], v[6:7], 0, s[34:35]
	s_mov_b32 m0, s49
	s_nop 0
	global_load_lds_dwordx4 v[32:33], off
	v_lshl_add_u64 v[32:33], v[8:9], 0, s[34:35]
	s_mov_b32 m0, s50
	s_nop 0
	global_load_lds_dwordx4 v[32:33], off
	ds_read_b128 v[32:35], v4 offset:24576
	ds_read_b128 v[36:39], v12 offset:32768
	ds_read_b128 v[40:43], v12 offset:34816
	ds_read_b128 v[44:47], v12 offset:36864
	ds_read_b128 v[48:51], v12 offset:38912
	ds_read_b128 v[52:55], v14 offset:24576
	ds_read_b128 v[56:59], v13 offset:32768
	ds_read_b128 v[60:63], v13 offset:34816
	ds_read_b128 v[64:67], v13 offset:36864
	ds_read_b128 v[68:71], v13 offset:38912
	s_waitcnt lgkmcnt(0)
	v_mfma_f32_16x16x32_bf16 v[20:23], v[36:39], v[32:35], v[20:23]
	v_mfma_f32_16x16x32_bf16 v[24:27], v[40:43], v[32:35], v[24:27]
	v_mfma_f32_16x16x32_bf16 v[28:31], v[44:47], v[32:35], v[28:31]
	v_mfma_f32_16x16x32_bf16 v[16:19], v[48:51], v[32:35], v[16:19]
	v_mfma_f32_16x16x32_bf16 v[20:23], v[56:59], v[52:55], v[20:23]
	v_mfma_f32_16x16x32_bf16 v[24:27], v[60:63], v[52:55], v[24:27]
	v_mfma_f32_16x16x32_bf16 v[28:31], v[64:67], v[52:55], v[28:31]
	v_mfma_f32_16x16x32_bf16 v[16:19], v[68:71], v[52:55], v[16:19]
	s_mov_b32 m0, s57
	s_waitcnt vmcnt(3)
	v_lshl_add_u64 v[32:33], v[10:11], 0, s[36:37]
	s_waitcnt lgkmcnt(0)
	s_barrier
; DI f32x4 mfma16(bf16x8 a, bf16x8 b, f32x4 c) { return __builtin_amdgcn_mfma_f32_16x16x32_bf16(a, b, c, 0, 0, 0); }
; #define RAW_BARRIER() do { asm volatile("s_waitcnt lgkmcnt(0)" ::: "memory"); __builtin_amdgcn_s_barrier(); } while (0)
; template <int N> DI void wait_vmcnt() { asm volatile("s_waitcnt vmcnt(%0)" ::"n"(N) : "memory"); }
;     ...
;   for (int kt = 0; kt < 16; kt++) {
;     if (NST == 3) { if (kt + 1 < 16) wait_vmcnt<NI>(); else wait_vmcnt<0>(); }
;     else wait_vmcnt<0>();
;     RAW_BARRIER();
;     if (NST == 3) { if (kt + 2 < 16) glds(kt + 2, (kt + 2) % 3); }
;     else { if (kt + 1 < 16) glds(kt + 1, (kt + 1) & 1); }
;     const char* As = smem + (NST == 3 ? kt % 3 : kt & 1) * STAGE;
;     const char* Bs = As + BM * 128;
;     bf16x8 af[2][TM], bfr[2][NJ];
; #pragma unroll
;     for (int kk = 0; kk < 2; kk++) {
;       const int coff = ((kk * 4 + l4) ^ swz) << 4;
; #pragma unroll
;       for (int i = 0; i < TM; i++) af[kk][i] = *(const bf16x8*)(As + (wm * (TM * 16) + i * 16 + l15) * 128 + coff);
; #pragma unroll
;       for (int j = 0; j < NJ; j++) {
;         int nrow = MERGE ? ((j >> 1) * 64 + wn * 32 + (j & 1) * 16) : (wn * 64 + j * 16);
;         bfr[kk][j] = *(const bf16x8*)(Bs + (nrow + l15) * 128 + coff);
;       }
;       __builtin_amdgcn_sched_barrier(0);
;     }
; #pragma unroll
;     for (int kk = 0; kk < 2; kk++) {
; #pragma unroll
;       for (int i = 0; i < TM; i++)
; #pragma unroll
;         for (int j = 0; j < NJ; j++) acc[i][j] = SWAP ? mfma16(bfr[kk][j], af[kk][i], acc[i][j]) : mfma16(af[kk][i], bfr[kk][j], acc[i][j]);
;       __builtin_amdgcn_sched_barrier(0);
;     }
;   }
	global_load_lds_dwordx4 v[32:33], off
	v_lshl_add_u64 v[32:33], v[6:7], 0, s[36:37]
	s_mov_b32 m0, s55
	s_nop 0
	global_load_lds_dwordx4 v[32:33], off
	v_lshl_add_u64 v[32:33], v[8:9], 0, s[36:37]
	s_mov_b32 m0, s56
	s_nop 0
	global_load_lds_dwordx4 v[32:33], off
	ds_read_b128 v[32:35], v4 offset:49152
	ds_read_b128 v[36:39], v12 offset:57344
	ds_read_b128 v[40:43], v12 offset:59392
	ds_read_b128 v[44:47], v12 offset:61440
	ds_read_b128 v[48:51], v12 offset:63488
	ds_read_b128 v[52:55], v14 offset:49152
	ds_read_b128 v[56:59], v13 offset:57344
	ds_read_b128 v[60:63], v13 offset:59392
	ds_read_b128 v[64:67], v13 offset:61440
	ds_read_b128 v[68:71], v13 offset:63488
	s_waitcnt lgkmcnt(0)
	v_mfma_f32_16x16x32_bf16 v[20:23], v[36:39], v[32:35], v[20:23]
	v_mfma_f32_16x16x32_bf16 v[24:27], v[40:43], v[32:35], v[24:27]
	v_mfma_f32_16x16x32_bf16 v[28:31], v[44:47], v[32:35], v[28:31]
	v_mfma_f32_16x16x32_bf16 v[16:19], v[48:51], v[32:35], v[16:19]
	v_mfma_f32_16x16x32_bf16 v[20:23], v[56:59], v[52:55], v[20:23]
	v_mfma_f32_16x16x32_bf16 v[24:27], v[60:63], v[52:55], v[24:27]
	v_mfma_f32_16x16x32_bf16 v[28:31], v[64:67], v[52:55], v[28:31]
	v_mfma_f32_16x16x32_bf16 v[16:19], v[68:71], v[52:55], v[16:19]
	s_mov_b32 m0, s54
	s_waitcnt vmcnt(3)
	v_lshl_add_u64 v[32:33], v[10:11], 0, s[38:39]
	s_waitcnt lgkmcnt(0)
	s_barrier
	global_load_lds_dwordx4 v[32:33], off
	v_lshl_add_u64 v[32:33], v[6:7], 0, s[38:39]
	s_mov_b32 m0, s52
	s_nop 0
	global_load_lds_dwordx4 v[32:33], off
	v_lshl_add_u64 v[32:33], v[8:9], 0, s[38:39]
	s_mov_b32 m0, s53
	s_nop 0
	global_load_lds_dwordx4 v[32:33], off
	ds_read_b128 v[32:35], v4
	ds_read_b128 v[36:39], v12 offset:8192
	ds_read_b128 v[40:43], v12 offset:10240
	ds_read_b128 v[44:47], v12 offset:12288
	ds_read_b128 v[48:51], v12 offset:14336
	ds_read_b128 v[52:55], v14
	ds_read_b128 v[56:59], v13 offset:8192
	ds_read_b128 v[60:63], v13 offset:10240
	ds_read_b128 v[64:67], v13 offset:12288
	ds_read_b128 v[68:71], v13 offset:14336
	s_waitcnt lgkmcnt(0)
	v_mfma_f32_16x16x32_bf16 v[20:23], v[36:39], v[32:35], v[20:23]
	v_mfma_f32_16x16x32_bf16 v[24:27], v[40:43], v[32:35], v[24:27]
	v_mfma_f32_16x16x32_bf16 v[28:31], v[44:47], v[32:35], v[28:31]
	v_mfma_f32_16x16x32_bf16 v[16:19], v[48:51], v[32:35], v[16:19]
	v_mfma_f32_16x16x32_bf16 v[20:23], v[56:59], v[52:55], v[20:23]
	v_mfma_f32_16x16x32_bf16 v[24:27], v[60:63], v[52:55], v[24:27]
	v_mfma_f32_16x16x32_bf16 v[28:31], v[64:67], v[52:55], v[28:31]
	v_mfma_f32_16x16x32_bf16 v[16:19], v[68:71], v[52:55], v[16:19]
	s_mov_b32 m0, s51
	s_waitcnt vmcnt(3)
	v_lshl_add_u64 v[10:11], v[10:11], 0, s[40:41]
	s_waitcnt lgkmcnt(0)
	s_barrier
	global_load_lds_dwordx4 v[10:11], off
	v_lshl_add_u64 v[6:7], v[6:7], 0, s[40:41]
	s_mov_b32 m0, s49
	s_nop 0
	global_load_lds_dwordx4 v[6:7], off
	v_lshl_add_u64 v[6:7], v[8:9], 0, s[40:41]
	s_mov_b32 m0, s50
	s_nop 0
	global_load_lds_dwordx4 v[6:7], off
	ds_read_b128 v[6:9], v4 offset:24576
	ds_read_b128 v[32:35], v12 offset:32768
	ds_read_b128 v[36:39], v12 offset:34816
	ds_read_b128 v[40:43], v12 offset:36864
	ds_read_b128 v[44:47], v12 offset:38912
	ds_read_b128 v[48:51], v14 offset:24576
	ds_read_b128 v[52:55], v13 offset:32768
	ds_read_b128 v[56:59], v13 offset:34816
	ds_read_b128 v[60:63], v13 offset:36864
	ds_read_b128 v[64:67], v13 offset:38912
	s_waitcnt lgkmcnt(0)
	v_mfma_f32_16x16x32_bf16 v[20:23], v[32:35], v[6:9], v[20:23]
	v_mfma_f32_16x16x32_bf16 v[24:27], v[36:39], v[6:9], v[24:27]
	v_mfma_f32_16x16x32_bf16 v[28:31], v[40:43], v[6:9], v[28:31]
	v_mfma_f32_16x16x32_bf16 v[6:9], v[44:47], v[6:9], v[16:19]
	v_mfma_f32_16x16x32_bf16 v[16:19], v[52:55], v[48:51], v[20:23]
	v_mfma_f32_16x16x32_bf16 v[20:23], v[56:59], v[48:51], v[24:27]
	v_mfma_f32_16x16x32_bf16 v[24:27], v[60:63], v[48:51], v[28:31]
	v_mfma_f32_16x16x32_bf16 v[6:9], v[64:67], v[48:51], v[6:9]
	s_waitcnt vmcnt(3)
	s_waitcnt lgkmcnt(0)
	s_barrier
; DI f32x4 mfma16(bf16x8 a, bf16x8 b, f32x4 c) { return __builtin_amdgcn_mfma_f32_16x16x32_bf16(a, b, c, 0, 0, 0); }
; #define RAW_BARRIER() do { asm volatile("s_waitcnt lgkmcnt(0)" ::: "memory"); __builtin_amdgcn_s_barrier(); } while (0)
; template <int N> DI void wait_vmcnt() { asm volatile("s_waitcnt vmcnt(%0)" ::"n"(N) : "memory"); }
;     ...
;   for (int kt = 0; kt < 16; kt++) {
;     if (NST == 3) { if (kt + 1 < 16) wait_vmcnt<NI>(); else wait_vmcnt<0>(); }
;     else wait_vmcnt<0>();
;     RAW_BARRIER();
;     if (NST == 3) { if (kt + 2 < 16) glds(kt + 2, (kt + 2) % 3); }
;     else { if (kt + 1 < 16) glds(kt + 1, (kt + 1) & 1); }
;     const char* As = smem + (NST == 3 ? kt % 3 : kt & 1) * STAGE;
;     const char* Bs = As + BM * 128;
;     bf16x8 af[2][TM], bfr[2][NJ];
; #pragma unroll
;     for (int kk = 0; kk < 2; kk++) {
;       const int coff = ((kk * 4 + l4) ^ swz) << 4;
; #pragma unroll
;       for (int i = 0; i < TM; i++) af[kk][i] = *(const bf16x8*)(As + (wm * (TM * 16) + i * 16 + l15) * 128 + coff);
; #pragma unroll
;       for (int j = 0; j < NJ; j++) {
;         int nrow = MERGE ? ((j >> 1) * 64 + wn * 32 + (j & 1) * 16) : (wn * 64 + j * 16);
;         bfr[kk][j] = *(const bf16x8*)(Bs + (nrow + l15) * 128 + coff);
;       }
;       __builtin_amdgcn_sched_barrier(0);
;     }
; #pragma unroll
;     for (int kk = 0; kk < 2; kk++) {
; #pragma unroll
;       for (int i = 0; i < TM; i++)
; #pragma unroll
;         for (int j = 0; j < NJ; j++) acc[i][j] = SWAP ? mfma16(bfr[kk][j], af[kk][i], acc[i][j]) : mfma16(af[kk][i], bfr[kk][j], acc[i][j]);
;       __builtin_amdgcn_sched_barrier(0);
;     }
;   }
;   __syncthreads();
; template <int TM>
; DI void phase7_tile(const P& p, char* smem, int m0, int n0) {
;     ...
; #pragma unroll
;   for (int i = 0; i < TM; i++) {
;     int tok = m0 + wm * (TM * 16) + i * 16 + (lane & 15);
;     const float* xr = tok < TP ? p.x_prompt + (size_t)tok * D : p.x_sample + (size_t)(tok - TP) * D;
; #pragma unroll
;     for (int j = 0; j < 4; j++) {
;       int n = n0 + wn * 64 + j * 16 + 4 * (lane >> 4);
;       float4 xv = *(const float4*)(xr + n);
;       f32x4 a = acc[i][j];
;       *(float4*)(p.out + (size_t)tok * 1024 + n) = make_float4(xv.x + a[0], xv.y + a[1], xv.z + a[2], xv.w + a[3]);
;     }
;   }
	s_nop 1
	ds_read_b128 v[28:31], v12 offset:63488
	ds_read_b128 v[32:35], v12 offset:61440
	ds_read_b128 v[36:39], v12 offset:59392
	ds_read_b128 v[40:43], v12 offset:57344
	ds_read_b128 v[44:47], v4 offset:49152
	ds_read_b128 v[48:51], v14 offset:49152
	ds_read_b128 v[52:55], v13 offset:57344
	ds_read_b128 v[56:59], v13 offset:59392
	ds_read_b128 v[60:63], v13 offset:61440
	ds_read_b128 v[64:67], v13 offset:63488
	s_waitcnt lgkmcnt(0)
	v_mfma_f32_16x16x32_bf16 v[16:19], v[40:43], v[44:47], v[16:19]
	v_mfma_f32_16x16x32_bf16 v[20:23], v[36:39], v[44:47], v[20:23]
	v_mfma_f32_16x16x32_bf16 v[24:27], v[32:35], v[44:47], v[24:27]
	v_mfma_f32_16x16x32_bf16 v[6:9], v[28:31], v[44:47], v[6:9]
	v_mfma_f32_16x16x32_bf16 v[16:19], v[52:55], v[48:51], v[16:19]
	v_mfma_f32_16x16x32_bf16 v[20:23], v[56:59], v[48:51], v[20:23]
	v_mfma_f32_16x16x32_bf16 v[24:27], v[60:63], v[48:51], v[24:27]
	v_mfma_f32_16x16x32_bf16 v[6:9], v[64:67], v[48:51], v[6:9]
	s_waitcnt vmcnt(0)
	s_waitcnt lgkmcnt(0)
	s_barrier
	ds_read_b128 v[28:31], v12 offset:14336
	ds_read_b128 v[32:35], v12 offset:12288
	ds_read_b128 v[36:39], v12 offset:10240
	ds_read_b128 v[40:43], v12 offset:8192
	ds_read_b128 v[44:47], v4
	ds_read_b128 v[48:51], v14
	ds_read_b128 v[52:55], v13 offset:8192
	ds_read_b128 v[56:59], v13 offset:10240
	ds_read_b128 v[60:63], v13 offset:12288
	ds_read_b128 v[10:13], v13 offset:14336
	s_waitcnt lgkmcnt(0)
	v_mfma_f32_16x16x32_bf16 v[14:17], v[40:43], v[44:47], v[16:19]
	v_mfma_f32_16x16x32_bf16 v[18:21], v[36:39], v[44:47], v[20:23]
	v_mfma_f32_16x16x32_bf16 v[22:25], v[32:35], v[44:47], v[24:27]
	v_mfma_f32_16x16x32_bf16 v[6:9], v[28:31], v[44:47], v[6:9]
	v_mfma_f32_16x16x32_bf16 v[14:17], v[52:55], v[48:51], v[14:17]
	v_mfma_f32_16x16x32_bf16 v[18:21], v[56:59], v[48:51], v[18:21]
	v_mfma_f32_16x16x32_bf16 v[22:25], v[60:63], v[48:51], v[22:25]
	v_mfma_f32_16x16x32_bf16 v[6:9], v[10:13], v[48:51], v[6:9]
	v_or_b32_e32 v4, s45, v195
	s_sub_i32 s45, s47, s46
	v_add_u32_e32 v10, s48, v4
	s_add_i32 s45, s45, s33
	v_add_u32_e32 v4, 0xffff8000, v10
	v_ashrrev_i32_e32 v11, 31, v10
	v_add_u32_e32 v12, s45, v89
	v_lshlrev_b64 v[26:27], 12, v[4:5]
	v_lshlrev_b64 v[28:29], 12, v[10:11]
	v_ashrrev_i32_e32 v13, 31, v12
	v_lshl_add_u64 v[30:31], s[20:21], 0, v[28:29]
	v_lshl_add_u64 v[26:27], s[22:23], 0, v[26:27]
	v_cmp_gt_i32_e32 vcc, s43, v10
	v_lshlrev_b64 v[32:33], 2, v[12:13]
	s_waitcnt vmcnt(0)
	v_cndmask_b32_e32 v11, v27, v31, vcc
	v_cndmask_b32_e32 v10, v26, v30, vcc
	v_lshl_add_u64 v[26:27], v[10:11], 0, v[32:33]
	s_barrier
	global_load_dwordx4 v[10:13], v[26:27], off
	v_lshl_add_u64 v[28:29], s[60:61], 0, v[28:29]
	v_lshl_add_u64 v[28:29], v[28:29], 0, v[32:33]
	s_add_i32 s44, s44, s64
	s_add_i32 s33, s33, s42
	s_cmp_lt_i32 s44, 32
	s_waitcnt vmcnt(0)
	v_pk_add_f32 v[10:11], v[14:15], v[10:11]
	v_pk_add_f32 v[12:13], v[16:17], v[12:13]
	global_store_dwordx4 v[28:29], v[10:13], off
	global_load_dwordx4 v[10:13], v[26:27], off offset:64
	s_waitcnt vmcnt(0)
	v_pk_add_f32 v[10:11], v[18:19], v[10:11]
	v_pk_add_f32 v[12:13], v[20:21], v[12:13]
	global_store_dwordx4 v[28:29], v[10:13], off offset:64
	global_load_dwordx4 v[10:13], v[26:27], off offset:128
	s_waitcnt vmcnt(0)
	v_pk_add_f32 v[10:11], v[22:23], v[10:11]
	v_pk_add_f32 v[12:13], v[24:25], v[12:13]
	global_store_dwordx4 v[28:29], v[10:13], off offset:128
	global_load_dwordx4 v[10:13], v[26:27], off offset:192
	s_waitcnt vmcnt(0)
	v_pk_add_f32 v[6:7], v[6:7], v[10:11]
	v_pk_add_f32 v[8:9], v[8:9], v[12:13]
	global_store_dwordx4 v[28:29], v[6:9], off offset:192
	s_cbranch_scc1 .LBB0_847

; DI f32x4 mfma16(bf16x8 a, bf16x8 b, f32x4 c) { return __builtin_amdgcn_mfma_f32_16x16x32_bf16(a, b, c, 0, 0, 0); }
; #define RAW_BARRIER() do { asm volatile("s_waitcnt lgkmcnt(0)" ::: "memory"); __builtin_amdgcn_s_barrier(); } while (0)
; template <int N> DI void wait_vmcnt() { asm volatile("s_waitcnt vmcnt(%0)" ::"n"(N) : "memory"); }
;     ...
;   const int l15 = lane & 15, l4 = lane >> 4;
;   const int swz = (l15 >> 1) & 7;
;   __syncthreads();
;   wait_vmcnt<0>();
;   glds(0, 0);
;   if (NST == 3) glds(1, 1);
;   for (int kt = 0; kt < 16; kt++) {
;     if (NST == 3) { if (kt + 1 < 16) wait_vmcnt<NI>(); else wait_vmcnt<0>(); }
;     else wait_vmcnt<0>();
;     RAW_BARRIER();
;     if (NST == 3) { if (kt + 2 < 16) glds(kt + 2, (kt + 2) % 3); }
;     else { if (kt + 1 < 16) glds(kt + 1, (kt + 1) & 1); }
;     const char* As = smem + (NST == 3 ? kt % 3 : kt & 1) * STAGE;
;     const char* Bs = As + BM * 128;
;     bf16x8 af[2][TM], bfr[2][NJ];
; #pragma unroll
;     for (int kk = 0; kk < 2; kk++) {
;       const int coff = ((kk * 4 + l4) ^ swz) << 4;
; #pragma unroll
;       for (int i = 0; i < TM; i++) af[kk][i] = *(const bf16x8*)(As + (wm * (TM * 16) + i * 16 + l15) * 128 + coff);
; #pragma unroll
;       for (int j = 0; j < NJ; j++) {
;         int nrow = MERGE ? ((j >> 1) * 64 + wn * 32 + (j & 1) * 16) : (wn * 64 + j * 16);
;         bfr[kk][j] = *(const bf16x8*)(Bs + (nrow + l15) * 128 + coff);
;       }
;       __builtin_amdgcn_sched_barrier(0);
;     }
; #pragma unroll
;     for (int kk = 0; kk < 2; kk++) {
; #pragma unroll
;       for (int i = 0; i < TM; i++)
; #pragma unroll
;         for (int j = 0; j < NJ; j++) acc[i][j] = SWAP ? mfma16(bfr[kk][j], af[kk][i], acc[i][j]) : mfma16(af[kk][i], bfr[kk][j], acc[i][j]);
;       __builtin_amdgcn_sched_barrier(0);
;     }
;   }
; template <int TM>
; DI void phase9_tile(const P& p, char* smem, int m0, int nt) {
;     ...
;     auto brow = [&](int r) { return WT + (size_t)(n0 + r) * 1024; };
;     gemm_main<128, false, true, 4, decltype(brow), TM>(HN, m0, brow, smem, acc);
.LBB0_893:
	s_ashr_i32 s44, s49, 31
	s_lshr_b32 s44, s44, 28
	s_add_i32 s44, s49, s44
	v_readfirstlane_b32 s47, v86
	s_lshl_b32 s45, s44, 2
	s_lshr_b32 s50, s47, 6
	s_andn2_b32 s45, s45, 63
	v_lshl_or_b32 v4, s50, 3, v187
	s_add_i32 s45, s45, 0x8000
	s_and_b32 s44, s44, -16
	v_lshrrev_b32_e32 v6, 1, v4
	s_sub_i32 s44, s49, s44
	v_xor_b32_e32 v19, v6, v86
	v_add_u32_e32 v6, s45, v4
	s_lshl_b32 s46, s44, 7
	v_ashrrev_i32_e32 v7, 31, v6
	v_lshl_or_b32 v4, s50, 4, v187
	v_lshlrev_b64 v[10:11], 11, v[6:7]
	v_add_u32_e32 v6, s46, v4
	v_or_b32_e32 v4, 8, v4
	v_lshrrev_b32_e32 v8, 1, v4
	v_xor_b32_e32 v20, v8, v86
	v_add_u32_e32 v8, s46, v4
	v_ashrrev_i32_e32 v9, 31, v8
	v_lshlrev_b64 v[8:9], 11, v[8:9]
	v_lshlrev_b32_e32 v4, 4, v20
	v_lshl_add_u64 v[8:9], s[8:9], 0, v[8:9]
	v_and_b32_e32 v4, 0x70, v4
	s_lshl_b32 s50, s50, 10
	v_ashrrev_i32_e32 v7, 31, v6
	v_lshl_add_u64 v[8:9], v[8:9], 0, v[4:5]
	v_lshlrev_b32_e32 v4, 4, v19
	s_add_i32 s52, s50, 0
	v_lshlrev_b64 v[6:7], 11, v[6:7]
	v_lshl_add_u64 v[10:11], s[6:7], 0, v[10:11]
	v_and_b32_e32 v4, 0x70, v4
	s_add_i32 s54, s52, s50
	v_lshl_add_u64 v[6:7], s[8:9], 0, v[6:7]
	v_lshl_add_u64 v[10:11], v[10:11], 0, v[4:5]
	s_barrier
	s_nop 0
	s_add_i32 s50, s54, 0x2000
	s_mov_b32 m0, s52
	v_lshl_add_u64 v[6:7], v[6:7], 0, v[2:3]
	global_load_lds_dwordx4 v[10:11], off
	s_mov_b32 m0, s50
	s_add_i32 s51, s54, 0x2400
	global_load_lds_dwordx4 v[6:7], off
	s_mov_b32 m0, s51
	s_add_i32 s58, s52, 0x6000
	global_load_lds_dwordx4 v[8:9], off
	s_add_i32 s56, s54, 0x8000
	v_lshl_add_u64 v[20:21], v[10:11], 0, s[12:13]
	s_mov_b32 m0, s58
	s_add_i32 s57, s54, 0x8400
	global_load_lds_dwordx4 v[20:21], off
	v_lshl_add_u64 v[20:21], v[6:7], 0, s[12:13]
	s_mov_b32 m0, s56
	s_add_i32 s55, s52, 0xc000
	global_load_lds_dwordx4 v[20:21], off
	v_lshl_add_u64 v[20:21], v[8:9], 0, s[12:13]
	s_mov_b32 m0, s57
	s_add_i32 s53, s54, 0xe000
	global_load_lds_dwordx4 v[20:21], off
	s_waitcnt vmcnt(3)
	v_lshl_add_u64 v[20:21], v[10:11], 0, s[14:15]
	s_mov_b32 m0, s55
	s_waitcnt lgkmcnt(0)
	s_barrier
	global_load_lds_dwordx4 v[20:21], off
	v_lshl_add_u64 v[20:21], v[6:7], 0, s[14:15]
	s_mov_b32 m0, s53
	s_add_i32 s54, s54, 0xe400
	global_load_lds_dwordx4 v[20:21], off
	v_lshl_add_u64 v[20:21], v[8:9], 0, s[14:15]
	s_mov_b32 m0, s54
	s_lshr_b32 s59, s47, 3
	global_load_lds_dwordx4 v[20:21], off
	s_and_b32 s59, s59, 0x1ffffff0
	v_or_b32_e32 v4, s59, v195
	v_and_or_b32 v19, s47, 64, v195
	v_lshl_add_u32 v22, v4, 7, 0
	v_lshlrev_b32_e32 v21, 7, v19
	v_add_u32_e32 v19, v22, v87
	v_add_u32_e32 v20, v89, v21
	ds_read_b128 v[24:27], v19
	ds_read_b128 v[28:31], v20 offset:8192
	ds_read_b128 v[32:35], v20 offset:10240
	ds_read_b128 v[36:39], v20 offset:12288
	ds_read_b128 v[40:43], v20 offset:14336
	v_add_u32_e32 v22, v22, v88
	v_add_u32_e32 v21, v90, v21
	ds_read_b128 v[44:47], v22
	ds_read_b128 v[48:51], v21 offset:8192
	ds_read_b128 v[52:55], v21 offset:10240
	ds_read_b128 v[56:59], v21 offset:12288
	ds_read_b128 v[60:63], v21 offset:14336
	s_waitcnt lgkmcnt(0)
	v_mfma_f32_16x16x32_bf16 v[28:31], v[28:31], v[24:27], 0
	v_mfma_f32_16x16x32_bf16 v[32:35], v[32:35], v[24:27], 0
	v_mfma_f32_16x16x32_bf16 v[36:39], v[36:39], v[24:27], 0
	v_mfma_f32_16x16x32_bf16 v[24:27], v[40:43], v[24:27], 0
	v_mfma_f32_16x16x32_bf16 v[24:27], v[60:63], v[44:47], v[24:27]
	v_mfma_f32_16x16x32_bf16 v[28:31], v[48:51], v[44:47], v[28:31]
	v_mfma_f32_16x16x32_bf16 v[32:35], v[52:55], v[44:47], v[32:35]
	v_mfma_f32_16x16x32_bf16 v[36:39], v[56:59], v[44:47], v[36:39]
	s_mov_b32 m0, s52
	s_waitcnt vmcnt(3)
	v_lshl_add_u64 v[40:41], v[10:11], 0, s[16:17]
	s_waitcnt lgkmcnt(0)
	s_barrier
	global_load_lds_dwordx4 v[40:41], off
	v_lshl_add_u64 v[40:41], v[6:7], 0, s[16:17]
	s_mov_b32 m0, s50
	s_nop 0
	global_load_lds_dwordx4 v[40:41], off
	v_lshl_add_u64 v[40:41], v[8:9], 0, s[16:17]
	s_mov_b32 m0, s51
	s_nop 0
	global_load_lds_dwordx4 v[40:41], off
	ds_read_b128 v[40:43], v19 offset:24576
	ds_read_b128 v[44:47], v20 offset:32768
	ds_read_b128 v[48:51], v20 offset:34816
	ds_read_b128 v[52:55], v20 offset:36864
	ds_read_b128 v[56:59], v20 offset:38912
	ds_read_b128 v[60:63], v22 offset:24576
	ds_read_b128 v[68:71], v21 offset:32768
	ds_read_b128 v[72:75], v21 offset:34816
	ds_read_b128 v[76:79], v21 offset:36864
	ds_read_b128 v[80:83], v21 offset:38912
	s_waitcnt lgkmcnt(0)
	v_mfma_f32_16x16x32_bf16 v[24:27], v[56:59], v[40:43], v[24:27]
	v_mfma_f32_16x16x32_bf16 v[28:31], v[44:47], v[40:43], v[28:31]
	v_mfma_f32_16x16x32_bf16 v[32:35], v[48:51], v[40:43], v[32:35]
	v_mfma_f32_16x16x32_bf16 v[36:39], v[52:55], v[40:43], v[36:39]
	v_mfma_f32_16x16x32_bf16 v[24:27], v[80:83], v[60:63], v[24:27]
	v_mfma_f32_16x16x32_bf16 v[28:31], v[68:71], v[60:63], v[28:31]
	v_mfma_f32_16x16x32_bf16 v[32:35], v[72:75], v[60:63], v[32:35]
	v_mfma_f32_16x16x32_bf16 v[36:39], v[76:79], v[60:63], v[36:39]
	s_mov_b32 m0, s58
	s_waitcnt vmcnt(3)
	v_lshl_add_u64 v[40:41], v[10:11], 0, s[18:19]
	s_waitcnt lgkmcnt(0)
	s_barrier
	global_load_lds_dwordx4 v[40:41], off
	v_lshl_add_u64 v[40:41], v[6:7], 0, s[18:19]
	s_mov_b32 m0, s56
	s_nop 0
	global_load_lds_dwordx4 v[40:41], off
	v_lshl_add_u64 v[40:41], v[8:9], 0, s[18:19]
	s_mov_b32 m0, s57
	s_nop 0
	global_load_lds_dwordx4 v[40:41], off
	ds_read_b128 v[40:43], v19 offset:49152
	ds_read_b128 v[44:47], v20 offset:57344
	ds_read_b128 v[48:51], v20 offset:59392
	ds_read_b128 v[52:55], v20 offset:61440
	ds_read_b128 v[56:59], v20 offset:63488
	ds_read_b128 v[60:63], v22 offset:49152
	ds_read_b128 v[68:71], v21 offset:57344
	ds_read_b128 v[72:75], v21 offset:59392
	ds_read_b128 v[76:79], v21 offset:61440
	ds_read_b128 v[80:83], v21 offset:63488
	s_waitcnt lgkmcnt(0)
	v_mfma_f32_16x16x32_bf16 v[24:27], v[56:59], v[40:43], v[24:27]
	v_mfma_f32_16x16x32_bf16 v[28:31], v[44:47], v[40:43], v[28:31]
	v_mfma_f32_16x16x32_bf16 v[32:35], v[48:51], v[40:43], v[32:35]
	v_mfma_f32_16x16x32_bf16 v[36:39], v[52:55], v[40:43], v[36:39]
	v_mfma_f32_16x16x32_bf16 v[24:27], v[80:83], v[60:63], v[24:27]
	v_mfma_f32_16x16x32_bf16 v[28:31], v[68:71], v[60:63], v[28:31]
	v_mfma_f32_16x16x32_bf16 v[32:35], v[72:75], v[60:63], v[32:35]
	v_mfma_f32_16x16x32_bf16 v[36:39], v[76:79], v[60:63], v[36:39]
	s_mov_b32 m0, s55
	s_waitcnt vmcnt(3)
	v_lshl_add_u64 v[40:41], v[10:11], 0, s[20:21]
	s_waitcnt lgkmcnt(0)
	s_barrier
; DI f32x4 mfma16(bf16x8 a, bf16x8 b, f32x4 c) { return __builtin_amdgcn_mfma_f32_16x16x32_bf16(a, b, c, 0, 0, 0); }
; #define RAW_BARRIER() do { asm volatile("s_waitcnt lgkmcnt(0)" ::: "memory"); __builtin_amdgcn_s_barrier(); } while (0)
; template <int N> DI void wait_vmcnt() { asm volatile("s_waitcnt vmcnt(%0)" ::"n"(N) : "memory"); }
;     ...
;   for (int kt = 0; kt < 16; kt++) {
;     if (NST == 3) { if (kt + 1 < 16) wait_vmcnt<NI>(); else wait_vmcnt<0>(); }
;     else wait_vmcnt<0>();
;     RAW_BARRIER();
;     if (NST == 3) { if (kt + 2 < 16) glds(kt + 2, (kt + 2) % 3); }
;     else { if (kt + 1 < 16) glds(kt + 1, (kt + 1) & 1); }
;     const char* As = smem + (NST == 3 ? kt % 3 : kt & 1) * STAGE;
;     const char* Bs = As + BM * 128;
;     bf16x8 af[2][TM], bfr[2][NJ];
; #pragma unroll
;     for (int kk = 0; kk < 2; kk++) {
;       const int coff = ((kk * 4 + l4) ^ swz) << 4;
; #pragma unroll
;       for (int i = 0; i < TM; i++) af[kk][i] = *(const bf16x8*)(As + (wm * (TM * 16) + i * 16 + l15) * 128 + coff);
; #pragma unroll
;       for (int j = 0; j < NJ; j++) {
;         int nrow = MERGE ? ((j >> 1) * 64 + wn * 32 + (j & 1) * 16) : (wn * 64 + j * 16);
;         bfr[kk][j] = *(const bf16x8*)(Bs + (nrow + l15) * 128 + coff);
;       }
;       __builtin_amdgcn_sched_barrier(0);
;     }
; #pragma unroll
;     for (int kk = 0; kk < 2; kk++) {
; #pragma unroll
;       for (int i = 0; i < TM; i++)
; #pragma unroll
;         for (int j = 0; j < NJ; j++) acc[i][j] = SWAP ? mfma16(bfr[kk][j], af[kk][i], acc[i][j]) : mfma16(af[kk][i], bfr[kk][j], acc[i][j]);
;       __builtin_amdgcn_sched_barrier(0);
;     }
;   }
	global_load_lds_dwordx4 v[40:41], off
	v_lshl_add_u64 v[40:41], v[6:7], 0, s[20:21]
	s_mov_b32 m0, s53
	s_nop 0
	global_load_lds_dwordx4 v[40:41], off
	v_lshl_add_u64 v[40:41], v[8:9], 0, s[20:21]
	s_mov_b32 m0, s54
	s_nop 0
	global_load_lds_dwordx4 v[40:41], off
	ds_read_b128 v[40:43], v19
	ds_read_b128 v[44:47], v20 offset:8192
	ds_read_b128 v[48:51], v20 offset:10240
	ds_read_b128 v[52:55], v20 offset:12288
	ds_read_b128 v[56:59], v20 offset:14336
	ds_read_b128 v[60:63], v22
	ds_read_b128 v[68:71], v21 offset:8192
	ds_read_b128 v[72:75], v21 offset:10240
	ds_read_b128 v[76:79], v21 offset:12288
	ds_read_b128 v[80:83], v21 offset:14336
	s_waitcnt lgkmcnt(0)
	v_mfma_f32_16x16x32_bf16 v[24:27], v[56:59], v[40:43], v[24:27]
	v_mfma_f32_16x16x32_bf16 v[28:31], v[44:47], v[40:43], v[28:31]
	v_mfma_f32_16x16x32_bf16 v[32:35], v[48:51], v[40:43], v[32:35]
	v_mfma_f32_16x16x32_bf16 v[36:39], v[52:55], v[40:43], v[36:39]
	v_mfma_f32_16x16x32_bf16 v[24:27], v[80:83], v[60:63], v[24:27]
	v_mfma_f32_16x16x32_bf16 v[28:31], v[68:71], v[60:63], v[28:31]
	v_mfma_f32_16x16x32_bf16 v[32:35], v[72:75], v[60:63], v[32:35]
	v_mfma_f32_16x16x32_bf16 v[36:39], v[76:79], v[60:63], v[36:39]
	s_mov_b32 m0, s52
	s_waitcnt vmcnt(3)
	v_lshl_add_u64 v[40:41], v[10:11], 0, s[22:23]
	s_waitcnt lgkmcnt(0)
	s_barrier
	global_load_lds_dwordx4 v[40:41], off
	v_lshl_add_u64 v[40:41], v[6:7], 0, s[22:23]
	s_mov_b32 m0, s50
	s_nop 0
	global_load_lds_dwordx4 v[40:41], off
	v_lshl_add_u64 v[40:41], v[8:9], 0, s[22:23]
	s_mov_b32 m0, s51
	s_nop 0
	global_load_lds_dwordx4 v[40:41], off
	ds_read_b128 v[40:43], v19 offset:24576
	ds_read_b128 v[44:47], v20 offset:32768
	ds_read_b128 v[48:51], v20 offset:34816
	ds_read_b128 v[52:55], v20 offset:36864
	ds_read_b128 v[56:59], v20 offset:38912
	ds_read_b128 v[60:63], v22 offset:24576
	ds_read_b128 v[68:71], v21 offset:32768
	ds_read_b128 v[72:75], v21 offset:34816
	ds_read_b128 v[76:79], v21 offset:36864
	ds_read_b128 v[80:83], v21 offset:38912
	s_waitcnt lgkmcnt(0)
	v_mfma_f32_16x16x32_bf16 v[24:27], v[56:59], v[40:43], v[24:27]
	v_mfma_f32_16x16x32_bf16 v[28:31], v[44:47], v[40:43], v[28:31]
	v_mfma_f32_16x16x32_bf16 v[32:35], v[48:51], v[40:43], v[32:35]
	v_mfma_f32_16x16x32_bf16 v[36:39], v[52:55], v[40:43], v[36:39]
	v_mfma_f32_16x16x32_bf16 v[24:27], v[80:83], v[60:63], v[24:27]
	v_mfma_f32_16x16x32_bf16 v[28:31], v[68:71], v[60:63], v[28:31]
	v_mfma_f32_16x16x32_bf16 v[32:35], v[72:75], v[60:63], v[32:35]
	v_mfma_f32_16x16x32_bf16 v[36:39], v[76:79], v[60:63], v[36:39]
	s_mov_b32 m0, s58
	s_waitcnt vmcnt(3)
	v_lshl_add_u64 v[40:41], v[10:11], 0, s[24:25]
	s_waitcnt lgkmcnt(0)
	s_barrier
	global_load_lds_dwordx4 v[40:41], off
	v_lshl_add_u64 v[40:41], v[6:7], 0, s[24:25]
	s_mov_b32 m0, s56
	s_nop 0
	global_load_lds_dwordx4 v[40:41], off
	v_lshl_add_u64 v[40:41], v[8:9], 0, s[24:25]
	s_mov_b32 m0, s57
	s_nop 0
	global_load_lds_dwordx4 v[40:41], off
	ds_read_b128 v[40:43], v19 offset:49152
	ds_read_b128 v[44:47], v20 offset:57344
	ds_read_b128 v[48:51], v20 offset:59392
	ds_read_b128 v[52:55], v20 offset:61440
	ds_read_b128 v[56:59], v20 offset:63488
	ds_read_b128 v[60:63], v22 offset:49152
	ds_read_b128 v[68:71], v21 offset:57344
	ds_read_b128 v[72:75], v21 offset:59392
	ds_read_b128 v[76:79], v21 offset:61440
	ds_read_b128 v[80:83], v21 offset:63488
	s_waitcnt lgkmcnt(0)
	v_mfma_f32_16x16x32_bf16 v[24:27], v[56:59], v[40:43], v[24:27]
	v_mfma_f32_16x16x32_bf16 v[28:31], v[44:47], v[40:43], v[28:31]
	v_mfma_f32_16x16x32_bf16 v[32:35], v[48:51], v[40:43], v[32:35]
	v_mfma_f32_16x16x32_bf16 v[36:39], v[52:55], v[40:43], v[36:39]
	v_mfma_f32_16x16x32_bf16 v[24:27], v[80:83], v[60:63], v[24:27]
	v_mfma_f32_16x16x32_bf16 v[28:31], v[68:71], v[60:63], v[28:31]
	v_mfma_f32_16x16x32_bf16 v[32:35], v[72:75], v[60:63], v[32:35]
	v_mfma_f32_16x16x32_bf16 v[36:39], v[76:79], v[60:63], v[36:39]
	s_mov_b32 m0, s55
	s_waitcnt vmcnt(3)
	v_lshl_add_u64 v[40:41], v[10:11], 0, s[26:27]
	s_waitcnt lgkmcnt(0)
	s_barrier
	global_load_lds_dwordx4 v[40:41], off
	v_lshl_add_u64 v[40:41], v[6:7], 0, s[26:27]
	s_mov_b32 m0, s53
	s_nop 0
	global_load_lds_dwordx4 v[40:41], off
	v_lshl_add_u64 v[40:41], v[8:9], 0, s[26:27]
	s_mov_b32 m0, s54
	s_nop 0
	global_load_lds_dwordx4 v[40:41], off
	ds_read_b128 v[40:43], v19
	ds_read_b128 v[44:47], v20 offset:8192
	ds_read_b128 v[48:51], v20 offset:10240
	ds_read_b128 v[52:55], v20 offset:12288
	ds_read_b128 v[56:59], v20 offset:14336
	ds_read_b128 v[60:63], v22
	ds_read_b128 v[68:71], v21 offset:8192
	ds_read_b128 v[72:75], v21 offset:10240
	ds_read_b128 v[76:79], v21 offset:12288
	ds_read_b128 v[80:83], v21 offset:14336
	s_waitcnt lgkmcnt(0)
	v_mfma_f32_16x16x32_bf16 v[24:27], v[56:59], v[40:43], v[24:27]
	v_mfma_f32_16x16x32_bf16 v[28:31], v[44:47], v[40:43], v[28:31]
	v_mfma_f32_16x16x32_bf16 v[32:35], v[48:51], v[40:43], v[32:35]
	v_mfma_f32_16x16x32_bf16 v[36:39], v[52:55], v[40:43], v[36:39]
	v_mfma_f32_16x16x32_bf16 v[24:27], v[80:83], v[60:63], v[24:27]
	v_mfma_f32_16x16x32_bf16 v[28:31], v[68:71], v[60:63], v[28:31]
	v_mfma_f32_16x16x32_bf16 v[32:35], v[72:75], v[60:63], v[32:35]
	v_mfma_f32_16x16x32_bf16 v[36:39], v[76:79], v[60:63], v[36:39]
	s_mov_b32 m0, s52
	s_waitcnt vmcnt(3)
	v_lshl_add_u64 v[40:41], v[10:11], 0, s[28:29]
	s_waitcnt lgkmcnt(0)
	s_barrier
; DI f32x4 mfma16(bf16x8 a, bf16x8 b, f32x4 c) { return __builtin_amdgcn_mfma_f32_16x16x32_bf16(a, b, c, 0, 0, 0); }
; #define RAW_BARRIER() do { asm volatile("s_waitcnt lgkmcnt(0)" ::: "memory"); __builtin_amdgcn_s_barrier(); } while (0)
; template <int N> DI void wait_vmcnt() { asm volatile("s_waitcnt vmcnt(%0)" ::"n"(N) : "memory"); }
;     ...
;   for (int kt = 0; kt < 16; kt++) {
;     if (NST == 3) { if (kt + 1 < 16) wait_vmcnt<NI>(); else wait_vmcnt<0>(); }
;     else wait_vmcnt<0>();
;     RAW_BARRIER();
;     if (NST == 3) { if (kt + 2 < 16) glds(kt + 2, (kt + 2) % 3); }
;     else { if (kt + 1 < 16) glds(kt + 1, (kt + 1) & 1); }
;     const char* As = smem + (NST == 3 ? kt % 3 : kt & 1) * STAGE;
;     const char* Bs = As + BM * 128;
;     bf16x8 af[2][TM], bfr[2][NJ];
; #pragma unroll
;     for (int kk = 0; kk < 2; kk++) {
;       const int coff = ((kk * 4 + l4) ^ swz) << 4;
; #pragma unroll
;       for (int i = 0; i < TM; i++) af[kk][i] = *(const bf16x8*)(As + (wm * (TM * 16) + i * 16 + l15) * 128 + coff);
; #pragma unroll
;       for (int j = 0; j < NJ; j++) {
;         int nrow = MERGE ? ((j >> 1) * 64 + wn * 32 + (j & 1) * 16) : (wn * 64 + j * 16);
;         bfr[kk][j] = *(const bf16x8*)(Bs + (nrow + l15) * 128 + coff);
;       }
;       __builtin_amdgcn_sched_barrier(0);
;     }
; #pragma unroll
;     for (int kk = 0; kk < 2; kk++) {
; #pragma unroll
;       for (int i = 0; i < TM; i++)
; #pragma unroll
;         for (int j = 0; j < NJ; j++) acc[i][j] = SWAP ? mfma16(bfr[kk][j], af[kk][i], acc[i][j]) : mfma16(af[kk][i], bfr[kk][j], acc[i][j]);
;       __builtin_amdgcn_sched_barrier(0);
;     }
;   }
	global_load_lds_dwordx4 v[40:41], off
	v_lshl_add_u64 v[40:41], v[6:7], 0, s[28:29]
	s_mov_b32 m0, s50
	s_nop 0
	global_load_lds_dwordx4 v[40:41], off
	v_lshl_add_u64 v[40:41], v[8:9], 0, s[28:29]
	s_mov_b32 m0, s51
	s_nop 0
	global_load_lds_dwordx4 v[40:41], off
	ds_read_b128 v[40:43], v19 offset:24576
	ds_read_b128 v[44:47], v20 offset:32768
	ds_read_b128 v[48:51], v20 offset:34816
	ds_read_b128 v[52:55], v20 offset:36864
	ds_read_b128 v[56:59], v20 offset:38912
	ds_read_b128 v[60:63], v22 offset:24576
	ds_read_b128 v[68:71], v21 offset:32768
	ds_read_b128 v[72:75], v21 offset:34816
	ds_read_b128 v[76:79], v21 offset:36864
	ds_read_b128 v[80:83], v21 offset:38912
	s_waitcnt lgkmcnt(0)
	v_mfma_f32_16x16x32_bf16 v[24:27], v[56:59], v[40:43], v[24:27]
	v_mfma_f32_16x16x32_bf16 v[28:31], v[44:47], v[40:43], v[28:31]
	v_mfma_f32_16x16x32_bf16 v[32:35], v[48:51], v[40:43], v[32:35]
	v_mfma_f32_16x16x32_bf16 v[36:39], v[52:55], v[40:43], v[36:39]
	v_mfma_f32_16x16x32_bf16 v[24:27], v[80:83], v[60:63], v[24:27]
	v_mfma_f32_16x16x32_bf16 v[28:31], v[68:71], v[60:63], v[28:31]
	v_mfma_f32_16x16x32_bf16 v[32:35], v[72:75], v[60:63], v[32:35]
	v_mfma_f32_16x16x32_bf16 v[36:39], v[76:79], v[60:63], v[36:39]
	s_mov_b32 m0, s58
	s_waitcnt vmcnt(3)
	v_lshl_add_u64 v[40:41], v[10:11], 0, s[30:31]
	s_waitcnt lgkmcnt(0)
	s_barrier
	global_load_lds_dwordx4 v[40:41], off
	v_lshl_add_u64 v[40:41], v[6:7], 0, s[30:31]
	s_mov_b32 m0, s56
	s_nop 0
	global_load_lds_dwordx4 v[40:41], off
	v_lshl_add_u64 v[40:41], v[8:9], 0, s[30:31]
	s_mov_b32 m0, s57
	s_nop 0
	global_load_lds_dwordx4 v[40:41], off
	ds_read_b128 v[40:43], v19 offset:49152
	ds_read_b128 v[44:47], v20 offset:57344
	ds_read_b128 v[48:51], v20 offset:59392
	ds_read_b128 v[52:55], v20 offset:61440
	ds_read_b128 v[56:59], v20 offset:63488
	ds_read_b128 v[60:63], v22 offset:49152
	ds_read_b128 v[68:71], v21 offset:57344
	ds_read_b128 v[72:75], v21 offset:59392
	ds_read_b128 v[76:79], v21 offset:61440
	ds_read_b128 v[80:83], v21 offset:63488
	s_waitcnt lgkmcnt(0)
	v_mfma_f32_16x16x32_bf16 v[24:27], v[56:59], v[40:43], v[24:27]
	v_mfma_f32_16x16x32_bf16 v[28:31], v[44:47], v[40:43], v[28:31]
	v_mfma_f32_16x16x32_bf16 v[32:35], v[48:51], v[40:43], v[32:35]
	v_mfma_f32_16x16x32_bf16 v[36:39], v[52:55], v[40:43], v[36:39]
	v_mfma_f32_16x16x32_bf16 v[24:27], v[80:83], v[60:63], v[24:27]
	v_mfma_f32_16x16x32_bf16 v[28:31], v[68:71], v[60:63], v[28:31]
	v_mfma_f32_16x16x32_bf16 v[32:35], v[72:75], v[60:63], v[32:35]
	v_mfma_f32_16x16x32_bf16 v[36:39], v[76:79], v[60:63], v[36:39]
	s_mov_b32 m0, s55
	s_waitcnt vmcnt(3)
	v_lshl_add_u64 v[40:41], v[10:11], 0, s[34:35]
	s_waitcnt lgkmcnt(0)
	s_barrier
	global_load_lds_dwordx4 v[40:41], off
	v_lshl_add_u64 v[40:41], v[6:7], 0, s[34:35]
	s_mov_b32 m0, s53
	s_nop 0
	global_load_lds_dwordx4 v[40:41], off
	v_lshl_add_u64 v[40:41], v[8:9], 0, s[34:35]
	s_mov_b32 m0, s54
	s_nop 0
	global_load_lds_dwordx4 v[40:41], off
	ds_read_b128 v[40:43], v19
	ds_read_b128 v[44:47], v20 offset:8192
	ds_read_b128 v[48:51], v20 offset:10240
	ds_read_b128 v[52:55], v20 offset:12288
	ds_read_b128 v[56:59], v20 offset:14336
	ds_read_b128 v[60:63], v22
	ds_read_b128 v[68:71], v21 offset:8192
	ds_read_b128 v[72:75], v21 offset:10240
	ds_read_b128 v[76:79], v21 offset:12288
	ds_read_b128 v[80:83], v21 offset:14336
	s_waitcnt lgkmcnt(0)
	v_mfma_f32_16x16x32_bf16 v[24:27], v[56:59], v[40:43], v[24:27]
	v_mfma_f32_16x16x32_bf16 v[28:31], v[44:47], v[40:43], v[28:31]
	v_mfma_f32_16x16x32_bf16 v[32:35], v[48:51], v[40:43], v[32:35]
	v_mfma_f32_16x16x32_bf16 v[36:39], v[52:55], v[40:43], v[36:39]
	v_mfma_f32_16x16x32_bf16 v[24:27], v[80:83], v[60:63], v[24:27]
	v_mfma_f32_16x16x32_bf16 v[28:31], v[68:71], v[60:63], v[28:31]
	v_mfma_f32_16x16x32_bf16 v[32:35], v[72:75], v[60:63], v[32:35]
	v_mfma_f32_16x16x32_bf16 v[36:39], v[76:79], v[60:63], v[36:39]
	s_mov_b32 m0, s52
	s_waitcnt vmcnt(3)
	v_lshl_add_u64 v[40:41], v[10:11], 0, s[36:37]
	s_waitcnt lgkmcnt(0)
	s_barrier
	global_load_lds_dwordx4 v[40:41], off
	v_lshl_add_u64 v[40:41], v[6:7], 0, s[36:37]
	s_mov_b32 m0, s50
	s_nop 0
	global_load_lds_dwordx4 v[40:41], off
	v_lshl_add_u64 v[40:41], v[8:9], 0, s[36:37]
	s_mov_b32 m0, s51
	s_nop 0
	global_load_lds_dwordx4 v[40:41], off
	ds_read_b128 v[40:43], v19 offset:24576
	ds_read_b128 v[44:47], v20 offset:32768
	ds_read_b128 v[48:51], v20 offset:34816
	ds_read_b128 v[52:55], v20 offset:36864
	ds_read_b128 v[56:59], v20 offset:38912
	ds_read_b128 v[60:63], v22 offset:24576
	ds_read_b128 v[68:71], v21 offset:32768
	ds_read_b128 v[72:75], v21 offset:34816
	ds_read_b128 v[76:79], v21 offset:36864
	ds_read_b128 v[80:83], v21 offset:38912
	s_waitcnt lgkmcnt(0)
	v_mfma_f32_16x16x32_bf16 v[24:27], v[56:59], v[40:43], v[24:27]
	v_mfma_f32_16x16x32_bf16 v[28:31], v[44:47], v[40:43], v[28:31]
	v_mfma_f32_16x16x32_bf16 v[32:35], v[48:51], v[40:43], v[32:35]
	v_mfma_f32_16x16x32_bf16 v[36:39], v[52:55], v[40:43], v[36:39]
	v_mfma_f32_16x16x32_bf16 v[24:27], v[80:83], v[60:63], v[24:27]
	v_mfma_f32_16x16x32_bf16 v[28:31], v[68:71], v[60:63], v[28:31]
	v_mfma_f32_16x16x32_bf16 v[32:35], v[72:75], v[60:63], v[32:35]
	v_mfma_f32_16x16x32_bf16 v[36:39], v[76:79], v[60:63], v[36:39]
	s_mov_b32 m0, s58
	s_waitcnt vmcnt(3)
	v_lshl_add_u64 v[40:41], v[10:11], 0, s[38:39]
	s_waitcnt lgkmcnt(0)
	s_barrier
; DI f32x4 mfma16(bf16x8 a, bf16x8 b, f32x4 c) { return __builtin_amdgcn_mfma_f32_16x16x32_bf16(a, b, c, 0, 0, 0); }
; #define RAW_BARRIER() do { asm volatile("s_waitcnt lgkmcnt(0)" ::: "memory"); __builtin_amdgcn_s_barrier(); } while (0)
; template <int N> DI void wait_vmcnt() { asm volatile("s_waitcnt vmcnt(%0)" ::"n"(N) : "memory"); }
;     ...
;   for (int kt = 0; kt < 16; kt++) {
;     if (NST == 3) { if (kt + 1 < 16) wait_vmcnt<NI>(); else wait_vmcnt<0>(); }
;     else wait_vmcnt<0>();
;     RAW_BARRIER();
;     if (NST == 3) { if (kt + 2 < 16) glds(kt + 2, (kt + 2) % 3); }
;     else { if (kt + 1 < 16) glds(kt + 1, (kt + 1) & 1); }
;     const char* As = smem + (NST == 3 ? kt % 3 : kt & 1) * STAGE;
;     const char* Bs = As + BM * 128;
;     bf16x8 af[2][TM], bfr[2][NJ];
; #pragma unroll
;     for (int kk = 0; kk < 2; kk++) {
;       const int coff = ((kk * 4 + l4) ^ swz) << 4;
; #pragma unroll
;       for (int i = 0; i < TM; i++) af[kk][i] = *(const bf16x8*)(As + (wm * (TM * 16) + i * 16 + l15) * 128 + coff);
; #pragma unroll
;       for (int j = 0; j < NJ; j++) {
;         int nrow = MERGE ? ((j >> 1) * 64 + wn * 32 + (j & 1) * 16) : (wn * 64 + j * 16);
;         bfr[kk][j] = *(const bf16x8*)(Bs + (nrow + l15) * 128 + coff);
;       }
;       __builtin_amdgcn_sched_barrier(0);
;     }
; #pragma unroll
;     for (int kk = 0; kk < 2; kk++) {
; #pragma unroll
;       for (int i = 0; i < TM; i++)
; #pragma unroll
;         for (int j = 0; j < NJ; j++) acc[i][j] = SWAP ? mfma16(bfr[kk][j], af[kk][i], acc[i][j]) : mfma16(af[kk][i], bfr[kk][j], acc[i][j]);
;       __builtin_amdgcn_sched_barrier(0);
;     }
;   }
;   __syncthreads();
; template <int TM>
; DI void phase9_tile(const P& p, char* smem, int m0, int nt) {
;     ...
; #pragma unroll
;     for (int i = 0; i < 4; i++) {
;       int c = tid + 512 * i, n = c >> 4, d8 = c & 15;
;       *(u32x4*)(Ks + n * 136 + d8 * 8) = *(const u32x4*)(SK + (size_t)(nt * 128 + n) * 128 + d8 * 8);
	global_load_lds_dwordx4 v[40:41], off
	v_lshl_add_u64 v[40:41], v[6:7], 0, s[38:39]
	s_mov_b32 m0, s56
	s_nop 0
	global_load_lds_dwordx4 v[40:41], off
	v_lshl_add_u64 v[40:41], v[8:9], 0, s[38:39]
	s_mov_b32 m0, s57
	s_nop 0
	global_load_lds_dwordx4 v[40:41], off
	ds_read_b128 v[40:43], v19 offset:49152
	ds_read_b128 v[44:47], v20 offset:57344
	ds_read_b128 v[48:51], v20 offset:59392
	ds_read_b128 v[52:55], v20 offset:61440
	ds_read_b128 v[56:59], v20 offset:63488
	ds_read_b128 v[60:63], v22 offset:49152
	ds_read_b128 v[68:71], v21 offset:57344
	ds_read_b128 v[72:75], v21 offset:59392
	ds_read_b128 v[76:79], v21 offset:61440
	ds_read_b128 v[80:83], v21 offset:63488
	s_waitcnt lgkmcnt(0)
	v_mfma_f32_16x16x32_bf16 v[24:27], v[56:59], v[40:43], v[24:27]
	v_mfma_f32_16x16x32_bf16 v[28:31], v[44:47], v[40:43], v[28:31]
	v_mfma_f32_16x16x32_bf16 v[32:35], v[48:51], v[40:43], v[32:35]
	v_mfma_f32_16x16x32_bf16 v[36:39], v[52:55], v[40:43], v[36:39]
	v_mfma_f32_16x16x32_bf16 v[24:27], v[80:83], v[60:63], v[24:27]
	v_mfma_f32_16x16x32_bf16 v[28:31], v[68:71], v[60:63], v[28:31]
	v_mfma_f32_16x16x32_bf16 v[32:35], v[72:75], v[60:63], v[32:35]
	v_mfma_f32_16x16x32_bf16 v[36:39], v[76:79], v[60:63], v[36:39]
	s_mov_b32 m0, s55
	s_waitcnt vmcnt(3)
	v_lshl_add_u64 v[40:41], v[10:11], 0, s[40:41]
	s_waitcnt lgkmcnt(0)
	s_barrier
	global_load_lds_dwordx4 v[40:41], off
	v_lshl_add_u64 v[40:41], v[6:7], 0, s[40:41]
	s_mov_b32 m0, s53
	s_nop 0
	global_load_lds_dwordx4 v[40:41], off
	v_lshl_add_u64 v[40:41], v[8:9], 0, s[40:41]
	s_mov_b32 m0, s54
	s_nop 0
	global_load_lds_dwordx4 v[40:41], off
	ds_read_b128 v[40:43], v19
	ds_read_b128 v[44:47], v20 offset:8192
	ds_read_b128 v[48:51], v20 offset:10240
	ds_read_b128 v[52:55], v20 offset:12288
	ds_read_b128 v[56:59], v20 offset:14336
	ds_read_b128 v[60:63], v22
	ds_read_b128 v[68:71], v21 offset:8192
	ds_read_b128 v[72:75], v21 offset:10240
	ds_read_b128 v[76:79], v21 offset:12288
	ds_read_b128 v[80:83], v21 offset:14336
	s_waitcnt lgkmcnt(0)
	v_mfma_f32_16x16x32_bf16 v[24:27], v[56:59], v[40:43], v[24:27]
	v_mfma_f32_16x16x32_bf16 v[28:31], v[44:47], v[40:43], v[28:31]
	v_mfma_f32_16x16x32_bf16 v[32:35], v[48:51], v[40:43], v[32:35]
	v_mfma_f32_16x16x32_bf16 v[36:39], v[52:55], v[40:43], v[36:39]
	v_mfma_f32_16x16x32_bf16 v[24:27], v[80:83], v[60:63], v[24:27]
	v_mfma_f32_16x16x32_bf16 v[28:31], v[68:71], v[60:63], v[28:31]
	v_mfma_f32_16x16x32_bf16 v[32:35], v[72:75], v[60:63], v[32:35]
	v_mfma_f32_16x16x32_bf16 v[36:39], v[76:79], v[60:63], v[36:39]
	s_mov_b32 m0, s52
	s_waitcnt vmcnt(3)
	v_lshl_add_u64 v[10:11], v[10:11], 0, s[42:43]
	s_waitcnt lgkmcnt(0)
	s_barrier
	global_load_lds_dwordx4 v[10:11], off
	v_lshl_add_u64 v[6:7], v[6:7], 0, s[42:43]
	s_mov_b32 m0, s50
	s_nop 0
	global_load_lds_dwordx4 v[6:7], off
	v_lshl_add_u64 v[6:7], v[8:9], 0, s[42:43]
	s_mov_b32 m0, s51
	s_nop 0
	global_load_lds_dwordx4 v[6:7], off
	ds_read_b128 v[6:9], v19 offset:24576
	ds_read_b128 v[40:43], v20 offset:32768
	ds_read_b128 v[44:47], v20 offset:34816
	ds_read_b128 v[48:51], v20 offset:36864
	ds_read_b128 v[52:55], v20 offset:38912
	ds_read_b128 v[56:59], v22 offset:24576
	ds_read_b128 v[60:63], v21 offset:32768
	ds_read_b128 v[68:71], v21 offset:34816
	ds_read_b128 v[72:75], v21 offset:36864
	ds_read_b128 v[76:79], v21 offset:38912
	s_waitcnt lgkmcnt(0)
	v_mfma_f32_16x16x32_bf16 v[28:31], v[40:43], v[6:9], v[28:31]
	v_mfma_f32_16x16x32_bf16 v[32:35], v[44:47], v[6:9], v[32:35]
	v_mfma_f32_16x16x32_bf16 v[36:39], v[48:51], v[6:9], v[36:39]
	v_mfma_f32_16x16x32_bf16 v[6:9], v[52:55], v[6:9], v[24:27]
	v_mfma_f32_16x16x32_bf16 v[24:27], v[60:63], v[56:59], v[28:31]
	v_mfma_f32_16x16x32_bf16 v[6:9], v[76:79], v[56:59], v[6:9]
	v_mfma_f32_16x16x32_bf16 v[28:31], v[68:71], v[56:59], v[32:35]
	v_mfma_f32_16x16x32_bf16 v[32:35], v[72:75], v[56:59], v[36:39]
	s_waitcnt vmcnt(3)
	s_waitcnt lgkmcnt(0)
	s_barrier
	s_nop 1
	ds_read_b128 v[36:39], v20 offset:63488
	ds_read_b128 v[40:43], v20 offset:61440
	ds_read_b128 v[44:47], v20 offset:59392
	ds_read_b128 v[48:51], v20 offset:57344
	ds_read_b128 v[52:55], v19 offset:49152
	ds_read_b128 v[56:59], v22 offset:49152
	ds_read_b128 v[60:63], v21 offset:57344
	ds_read_b128 v[68:71], v21 offset:59392
	ds_read_b128 v[72:75], v21 offset:61440
	ds_read_b128 v[76:79], v21 offset:63488
	s_waitcnt lgkmcnt(0)
	v_mfma_f32_16x16x32_bf16 v[24:27], v[48:51], v[52:55], v[24:27]
	v_mfma_f32_16x16x32_bf16 v[6:9], v[36:39], v[52:55], v[6:9]
	v_mfma_f32_16x16x32_bf16 v[28:31], v[44:47], v[52:55], v[28:31]
	v_mfma_f32_16x16x32_bf16 v[32:35], v[40:43], v[52:55], v[32:35]
	v_mfma_f32_16x16x32_bf16 v[24:27], v[60:63], v[56:59], v[24:27]
	v_mfma_f32_16x16x32_bf16 v[6:9], v[76:79], v[56:59], v[6:9]
	v_mfma_f32_16x16x32_bf16 v[28:31], v[68:71], v[56:59], v[28:31]
	v_mfma_f32_16x16x32_bf16 v[32:35], v[72:75], v[56:59], v[32:35]
	s_waitcnt vmcnt(0)
	s_waitcnt lgkmcnt(0)
	s_barrier
	ds_read_b128 v[36:39], v20 offset:14336
	ds_read_b128 v[40:43], v20 offset:12288
	ds_read_b128 v[44:47], v20 offset:10240
	ds_read_b128 v[48:51], v20 offset:8192
	ds_read_b128 v[52:55], v19
	s_bfe_u32 s47, s47, 0x10006
	ds_read_b128 v[56:59], v22
	ds_read_b128 v[60:63], v21 offset:8192
	ds_read_b128 v[68:71], v21 offset:10240
	ds_read_b128 v[72:75], v21 offset:12288
	ds_read_b128 v[20:23], v21 offset:14336
	s_waitcnt lgkmcnt(0)
	v_mfma_f32_16x16x32_bf16 v[24:27], v[48:51], v[52:55], v[24:27]
	v_mfma_f32_16x16x32_bf16 v[6:9], v[36:39], v[52:55], v[6:9]
	v_mfma_f32_16x16x32_bf16 v[28:31], v[44:47], v[52:55], v[28:31]
	v_mfma_f32_16x16x32_bf16 v[32:35], v[40:43], v[52:55], v[32:35]
	v_mfma_f32_16x16x32_bf16 v[24:27], v[60:63], v[56:59], v[24:27]
	v_mfma_f32_16x16x32_bf16 v[6:9], v[20:23], v[56:59], v[6:9]
	v_mfma_f32_16x16x32_bf16 v[28:31], v[68:71], v[56:59], v[28:31]
	v_mfma_f32_16x16x32_bf16 v[32:35], v[72:75], v[56:59], v[32:35]
	v_or_b32_e32 v10, s46, v160
	v_or_b32_e32 v20, s46, v92
	v_ashrrev_i32_e32 v11, 31, v10
	v_ashrrev_i32_e32 v21, 31, v20
	v_lshlrev_b64 v[10:11], 8, v[10:11]
	v_lshlrev_b64 v[20:21], 8, v[20:21]
	v_lshl_add_u64 v[10:11], v[66:67], 0, v[10:11]
	v_lshl_add_u64 v[36:37], v[66:67], 0, v[20:21]
	s_waitcnt vmcnt(0)
	s_barrier
; DI u32 pack2(float a, float b) { f32x2 v = {a, b}; bfx2 r = __builtin_convertvector(v, bfx2); return __builtin_bit_cast(u32, r); }
; DI f32x4 mfma16(bf16x8 a, bf16x8 b, f32x4 c) { return __builtin_amdgcn_mfma_f32_16x16x32_bf16(a, b, c, 0, 0, 0); }
; template <int TM>
; DI void phase9_tile(const P& p, char* smem, int m0, int nt) {
;     ...
; #pragma unroll
;     for (int i = 0; i < TM; i++)
; #pragma unroll
;       for (int j = 0; j < 4; j++) {
;         int tl = wm * (TM * 16) + i * 16 + (lane & 15), d = wn * 64 + j * 16 + 4 * (lane >> 4);
;         u32x2 ov = {pack2(acc[i][j][0], acc[i][j][1]), pack2(acc[i][j][2], acc[i][j][3])};
;         *(u32x2*)(Qs + tl * 136 + d) = ov;
;       }
; #pragma unroll
;     for (int i = 0; i < 4; i++) {
;       int c = tid + 512 * i, n = c >> 4, d8 = c & 15;
;       *(u32x4*)(Ks + n * 136 + d8 * 8) = *(const u32x4*)(SK + (size_t)(nt * 128 + n) * 128 + d8 * 8);
;     }
;     __syncthreads();
; #pragma unroll
;     for (int i = 0; i < TM; i++)
; #pragma unroll
;       for (int j = 0; j < 4; j++) acc[i][j] = f32x4{0.f, 0.f, 0.f, 0.f};
; #pragma unroll
;     for (int kk = 0; kk < 4; kk++) {
;       bf16x8 qfr[TM], kfr[4];
; #pragma unroll
;       for (int i = 0; i < TM; i++) qfr[i] = ldfrag(Qs + (wm * (TM * 16) + i * 16 + (lane & 15)) * 136 + kk * 32 + (lane >> 4) * 8);
; #pragma unroll
;       for (int j = 0; j < 4; j++) kfr[j] = ldfrag(Ks + (wn * 64 + j * 16 + (lane & 15)) * 136 + kk * 32 + (lane >> 4) * 8);
; #pragma unroll
;       for (int i = 0; i < TM; i++)
; #pragma unroll
;         for (int j = 0; j < 4; j++) acc[i][j] = mfma16(kfr[j], qfr[i], acc[i][j]);
;     }
;     __syncthreads();
; #pragma unroll
;     for (int i = 0; i < TM; i++)
; #pragma unroll
;       for (int j = 0; j < 4; j++)
; #pragma unroll
;         for (int rr = 0; rr < 4; rr++) {
;           int tl = wm * (TM * 16) + i * 16 + (lane & 15), n = wn * 64 + j * 16 + 4 * (lane >> 4) + rr;
;           Sc[tl * 129 + n] = mono_key(acc[i][j][rr], n);
;         }
;     __syncthreads();
	global_load_dwordx4 v[20:23], v[10:11], off
	s_nop 0
	global_load_dwordx4 v[36:39], v[36:37], off
	v_or_b32_e32 v10, s46, v93
	v_or_b32_e32 v40, s46, v94
	v_ashrrev_i32_e32 v11, 31, v10
	v_ashrrev_i32_e32 v41, 31, v40
	v_lshlrev_b64 v[10:11], 8, v[10:11]
	v_lshlrev_b64 v[40:41], 8, v[40:41]
	v_lshl_add_u64 v[10:11], v[66:67], 0, v[10:11]
	v_lshl_add_u64 v[44:45], v[66:67], 0, v[40:41]
	global_load_dwordx4 v[40:43], v[10:11], off
	s_nop 0
	global_load_dwordx4 v[44:47], v[44:45], off
	v_mul_lo_u32 v19, v4, s33
	s_lshl_b32 s46, s47, 7
	s_lshl_b32 s47, s47, 6
	v_cvt_pk_bf16_f32 v6, v6, v7
	v_cvt_pk_bf16_f32 v7, v8, v9
	v_add_u32_e32 v19, 0, v19
	v_or_b32_e32 v8, s47, v195
	v_cvt_pk_bf16_f32 v10, v24, v25
	v_cvt_pk_bf16_f32 v11, v26, v27
	v_cvt_pk_bf16_f32 v24, v28, v29
	v_cvt_pk_bf16_f32 v25, v30, v31
	v_add3_u32 v9, v19, s46, v14
	v_mad_u32_u24 v56, v8, s33, v96
	v_cvt_pk_bf16_f32 v26, v32, v33
	v_cvt_pk_bf16_f32 v27, v34, v35
	v_mul_lo_u32 v4, v4, s48
	v_add_u32_e32 v4, 0, v4
	s_mov_b32 s46, 64
	ds_write2_b64 v9, v[10:11], v[24:25] offset1:4
	ds_write2_b64 v9, v[26:27], v[6:7] offset0:8 offset1:12
	s_waitcnt vmcnt(3)
	ds_write_b128 v15, v[20:23]
	s_waitcnt vmcnt(2)
	ds_write_b128 v16, v[36:39]
	s_waitcnt vmcnt(1)
	ds_write_b128 v15, v[40:43] offset:17408
	s_waitcnt vmcnt(0)
	ds_write_b128 v17, v[44:47]
	s_waitcnt lgkmcnt(0)
	s_barrier
	ds_read_b128 v[6:9], v56
	v_lshl_add_u32 v10, v95, 1, v19
	ds_read_b128 v[20:23], v10
	ds_read_b128 v[24:27], v10 offset:64
	ds_read_b128 v[28:31], v56 offset:64
	ds_read_b128 v[32:35], v56 offset:4352
	ds_read_b128 v[36:39], v56 offset:4416
	s_waitcnt lgkmcnt(4)
	v_mfma_f32_16x16x32_bf16 v[6:9], v[6:9], v[20:23], 0
	ds_read_b128 v[40:43], v56 offset:8704
	ds_read_b128 v[44:47], v56 offset:8768
	ds_read_b128 v[48:51], v56 offset:13056
	ds_read_b128 v[52:55], v56 offset:13120
	s_waitcnt lgkmcnt(5)
	v_mfma_f32_16x16x32_bf16 v[32:35], v[32:35], v[20:23], 0
	v_mfma_f32_16x16x32_bf16 v[6:9], v[28:31], v[24:27], v[6:9]
	s_waitcnt lgkmcnt(4)
	v_mfma_f32_16x16x32_bf16 v[28:31], v[36:39], v[24:27], v[32:35]
	ds_read_b128 v[36:39], v56 offset:128
	s_waitcnt lgkmcnt(4)
	v_mfma_f32_16x16x32_bf16 v[40:43], v[40:43], v[20:23], 0
	s_waitcnt lgkmcnt(2)
	v_mfma_f32_16x16x32_bf16 v[20:23], v[48:51], v[20:23], 0
	v_mfma_f32_16x16x32_bf16 v[32:35], v[44:47], v[24:27], v[40:43]
	s_waitcnt lgkmcnt(1)
	v_mfma_f32_16x16x32_bf16 v[20:23], v[52:55], v[24:27], v[20:23]
	ds_read_b128 v[24:27], v10 offset:128
	s_nop 1
	ds_read_b128 v[40:43], v10 offset:192
	ds_read_b128 v[44:47], v56 offset:192
	v_or_b32_e32 v10, s47, v91
	v_or_b32_e32 v19, 1, v10
	s_waitcnt lgkmcnt(2)
	v_mfma_f32_16x16x32_bf16 v[6:9], v[36:39], v[24:27], v[6:9]
	ds_read_b128 v[36:39], v56 offset:4480
	ds_read_b128 v[48:51], v56 offset:4544
	v_lshl_add_u32 v11, v10, 2, v4
	s_waitcnt lgkmcnt(1)
	v_mfma_f32_16x16x32_bf16 v[28:31], v[36:39], v[24:27], v[28:31]
	ds_read_b128 v[36:39], v56 offset:8832
	ds_read_b128 v[52:55], v56 offset:8896
	v_mfma_f32_16x16x32_bf16 v[6:9], v[44:47], v[40:43], v[6:9]
	s_waitcnt lgkmcnt(1)
	v_mfma_f32_16x16x32_bf16 v[32:35], v[36:39], v[24:27], v[32:35]
	ds_read_b128 v[36:39], v56 offset:13184
	ds_read_b128 v[56:59], v56 offset:13248
	s_nop 3
	v_cmp_lt_i32_e32 vcc, -1, v7
	s_waitcnt lgkmcnt(0)
	v_mfma_f32_16x16x32_bf16 v[20:23], v[36:39], v[24:27], v[20:23]
	v_or_b32_e32 v36, 3, v10
	v_or_b32_e32 v37, 2, v10
	s_barrier
	v_mfma_f32_16x16x32_bf16 v[24:27], v[48:51], v[40:43], v[28:31]
	v_lshl_add_u32 v38, v37, 2, v4
	v_mfma_f32_16x16x32_bf16 v[28:31], v[52:55], v[40:43], v[32:35]
	s_nop 2
	v_cndmask_b32_e32 v32, -1, v18, vcc
	v_cmp_lt_i32_e32 vcc, -1, v6
	v_xor_b32_e32 v7, v32, v7
	v_and_b32_e32 v7, 0xffffff80, v7
	v_cndmask_b32_e32 v33, -1, v18, vcc
	v_cmp_lt_i32_e32 vcc, -1, v9
	v_xor_b32_e32 v6, v33, v6
	v_and_b32_e32 v6, 0xffffff80, v6
	v_cndmask_b32_e32 v34, -1, v18, vcc
	v_cmp_lt_i32_e32 vcc, -1, v8
	v_xor_b32_e32 v9, v34, v9
	v_and_b32_e32 v9, 0xffffff80, v9
	v_cndmask_b32_e32 v35, -1, v18, vcc
	v_xor_b32_e32 v8, v35, v8
	v_or_b32_e32 v7, v7, v19
	v_or_b32_e32 v6, v6, v10
	v_cmp_lt_i32_e32 vcc, -1, v25
	v_and_b32_e32 v8, 0xffffff80, v8
	ds_write2_b32 v11, v6, v7 offset1:1
	v_or_b32_e32 v6, v9, v36
	v_cndmask_b32_e32 v9, -1, v18, vcc
	v_cmp_lt_i32_e32 vcc, -1, v24
	v_or_b32_e32 v7, v8, v37
	v_xor_b32_e32 v9, v9, v25
	v_cndmask_b32_e32 v11, -1, v18, vcc
	ds_write2_b32 v38, v7, v6 offset1:1
	v_or_b32_e32 v6, 17, v10
	v_xor_b32_e32 v11, v11, v24
	v_and_b32_e32 v9, 0xffffff80, v9
	v_cmp_lt_i32_e32 vcc, -1, v27
	v_or_b32_e32 v7, 16, v10
	v_and_b32_e32 v11, 0xffffff80, v11
	v_or_b32_e32 v6, v9, v6
	v_cndmask_b32_e32 v9, -1, v18, vcc
	v_cmp_lt_i32_e32 vcc, -1, v26
	v_lshl_add_u32 v8, v7, 2, v4
	v_or_b32_e32 v7, v11, v7
	v_cndmask_b32_e32 v11, -1, v18, vcc
	v_xor_b32_e32 v9, v9, v27
	ds_write2_b32 v8, v7, v6 offset1:1
	v_or_b32_e32 v6, 19, v10
	v_xor_b32_e32 v11, v11, v26
	v_and_b32_e32 v9, 0xffffff80, v9
	v_cmp_lt_i32_e32 vcc, -1, v29
	v_or_b32_e32 v7, 18, v10
	v_and_b32_e32 v11, 0xffffff80, v11
	v_or_b32_e32 v6, v9, v6
	v_cndmask_b32_e32 v9, -1, v18, vcc
	v_cmp_lt_i32_e32 vcc, -1, v28
	v_mfma_f32_16x16x32_bf16 v[20:23], v[56:59], v[40:43], v[20:23]
	v_lshl_add_u32 v8, v7, 2, v4
	v_or_b32_e32 v7, v11, v7
	v_cndmask_b32_e32 v11, -1, v18, vcc
	v_xor_b32_e32 v9, v9, v29
	ds_write2_b32 v8, v7, v6 offset1:1
	v_or_b32_e32 v6, 33, v10
	v_xor_b32_e32 v11, v11, v28
	v_and_b32_e32 v9, 0xffffff80, v9
	v_cmp_lt_i32_e32 vcc, -1, v31
	v_or_b32_e32 v7, 32, v10
	v_and_b32_e32 v11, 0xffffff80, v11
	v_or_b32_e32 v6, v9, v6
	v_cndmask_b32_e32 v9, -1, v18, vcc
	v_cmp_lt_i32_e32 vcc, -1, v30
	v_lshl_add_u32 v8, v7, 2, v4
	v_or_b32_e32 v7, v11, v7
	v_cndmask_b32_e32 v11, -1, v18, vcc
	v_xor_b32_e32 v9, v9, v31
	ds_write2_b32 v8, v7, v6 offset1:1
	v_or_b32_e32 v6, 35, v10
	v_xor_b32_e32 v11, v11, v30
	v_and_b32_e32 v9, 0xffffff80, v9
	v_cmp_lt_i32_e32 vcc, -1, v21
	v_or_b32_e32 v7, 34, v10
	v_and_b32_e32 v11, 0xffffff80, v11
	v_or_b32_e32 v6, v9, v6
	v_cndmask_b32_e32 v9, -1, v18, vcc
	v_cmp_lt_i32_e32 vcc, -1, v20
	v_lshl_add_u32 v8, v7, 2, v4
	v_or_b32_e32 v7, v11, v7
	v_cndmask_b32_e32 v11, -1, v18, vcc
	v_xor_b32_e32 v9, v9, v21
	v_xor_b32_e32 v11, v11, v20
	ds_write2_b32 v8, v7, v6 offset1:1
	v_or_b32_e32 v6, 49, v10
	v_or_b32_e32 v7, 48, v10
	v_and_b32_e32 v9, 0xffffff80, v9
	v_and_b32_e32 v11, 0xffffff80, v11
	v_lshl_add_u32 v8, v7, 2, v4
	v_or_b32_e32 v6, v9, v6
	v_or_b32_e32 v7, v11, v7
	v_cmp_lt_i32_e32 vcc, -1, v23
	ds_write2_b32 v8, v7, v6 offset1:1
	v_or_b32_e32 v6, 51, v10
	v_cndmask_b32_e32 v8, -1, v18, vcc
	v_cmp_lt_i32_e32 vcc, -1, v22
	v_xor_b32_e32 v8, v8, v23
	v_or_b32_e32 v7, 50, v10
	v_cndmask_b32_e32 v9, -1, v18, vcc
	v_xor_b32_e32 v9, v9, v22
	v_and_b32_e32 v8, 0xffffff80, v8
	v_and_b32_e32 v9, 0xffffff80, v9
	v_lshl_add_u32 v4, v7, 2, v4
	v_or_b32_e32 v6, v8, v6
	v_or_b32_e32 v7, v9, v7
	ds_write2_b32 v4, v7, v6 offset1:1
	s_waitcnt lgkmcnt(0)
	s_barrier
; DI void bitonic_sort16_desc(u32 (&a)[16]) {
; #pragma unroll
;   for (int k = 2; k <= 16; k <<= 1)
; #pragma unroll
;     for (int j = k >> 1; j > 0; j >>= 1)
; #pragma unroll
;       for (int i = 0; i < 16; i++) {
;         const int l = i ^ j;
;         if (l > i) { if ((i & k) == 0) ce_desc(a[i], a[l]); else ce_desc(a[l], a[i]); }
;       }
; }
; template <int TM>
; DI void phase9_tile(const P& p, char* smem, int m0, int nt) {
;     ...
;     {
;       const int row = tid & 255, half = tid >> 8;
;       const bool rowok = row < TM * 64;
;       u32 tk[16];
;       const u32* src = Sc + (rowok ? row : 0) * 129 + half * 64;
; #pragma unroll
;       for (int i = 0; i < 16; i++) tk[i] = src[i];
;       bitonic_sort16_desc(tk);
	ds_read2_b32 v[6:7], v12 offset1:1
	ds_read2_b32 v[8:9], v12 offset0:2 offset1:3
	ds_read2_b32 v[10:11], v12 offset0:4 offset1:5
	ds_read2_b32 v[20:21], v12 offset0:6 offset1:7
	ds_read2_b32 v[22:23], v12 offset0:8 offset1:9
	ds_read2_b32 v[24:25], v12 offset0:10 offset1:11
	ds_read2_b32 v[26:27], v12 offset0:12 offset1:13
	ds_read2_b32 v[28:29], v12 offset0:14 offset1:15
	s_waitcnt lgkmcnt(7)
	v_max_u32_e32 v4, v6, v7
	v_min_u32_e32 v6, v6, v7
	s_waitcnt lgkmcnt(6)
	v_max_u32_e32 v7, v9, v8
	v_min_u32_e32 v8, v9, v8
	s_waitcnt lgkmcnt(5)
	v_max_u32_e32 v9, v10, v11
	v_min_u32_e32 v10, v10, v11
	s_waitcnt lgkmcnt(4)
	v_max_u32_e32 v11, v21, v20
	v_min_u32_e32 v19, v21, v20
	s_waitcnt lgkmcnt(3)
	v_max_u32_e32 v20, v22, v23
	v_min_u32_e32 v21, v22, v23
	s_waitcnt lgkmcnt(2)
	v_max_u32_e32 v22, v25, v24
	v_min_u32_e32 v23, v25, v24
	s_waitcnt lgkmcnt(1)
	v_max_u32_e32 v24, v26, v27
	v_min_u32_e32 v25, v26, v27
	s_waitcnt lgkmcnt(0)
	v_max_u32_e32 v26, v29, v28
	v_min_u32_e32 v27, v29, v28
	v_max_u32_e32 v28, v4, v8
	v_min_u32_e32 v4, v4, v8
	v_max_u32_e32 v8, v6, v7
	v_min_u32_e32 v6, v6, v7
	v_max_u32_e32 v7, v19, v9
	v_min_u32_e32 v9, v19, v9
	v_max_u32_e32 v19, v11, v10
	v_min_u32_e32 v10, v11, v10
	v_max_u32_e32 v11, v20, v23
	v_min_u32_e32 v20, v20, v23
	v_max_u32_e32 v23, v21, v22
	v_min_u32_e32 v21, v21, v22
	v_max_u32_e32 v22, v27, v24
	v_min_u32_e32 v24, v27, v24
	v_max_u32_e32 v27, v26, v25
	v_min_u32_e32 v25, v26, v25
	v_max_u32_e32 v26, v28, v8
	v_min_u32_e32 v8, v28, v8
	v_max_u32_e32 v28, v4, v6
	v_min_u32_e32 v4, v4, v6
	v_max_u32_e32 v6, v10, v9
	v_min_u32_e32 v9, v10, v9
	v_max_u32_e32 v10, v19, v7
	v_min_u32_e32 v7, v19, v7
	v_max_u32_e32 v19, v11, v23
	v_min_u32_e32 v11, v11, v23
	v_max_u32_e32 v23, v20, v21
	v_min_u32_e32 v20, v20, v21
	v_max_u32_e32 v21, v25, v24
	v_min_u32_e32 v24, v25, v24
	v_max_u32_e32 v25, v27, v22
	v_min_u32_e32 v22, v27, v22
	v_max_u32_e32 v27, v26, v9
	v_min_u32_e32 v9, v26, v9
	v_max_u32_e32 v26, v8, v6
	v_min_u32_e32 v6, v8, v6
	v_max_u32_e32 v8, v28, v7
	v_min_u32_e32 v7, v28, v7
	v_max_u32_e32 v28, v4, v10
	v_min_u32_e32 v4, v4, v10
	v_max_u32_e32 v10, v24, v19
	v_min_u32_e32 v19, v24, v19
	v_max_u32_e32 v24, v21, v11
	v_min_u32_e32 v11, v21, v11
	v_max_u32_e32 v21, v22, v23
	v_min_u32_e32 v22, v22, v23
	v_max_u32_e32 v23, v25, v20
	v_min_u32_e32 v20, v25, v20
	v_max_u32_e32 v25, v27, v8
	v_min_u32_e32 v8, v27, v8
	v_max_u32_e32 v27, v26, v28
	v_min_u32_e32 v26, v26, v28
	v_max_u32_e32 v28, v9, v7
	v_min_u32_e32 v7, v9, v7
	v_max_u32_e32 v9, v6, v4
	v_min_u32_e32 v4, v6, v4
	v_max_u32_e32 v6, v22, v19
	v_min_u32_e32 v19, v22, v19
	v_max_u32_e32 v22, v20, v11
	v_min_u32_e32 v11, v20, v11
	v_max_u32_e32 v20, v21, v10
	v_min_u32_e32 v10, v21, v10
	v_max_u32_e32 v21, v23, v24
	v_min_u32_e32 v23, v23, v24
	v_max_u32_e32 v24, v25, v27
	v_min_u32_e32 v25, v25, v27
	v_max_u32_e32 v27, v8, v26
	v_min_u32_e32 v8, v8, v26
	v_max_u32_e32 v26, v28, v9
	v_min_u32_e32 v9, v28, v9
	v_max_u32_e32 v28, v7, v4
	v_min_u32_e32 v4, v7, v4
	v_max_u32_e32 v7, v11, v19
	v_min_u32_e32 v11, v11, v19
	v_max_u32_e32 v19, v22, v6
	v_min_u32_e32 v6, v22, v6
	v_max_u32_e32 v22, v23, v10
	v_min_u32_e32 v10, v23, v10
	v_max_u32_e32 v23, v21, v20
	v_min_u32_e32 v20, v21, v20
	v_max_u32_e32 v21, v24, v11
	v_min_u32_e32 v11, v24, v11
	v_max_u32_e32 v24, v25, v7
	v_min_u32_e32 v7, v25, v7
	v_max_u32_e32 v25, v27, v6
	v_min_u32_e32 v6, v27, v6
	v_max_u32_e32 v27, v8, v19
	v_min_u32_e32 v8, v8, v19
	v_max_u32_e32 v19, v26, v10
	v_min_u32_e32 v10, v26, v10
	v_max_u32_e32 v26, v9, v22
	v_min_u32_e32 v9, v9, v22
	v_max_u32_e32 v22, v28, v20
	v_min_u32_e32 v20, v28, v20
	v_max_u32_e32 v28, v4, v23
	v_min_u32_e32 v4, v4, v23
	v_max_u32_e32 v23, v21, v19
	v_min_u32_e32 v19, v21, v19
	v_max_u32_e32 v21, v24, v26
	v_min_u32_e32 v24, v24, v26
	v_max_u32_e32 v26, v25, v22
	v_min_u32_e32 v22, v25, v22
	v_max_u32_e32 v25, v27, v28
	v_min_u32_e32 v27, v27, v28
	v_max_u32_e32 v28, v11, v10
	v_min_u32_e32 v10, v11, v10
	v_max_u32_e32 v11, v7, v9
	v_min_u32_e32 v7, v7, v9
	v_max_u32_e32 v9, v6, v20
	v_min_u32_e32 v6, v6, v20
	v_max_u32_e32 v20, v8, v4
	v_min_u32_e32 v4, v8, v4
	v_max_u32_e32 v8, v23, v26
	v_min_u32_e32 v23, v23, v26
	v_max_u32_e32 v26, v21, v25
	v_min_u32_e32 v21, v21, v25
	v_max_u32_e32 v25, v19, v22
	v_min_u32_e32 v19, v19, v22
	v_max_u32_e32 v22, v24, v27
	v_min_u32_e32 v24, v24, v27
	v_max_u32_e32 v27, v28, v9
	v_min_u32_e32 v28, v28, v9
	v_max_u32_e32 v29, v11, v20
	v_min_u32_e32 v11, v11, v20
	v_max_u32_e32 v30, v10, v6
	v_min_u32_e32 v31, v10, v6
	v_max_u32_e32 v32, v7, v4
	v_min_u32_e32 v33, v7, v4
	v_max_u32_e32 v4, v8, v26
	v_min_u32_e32 v20, v8, v26
	v_max_u32_e32 v6, v23, v21
	v_min_u32_e32 v21, v23, v21
	v_max_u32_e32 v7, v25, v22
	v_min_u32_e32 v22, v25, v22
	v_max_u32_e32 v8, v19, v24
	v_min_u32_e32 v23, v19, v24
	v_max_u32_e32 v9, v27, v29
	v_min_u32_e32 v24, v27, v29
	v_max_u32_e32 v10, v28, v11
	v_min_u32_e32 v25, v28, v11
	v_max_u32_e32 v11, v30, v32
	v_min_u32_e32 v26, v30, v32
	v_max_u32_e32 v19, v31, v33
	v_min_u32_e32 v27, v31, v33
